# prio00
# baseline (speedup 1.0000x reference)
; #define STAGE(P, BASE, LD, br, kt) do { const char* _g = (const char*)((BASE) + (size_t)(br) * (LD) + (size_t)(kt) * 64); \
;     for (int _i = 0; _i < 2; ++_i) { int _b = tidx * 16 + _i * 8192; int _r, _c; stage_rc(_b, _r, _c); \
;       __builtin_amdgcn_global_load_lds((const unsigned*)(_g + (unsigned)((_r * (LD) + _c) * 2)), (unsigned*)((char*)(P) + _b), 16, 0, 0); } } while (0)
; #define LDA(dst, b, h) for (int m = 0; m < 4; ++m) for (int k = 0; k < 2; ++k) \
;     dst[m][k] = *reinterpret_cast<const bf16x8*>((char*)SA(b, h) + lds_byte(wr * 64 + m * 16 + fr, k * 32 + fq * 8))
; #define LDB(dst, b, h) for (int n = 0; n < 2; ++n) for (int k = 0; k < 2; ++k) \
;     dst[n][k] = *reinterpret_cast<const bf16x8*>((char*)SB(b, h) + lds_byte(wc * 32 + n * 16 + fr, k * 32 + fq * 8))
; #define MMA(ai, bj, At_, Bt_) do { __builtin_amdgcn_s_setprio(1); \
;     for (int k = 0; k < 2; ++k) for (int m = 0; m < 4; ++m) for (int n = 0; n < 2; ++n) \
;       acc[ai][bj][m][n] = __builtin_amdgcn_mfma_f32_16x16x32_bf16(At_[m][k], Bt_[n][k], acc[ai][bj][m][n], 0, 0, 0); \
;     __builtin_amdgcn_s_setprio(0); } while (0)
; #define WAIT_L(n) asm volatile("s_waitcnt lgkmcnt(" #n ")" ::: "memory")
; #define BAR __builtin_amdgcn_s_barrier()
; #define SCHED __builtin_amdgcn_sched_barrier(0)
; template <int EPI, int lda, int ldb, int N, int K>
; __device__ __forceinline__ void gemm_phase(const u16* __restrict__ A, const u16* __restrict__ Bt, const GemmEpi ep, int wv) {
;     ...
;     for (int t = 0; t < nt - 2; t += 2) {
;       LDB(B0, 0, 0); SCHED; LDA(At, 0, 0); STAGE(SA(1, 1), Ab, lda, brow + HALF, t + 1);
;       WAIT_L(8); BAR; WAIT_L(0); MMA(0, 0, At, B0); BAR; SCHED;
;       LDB(B1, 0, 1); STAGE(SB(0, 0), Bt, ldb, bcol, t + 2);
;       BAR; WAIT_L(0); MMA(0, 1, At, B1); BAR;
;       LDA(At, 0, 1); STAGE(SA(0, 0), Ab, lda, brow, t + 2);
;       BAR; WAIT_L(0); MMA(1, 0, At, B0); BAR; SCHED;
.LBB0_53:
	ds_read_b128 v[172:175], v161
	ds_read_b128 v[176:179], v161 offset:1024
	ds_read_b128 v[180:183], v161 offset:2048
	ds_read_b128 v[184:187], v161 offset:3072
	v_add_u32_e32 v169, 0xc000, v148
	v_lshl_add_u64 v[236:237], v[136:137], 0, s[42:43]
	v_readfirstlane_b32 s45, v169
	v_add_u32_e32 v170, 0xe000, v148
	v_lshl_add_u64 v[162:163], v[236:237], 0, s[14:15]
	s_mov_b32 m0, s45
	v_lshl_add_u64 v[238:239], v[134:135], 0, s[42:43]
	v_readfirstlane_b32 s45, v170
	ds_read_b128 v[164:167], v152
	ds_read_b128 v[188:191], v152 offset:1024
	ds_read_b128 v[192:195], v151
	ds_read_b128 v[196:199], v151 offset:1024
	ds_read_b128 v[200:203], v150
	ds_read_b128 v[204:207], v150 offset:1024
	ds_read_b128 v[208:211], v149
	ds_read_b128 v[212:215], v149 offset:1024
	global_load_lds_dwordx4 v[162:163], off
	v_lshl_add_u64 v[162:163], v[238:239], 0, s[14:15]
	s_mov_b32 m0, s45
	s_nop 0
	global_load_lds_dwordx4 v[162:163], off
	s_waitcnt lgkmcnt(8)
	s_barrier
	s_waitcnt lgkmcnt(0)
	s_setprio 0
	s_waitcnt lgkmcnt(0)
	v_mfma_f32_16x16x32_bf16 v[124:127], v[172:175], v[164:167], v[124:127]
	v_mfma_f32_16x16x32_bf16 v[120:123], v[180:183], v[164:167], v[120:123]
	v_mfma_f32_16x16x32_bf16 v[116:119], v[172:175], v[192:195], v[116:119]
	v_mfma_f32_16x16x32_bf16 v[112:115], v[180:183], v[192:195], v[112:115]
	v_mfma_f32_16x16x32_bf16 v[108:111], v[172:175], v[200:203], v[108:111]
	v_mfma_f32_16x16x32_bf16 v[104:107], v[180:183], v[200:203], v[104:107]
	v_mfma_f32_16x16x32_bf16 v[100:103], v[172:175], v[208:211], v[100:103]
	v_mfma_f32_16x16x32_bf16 v[96:99], v[180:183], v[208:211], v[96:99]
	v_mfma_f32_16x16x32_bf16 v[124:127], v[176:179], v[188:191], v[124:127]
	v_mfma_f32_16x16x32_bf16 v[120:123], v[184:187], v[188:191], v[120:123]
	v_mfma_f32_16x16x32_bf16 v[116:119], v[176:179], v[196:199], v[116:119]
	v_mfma_f32_16x16x32_bf16 v[112:115], v[184:187], v[196:199], v[112:115]
	v_mfma_f32_16x16x32_bf16 v[108:111], v[176:179], v[204:207], v[108:111]
	v_mfma_f32_16x16x32_bf16 v[104:107], v[184:187], v[204:207], v[104:107]
	v_mfma_f32_16x16x32_bf16 v[100:103], v[176:179], v[212:215], v[100:103]
	v_mfma_f32_16x16x32_bf16 v[96:99], v[184:187], v[212:215], v[96:99]
	s_setprio 0
	s_barrier
	v_add_u32_e32 v162, s54, v153
	v_lshl_add_u64 v[240:241], v[140:141], 0, s[42:43]
	v_readfirstlane_b32 s45, v162
	v_add_u32_e32 v163, 0x2000, v162
	v_lshl_add_u64 v[232:233], v[240:241], 0, s[16:17]
	s_mov_b32 m0, s45
	v_lshl_add_u64 v[242:243], v[138:139], 0, s[42:43]
	v_readfirstlane_b32 s45, v163
	ds_read_b128 v[216:219], v160
	ds_read_b128 v[220:223], v160 offset:1024
	ds_read_b128 v[224:227], v160 offset:2048
	ds_read_b128 v[228:231], v160 offset:3072
	global_load_lds_dwordx4 v[232:233], off
	v_lshl_add_u64 v[232:233], v[242:243], 0, s[16:17]
	s_mov_b32 m0, s45
	s_nop 0
	global_load_lds_dwordx4 v[232:233], off
	s_barrier
	s_waitcnt lgkmcnt(0)
	s_setprio 0
	s_waitcnt lgkmcnt(0)
	v_mfma_f32_16x16x32_bf16 v[92:95], v[216:219], v[164:167], v[92:95]
	v_mfma_f32_16x16x32_bf16 v[88:91], v[224:227], v[164:167], v[88:91]
	v_mfma_f32_16x16x32_bf16 v[84:87], v[216:219], v[192:195], v[84:87]
	v_mfma_f32_16x16x32_bf16 v[80:83], v[224:227], v[192:195], v[80:83]
	v_mfma_f32_16x16x32_bf16 v[76:79], v[216:219], v[200:203], v[76:79]
	v_mfma_f32_16x16x32_bf16 v[72:75], v[224:227], v[200:203], v[72:75]
	v_mfma_f32_16x16x32_bf16 v[68:71], v[216:219], v[208:211], v[68:71]
	v_mfma_f32_16x16x32_bf16 v[64:67], v[224:227], v[208:211], v[64:67]
	v_mfma_f32_16x16x32_bf16 v[92:95], v[220:223], v[188:191], v[92:95]
	v_mfma_f32_16x16x32_bf16 v[88:91], v[228:231], v[188:191], v[88:91]
	v_mfma_f32_16x16x32_bf16 v[84:87], v[220:223], v[196:199], v[84:87]
	v_mfma_f32_16x16x32_bf16 v[80:83], v[228:231], v[196:199], v[80:83]
	v_mfma_f32_16x16x32_bf16 v[76:79], v[220:223], v[204:207], v[76:79]
	v_mfma_f32_16x16x32_bf16 v[72:75], v[228:231], v[204:207], v[72:75]
	v_mfma_f32_16x16x32_bf16 v[68:71], v[220:223], v[212:215], v[68:71]
	v_mfma_f32_16x16x32_bf16 v[64:67], v[228:231], v[212:215], v[64:67]
	s_setprio 0
	v_readfirstlane_b32 s45, v148
	v_lshl_add_u64 v[164:165], v[236:237], 0, s[18:19]
	s_mov_b32 m0, s45
	s_barrier
	ds_read_b128 v[188:191], v152 offset:16384
	ds_read_b128 v[192:195], v152 offset:17408
	ds_read_b128 v[196:199], v151 offset:16384
	ds_read_b128 v[200:203], v151 offset:17408
	ds_read_b128 v[204:207], v150 offset:16384
	ds_read_b128 v[208:211], v150 offset:17408
	ds_read_b128 v[212:215], v149 offset:16384
	ds_read_b128 v[232:235], v149 offset:17408
	global_load_lds_dwordx4 v[164:165], off
	v_add_u32_e32 v164, 0x2000, v148
	v_lshl_add_u64 v[166:167], v[238:239], 0, s[18:19]
	v_readfirstlane_b32 s45, v164
	s_mov_b32 m0, s45
	s_nop 0
	global_load_lds_dwordx4 v[166:167], off
	s_barrier
	s_waitcnt lgkmcnt(0)
	s_setprio 0
	s_waitcnt lgkmcnt(0)
	v_mfma_f32_16x16x32_bf16 v[60:63], v[172:175], v[188:191], v[60:63]
	v_mfma_f32_16x16x32_bf16 v[56:59], v[180:183], v[188:191], v[56:59]
	v_mfma_f32_16x16x32_bf16 v[52:55], v[172:175], v[196:199], v[52:55]
	v_mfma_f32_16x16x32_bf16 v[48:51], v[180:183], v[196:199], v[48:51]
	v_mfma_f32_16x16x32_bf16 v[44:47], v[172:175], v[204:207], v[44:47]
	v_mfma_f32_16x16x32_bf16 v[40:43], v[180:183], v[204:207], v[40:43]
	v_mfma_f32_16x16x32_bf16 v[36:39], v[172:175], v[212:215], v[36:39]
	v_mfma_f32_16x16x32_bf16 v[32:35], v[180:183], v[212:215], v[32:35]
	v_mfma_f32_16x16x32_bf16 v[60:63], v[176:179], v[192:195], v[60:63]
	v_mfma_f32_16x16x32_bf16 v[56:59], v[184:187], v[192:195], v[56:59]
	v_mfma_f32_16x16x32_bf16 v[52:55], v[176:179], v[200:203], v[52:55]
	v_mfma_f32_16x16x32_bf16 v[48:51], v[184:187], v[200:203], v[48:51]
	v_mfma_f32_16x16x32_bf16 v[44:47], v[176:179], v[208:211], v[44:47]
	v_mfma_f32_16x16x32_bf16 v[40:43], v[184:187], v[208:211], v[40:43]
	v_mfma_f32_16x16x32_bf16 v[36:39], v[176:179], v[232:235], v[36:39]
	v_mfma_f32_16x16x32_bf16 v[32:35], v[184:187], v[232:235], v[32:35]
	s_setprio 0
	s_barrier
; #define STAGE(P, BASE, LD, br, kt) do { const char* _g = (const char*)((BASE) + (size_t)(br) * (LD) + (size_t)(kt) * 64); \
;     for (int _i = 0; _i < 2; ++_i) { int _b = tidx * 16 + _i * 8192; int _r, _c; stage_rc(_b, _r, _c); \
;       __builtin_amdgcn_global_load_lds((const unsigned*)(_g + (unsigned)((_r * (LD) + _c) * 2)), (unsigned*)((char*)(P) + _b), 16, 0, 0); } } while (0)
; #define LDA(dst, b, h) for (int m = 0; m < 4; ++m) for (int k = 0; k < 2; ++k) \
;     dst[m][k] = *reinterpret_cast<const bf16x8*>((char*)SA(b, h) + lds_byte(wr * 64 + m * 16 + fr, k * 32 + fq * 8))
; #define LDB(dst, b, h) for (int n = 0; n < 2; ++n) for (int k = 0; k < 2; ++k) \
;     dst[n][k] = *reinterpret_cast<const bf16x8*>((char*)SB(b, h) + lds_byte(wc * 32 + n * 16 + fr, k * 32 + fq * 8))
; #define MMA(ai, bj, At_, Bt_) do { __builtin_amdgcn_s_setprio(1); \
;     for (int k = 0; k < 2; ++k) for (int m = 0; m < 4; ++m) for (int n = 0; n < 2; ++n) \
;       acc[ai][bj][m][n] = __builtin_amdgcn_mfma_f32_16x16x32_bf16(At_[m][k], Bt_[n][k], acc[ai][bj][m][n], 0, 0, 0); \
;     __builtin_amdgcn_s_setprio(0); } while (0)
; #define WAIT_V(n) asm volatile("s_waitcnt vmcnt(" #n ")" ::: "memory")
; #define WAIT_L(n) asm volatile("s_waitcnt lgkmcnt(" #n ")" ::: "memory")
; #define BAR __builtin_amdgcn_s_barrier()
; #define SCHED __builtin_amdgcn_sched_barrier(0)
; template <int EPI, int lda, int ldb, int N, int K>
; __device__ __forceinline__ void gemm_phase(const u16* __restrict__ A, const u16* __restrict__ Bt, const GemmEpi ep, int wv) {
;     ...
;       STAGE(SB(0, 1), Bt, ldb, bcol + HALF, t + 2);
;       WAIT_V(6); BAR; MMA(1, 1, At, B1); BAR;
;       LDB(B0, 1, 0); SCHED; LDA(At, 1, 0); STAGE(SA(0, 1), Ab, lda, brow + HALF, t + 2);
;       WAIT_L(8); BAR; WAIT_L(0); MMA(0, 0, At, B0); BAR; SCHED;
;       LDB(B1, 1, 1); STAGE(SB(1, 0), Bt, ldb, bcol, t + 3);
;       BAR; WAIT_L(0); MMA(0, 1, At, B1); BAR;
;       LDA(At, 1, 1); STAGE(SA(1, 0), Ab, lda, brow, t + 3);
	v_add_u32_e32 v165, s55, v153
	v_lshl_add_u64 v[166:167], v[240:241], 0, s[20:21]
	v_readfirstlane_b32 s45, v165
	s_mov_b32 m0, s45
	v_lshl_add_u64 v[172:173], v[242:243], 0, s[20:21]
	global_load_lds_dwordx4 v[166:167], off
	v_add_u32_e32 v166, 0x2000, v165
	s_nop 0
	v_readfirstlane_b32 s45, v166
	s_mov_b32 m0, s45
	s_nop 0
	global_load_lds_dwordx4 v[172:173], off
	s_waitcnt vmcnt(6)
	s_barrier
	s_setprio 0
	v_mfma_f32_16x16x32_bf16 v[28:31], v[216:219], v[188:191], v[28:31]
	v_mfma_f32_16x16x32_bf16 v[24:27], v[224:227], v[188:191], v[24:27]
	v_mfma_f32_16x16x32_bf16 v[20:23], v[216:219], v[196:199], v[20:23]
	v_mfma_f32_16x16x32_bf16 v[16:19], v[224:227], v[196:199], v[16:19]
	v_mfma_f32_16x16x32_bf16 v[12:15], v[216:219], v[204:207], v[12:15]
	v_mfma_f32_16x16x32_bf16 v[8:11], v[224:227], v[204:207], v[8:11]
	v_mfma_f32_16x16x32_bf16 v[4:7], v[216:219], v[212:215], v[4:7]
	v_mfma_f32_16x16x32_bf16 v[0:3], v[224:227], v[212:215], v[0:3]
	v_mfma_f32_16x16x32_bf16 v[28:31], v[220:223], v[192:195], v[28:31]
	v_mfma_f32_16x16x32_bf16 v[24:27], v[228:231], v[192:195], v[24:27]
	v_mfma_f32_16x16x32_bf16 v[20:23], v[220:223], v[200:203], v[20:23]
	v_mfma_f32_16x16x32_bf16 v[16:19], v[228:231], v[200:203], v[16:19]
	v_mfma_f32_16x16x32_bf16 v[12:15], v[220:223], v[208:211], v[12:15]
	v_mfma_f32_16x16x32_bf16 v[8:11], v[228:231], v[208:211], v[8:11]
	v_mfma_f32_16x16x32_bf16 v[4:7], v[220:223], v[232:235], v[4:7]
	v_mfma_f32_16x16x32_bf16 v[0:3], v[228:231], v[232:235], v[0:3]
	s_setprio 0
	s_barrier
	ds_read_b128 v[172:175], v156
	ds_read_b128 v[176:179], v156 offset:1024
	ds_read_b128 v[180:183], v156 offset:2048
	ds_read_b128 v[184:187], v156 offset:3072
	v_add_u32_e32 v167, 0x4000, v148
	v_add_u32_e32 v168, 0x6000, v148
	v_readfirstlane_b32 s45, v167
	v_lshl_add_u64 v[220:221], v[236:237], 0, s[22:23]
	s_mov_b32 m0, s45
	v_readfirstlane_b32 s45, v168
	ds_read_b128 v[188:191], v152 offset:32768
	ds_read_b128 v[192:195], v152 offset:33792
	ds_read_b128 v[196:199], v151 offset:32768
	ds_read_b128 v[200:203], v151 offset:33792
	ds_read_b128 v[204:207], v150 offset:32768
	ds_read_b128 v[208:211], v150 offset:33792
	ds_read_b128 v[212:215], v149 offset:32768
	ds_read_b128 v[216:219], v149 offset:33792
	global_load_lds_dwordx4 v[220:221], off
	v_lshl_add_u64 v[220:221], v[238:239], 0, s[22:23]
	s_mov_b32 m0, s45
	s_nop 0
	global_load_lds_dwordx4 v[220:221], off
	s_waitcnt lgkmcnt(8)
	s_barrier
	s_waitcnt lgkmcnt(0)
	s_setprio 0
	s_waitcnt lgkmcnt(0)
	v_mfma_f32_16x16x32_bf16 v[124:127], v[172:175], v[188:191], v[124:127]
	v_mfma_f32_16x16x32_bf16 v[120:123], v[180:183], v[188:191], v[120:123]
	v_mfma_f32_16x16x32_bf16 v[116:119], v[172:175], v[196:199], v[116:119]
	v_mfma_f32_16x16x32_bf16 v[112:115], v[180:183], v[196:199], v[112:115]
	v_mfma_f32_16x16x32_bf16 v[108:111], v[172:175], v[204:207], v[108:111]
	v_mfma_f32_16x16x32_bf16 v[104:107], v[180:183], v[204:207], v[104:107]
	v_mfma_f32_16x16x32_bf16 v[100:103], v[172:175], v[212:215], v[100:103]
	v_mfma_f32_16x16x32_bf16 v[96:99], v[180:183], v[212:215], v[96:99]
	v_mfma_f32_16x16x32_bf16 v[124:127], v[176:179], v[192:195], v[124:127]
	v_mfma_f32_16x16x32_bf16 v[120:123], v[184:187], v[192:195], v[120:123]
	v_mfma_f32_16x16x32_bf16 v[116:119], v[176:179], v[200:203], v[116:119]
	v_mfma_f32_16x16x32_bf16 v[112:115], v[184:187], v[200:203], v[112:115]
	v_mfma_f32_16x16x32_bf16 v[108:111], v[176:179], v[208:211], v[108:111]
	v_mfma_f32_16x16x32_bf16 v[104:107], v[184:187], v[208:211], v[104:107]
	v_mfma_f32_16x16x32_bf16 v[100:103], v[176:179], v[216:219], v[100:103]
	v_mfma_f32_16x16x32_bf16 v[96:99], v[184:187], v[216:219], v[96:99]
	s_setprio 0
	s_barrier
	v_readfirstlane_b32 s45, v155
	v_add_u32_e32 v171, 0x2000, v155
	v_lshl_add_u64 v[244:245], v[240:241], 0, s[24:25]
	s_mov_b32 m0, s45
	v_readfirstlane_b32 s45, v171
	ds_read_b128 v[220:223], v154
	ds_read_b128 v[224:227], v154 offset:1024
	ds_read_b128 v[228:231], v154 offset:2048
	ds_read_b128 v[232:235], v154 offset:3072
	global_load_lds_dwordx4 v[244:245], off
	v_lshl_add_u64 v[244:245], v[242:243], 0, s[24:25]
	s_mov_b32 m0, s45
	s_nop 0
	global_load_lds_dwordx4 v[244:245], off
	s_barrier
	s_waitcnt lgkmcnt(0)
	s_setprio 0
	s_waitcnt lgkmcnt(0)
	v_mfma_f32_16x16x32_bf16 v[92:95], v[220:223], v[188:191], v[92:95]
	v_mfma_f32_16x16x32_bf16 v[88:91], v[228:231], v[188:191], v[88:91]
	v_mfma_f32_16x16x32_bf16 v[84:87], v[220:223], v[196:199], v[84:87]
	v_mfma_f32_16x16x32_bf16 v[80:83], v[228:231], v[196:199], v[80:83]
	v_mfma_f32_16x16x32_bf16 v[76:79], v[220:223], v[204:207], v[76:79]
	v_mfma_f32_16x16x32_bf16 v[72:75], v[228:231], v[204:207], v[72:75]
	v_mfma_f32_16x16x32_bf16 v[68:71], v[220:223], v[212:215], v[68:71]
	v_mfma_f32_16x16x32_bf16 v[64:67], v[228:231], v[212:215], v[64:67]
	v_mfma_f32_16x16x32_bf16 v[92:95], v[224:227], v[192:195], v[92:95]
	v_mfma_f32_16x16x32_bf16 v[88:91], v[232:235], v[192:195], v[88:91]
	v_mfma_f32_16x16x32_bf16 v[84:87], v[224:227], v[200:203], v[84:87]
	v_mfma_f32_16x16x32_bf16 v[80:83], v[232:235], v[200:203], v[80:83]
	v_mfma_f32_16x16x32_bf16 v[76:79], v[224:227], v[208:211], v[76:79]
	v_mfma_f32_16x16x32_bf16 v[72:75], v[232:235], v[208:211], v[72:75]
	v_mfma_f32_16x16x32_bf16 v[68:71], v[224:227], v[216:219], v[68:71]
	v_mfma_f32_16x16x32_bf16 v[64:67], v[232:235], v[216:219], v[64:67]
	s_setprio 0
	v_readfirstlane_b32 s45, v157
	v_lshl_add_u64 v[236:237], v[236:237], 0, s[26:27]
	s_mov_b32 m0, s45
	v_readfirstlane_b32 s45, v158
	s_barrier
; #define STAGE(P, BASE, LD, br, kt) do { const char* _g = (const char*)((BASE) + (size_t)(br) * (LD) + (size_t)(kt) * 64); \
;     for (int _i = 0; _i < 2; ++_i) { int _b = tidx * 16 + _i * 8192; int _r, _c; stage_rc(_b, _r, _c); \
;       __builtin_amdgcn_global_load_lds((const unsigned*)(_g + (unsigned)((_r * (LD) + _c) * 2)), (unsigned*)((char*)(P) + _b), 16, 0, 0); } } while (0)
; #define LDA(dst, b, h) for (int m = 0; m < 4; ++m) for (int k = 0; k < 2; ++k) \
;     dst[m][k] = *reinterpret_cast<const bf16x8*>((char*)SA(b, h) + lds_byte(wr * 64 + m * 16 + fr, k * 32 + fq * 8))
; #define LDB(dst, b, h) for (int n = 0; n < 2; ++n) for (int k = 0; k < 2; ++k) \
;     dst[n][k] = *reinterpret_cast<const bf16x8*>((char*)SB(b, h) + lds_byte(wc * 32 + n * 16 + fr, k * 32 + fq * 8))
; #define MMA(ai, bj, At_, Bt_) do { __builtin_amdgcn_s_setprio(1); \
;     for (int k = 0; k < 2; ++k) for (int m = 0; m < 4; ++m) for (int n = 0; n < 2; ++n) \
;       acc[ai][bj][m][n] = __builtin_amdgcn_mfma_f32_16x16x32_bf16(At_[m][k], Bt_[n][k], acc[ai][bj][m][n], 0, 0, 0); \
;     __builtin_amdgcn_s_setprio(0); } while (0)
; #define WAIT_V(n) asm volatile("s_waitcnt vmcnt(" #n ")" ::: "memory")
; #define WAIT_L(n) asm volatile("s_waitcnt lgkmcnt(" #n ")" ::: "memory")
; #define BAR __builtin_amdgcn_s_barrier()
; #define SCHED __builtin_amdgcn_sched_barrier(0)
; template <int EPI, int lda, int ldb, int N, int K>
; __device__ __forceinline__ void gemm_phase(const u16* __restrict__ A, const u16* __restrict__ Bt, const GemmEpi ep, int wv) {
;     ...
;       LDA(At, 1, 1); STAGE(SA(1, 0), Ab, lda, brow, t + 3);
;       BAR; WAIT_L(0); MMA(1, 0, At, B0); BAR; SCHED;
;       STAGE(SB(1, 1), Bt, ldb, bcol + HALF, t + 3);
;       WAIT_V(6); BAR; MMA(1, 1, At, B1); BAR;
;     }
;     { LDB(B0, 0, 0); LDA(At, 0, 0); STAGE(SA(1, 1), Ab, lda, brow + HALF, nt - 1);
;       BAR; WAIT_L(0); MMA(0, 0, At, B0); BAR;
;       LDB(B1, 0, 1); BAR; WAIT_L(0); MMA(0, 1, At, B1); BAR;
	ds_read_b128 v[188:191], v152 offset:49152
	ds_read_b128 v[192:195], v152 offset:50176
	ds_read_b128 v[196:199], v151 offset:49152
	ds_read_b128 v[200:203], v151 offset:50176
	ds_read_b128 v[204:207], v150 offset:49152
	ds_read_b128 v[208:211], v150 offset:50176
	ds_read_b128 v[212:215], v149 offset:49152
	ds_read_b128 v[216:219], v149 offset:50176
	global_load_lds_dwordx4 v[236:237], off
	v_lshl_add_u64 v[236:237], v[238:239], 0, s[26:27]
	s_mov_b32 m0, s45
	s_nop 0
	global_load_lds_dwordx4 v[236:237], off
	s_barrier
	s_waitcnt lgkmcnt(0)
	s_setprio 0
	s_waitcnt lgkmcnt(0)
	v_mfma_f32_16x16x32_bf16 v[60:63], v[172:175], v[188:191], v[60:63]
	v_mfma_f32_16x16x32_bf16 v[56:59], v[180:183], v[188:191], v[56:59]
	v_mfma_f32_16x16x32_bf16 v[52:55], v[172:175], v[196:199], v[52:55]
	v_mfma_f32_16x16x32_bf16 v[48:51], v[180:183], v[196:199], v[48:51]
	v_mfma_f32_16x16x32_bf16 v[44:47], v[172:175], v[204:207], v[44:47]
	v_mfma_f32_16x16x32_bf16 v[40:43], v[180:183], v[204:207], v[40:43]
	v_mfma_f32_16x16x32_bf16 v[36:39], v[172:175], v[212:215], v[36:39]
	v_mfma_f32_16x16x32_bf16 v[32:35], v[180:183], v[212:215], v[32:35]
	v_mfma_f32_16x16x32_bf16 v[60:63], v[176:179], v[192:195], v[60:63]
	v_mfma_f32_16x16x32_bf16 v[56:59], v[184:187], v[192:195], v[56:59]
	v_mfma_f32_16x16x32_bf16 v[52:55], v[176:179], v[200:203], v[52:55]
	v_mfma_f32_16x16x32_bf16 v[48:51], v[184:187], v[200:203], v[48:51]
	v_mfma_f32_16x16x32_bf16 v[44:47], v[176:179], v[208:211], v[44:47]
	v_mfma_f32_16x16x32_bf16 v[40:43], v[184:187], v[208:211], v[40:43]
	v_mfma_f32_16x16x32_bf16 v[36:39], v[176:179], v[216:219], v[36:39]
	v_mfma_f32_16x16x32_bf16 v[32:35], v[184:187], v[216:219], v[32:35]
	s_setprio 0
	s_barrier
	v_readfirstlane_b32 s45, v159
	v_add_u32_e32 v171, 0x2000, v159
	v_lshl_add_u64 v[172:173], v[240:241], 0, s[34:35]
	s_mov_b32 m0, s45
	v_readfirstlane_b32 s45, v171
	global_load_lds_dwordx4 v[172:173], off
	v_lshl_add_u64 v[172:173], v[242:243], 0, s[34:35]
	s_mov_b32 m0, s45
	s_nop 0
	global_load_lds_dwordx4 v[172:173], off
	s_waitcnt vmcnt(6)
	s_barrier
	s_setprio 0
	v_mfma_f32_16x16x32_bf16 v[28:31], v[220:223], v[188:191], v[28:31]
	v_mfma_f32_16x16x32_bf16 v[24:27], v[228:231], v[188:191], v[24:27]
	v_mfma_f32_16x16x32_bf16 v[20:23], v[220:223], v[196:199], v[20:23]
	v_mfma_f32_16x16x32_bf16 v[16:19], v[228:231], v[196:199], v[16:19]
	v_mfma_f32_16x16x32_bf16 v[12:15], v[220:223], v[204:207], v[12:15]
	v_mfma_f32_16x16x32_bf16 v[8:11], v[228:231], v[204:207], v[8:11]
	v_mfma_f32_16x16x32_bf16 v[4:7], v[220:223], v[212:215], v[4:7]
	v_mfma_f32_16x16x32_bf16 v[0:3], v[228:231], v[212:215], v[0:3]
	v_mfma_f32_16x16x32_bf16 v[28:31], v[224:227], v[192:195], v[28:31]
	v_mfma_f32_16x16x32_bf16 v[24:27], v[232:235], v[192:195], v[24:27]
	v_mfma_f32_16x16x32_bf16 v[20:23], v[224:227], v[200:203], v[20:23]
	v_mfma_f32_16x16x32_bf16 v[16:19], v[232:235], v[200:203], v[16:19]
	v_mfma_f32_16x16x32_bf16 v[12:15], v[224:227], v[208:211], v[12:15]
	v_mfma_f32_16x16x32_bf16 v[8:11], v[232:235], v[208:211], v[8:11]
	v_mfma_f32_16x16x32_bf16 v[4:7], v[224:227], v[216:219], v[4:7]
	v_mfma_f32_16x16x32_bf16 v[0:3], v[232:235], v[216:219], v[0:3]
	s_setprio 0
	s_add_i32 s44, s44, 2
	s_add_u32 s42, s42, 0x100
	s_addc_u32 s43, s43, 0
	s_cmp_gt_u32 s44, 27
	s_barrier
	s_cbranch_scc0 .LBB0_53
	s_add_i32 s42, s38, 0x80
	s_mul_hi_i32 s43, s42, 0x1080
	s_mulk_i32 s42, 0x1080
	s_add_u32 s42, s51, s42
	s_addc_u32 s43, s52, s43
	v_lshl_add_u64 v[158:159], s[42:43], 0, v[128:129]
	v_readfirstlane_b32 s44, v169
	v_lshl_add_u64 v[158:159], v[158:159], 0, s[36:37]
	s_mov_b32 m0, s44
	ds_read_b128 v[134:137], v161
	ds_read_b128 v[138:141], v161 offset:1024
	ds_read_b128 v[172:175], v161 offset:2048
	ds_read_b128 v[176:179], v161 offset:3072
	ds_read_b128 v[180:183], v152
	ds_read_b128 v[184:187], v152 offset:1024
	ds_read_b128 v[188:191], v151
	ds_read_b128 v[192:195], v151 offset:1024
	ds_read_b128 v[196:199], v150
	ds_read_b128 v[200:203], v150 offset:1024
	ds_read_b128 v[204:207], v149
	ds_read_b128 v[208:211], v149 offset:1024
	global_load_lds_dwordx4 v[158:159], off
	v_lshl_add_u64 v[158:159], s[42:43], 0, v[132:133]
	v_readfirstlane_b32 s42, v170
	v_lshl_add_u64 v[158:159], v[158:159], 0, s[36:37]
	s_mov_b32 m0, s42
	s_nop 0
	global_load_lds_dwordx4 v[158:159], off
	s_barrier
	s_waitcnt lgkmcnt(0)
	s_setprio 0
	s_waitcnt lgkmcnt(0)
	v_mfma_f32_16x16x32_bf16 v[124:127], v[134:137], v[180:183], v[124:127]
	v_mfma_f32_16x16x32_bf16 v[120:123], v[172:175], v[180:183], v[120:123]
	v_mfma_f32_16x16x32_bf16 v[116:119], v[134:137], v[188:191], v[116:119]
	v_mfma_f32_16x16x32_bf16 v[112:115], v[172:175], v[188:191], v[112:115]
	v_mfma_f32_16x16x32_bf16 v[108:111], v[134:137], v[196:199], v[108:111]
	v_mfma_f32_16x16x32_bf16 v[104:107], v[172:175], v[196:199], v[104:107]
	v_mfma_f32_16x16x32_bf16 v[100:103], v[134:137], v[204:207], v[100:103]
	v_mfma_f32_16x16x32_bf16 v[96:99], v[172:175], v[204:207], v[96:99]
	v_mfma_f32_16x16x32_bf16 v[124:127], v[138:141], v[184:187], v[124:127]
	v_mfma_f32_16x16x32_bf16 v[120:123], v[176:179], v[184:187], v[120:123]
	v_mfma_f32_16x16x32_bf16 v[116:119], v[138:141], v[192:195], v[116:119]
	v_mfma_f32_16x16x32_bf16 v[112:115], v[176:179], v[192:195], v[112:115]
	v_mfma_f32_16x16x32_bf16 v[108:111], v[138:141], v[200:203], v[108:111]
	v_mfma_f32_16x16x32_bf16 v[104:107], v[176:179], v[200:203], v[104:107]
	v_mfma_f32_16x16x32_bf16 v[100:103], v[138:141], v[208:211], v[100:103]
	v_mfma_f32_16x16x32_bf16 v[96:99], v[176:179], v[208:211], v[96:99]
	s_setprio 0
	s_barrier
	ds_read_b128 v[212:215], v160
	ds_read_b128 v[216:219], v160 offset:1024
	ds_read_b128 v[220:223], v160 offset:2048
	ds_read_b128 v[158:161], v160 offset:3072
	s_barrier
; #define LDA(dst, b, h) for (int m = 0; m < 4; ++m) for (int k = 0; k < 2; ++k) \
;     dst[m][k] = *reinterpret_cast<const bf16x8*>((char*)SA(b, h) + lds_byte(wr * 64 + m * 16 + fr, k * 32 + fq * 8))
; #define LDB(dst, b, h) for (int n = 0; n < 2; ++n) for (int k = 0; k < 2; ++k) \
;     dst[n][k] = *reinterpret_cast<const bf16x8*>((char*)SB(b, h) + lds_byte(wc * 32 + n * 16 + fr, k * 32 + fq * 8))
; #define MMA(ai, bj, At_, Bt_) do { __builtin_amdgcn_s_setprio(1); \
;     for (int k = 0; k < 2; ++k) for (int m = 0; m < 4; ++m) for (int n = 0; n < 2; ++n) \
;       acc[ai][bj][m][n] = __builtin_amdgcn_mfma_f32_16x16x32_bf16(At_[m][k], Bt_[n][k], acc[ai][bj][m][n], 0, 0, 0); \
;     __builtin_amdgcn_s_setprio(0); } while (0)
; #define WAIT_V(n) asm volatile("s_waitcnt vmcnt(" #n ")" ::: "memory")
; #define WAIT_L(n) asm volatile("s_waitcnt lgkmcnt(" #n ")" ::: "memory")
; #define BAR __builtin_amdgcn_s_barrier()
; template <int EPI, int lda, int ldb, int N, int K>
; __device__ __forceinline__ void gemm_phase(const u16* __restrict__ A, const u16* __restrict__ Bt, const GemmEpi ep, int wv) {
;     ...
;       BAR; WAIT_L(0); MMA(0, 0, At, B0); BAR;
;       LDB(B1, 0, 1); BAR; WAIT_L(0); MMA(0, 1, At, B1); BAR;
;       LDA(At, 0, 1); WAIT_V(4); BAR; WAIT_L(0); MMA(1, 0, At, B0); MMA(1, 1, At, B1); BAR; }
;     { LDB(B0, 1, 0); LDA(At, 1, 0); WAIT_V(2); BAR; WAIT_L(0); MMA(0, 0, At, B0); BAR;
	s_waitcnt lgkmcnt(0)
	s_setprio 0
	s_waitcnt lgkmcnt(0)
	v_mfma_f32_16x16x32_bf16 v[92:95], v[212:215], v[180:183], v[92:95]
	v_mfma_f32_16x16x32_bf16 v[88:91], v[220:223], v[180:183], v[88:91]
	v_mfma_f32_16x16x32_bf16 v[76:79], v[212:215], v[196:199], v[76:79]
	v_mfma_f32_16x16x32_bf16 v[72:75], v[220:223], v[196:199], v[72:75]
	v_mfma_f32_16x16x32_bf16 v[84:87], v[212:215], v[188:191], v[84:87]
	v_mfma_f32_16x16x32_bf16 v[80:83], v[220:223], v[188:191], v[80:83]
	v_mfma_f32_16x16x32_bf16 v[68:71], v[212:215], v[204:207], v[68:71]
	v_mfma_f32_16x16x32_bf16 v[64:67], v[220:223], v[204:207], v[64:67]
	v_mfma_f32_16x16x32_bf16 v[92:95], v[216:219], v[184:187], v[92:95]
	v_mfma_f32_16x16x32_bf16 v[88:91], v[158:161], v[184:187], v[88:91]
	v_mfma_f32_16x16x32_bf16 v[76:79], v[216:219], v[200:203], v[76:79]
	v_mfma_f32_16x16x32_bf16 v[72:75], v[158:161], v[200:203], v[72:75]
	v_mfma_f32_16x16x32_bf16 v[180:183], v[216:219], v[192:195], v[84:87]
	v_mfma_f32_16x16x32_bf16 v[184:187], v[158:161], v[192:195], v[80:83]
	v_mfma_f32_16x16x32_bf16 v[188:191], v[216:219], v[208:211], v[68:71]
	v_mfma_f32_16x16x32_bf16 v[192:195], v[158:161], v[208:211], v[64:67]
	s_setprio 0
	s_barrier
	s_nop 0
	ds_read_b128 v[64:67], v152 offset:16384
	ds_read_b128 v[68:71], v152 offset:17408
	ds_read_b128 v[80:83], v151 offset:16384
	ds_read_b128 v[84:87], v151 offset:17408
	ds_read_b128 v[196:199], v150 offset:16384
	ds_read_b128 v[200:203], v150 offset:17408
	ds_read_b128 v[204:207], v149 offset:16384
	ds_read_b128 v[208:211], v149 offset:17408
	s_waitcnt vmcnt(4)
	s_barrier
	s_waitcnt lgkmcnt(0)
	s_setprio 0
	s_waitcnt lgkmcnt(0)
	v_mfma_f32_16x16x32_bf16 v[60:63], v[134:137], v[64:67], v[60:63]
	v_mfma_f32_16x16x32_bf16 v[56:59], v[172:175], v[64:67], v[56:59]
	v_mfma_f32_16x16x32_bf16 v[52:55], v[134:137], v[80:83], v[52:55]
	v_mfma_f32_16x16x32_bf16 v[48:51], v[172:175], v[80:83], v[48:51]
	v_mfma_f32_16x16x32_bf16 v[44:47], v[134:137], v[196:199], v[44:47]
	v_mfma_f32_16x16x32_bf16 v[40:43], v[172:175], v[196:199], v[40:43]
	v_mfma_f32_16x16x32_bf16 v[36:39], v[134:137], v[204:207], v[36:39]
	v_mfma_f32_16x16x32_bf16 v[32:35], v[172:175], v[204:207], v[32:35]
	v_mfma_f32_16x16x32_bf16 v[60:63], v[138:141], v[68:71], v[60:63]
	v_mfma_f32_16x16x32_bf16 v[56:59], v[176:179], v[68:71], v[56:59]
	v_mfma_f32_16x16x32_bf16 v[52:55], v[138:141], v[84:87], v[52:55]
	v_mfma_f32_16x16x32_bf16 v[48:51], v[176:179], v[84:87], v[48:51]
	v_mfma_f32_16x16x32_bf16 v[44:47], v[138:141], v[200:203], v[44:47]
	v_mfma_f32_16x16x32_bf16 v[40:43], v[176:179], v[200:203], v[40:43]
	v_mfma_f32_16x16x32_bf16 v[36:39], v[138:141], v[208:211], v[36:39]
	v_mfma_f32_16x16x32_bf16 v[32:35], v[176:179], v[208:211], v[32:35]
	s_setprio 0
	s_setprio 0
	v_mfma_f32_16x16x32_bf16 v[28:31], v[212:215], v[64:67], v[28:31]
	v_mfma_f32_16x16x32_bf16 v[24:27], v[220:223], v[64:67], v[24:27]
	v_mfma_f32_16x16x32_bf16 v[12:15], v[212:215], v[196:199], v[12:15]
	v_mfma_f32_16x16x32_bf16 v[8:11], v[220:223], v[196:199], v[8:11]
	v_mfma_f32_16x16x32_bf16 v[20:23], v[212:215], v[80:83], v[20:23]
	v_mfma_f32_16x16x32_bf16 v[16:19], v[220:223], v[80:83], v[16:19]
	v_mfma_f32_16x16x32_bf16 v[4:7], v[212:215], v[204:207], v[4:7]
	v_mfma_f32_16x16x32_bf16 v[0:3], v[220:223], v[204:207], v[0:3]
	v_mfma_f32_16x16x32_bf16 v[28:31], v[216:219], v[68:71], v[28:31]
	v_mfma_f32_16x16x32_bf16 v[24:27], v[158:161], v[68:71], v[24:27]
	v_mfma_f32_16x16x32_bf16 v[12:15], v[216:219], v[200:203], v[12:15]
	v_mfma_f32_16x16x32_bf16 v[8:11], v[158:161], v[200:203], v[8:11]
	v_mfma_f32_16x16x32_bf16 v[134:137], v[216:219], v[84:87], v[20:23]
	v_mfma_f32_16x16x32_bf16 v[138:141], v[158:161], v[84:87], v[16:19]
	v_mfma_f32_16x16x32_bf16 v[170:173], v[216:219], v[208:211], v[4:7]
	v_mfma_f32_16x16x32_bf16 v[158:161], v[158:161], v[208:211], v[0:3]
	s_setprio 0
	s_barrier
	s_nop 0
	ds_read_b128 v[0:3], v156
	ds_read_b128 v[4:7], v156 offset:1024
	ds_read_b128 v[16:19], v156 offset:2048
	ds_read_b128 v[174:177], v156 offset:3072
	ds_read_b128 v[20:23], v152 offset:32768
	ds_read_b128 v[196:199], v152 offset:33792
	ds_read_b128 v[200:203], v151 offset:32768
	ds_read_b128 v[204:207], v151 offset:33792
	ds_read_b128 v[208:211], v150 offset:32768
	ds_read_b128 v[212:215], v150 offset:33792
	ds_read_b128 v[216:219], v149 offset:32768
	ds_read_b128 v[220:223], v149 offset:33792
	s_waitcnt vmcnt(2)
	s_barrier
; #define LDA(dst, b, h) for (int m = 0; m < 4; ++m) for (int k = 0; k < 2; ++k) \
;     dst[m][k] = *reinterpret_cast<const bf16x8*>((char*)SA(b, h) + lds_byte(wr * 64 + m * 16 + fr, k * 32 + fq * 8))
; #define LDB(dst, b, h) for (int n = 0; n < 2; ++n) for (int k = 0; k < 2; ++k) \
;     dst[n][k] = *reinterpret_cast<const bf16x8*>((char*)SB(b, h) + lds_byte(wc * 32 + n * 16 + fr, k * 32 + fq * 8))
; #define MMA(ai, bj, At_, Bt_) do { __builtin_amdgcn_s_setprio(1); \
;     for (int k = 0; k < 2; ++k) for (int m = 0; m < 4; ++m) for (int n = 0; n < 2; ++n) \
;       acc[ai][bj][m][n] = __builtin_amdgcn_mfma_f32_16x16x32_bf16(At_[m][k], Bt_[n][k], acc[ai][bj][m][n], 0, 0, 0); \
;     __builtin_amdgcn_s_setprio(0); } while (0)
; #define WAIT_V(n) asm volatile("s_waitcnt vmcnt(" #n ")" ::: "memory")
; #define WAIT_L(n) asm volatile("s_waitcnt lgkmcnt(" #n ")" ::: "memory")
; #define BAR __builtin_amdgcn_s_barrier()
; template <int EPI, int lda, int ldb, int N, int K>
; __device__ __forceinline__ void gemm_phase(const u16* __restrict__ A, const u16* __restrict__ Bt, const GemmEpi ep, int wv) {
;     ...
;     { LDB(B0, 1, 0); LDA(At, 1, 0); WAIT_V(2); BAR; WAIT_L(0); MMA(0, 0, At, B0); BAR;
;       LDB(B1, 1, 1); WAIT_V(0); BAR; WAIT_L(0); MMA(0, 1, At, B1); BAR;
;       LDA(At, 1, 1); BAR; WAIT_L(0); MMA(1, 0, At, B0); MMA(1, 1, At, B1); BAR; }
;     if (wr == 0) BAR;
	s_waitcnt lgkmcnt(0)
	s_setprio 0
	s_waitcnt lgkmcnt(0)
	v_mfma_f32_16x16x32_bf16 v[64:67], v[0:3], v[20:23], v[124:127]
	v_mfma_f32_16x16x32_bf16 v[68:71], v[16:19], v[20:23], v[120:123]
	v_mfma_f32_16x16x32_bf16 v[80:83], v[0:3], v[200:203], v[116:119]
	v_mfma_f32_16x16x32_bf16 v[84:87], v[16:19], v[200:203], v[112:115]
	v_mfma_f32_16x16x32_bf16 v[108:111], v[0:3], v[208:211], v[108:111]
	v_mfma_f32_16x16x32_bf16 v[104:107], v[16:19], v[208:211], v[104:107]
	v_mfma_f32_16x16x32_bf16 v[120:123], v[0:3], v[216:219], v[100:103]
	v_mfma_f32_16x16x32_bf16 v[124:127], v[16:19], v[216:219], v[96:99]
	v_mfma_f32_16x16x32_bf16 v[116:119], v[4:7], v[196:199], v[64:67]
	v_mfma_f32_16x16x32_bf16 v[112:115], v[174:177], v[196:199], v[68:71]
	v_mfma_f32_16x16x32_bf16 v[100:103], v[4:7], v[204:207], v[80:83]
	v_mfma_f32_16x16x32_bf16 v[96:99], v[174:177], v[204:207], v[84:87]
	v_mfma_f32_16x16x32_bf16 v[84:87], v[4:7], v[212:215], v[108:111]
	v_mfma_f32_16x16x32_bf16 v[80:83], v[174:177], v[212:215], v[104:107]
	v_mfma_f32_16x16x32_bf16 v[68:71], v[4:7], v[220:223], v[120:123]
	v_mfma_f32_16x16x32_bf16 v[64:67], v[174:177], v[220:223], v[124:127]
	s_setprio 0
	s_barrier
	ds_read_b128 v[224:227], v154
	ds_read_b128 v[228:231], v154 offset:1024
	ds_read_b128 v[232:235], v154 offset:2048
	ds_read_b128 v[154:157], v154 offset:3072
	s_waitcnt vmcnt(0)
	s_barrier
	s_waitcnt lgkmcnt(0)
	s_setprio 0
	s_waitcnt lgkmcnt(0)
	v_mfma_f32_16x16x32_bf16 v[92:95], v[224:227], v[20:23], v[92:95]
	v_mfma_f32_16x16x32_bf16 v[20:23], v[232:235], v[20:23], v[88:91]
	v_mfma_f32_16x16x32_bf16 v[88:91], v[224:227], v[200:203], v[180:183]
	v_mfma_f32_16x16x32_bf16 v[104:107], v[232:235], v[200:203], v[184:187]
	v_mfma_f32_16x16x32_bf16 v[76:79], v[224:227], v[208:211], v[76:79]
	v_mfma_f32_16x16x32_bf16 v[72:75], v[232:235], v[208:211], v[72:75]
	v_mfma_f32_16x16x32_bf16 v[178:181], v[224:227], v[216:219], v[188:191]
	v_mfma_f32_16x16x32_bf16 v[182:185], v[232:235], v[216:219], v[192:195]
	v_mfma_f32_16x16x32_bf16 v[124:127], v[228:231], v[196:199], v[92:95]
	v_mfma_f32_16x16x32_bf16 v[120:123], v[154:157], v[196:199], v[20:23]
	v_mfma_f32_16x16x32_bf16 v[108:111], v[228:231], v[204:207], v[88:91]
	v_mfma_f32_16x16x32_bf16 v[104:107], v[154:157], v[204:207], v[104:107]
	v_mfma_f32_16x16x32_bf16 v[92:95], v[228:231], v[212:215], v[76:79]
	v_mfma_f32_16x16x32_bf16 v[88:91], v[154:157], v[212:215], v[72:75]
	v_mfma_f32_16x16x32_bf16 v[76:79], v[228:231], v[220:223], v[178:181]
	v_mfma_f32_16x16x32_bf16 v[72:75], v[154:157], v[220:223], v[182:185]
	s_setprio 0
	s_barrier
	ds_read_b128 v[178:181], v152 offset:49152
	ds_read_b128 v[182:185], v152 offset:50176
	ds_read_b128 v[186:189], v151 offset:49152
	ds_read_b128 v[190:193], v151 offset:50176
	ds_read_b128 v[194:197], v150 offset:49152
	ds_read_b128 v[150:153], v150 offset:50176
	ds_read_b128 v[198:201], v149 offset:49152
	ds_read_b128 v[202:205], v149 offset:50176
	s_barrier
	s_waitcnt lgkmcnt(0)
	s_setprio 0
	s_waitcnt lgkmcnt(0)
	v_mfma_f32_16x16x32_bf16 v[20:23], v[0:3], v[178:181], v[60:63]
	v_mfma_f32_16x16x32_bf16 v[56:59], v[16:19], v[178:181], v[56:59]
	v_mfma_f32_16x16x32_bf16 v[60:63], v[0:3], v[186:189], v[52:55]
	v_mfma_f32_16x16x32_bf16 v[206:209], v[16:19], v[186:189], v[48:51]
	v_mfma_f32_16x16x32_bf16 v[44:47], v[0:3], v[194:197], v[44:47]
	v_mfma_f32_16x16x32_bf16 v[40:43], v[16:19], v[194:197], v[40:43]
	v_mfma_f32_16x16x32_bf16 v[0:3], v[0:3], v[198:201], v[36:39]
	v_mfma_f32_16x16x32_bf16 v[210:213], v[16:19], v[198:201], v[32:35]
	v_mfma_f32_16x16x32_bf16 v[52:55], v[4:7], v[182:185], v[20:23]
	v_mfma_f32_16x16x32_bf16 v[48:51], v[174:177], v[182:185], v[56:59]
	v_mfma_f32_16x16x32_bf16 v[36:39], v[4:7], v[190:193], v[60:63]
	v_mfma_f32_16x16x32_bf16 v[32:35], v[174:177], v[190:193], v[206:209]
	v_mfma_f32_16x16x32_bf16 v[20:23], v[4:7], v[150:153], v[44:47]
	v_mfma_f32_16x16x32_bf16 v[16:19], v[174:177], v[150:153], v[40:43]
	v_mfma_f32_16x16x32_bf16 v[4:7], v[4:7], v[202:205], v[0:3]
	v_mfma_f32_16x16x32_bf16 v[0:3], v[174:177], v[202:205], v[210:213]
	s_setprio 0
	s_setprio 0
	v_mfma_f32_16x16x32_bf16 v[28:31], v[224:227], v[178:181], v[28:31]
	v_mfma_f32_16x16x32_bf16 v[24:27], v[232:235], v[178:181], v[24:27]
	v_mfma_f32_16x16x32_bf16 v[40:43], v[224:227], v[186:189], v[134:137]
	v_mfma_f32_16x16x32_bf16 v[134:137], v[232:235], v[186:189], v[138:141]
	v_mfma_f32_16x16x32_bf16 v[12:15], v[224:227], v[194:197], v[12:15]
	v_mfma_f32_16x16x32_bf16 v[8:11], v[232:235], v[194:197], v[8:11]
	v_mfma_f32_16x16x32_bf16 v[138:141], v[224:227], v[198:201], v[170:173]
	v_mfma_f32_16x16x32_bf16 v[158:161], v[232:235], v[198:201], v[158:161]
	v_mfma_f32_16x16x32_bf16 v[60:63], v[228:231], v[182:185], v[28:31]
	v_mfma_f32_16x16x32_bf16 v[56:59], v[154:157], v[182:185], v[24:27]
	v_mfma_f32_16x16x32_bf16 v[44:47], v[228:231], v[190:193], v[40:43]
	v_mfma_f32_16x16x32_bf16 v[40:43], v[154:157], v[190:193], v[134:137]
	v_mfma_f32_16x16x32_bf16 v[28:31], v[228:231], v[150:153], v[12:15]
	v_mfma_f32_16x16x32_bf16 v[24:27], v[154:157], v[150:153], v[8:11]
	v_mfma_f32_16x16x32_bf16 v[12:15], v[228:231], v[202:205], v[138:141]
	v_mfma_f32_16x16x32_bf16 v[8:11], v[154:157], v[202:205], v[158:161]
	s_setprio 0
	v_cmp_gt_u32_e32 vcc, s56, v130
	s_barrier
	s_and_saveexec_b64 s[42:43], vcc
	s_cbranch_execz .LBB0_56
	s_barrier

; #define STAGE(P, BASE, LD, br, kt) do { const char* _g = (const char*)((BASE) + (size_t)(br) * (LD) + (size_t)(kt) * 64); \
;     for (int _i = 0; _i < 2; ++_i) { int _b = tidx * 16 + _i * 8192; int _r, _c; stage_rc(_b, _r, _c); \
;       __builtin_amdgcn_global_load_lds((const unsigned*)(_g + (unsigned)((_r * (LD) + _c) * 2)), (unsigned*)((char*)(P) + _b), 16, 0, 0); } } while (0)
; #define LDA(dst, b, h) for (int m = 0; m < 4; ++m) for (int k = 0; k < 2; ++k) \
;     dst[m][k] = *reinterpret_cast<const bf16x8*>((char*)SA(b, h) + lds_byte(wr * 64 + m * 16 + fr, k * 32 + fq * 8))
; #define LDB(dst, b, h) for (int n = 0; n < 2; ++n) for (int k = 0; k < 2; ++k) \
;     dst[n][k] = *reinterpret_cast<const bf16x8*>((char*)SB(b, h) + lds_byte(wc * 32 + n * 16 + fr, k * 32 + fq * 8))
; #define MMA(ai, bj, At_, Bt_) do { __builtin_amdgcn_s_setprio(1); \
;     for (int k = 0; k < 2; ++k) for (int m = 0; m < 4; ++m) for (int n = 0; n < 2; ++n) \
;       acc[ai][bj][m][n] = __builtin_amdgcn_mfma_f32_16x16x32_bf16(At_[m][k], Bt_[n][k], acc[ai][bj][m][n], 0, 0, 0); \
;     __builtin_amdgcn_s_setprio(0); } while (0)
; #define WAIT_L(n) asm volatile("s_waitcnt lgkmcnt(" #n ")" ::: "memory")
; #define BAR __builtin_amdgcn_s_barrier()
; #define SCHED __builtin_amdgcn_sched_barrier(0)
; template <int EPI, int lda, int ldb, int N, int K>
; __device__ __forceinline__ void gemm_phase(const u16* __restrict__ A, const u16* __restrict__ Bt, const GemmEpi ep, int wv) {
;     ...
;     for (int t = 0; t < nt - 2; t += 2) {
;       LDB(B0, 0, 0); SCHED; LDA(At, 0, 0); STAGE(SA(1, 1), Ab, lda, brow + HALF, t + 1);
;       WAIT_L(8); BAR; WAIT_L(0); MMA(0, 0, At, B0); BAR; SCHED;
;       LDB(B1, 0, 1); STAGE(SB(0, 0), Bt, ldb, bcol, t + 2);
;       BAR; WAIT_L(0); MMA(0, 1, At, B1); BAR;
;       LDA(At, 0, 1); STAGE(SA(0, 0), Ab, lda, brow, t + 2);
;       BAR; WAIT_L(0); MMA(1, 0, At, B0); BAR; SCHED;
.LBB0_224:
	ds_read_b128 v[168:171], v164
	ds_read_b128 v[174:177], v164 offset:1024
	ds_read_b128 v[178:181], v164 offset:2048
	ds_read_b128 v[182:185], v164 offset:3072
	v_add_u32_e32 v172, 0xc000, v147
	v_lshl_add_u64 v[238:239], v[136:137], 0, s[44:45]
	v_readfirstlane_b32 s66, v172
	v_add_u32_e32 v173, 0xe000, v147
	v_lshl_add_u64 v[166:167], v[238:239], 0, s[18:19]
	s_mov_b32 m0, s66
	v_lshl_add_u64 v[240:241], v[134:135], 0, s[44:45]
	v_readfirstlane_b32 s66, v173
	ds_read_b128 v[186:189], v155
	ds_read_b128 v[190:193], v155 offset:1024
	ds_read_b128 v[194:197], v154
	ds_read_b128 v[198:201], v154 offset:1024
	ds_read_b128 v[202:205], v153
	ds_read_b128 v[206:209], v153 offset:1024
	ds_read_b128 v[210:213], v152
	ds_read_b128 v[214:217], v152 offset:1024
	global_load_lds_dwordx4 v[166:167], off
	v_lshl_add_u64 v[166:167], v[240:241], 0, s[18:19]
	s_mov_b32 m0, s66
	s_nop 0
	global_load_lds_dwordx4 v[166:167], off
	s_waitcnt lgkmcnt(8)
	s_barrier
	s_waitcnt lgkmcnt(0)
	s_setprio 0
	s_waitcnt lgkmcnt(0)
	v_mfma_f32_16x16x32_bf16 v[124:127], v[168:171], v[186:189], v[124:127]
	v_mfma_f32_16x16x32_bf16 v[120:123], v[178:181], v[186:189], v[120:123]
	v_mfma_f32_16x16x32_bf16 v[116:119], v[168:171], v[194:197], v[116:119]
	v_mfma_f32_16x16x32_bf16 v[112:115], v[178:181], v[194:197], v[112:115]
	v_mfma_f32_16x16x32_bf16 v[108:111], v[168:171], v[202:205], v[108:111]
	v_mfma_f32_16x16x32_bf16 v[104:107], v[178:181], v[202:205], v[104:107]
	v_mfma_f32_16x16x32_bf16 v[100:103], v[168:171], v[210:213], v[100:103]
	v_mfma_f32_16x16x32_bf16 v[96:99], v[178:181], v[210:213], v[96:99]
	v_mfma_f32_16x16x32_bf16 v[124:127], v[174:177], v[190:193], v[124:127]
	v_mfma_f32_16x16x32_bf16 v[120:123], v[182:185], v[190:193], v[120:123]
	v_mfma_f32_16x16x32_bf16 v[116:119], v[174:177], v[198:201], v[116:119]
	v_mfma_f32_16x16x32_bf16 v[112:115], v[182:185], v[198:201], v[112:115]
	v_mfma_f32_16x16x32_bf16 v[108:111], v[174:177], v[206:209], v[108:111]
	v_mfma_f32_16x16x32_bf16 v[104:107], v[182:185], v[206:209], v[104:107]
	v_mfma_f32_16x16x32_bf16 v[100:103], v[174:177], v[214:217], v[100:103]
	v_mfma_f32_16x16x32_bf16 v[96:99], v[182:185], v[214:217], v[96:99]
	s_setprio 0
	s_barrier
	v_add_u32_e32 v165, s55, v156
	v_lshl_add_u64 v[242:243], v[144:145], 0, s[44:45]
	v_readfirstlane_b32 s66, v165
	v_lshl_add_u64 v[166:167], v[242:243], 0, s[20:21]
	s_mov_b32 m0, s66
	ds_read_b128 v[218:221], v163
	ds_read_b128 v[222:225], v163 offset:1024
	ds_read_b128 v[226:229], v163 offset:2048
	ds_read_b128 v[230:233], v163 offset:3072
	global_load_lds_dwordx4 v[166:167], off
	v_add_u32_e32 v166, 0x2000, v165
	v_lshl_add_u64 v[244:245], v[142:143], 0, s[44:45]
	v_readfirstlane_b32 s66, v166
	v_lshl_add_u64 v[234:235], v[244:245], 0, s[20:21]
	s_mov_b32 m0, s66
	s_nop 0
	global_load_lds_dwordx4 v[234:235], off
	s_barrier
	s_waitcnt lgkmcnt(0)
	s_setprio 0
	s_waitcnt lgkmcnt(0)
	v_mfma_f32_16x16x32_bf16 v[92:95], v[218:221], v[186:189], v[92:95]
	v_mfma_f32_16x16x32_bf16 v[88:91], v[226:229], v[186:189], v[88:91]
	v_mfma_f32_16x16x32_bf16 v[84:87], v[218:221], v[194:197], v[84:87]
	v_mfma_f32_16x16x32_bf16 v[80:83], v[226:229], v[194:197], v[80:83]
	v_mfma_f32_16x16x32_bf16 v[76:79], v[218:221], v[202:205], v[76:79]
	v_mfma_f32_16x16x32_bf16 v[72:75], v[226:229], v[202:205], v[72:75]
	v_mfma_f32_16x16x32_bf16 v[68:71], v[218:221], v[210:213], v[68:71]
	v_mfma_f32_16x16x32_bf16 v[64:67], v[226:229], v[210:213], v[64:67]
	v_mfma_f32_16x16x32_bf16 v[92:95], v[222:225], v[190:193], v[92:95]
	v_mfma_f32_16x16x32_bf16 v[88:91], v[230:233], v[190:193], v[88:91]
	v_mfma_f32_16x16x32_bf16 v[84:87], v[222:225], v[198:201], v[84:87]
	v_mfma_f32_16x16x32_bf16 v[80:83], v[230:233], v[198:201], v[80:83]
	v_mfma_f32_16x16x32_bf16 v[76:79], v[222:225], v[206:209], v[76:79]
	v_mfma_f32_16x16x32_bf16 v[72:75], v[230:233], v[206:209], v[72:75]
	v_mfma_f32_16x16x32_bf16 v[68:71], v[222:225], v[214:217], v[68:71]
	v_mfma_f32_16x16x32_bf16 v[64:67], v[230:233], v[214:217], v[64:67]
	s_setprio 0
	v_readfirstlane_b32 s66, v147
	v_add_u32_e32 v167, 0x2000, v147
	v_lshl_add_u64 v[234:235], v[238:239], 0, s[22:23]
	s_mov_b32 m0, s66
	v_readfirstlane_b32 s66, v167
	s_barrier
	ds_read_b128 v[186:189], v155 offset:16384
	ds_read_b128 v[190:193], v155 offset:17408
	ds_read_b128 v[194:197], v154 offset:16384
	ds_read_b128 v[198:201], v154 offset:17408
	ds_read_b128 v[202:205], v153 offset:16384
	ds_read_b128 v[206:209], v153 offset:17408
	ds_read_b128 v[210:213], v152 offset:16384
	ds_read_b128 v[214:217], v152 offset:17408
	global_load_lds_dwordx4 v[234:235], off
	v_lshl_add_u64 v[234:235], v[240:241], 0, s[22:23]
	s_mov_b32 m0, s66
	s_nop 0
	global_load_lds_dwordx4 v[234:235], off
	s_barrier
	s_waitcnt lgkmcnt(0)
	s_setprio 0
	s_waitcnt lgkmcnt(0)
	v_mfma_f32_16x16x32_bf16 v[60:63], v[168:171], v[186:189], v[60:63]
	v_mfma_f32_16x16x32_bf16 v[56:59], v[178:181], v[186:189], v[56:59]
	v_mfma_f32_16x16x32_bf16 v[52:55], v[168:171], v[194:197], v[52:55]
	v_mfma_f32_16x16x32_bf16 v[48:51], v[178:181], v[194:197], v[48:51]
	v_mfma_f32_16x16x32_bf16 v[44:47], v[168:171], v[202:205], v[44:47]
	v_mfma_f32_16x16x32_bf16 v[40:43], v[178:181], v[202:205], v[40:43]
	v_mfma_f32_16x16x32_bf16 v[36:39], v[168:171], v[210:213], v[36:39]
	v_mfma_f32_16x16x32_bf16 v[32:35], v[178:181], v[210:213], v[32:35]
	v_mfma_f32_16x16x32_bf16 v[60:63], v[174:177], v[190:193], v[60:63]
	v_mfma_f32_16x16x32_bf16 v[56:59], v[182:185], v[190:193], v[56:59]
	v_mfma_f32_16x16x32_bf16 v[52:55], v[174:177], v[198:201], v[52:55]
	v_mfma_f32_16x16x32_bf16 v[48:51], v[182:185], v[198:201], v[48:51]
	v_mfma_f32_16x16x32_bf16 v[44:47], v[174:177], v[206:209], v[44:47]
	v_mfma_f32_16x16x32_bf16 v[40:43], v[182:185], v[206:209], v[40:43]
	v_mfma_f32_16x16x32_bf16 v[36:39], v[174:177], v[214:217], v[36:39]
	v_mfma_f32_16x16x32_bf16 v[32:35], v[182:185], v[214:217], v[32:35]
	s_setprio 0
	s_barrier
; #define STAGE(P, BASE, LD, br, kt) do { const char* _g = (const char*)((BASE) + (size_t)(br) * (LD) + (size_t)(kt) * 64); \
;     for (int _i = 0; _i < 2; ++_i) { int _b = tidx * 16 + _i * 8192; int _r, _c; stage_rc(_b, _r, _c); \
;       __builtin_amdgcn_global_load_lds((const unsigned*)(_g + (unsigned)((_r * (LD) + _c) * 2)), (unsigned*)((char*)(P) + _b), 16, 0, 0); } } while (0)
; #define LDA(dst, b, h) for (int m = 0; m < 4; ++m) for (int k = 0; k < 2; ++k) \
;     dst[m][k] = *reinterpret_cast<const bf16x8*>((char*)SA(b, h) + lds_byte(wr * 64 + m * 16 + fr, k * 32 + fq * 8))
; #define LDB(dst, b, h) for (int n = 0; n < 2; ++n) for (int k = 0; k < 2; ++k) \
;     dst[n][k] = *reinterpret_cast<const bf16x8*>((char*)SB(b, h) + lds_byte(wc * 32 + n * 16 + fr, k * 32 + fq * 8))
; #define MMA(ai, bj, At_, Bt_) do { __builtin_amdgcn_s_setprio(1); \
;     for (int k = 0; k < 2; ++k) for (int m = 0; m < 4; ++m) for (int n = 0; n < 2; ++n) \
;       acc[ai][bj][m][n] = __builtin_amdgcn_mfma_f32_16x16x32_bf16(At_[m][k], Bt_[n][k], acc[ai][bj][m][n], 0, 0, 0); \
;     __builtin_amdgcn_s_setprio(0); } while (0)
; #define WAIT_V(n) asm volatile("s_waitcnt vmcnt(" #n ")" ::: "memory")
; #define WAIT_L(n) asm volatile("s_waitcnt lgkmcnt(" #n ")" ::: "memory")
; #define BAR __builtin_amdgcn_s_barrier()
; #define SCHED __builtin_amdgcn_sched_barrier(0)
; template <int EPI, int lda, int ldb, int N, int K>
; __device__ __forceinline__ void gemm_phase(const u16* __restrict__ A, const u16* __restrict__ Bt, const GemmEpi ep, int wv) {
;     ...
;       STAGE(SB(0, 1), Bt, ldb, bcol + HALF, t + 2);
;       WAIT_V(6); BAR; MMA(1, 1, At, B1); BAR;
;       LDB(B0, 1, 0); SCHED; LDA(At, 1, 0); STAGE(SA(0, 1), Ab, lda, brow + HALF, t + 2);
;       WAIT_L(8); BAR; WAIT_L(0); MMA(0, 0, At, B0); BAR; SCHED;
;       LDB(B1, 1, 1); STAGE(SB(1, 0), Bt, ldb, bcol, t + 3);
;       BAR; WAIT_L(0); MMA(0, 1, At, B1); BAR;
;       LDA(At, 1, 1); STAGE(SA(1, 0), Ab, lda, brow, t + 3);
	v_add_u32_e32 v168, s56, v156
	v_lshl_add_u64 v[246:247], v[140:141], 0, s[44:45]
	v_readfirstlane_b32 s66, v168
	v_add_u32_e32 v169, 0x2000, v168
	v_lshl_add_u64 v[170:171], v[246:247], 0, s[24:25]
	s_mov_b32 m0, s66
	v_lshl_add_u64 v[248:249], v[138:139], 0, s[44:45]
	v_readfirstlane_b32 s66, v169
	global_load_lds_dwordx4 v[170:171], off
	v_lshl_add_u64 v[170:171], v[248:249], 0, s[24:25]
	s_mov_b32 m0, s66
	s_nop 0
	global_load_lds_dwordx4 v[170:171], off
	s_waitcnt vmcnt(6)
	s_barrier
	s_setprio 0
	v_mfma_f32_16x16x32_bf16 v[28:31], v[218:221], v[186:189], v[28:31]
	v_mfma_f32_16x16x32_bf16 v[24:27], v[226:229], v[186:189], v[24:27]
	v_mfma_f32_16x16x32_bf16 v[20:23], v[218:221], v[194:197], v[20:23]
	v_mfma_f32_16x16x32_bf16 v[16:19], v[226:229], v[194:197], v[16:19]
	v_mfma_f32_16x16x32_bf16 v[12:15], v[218:221], v[202:205], v[12:15]
	v_mfma_f32_16x16x32_bf16 v[8:11], v[226:229], v[202:205], v[8:11]
	v_mfma_f32_16x16x32_bf16 v[4:7], v[218:221], v[210:213], v[4:7]
	v_mfma_f32_16x16x32_bf16 v[0:3], v[226:229], v[210:213], v[0:3]
	v_mfma_f32_16x16x32_bf16 v[28:31], v[222:225], v[190:193], v[28:31]
	v_mfma_f32_16x16x32_bf16 v[24:27], v[230:233], v[190:193], v[24:27]
	v_mfma_f32_16x16x32_bf16 v[20:23], v[222:225], v[198:201], v[20:23]
	v_mfma_f32_16x16x32_bf16 v[16:19], v[230:233], v[198:201], v[16:19]
	v_mfma_f32_16x16x32_bf16 v[12:15], v[222:225], v[206:209], v[12:15]
	v_mfma_f32_16x16x32_bf16 v[8:11], v[230:233], v[206:209], v[8:11]
	v_mfma_f32_16x16x32_bf16 v[4:7], v[222:225], v[214:217], v[4:7]
	v_mfma_f32_16x16x32_bf16 v[0:3], v[230:233], v[214:217], v[0:3]
	s_setprio 0
	s_barrier
	ds_read_b128 v[174:177], v159
	ds_read_b128 v[178:181], v159 offset:1024
	ds_read_b128 v[182:185], v159 offset:2048
	ds_read_b128 v[186:189], v159 offset:3072
	v_add_u32_e32 v170, 0x4000, v147
	v_add_u32_e32 v171, 0x6000, v147
	v_readfirstlane_b32 s66, v170
	v_lshl_add_u64 v[222:223], v[238:239], 0, s[26:27]
	s_mov_b32 m0, s66
	v_readfirstlane_b32 s66, v171
	ds_read_b128 v[190:193], v155 offset:32768
	ds_read_b128 v[194:197], v155 offset:33792
	ds_read_b128 v[198:201], v154 offset:32768
	ds_read_b128 v[202:205], v154 offset:33792
	ds_read_b128 v[206:209], v153 offset:32768
	ds_read_b128 v[210:213], v153 offset:33792
	ds_read_b128 v[214:217], v152 offset:32768
	ds_read_b128 v[218:221], v152 offset:33792
	global_load_lds_dwordx4 v[222:223], off
	v_lshl_add_u64 v[222:223], v[240:241], 0, s[26:27]
	s_mov_b32 m0, s66
	s_nop 0
	global_load_lds_dwordx4 v[222:223], off
	s_waitcnt lgkmcnt(8)
	s_barrier
	s_waitcnt lgkmcnt(0)
	s_setprio 0
	s_waitcnt lgkmcnt(0)
	v_mfma_f32_16x16x32_bf16 v[124:127], v[174:177], v[190:193], v[124:127]
	v_mfma_f32_16x16x32_bf16 v[120:123], v[182:185], v[190:193], v[120:123]
	v_mfma_f32_16x16x32_bf16 v[116:119], v[174:177], v[198:201], v[116:119]
	v_mfma_f32_16x16x32_bf16 v[112:115], v[182:185], v[198:201], v[112:115]
	v_mfma_f32_16x16x32_bf16 v[108:111], v[174:177], v[206:209], v[108:111]
	v_mfma_f32_16x16x32_bf16 v[104:107], v[182:185], v[206:209], v[104:107]
	v_mfma_f32_16x16x32_bf16 v[100:103], v[174:177], v[214:217], v[100:103]
	v_mfma_f32_16x16x32_bf16 v[96:99], v[182:185], v[214:217], v[96:99]
	v_mfma_f32_16x16x32_bf16 v[124:127], v[178:181], v[194:197], v[124:127]
	v_mfma_f32_16x16x32_bf16 v[120:123], v[186:189], v[194:197], v[120:123]
	v_mfma_f32_16x16x32_bf16 v[116:119], v[178:181], v[202:205], v[116:119]
	v_mfma_f32_16x16x32_bf16 v[112:115], v[186:189], v[202:205], v[112:115]
	v_mfma_f32_16x16x32_bf16 v[108:111], v[178:181], v[210:213], v[108:111]
	v_mfma_f32_16x16x32_bf16 v[104:107], v[186:189], v[210:213], v[104:107]
	v_mfma_f32_16x16x32_bf16 v[100:103], v[178:181], v[218:221], v[100:103]
	v_mfma_f32_16x16x32_bf16 v[96:99], v[186:189], v[218:221], v[96:99]
	s_setprio 0
	s_barrier
	v_readfirstlane_b32 s66, v158
	v_lshl_add_u64 v[242:243], v[242:243], 0, s[36:37]
	s_mov_b32 m0, s66
	ds_read_b128 v[222:225], v157
	ds_read_b128 v[226:229], v157 offset:1024
	ds_read_b128 v[230:233], v157 offset:2048
	ds_read_b128 v[234:237], v157 offset:3072
	global_load_lds_dwordx4 v[242:243], off
	v_lshl_add_u64 v[242:243], v[244:245], 0, s[36:37]
	v_add_u32_e32 v244, 0x2000, v158
	s_nop 0
	v_readfirstlane_b32 s66, v244
	s_mov_b32 m0, s66
	s_nop 0
	global_load_lds_dwordx4 v[242:243], off
	s_barrier
	s_waitcnt lgkmcnt(0)
	s_setprio 0
	s_waitcnt lgkmcnt(0)
	v_mfma_f32_16x16x32_bf16 v[92:95], v[222:225], v[190:193], v[92:95]
	v_mfma_f32_16x16x32_bf16 v[88:91], v[230:233], v[190:193], v[88:91]
	v_mfma_f32_16x16x32_bf16 v[84:87], v[222:225], v[198:201], v[84:87]
	v_mfma_f32_16x16x32_bf16 v[80:83], v[230:233], v[198:201], v[80:83]
	v_mfma_f32_16x16x32_bf16 v[76:79], v[222:225], v[206:209], v[76:79]
	v_mfma_f32_16x16x32_bf16 v[72:75], v[230:233], v[206:209], v[72:75]
	v_mfma_f32_16x16x32_bf16 v[68:71], v[222:225], v[214:217], v[68:71]
	v_mfma_f32_16x16x32_bf16 v[64:67], v[230:233], v[214:217], v[64:67]
	v_mfma_f32_16x16x32_bf16 v[92:95], v[226:229], v[194:197], v[92:95]
	v_mfma_f32_16x16x32_bf16 v[88:91], v[234:237], v[194:197], v[88:91]
	v_mfma_f32_16x16x32_bf16 v[84:87], v[226:229], v[202:205], v[84:87]
	v_mfma_f32_16x16x32_bf16 v[80:83], v[234:237], v[202:205], v[80:83]
	v_mfma_f32_16x16x32_bf16 v[76:79], v[226:229], v[210:213], v[76:79]
	v_mfma_f32_16x16x32_bf16 v[72:75], v[234:237], v[210:213], v[72:75]
	v_mfma_f32_16x16x32_bf16 v[68:71], v[226:229], v[218:221], v[68:71]
	v_mfma_f32_16x16x32_bf16 v[64:67], v[234:237], v[218:221], v[64:67]
	s_setprio 0
	v_readfirstlane_b32 s66, v160
	v_lshl_add_u64 v[238:239], v[238:239], 0, s[38:39]
	s_mov_b32 m0, s66
	v_readfirstlane_b32 s66, v161
	s_barrier
; #define STAGE(P, BASE, LD, br, kt) do { const char* _g = (const char*)((BASE) + (size_t)(br) * (LD) + (size_t)(kt) * 64); \
;     for (int _i = 0; _i < 2; ++_i) { int _b = tidx * 16 + _i * 8192; int _r, _c; stage_rc(_b, _r, _c); \
;       __builtin_amdgcn_global_load_lds((const unsigned*)(_g + (unsigned)((_r * (LD) + _c) * 2)), (unsigned*)((char*)(P) + _b), 16, 0, 0); } } while (0)
; #define LDA(dst, b, h) for (int m = 0; m < 4; ++m) for (int k = 0; k < 2; ++k) \
;     dst[m][k] = *reinterpret_cast<const bf16x8*>((char*)SA(b, h) + lds_byte(wr * 64 + m * 16 + fr, k * 32 + fq * 8))
; #define LDB(dst, b, h) for (int n = 0; n < 2; ++n) for (int k = 0; k < 2; ++k) \
;     dst[n][k] = *reinterpret_cast<const bf16x8*>((char*)SB(b, h) + lds_byte(wc * 32 + n * 16 + fr, k * 32 + fq * 8))
; #define MMA(ai, bj, At_, Bt_) do { __builtin_amdgcn_s_setprio(1); \
;     for (int k = 0; k < 2; ++k) for (int m = 0; m < 4; ++m) for (int n = 0; n < 2; ++n) \
;       acc[ai][bj][m][n] = __builtin_amdgcn_mfma_f32_16x16x32_bf16(At_[m][k], Bt_[n][k], acc[ai][bj][m][n], 0, 0, 0); \
;     __builtin_amdgcn_s_setprio(0); } while (0)
; #define WAIT_V(n) asm volatile("s_waitcnt vmcnt(" #n ")" ::: "memory")
; #define WAIT_L(n) asm volatile("s_waitcnt lgkmcnt(" #n ")" ::: "memory")
; #define BAR __builtin_amdgcn_s_barrier()
; #define SCHED __builtin_amdgcn_sched_barrier(0)
; template <int EPI, int lda, int ldb, int N, int K>
; __device__ __forceinline__ void gemm_phase(const u16* __restrict__ A, const u16* __restrict__ Bt, const GemmEpi ep, int wv) {
;     ...
;       LDA(At, 1, 1); STAGE(SA(1, 0), Ab, lda, brow, t + 3);
;       BAR; WAIT_L(0); MMA(1, 0, At, B0); BAR; SCHED;
;       STAGE(SB(1, 1), Bt, ldb, bcol + HALF, t + 3);
;       WAIT_V(6); BAR; MMA(1, 1, At, B1); BAR;
;     }
;     { LDB(B0, 0, 0); LDA(At, 0, 0); STAGE(SA(1, 1), Ab, lda, brow + HALF, nt - 1);
;       BAR; WAIT_L(0); MMA(0, 0, At, B0); BAR;
;       LDB(B1, 0, 1); BAR; WAIT_L(0); MMA(0, 1, At, B1); BAR;
	ds_read_b128 v[190:193], v155 offset:49152
	ds_read_b128 v[194:197], v155 offset:50176
	ds_read_b128 v[198:201], v154 offset:49152
	ds_read_b128 v[202:205], v154 offset:50176
	ds_read_b128 v[206:209], v153 offset:49152
	ds_read_b128 v[210:213], v153 offset:50176
	ds_read_b128 v[214:217], v152 offset:49152
	ds_read_b128 v[218:221], v152 offset:50176
	global_load_lds_dwordx4 v[238:239], off
	v_lshl_add_u64 v[238:239], v[240:241], 0, s[38:39]
	s_mov_b32 m0, s66
	s_nop 0
	global_load_lds_dwordx4 v[238:239], off
	s_barrier
	s_waitcnt lgkmcnt(0)
	s_setprio 0
	s_waitcnt lgkmcnt(0)
	v_mfma_f32_16x16x32_bf16 v[60:63], v[174:177], v[190:193], v[60:63]
	v_mfma_f32_16x16x32_bf16 v[56:59], v[182:185], v[190:193], v[56:59]
	v_mfma_f32_16x16x32_bf16 v[52:55], v[174:177], v[198:201], v[52:55]
	v_mfma_f32_16x16x32_bf16 v[48:51], v[182:185], v[198:201], v[48:51]
	v_mfma_f32_16x16x32_bf16 v[44:47], v[174:177], v[206:209], v[44:47]
	v_mfma_f32_16x16x32_bf16 v[40:43], v[182:185], v[206:209], v[40:43]
	v_mfma_f32_16x16x32_bf16 v[36:39], v[174:177], v[214:217], v[36:39]
	v_mfma_f32_16x16x32_bf16 v[32:35], v[182:185], v[214:217], v[32:35]
	v_mfma_f32_16x16x32_bf16 v[60:63], v[178:181], v[194:197], v[60:63]
	v_mfma_f32_16x16x32_bf16 v[56:59], v[186:189], v[194:197], v[56:59]
	v_mfma_f32_16x16x32_bf16 v[52:55], v[178:181], v[202:205], v[52:55]
	v_mfma_f32_16x16x32_bf16 v[48:51], v[186:189], v[202:205], v[48:51]
	v_mfma_f32_16x16x32_bf16 v[44:47], v[178:181], v[210:213], v[44:47]
	v_mfma_f32_16x16x32_bf16 v[40:43], v[186:189], v[210:213], v[40:43]
	v_mfma_f32_16x16x32_bf16 v[36:39], v[178:181], v[218:221], v[36:39]
	v_mfma_f32_16x16x32_bf16 v[32:35], v[186:189], v[218:221], v[32:35]
	s_setprio 0
	s_barrier
	v_readfirstlane_b32 s66, v162
	v_add_u32_e32 v176, 0x2000, v162
	v_lshl_add_u64 v[174:175], v[246:247], 0, s[42:43]
	s_mov_b32 m0, s66
	v_readfirstlane_b32 s66, v176
	global_load_lds_dwordx4 v[174:175], off
	v_lshl_add_u64 v[174:175], v[248:249], 0, s[42:43]
	s_mov_b32 m0, s66
	s_nop 0
	global_load_lds_dwordx4 v[174:175], off
	s_waitcnt vmcnt(6)
	s_barrier
	s_setprio 0
	v_mfma_f32_16x16x32_bf16 v[28:31], v[222:225], v[190:193], v[28:31]
	v_mfma_f32_16x16x32_bf16 v[24:27], v[230:233], v[190:193], v[24:27]
	v_mfma_f32_16x16x32_bf16 v[20:23], v[222:225], v[198:201], v[20:23]
	v_mfma_f32_16x16x32_bf16 v[16:19], v[230:233], v[198:201], v[16:19]
	v_mfma_f32_16x16x32_bf16 v[12:15], v[222:225], v[206:209], v[12:15]
	v_mfma_f32_16x16x32_bf16 v[8:11], v[230:233], v[206:209], v[8:11]
	v_mfma_f32_16x16x32_bf16 v[4:7], v[222:225], v[214:217], v[4:7]
	v_mfma_f32_16x16x32_bf16 v[0:3], v[230:233], v[214:217], v[0:3]
	v_mfma_f32_16x16x32_bf16 v[28:31], v[226:229], v[194:197], v[28:31]
	v_mfma_f32_16x16x32_bf16 v[24:27], v[234:237], v[194:197], v[24:27]
	v_mfma_f32_16x16x32_bf16 v[20:23], v[226:229], v[202:205], v[20:23]
	v_mfma_f32_16x16x32_bf16 v[16:19], v[234:237], v[202:205], v[16:19]
	v_mfma_f32_16x16x32_bf16 v[12:15], v[226:229], v[210:213], v[12:15]
	v_mfma_f32_16x16x32_bf16 v[8:11], v[234:237], v[210:213], v[8:11]
	v_mfma_f32_16x16x32_bf16 v[4:7], v[226:229], v[218:221], v[4:7]
	v_mfma_f32_16x16x32_bf16 v[0:3], v[234:237], v[218:221], v[0:3]
	s_setprio 0
	s_add_i32 s65, s65, 2
	s_add_u32 s44, s44, 0x100
	s_addc_u32 s45, s45, 0
	s_cmpk_gt_u32 s65, 0x51
	s_barrier
	s_cbranch_scc0 .LBB0_224
	s_add_i32 s44, s14, 0x80
	s_mul_hi_i32 s45, s44, 0x2b00
	s_mulk_i32 s44, 0x2b00
	s_add_u32 s44, s48, s44
	s_addc_u32 s45, s49, s45
	s_add_u32 s44, s44, 0x2a80
	s_addc_u32 s45, s45, 0
	v_readfirstlane_b32 s65, v172
	v_lshl_add_u64 v[160:161], s[44:45], 0, v[128:129]
	s_mov_b32 m0, s65
	ds_read_b128 v[134:137], v164
	ds_read_b128 v[138:141], v164 offset:1024
	ds_read_b128 v[142:145], v164 offset:2048
	ds_read_b128 v[174:177], v164 offset:3072
	ds_read_b128 v[178:181], v155
	ds_read_b128 v[182:185], v155 offset:1024
	ds_read_b128 v[186:189], v154
	ds_read_b128 v[190:193], v154 offset:1024
	ds_read_b128 v[194:197], v153
	ds_read_b128 v[198:201], v153 offset:1024
	ds_read_b128 v[202:205], v152
	ds_read_b128 v[206:209], v152 offset:1024
	global_load_lds_dwordx4 v[160:161], off
	v_lshl_add_u64 v[160:161], s[44:45], 0, v[132:133]
	v_readfirstlane_b32 s44, v173
	s_mov_b32 m0, s44
	s_nop 0
	global_load_lds_dwordx4 v[160:161], off
	s_barrier
	s_waitcnt lgkmcnt(0)
	s_setprio 0
	s_waitcnt lgkmcnt(0)
	v_mfma_f32_16x16x32_bf16 v[124:127], v[134:137], v[178:181], v[124:127]
	v_mfma_f32_16x16x32_bf16 v[120:123], v[142:145], v[178:181], v[120:123]
	v_mfma_f32_16x16x32_bf16 v[116:119], v[134:137], v[186:189], v[116:119]
	v_mfma_f32_16x16x32_bf16 v[112:115], v[142:145], v[186:189], v[112:115]
	v_mfma_f32_16x16x32_bf16 v[108:111], v[134:137], v[194:197], v[108:111]
	v_mfma_f32_16x16x32_bf16 v[104:107], v[142:145], v[194:197], v[104:107]
	v_mfma_f32_16x16x32_bf16 v[100:103], v[134:137], v[202:205], v[100:103]
	v_mfma_f32_16x16x32_bf16 v[96:99], v[142:145], v[202:205], v[96:99]
	v_mfma_f32_16x16x32_bf16 v[124:127], v[138:141], v[182:185], v[124:127]
	v_mfma_f32_16x16x32_bf16 v[120:123], v[174:177], v[182:185], v[120:123]
	v_mfma_f32_16x16x32_bf16 v[116:119], v[138:141], v[190:193], v[116:119]
	v_mfma_f32_16x16x32_bf16 v[112:115], v[174:177], v[190:193], v[112:115]
	v_mfma_f32_16x16x32_bf16 v[108:111], v[138:141], v[198:201], v[108:111]
	v_mfma_f32_16x16x32_bf16 v[104:107], v[174:177], v[198:201], v[104:107]
	v_mfma_f32_16x16x32_bf16 v[100:103], v[138:141], v[206:209], v[100:103]
	v_mfma_f32_16x16x32_bf16 v[96:99], v[174:177], v[206:209], v[96:99]
	s_setprio 0
	s_barrier
	ds_read_b128 v[210:213], v163
	ds_read_b128 v[214:217], v163 offset:1024
	ds_read_b128 v[218:221], v163 offset:2048
	ds_read_b128 v[160:163], v163 offset:3072
	s_barrier
; #define LDA(dst, b, h) for (int m = 0; m < 4; ++m) for (int k = 0; k < 2; ++k) \
;     dst[m][k] = *reinterpret_cast<const bf16x8*>((char*)SA(b, h) + lds_byte(wr * 64 + m * 16 + fr, k * 32 + fq * 8))
; #define LDB(dst, b, h) for (int n = 0; n < 2; ++n) for (int k = 0; k < 2; ++k) \
;     dst[n][k] = *reinterpret_cast<const bf16x8*>((char*)SB(b, h) + lds_byte(wc * 32 + n * 16 + fr, k * 32 + fq * 8))
; #define MMA(ai, bj, At_, Bt_) do { __builtin_amdgcn_s_setprio(1); \
;     for (int k = 0; k < 2; ++k) for (int m = 0; m < 4; ++m) for (int n = 0; n < 2; ++n) \
;       acc[ai][bj][m][n] = __builtin_amdgcn_mfma_f32_16x16x32_bf16(At_[m][k], Bt_[n][k], acc[ai][bj][m][n], 0, 0, 0); \
;     __builtin_amdgcn_s_setprio(0); } while (0)
; #define WAIT_V(n) asm volatile("s_waitcnt vmcnt(" #n ")" ::: "memory")
; #define WAIT_L(n) asm volatile("s_waitcnt lgkmcnt(" #n ")" ::: "memory")
; #define BAR __builtin_amdgcn_s_barrier()
; template <int EPI, int lda, int ldb, int N, int K>
; __device__ __forceinline__ void gemm_phase(const u16* __restrict__ A, const u16* __restrict__ Bt, const GemmEpi ep, int wv) {
;     ...
;       BAR; WAIT_L(0); MMA(0, 0, At, B0); BAR;
;       LDB(B1, 0, 1); BAR; WAIT_L(0); MMA(0, 1, At, B1); BAR;
;       LDA(At, 0, 1); WAIT_V(4); BAR; WAIT_L(0); MMA(1, 0, At, B0); MMA(1, 1, At, B1); BAR; }
;     { LDB(B0, 1, 0); LDA(At, 1, 0); WAIT_V(2); BAR; WAIT_L(0); MMA(0, 0, At, B0); BAR;
	s_waitcnt lgkmcnt(0)
	s_setprio 0
	s_waitcnt lgkmcnt(0)
	v_mfma_f32_16x16x32_bf16 v[92:95], v[210:213], v[178:181], v[92:95]
	v_mfma_f32_16x16x32_bf16 v[88:91], v[218:221], v[178:181], v[88:91]
	v_mfma_f32_16x16x32_bf16 v[76:79], v[210:213], v[194:197], v[76:79]
	v_mfma_f32_16x16x32_bf16 v[72:75], v[218:221], v[194:197], v[72:75]
	v_mfma_f32_16x16x32_bf16 v[84:87], v[210:213], v[186:189], v[84:87]
	v_mfma_f32_16x16x32_bf16 v[80:83], v[218:221], v[186:189], v[80:83]
	v_mfma_f32_16x16x32_bf16 v[68:71], v[210:213], v[202:205], v[68:71]
	v_mfma_f32_16x16x32_bf16 v[64:67], v[218:221], v[202:205], v[64:67]
	v_mfma_f32_16x16x32_bf16 v[92:95], v[214:217], v[182:185], v[92:95]
	v_mfma_f32_16x16x32_bf16 v[88:91], v[160:163], v[182:185], v[88:91]
	v_mfma_f32_16x16x32_bf16 v[76:79], v[214:217], v[198:201], v[76:79]
	v_mfma_f32_16x16x32_bf16 v[72:75], v[160:163], v[198:201], v[72:75]
	v_mfma_f32_16x16x32_bf16 v[178:181], v[214:217], v[190:193], v[84:87]
	v_mfma_f32_16x16x32_bf16 v[182:185], v[160:163], v[190:193], v[80:83]
	v_mfma_f32_16x16x32_bf16 v[186:189], v[214:217], v[206:209], v[68:71]
	v_mfma_f32_16x16x32_bf16 v[190:193], v[160:163], v[206:209], v[64:67]
	s_setprio 0
	s_barrier
	s_nop 0
	ds_read_b128 v[64:67], v155 offset:16384
	ds_read_b128 v[68:71], v155 offset:17408
	ds_read_b128 v[80:83], v154 offset:16384
	ds_read_b128 v[84:87], v154 offset:17408
	ds_read_b128 v[194:197], v153 offset:16384
	ds_read_b128 v[198:201], v153 offset:17408
	ds_read_b128 v[202:205], v152 offset:16384
	ds_read_b128 v[206:209], v152 offset:17408
	s_waitcnt vmcnt(4)
	s_barrier
	s_waitcnt lgkmcnt(0)
	s_setprio 0
	s_waitcnt lgkmcnt(0)
	v_mfma_f32_16x16x32_bf16 v[60:63], v[134:137], v[64:67], v[60:63]
	v_mfma_f32_16x16x32_bf16 v[56:59], v[142:145], v[64:67], v[56:59]
	v_mfma_f32_16x16x32_bf16 v[52:55], v[134:137], v[80:83], v[52:55]
	v_mfma_f32_16x16x32_bf16 v[48:51], v[142:145], v[80:83], v[48:51]
	v_mfma_f32_16x16x32_bf16 v[44:47], v[134:137], v[194:197], v[44:47]
	v_mfma_f32_16x16x32_bf16 v[40:43], v[142:145], v[194:197], v[40:43]
	v_mfma_f32_16x16x32_bf16 v[36:39], v[134:137], v[202:205], v[36:39]
	v_mfma_f32_16x16x32_bf16 v[32:35], v[142:145], v[202:205], v[32:35]
	v_mfma_f32_16x16x32_bf16 v[60:63], v[138:141], v[68:71], v[60:63]
	v_mfma_f32_16x16x32_bf16 v[56:59], v[174:177], v[68:71], v[56:59]
	v_mfma_f32_16x16x32_bf16 v[52:55], v[138:141], v[84:87], v[52:55]
	v_mfma_f32_16x16x32_bf16 v[48:51], v[174:177], v[84:87], v[48:51]
	v_mfma_f32_16x16x32_bf16 v[44:47], v[138:141], v[198:201], v[44:47]
	v_mfma_f32_16x16x32_bf16 v[40:43], v[174:177], v[198:201], v[40:43]
	v_mfma_f32_16x16x32_bf16 v[36:39], v[138:141], v[206:209], v[36:39]
	v_mfma_f32_16x16x32_bf16 v[32:35], v[174:177], v[206:209], v[32:35]
	s_setprio 0
	s_setprio 0
	v_mfma_f32_16x16x32_bf16 v[28:31], v[210:213], v[64:67], v[28:31]
	v_mfma_f32_16x16x32_bf16 v[16:19], v[218:221], v[80:83], v[16:19]
	v_mfma_f32_16x16x32_bf16 v[12:15], v[210:213], v[194:197], v[12:15]
	v_mfma_f32_16x16x32_bf16 v[0:3], v[218:221], v[202:205], v[0:3]
	v_mfma_f32_16x16x32_bf16 v[24:27], v[218:221], v[64:67], v[24:27]
	v_mfma_f32_16x16x32_bf16 v[20:23], v[210:213], v[80:83], v[20:23]
	v_mfma_f32_16x16x32_bf16 v[8:11], v[218:221], v[194:197], v[8:11]
	v_mfma_f32_16x16x32_bf16 v[4:7], v[210:213], v[202:205], v[4:7]
	v_mfma_f32_16x16x32_bf16 v[28:31], v[214:217], v[68:71], v[28:31]
	v_mfma_f32_16x16x32_bf16 v[16:19], v[160:163], v[84:87], v[16:19]
	v_mfma_f32_16x16x32_bf16 v[12:15], v[214:217], v[198:201], v[12:15]
	v_mfma_f32_16x16x32_bf16 v[0:3], v[160:163], v[206:209], v[0:3]
	v_mfma_f32_16x16x32_bf16 v[134:137], v[160:163], v[68:71], v[24:27]
	v_mfma_f32_16x16x32_bf16 v[138:141], v[214:217], v[84:87], v[20:23]
	v_mfma_f32_16x16x32_bf16 v[142:145], v[160:163], v[198:201], v[8:11]
	v_mfma_f32_16x16x32_bf16 v[172:175], v[214:217], v[206:209], v[4:7]
	s_setprio 0
	s_barrier
	s_nop 0
	ds_read_b128 v[4:7], v159
	ds_read_b128 v[8:11], v159 offset:1024
	ds_read_b128 v[20:23], v159 offset:2048
	ds_read_b128 v[158:161], v159 offset:3072
	ds_read_b128 v[24:27], v155 offset:32768
	ds_read_b128 v[194:197], v155 offset:33792
	ds_read_b128 v[198:201], v154 offset:32768
	ds_read_b128 v[202:205], v154 offset:33792
	ds_read_b128 v[206:209], v153 offset:32768
	ds_read_b128 v[210:213], v153 offset:33792
	ds_read_b128 v[214:217], v152 offset:32768
	ds_read_b128 v[218:221], v152 offset:33792
	s_waitcnt vmcnt(2)
	s_barrier
; #define LDA(dst, b, h) for (int m = 0; m < 4; ++m) for (int k = 0; k < 2; ++k) \
;     dst[m][k] = *reinterpret_cast<const bf16x8*>((char*)SA(b, h) + lds_byte(wr * 64 + m * 16 + fr, k * 32 + fq * 8))
; #define LDB(dst, b, h) for (int n = 0; n < 2; ++n) for (int k = 0; k < 2; ++k) \
;     dst[n][k] = *reinterpret_cast<const bf16x8*>((char*)SB(b, h) + lds_byte(wc * 32 + n * 16 + fr, k * 32 + fq * 8))
; #define MMA(ai, bj, At_, Bt_) do { __builtin_amdgcn_s_setprio(1); \
;     for (int k = 0; k < 2; ++k) for (int m = 0; m < 4; ++m) for (int n = 0; n < 2; ++n) \
;       acc[ai][bj][m][n] = __builtin_amdgcn_mfma_f32_16x16x32_bf16(At_[m][k], Bt_[n][k], acc[ai][bj][m][n], 0, 0, 0); \
;     __builtin_amdgcn_s_setprio(0); } while (0)
; #define WAIT_V(n) asm volatile("s_waitcnt vmcnt(" #n ")" ::: "memory")
; #define WAIT_L(n) asm volatile("s_waitcnt lgkmcnt(" #n ")" ::: "memory")
; #define BAR __builtin_amdgcn_s_barrier()
; template <int EPI, int lda, int ldb, int N, int K>
; __device__ __forceinline__ void gemm_phase(const u16* __restrict__ A, const u16* __restrict__ Bt, const GemmEpi ep, int wv) {
;     ...
;     { LDB(B0, 1, 0); LDA(At, 1, 0); WAIT_V(2); BAR; WAIT_L(0); MMA(0, 0, At, B0); BAR;
;       LDB(B1, 1, 1); WAIT_V(0); BAR; WAIT_L(0); MMA(0, 1, At, B1); BAR;
;       LDA(At, 1, 1); BAR; WAIT_L(0); MMA(1, 0, At, B0); MMA(1, 1, At, B1); BAR; }
;     if (wr == 0) BAR;
	s_waitcnt lgkmcnt(0)
	s_setprio 0
	s_waitcnt lgkmcnt(0)
	v_mfma_f32_16x16x32_bf16 v[64:67], v[4:7], v[24:27], v[124:127]
	v_mfma_f32_16x16x32_bf16 v[68:71], v[20:23], v[24:27], v[120:123]
	v_mfma_f32_16x16x32_bf16 v[80:83], v[4:7], v[198:201], v[116:119]
	v_mfma_f32_16x16x32_bf16 v[84:87], v[20:23], v[198:201], v[112:115]
	v_mfma_f32_16x16x32_bf16 v[108:111], v[4:7], v[206:209], v[108:111]
	v_mfma_f32_16x16x32_bf16 v[104:107], v[20:23], v[206:209], v[104:107]
	v_mfma_f32_16x16x32_bf16 v[120:123], v[4:7], v[214:217], v[100:103]
	v_mfma_f32_16x16x32_bf16 v[124:127], v[20:23], v[214:217], v[96:99]
	v_mfma_f32_16x16x32_bf16 v[116:119], v[8:11], v[194:197], v[64:67]
	v_mfma_f32_16x16x32_bf16 v[112:115], v[158:161], v[194:197], v[68:71]
	v_mfma_f32_16x16x32_bf16 v[100:103], v[8:11], v[202:205], v[80:83]
	v_mfma_f32_16x16x32_bf16 v[96:99], v[158:161], v[202:205], v[84:87]
	v_mfma_f32_16x16x32_bf16 v[84:87], v[8:11], v[210:213], v[108:111]
	v_mfma_f32_16x16x32_bf16 v[80:83], v[158:161], v[210:213], v[104:107]
	v_mfma_f32_16x16x32_bf16 v[68:71], v[8:11], v[218:221], v[120:123]
	v_mfma_f32_16x16x32_bf16 v[64:67], v[158:161], v[218:221], v[124:127]
	s_setprio 0
	s_barrier
	ds_read_b128 v[222:225], v157
	ds_read_b128 v[226:229], v157 offset:1024
	ds_read_b128 v[230:233], v157 offset:2048
	ds_read_b128 v[234:237], v157 offset:3072
	s_waitcnt vmcnt(0)
	s_barrier
	s_waitcnt lgkmcnt(0)
	s_setprio 0
	s_waitcnt lgkmcnt(0)
	v_mfma_f32_16x16x32_bf16 v[92:95], v[222:225], v[24:27], v[92:95]
	v_mfma_f32_16x16x32_bf16 v[24:27], v[230:233], v[24:27], v[88:91]
	v_mfma_f32_16x16x32_bf16 v[88:91], v[222:225], v[198:201], v[178:181]
	v_mfma_f32_16x16x32_bf16 v[104:107], v[230:233], v[198:201], v[182:185]
	v_mfma_f32_16x16x32_bf16 v[76:79], v[222:225], v[206:209], v[76:79]
	v_mfma_f32_16x16x32_bf16 v[72:75], v[230:233], v[206:209], v[72:75]
	v_mfma_f32_16x16x32_bf16 v[176:179], v[222:225], v[214:217], v[186:189]
	v_mfma_f32_16x16x32_bf16 v[180:183], v[230:233], v[214:217], v[190:193]
	v_mfma_f32_16x16x32_bf16 v[124:127], v[226:229], v[194:197], v[92:95]
	v_mfma_f32_16x16x32_bf16 v[120:123], v[234:237], v[194:197], v[24:27]
	v_mfma_f32_16x16x32_bf16 v[108:111], v[226:229], v[202:205], v[88:91]
	v_mfma_f32_16x16x32_bf16 v[104:107], v[234:237], v[202:205], v[104:107]
	v_mfma_f32_16x16x32_bf16 v[92:95], v[226:229], v[210:213], v[76:79]
	v_mfma_f32_16x16x32_bf16 v[88:91], v[234:237], v[210:213], v[72:75]
	v_mfma_f32_16x16x32_bf16 v[76:79], v[226:229], v[218:221], v[176:179]
	v_mfma_f32_16x16x32_bf16 v[72:75], v[234:237], v[218:221], v[180:183]
	s_setprio 0
	s_barrier
	ds_read_b128 v[176:179], v155 offset:49152
	ds_read_b128 v[180:183], v155 offset:50176
	ds_read_b128 v[184:187], v154 offset:49152
	ds_read_b128 v[154:157], v154 offset:50176
	ds_read_b128 v[188:191], v153 offset:49152
	ds_read_b128 v[192:195], v153 offset:50176
	ds_read_b128 v[196:199], v152 offset:49152
	ds_read_b128 v[200:203], v152 offset:50176
	s_barrier
	s_waitcnt lgkmcnt(0)
	s_setprio 0
	s_waitcnt lgkmcnt(0)
	v_mfma_f32_16x16x32_bf16 v[24:27], v[4:7], v[176:179], v[60:63]
	v_mfma_f32_16x16x32_bf16 v[60:63], v[20:23], v[176:179], v[56:59]
	v_mfma_f32_16x16x32_bf16 v[204:207], v[4:7], v[184:187], v[52:55]
	v_mfma_f32_16x16x32_bf16 v[48:51], v[20:23], v[184:187], v[48:51]
	v_mfma_f32_16x16x32_bf16 v[44:47], v[4:7], v[188:191], v[44:47]
	v_mfma_f32_16x16x32_bf16 v[208:211], v[20:23], v[188:191], v[40:43]
	v_mfma_f32_16x16x32_bf16 v[4:7], v[4:7], v[196:199], v[36:39]
	v_mfma_f32_16x16x32_bf16 v[32:35], v[20:23], v[196:199], v[32:35]
	v_mfma_f32_16x16x32_bf16 v[56:59], v[8:11], v[180:183], v[24:27]
	v_mfma_f32_16x16x32_bf16 v[52:55], v[158:161], v[180:183], v[60:63]
	v_mfma_f32_16x16x32_bf16 v[40:43], v[8:11], v[154:157], v[204:207]
	v_mfma_f32_16x16x32_bf16 v[36:39], v[158:161], v[154:157], v[48:51]
	v_mfma_f32_16x16x32_bf16 v[24:27], v[8:11], v[192:195], v[44:47]
	v_mfma_f32_16x16x32_bf16 v[20:23], v[158:161], v[192:195], v[208:211]
	v_mfma_f32_16x16x32_bf16 v[8:11], v[8:11], v[200:203], v[4:7]
	v_mfma_f32_16x16x32_bf16 v[4:7], v[158:161], v[200:203], v[32:35]
	s_setprio 0
	s_setprio 0
	v_mfma_f32_16x16x32_bf16 v[28:31], v[222:225], v[176:179], v[28:31]
	v_mfma_f32_16x16x32_bf16 v[32:35], v[230:233], v[176:179], v[134:137]
	v_mfma_f32_16x16x32_bf16 v[44:47], v[222:225], v[184:187], v[138:141]
	v_mfma_f32_16x16x32_bf16 v[16:19], v[230:233], v[184:187], v[16:19]
	v_mfma_f32_16x16x32_bf16 v[12:15], v[222:225], v[188:191], v[12:15]
	v_mfma_f32_16x16x32_bf16 v[134:137], v[230:233], v[188:191], v[142:145]
	v_mfma_f32_16x16x32_bf16 v[138:141], v[222:225], v[196:199], v[172:175]
	v_mfma_f32_16x16x32_bf16 v[0:3], v[230:233], v[196:199], v[0:3]
	v_mfma_f32_16x16x32_bf16 v[60:63], v[226:229], v[180:183], v[28:31]
	v_mfma_f32_16x16x32_bf16 v[48:51], v[234:237], v[180:183], v[32:35]
	v_mfma_f32_16x16x32_bf16 v[44:47], v[226:229], v[154:157], v[44:47]
	v_mfma_f32_16x16x32_bf16 v[32:35], v[234:237], v[154:157], v[16:19]
	v_mfma_f32_16x16x32_bf16 v[28:31], v[226:229], v[192:195], v[12:15]
	v_mfma_f32_16x16x32_bf16 v[16:19], v[234:237], v[192:195], v[134:137]
	v_mfma_f32_16x16x32_bf16 v[12:15], v[226:229], v[200:203], v[138:141]
	v_mfma_f32_16x16x32_bf16 v[0:3], v[234:237], v[200:203], v[0:3]
	s_setprio 0
	v_cmp_gt_u32_e32 vcc, s62, v130
	s_barrier
	s_and_saveexec_b64 s[44:45], vcc
	s_cbranch_execz .LBB0_227
	s_barrier

; #define STAGE(P, BASE, LD, br, kt) do { const char* _g = (const char*)((BASE) + (size_t)(br) * (LD) + (size_t)(kt) * 64); \
;     for (int _i = 0; _i < 2; ++_i) { int _b = tidx * 16 + _i * 8192; int _r, _c; stage_rc(_b, _r, _c); \
;       __builtin_amdgcn_global_load_lds((const unsigned*)(_g + (unsigned)((_r * (LD) + _c) * 2)), (unsigned*)((char*)(P) + _b), 16, 0, 0); } } while (0)
; #define LDA(dst, b, h) for (int m = 0; m < 4; ++m) for (int k = 0; k < 2; ++k) \
;     dst[m][k] = *reinterpret_cast<const bf16x8*>((char*)SA(b, h) + lds_byte(wr * 64 + m * 16 + fr, k * 32 + fq * 8))
; #define LDB(dst, b, h) for (int n = 0; n < 2; ++n) for (int k = 0; k < 2; ++k) \
;     dst[n][k] = *reinterpret_cast<const bf16x8*>((char*)SB(b, h) + lds_byte(wc * 32 + n * 16 + fr, k * 32 + fq * 8))
; #define MMA(ai, bj, At_, Bt_) do { __builtin_amdgcn_s_setprio(1); \
;     for (int k = 0; k < 2; ++k) for (int m = 0; m < 4; ++m) for (int n = 0; n < 2; ++n) \
;       acc[ai][bj][m][n] = __builtin_amdgcn_mfma_f32_16x16x32_bf16(At_[m][k], Bt_[n][k], acc[ai][bj][m][n], 0, 0, 0); \
;     __builtin_amdgcn_s_setprio(0); } while (0)
; #define WAIT_L(n) asm volatile("s_waitcnt lgkmcnt(" #n ")" ::: "memory")
; #define BAR __builtin_amdgcn_s_barrier()
; #define SCHED __builtin_amdgcn_sched_barrier(0)
; template <int EPI, int lda, int ldb, int N, int K>
; __device__ __forceinline__ void gemm_phase(const u16* __restrict__ A, const u16* __restrict__ Bt, const GemmEpi ep, int wv) {
;     ...
;     for (int t = 0; t < nt - 2; t += 2) {
;       LDB(B0, 0, 0); SCHED; LDA(At, 0, 0); STAGE(SA(1, 1), Ab, lda, brow + HALF, t + 1);
;       WAIT_L(8); BAR; WAIT_L(0); MMA(0, 0, At, B0); BAR; SCHED;
;       LDB(B1, 0, 1); STAGE(SB(0, 0), Bt, ldb, bcol, t + 2);
;       BAR; WAIT_L(0); MMA(0, 1, At, B1); BAR;
;       LDA(At, 0, 1); STAGE(SA(0, 0), Ab, lda, brow, t + 2);
;       BAR; WAIT_L(0); MMA(1, 0, At, B0); BAR; SCHED;
.LBB0_340:
	ds_read_b128 v[166:169], v162
	ds_read_b128 v[172:175], v162 offset:1024
	ds_read_b128 v[176:179], v162 offset:2048
	ds_read_b128 v[180:183], v162 offset:3072
	v_add_u32_e32 v170, 0xc000, v149
	v_lshl_add_u64 v[236:237], v[138:139], 0, s[48:49]
	v_readfirstlane_b32 s51, v170
	v_add_u32_e32 v171, 0xe000, v149
	v_lshl_add_u64 v[164:165], v[236:237], 0, s[18:19]
	s_mov_b32 m0, s51
	v_lshl_add_u64 v[238:239], v[140:141], 0, s[48:49]
	v_readfirstlane_b32 s51, v171
	ds_read_b128 v[184:187], v153
	ds_read_b128 v[188:191], v153 offset:1024
	ds_read_b128 v[192:195], v152
	ds_read_b128 v[196:199], v152 offset:1024
	ds_read_b128 v[200:203], v151
	ds_read_b128 v[204:207], v151 offset:1024
	ds_read_b128 v[208:211], v150
	ds_read_b128 v[212:215], v150 offset:1024
	global_load_lds_dwordx4 v[164:165], off
	v_lshl_add_u64 v[164:165], v[238:239], 0, s[18:19]
	s_mov_b32 m0, s51
	s_nop 0
	global_load_lds_dwordx4 v[164:165], off
	s_waitcnt lgkmcnt(8)
	s_barrier
	s_waitcnt lgkmcnt(0)
	s_setprio 0
	s_waitcnt lgkmcnt(0)
	v_mfma_f32_16x16x32_bf16 v[124:127], v[184:187], v[166:169], v[124:127]
	v_mfma_f32_16x16x32_bf16 v[120:123], v[184:187], v[176:179], v[120:123]
	v_mfma_f32_16x16x32_bf16 v[116:119], v[192:195], v[166:169], v[116:119]
	v_mfma_f32_16x16x32_bf16 v[112:115], v[192:195], v[176:179], v[112:115]
	v_mfma_f32_16x16x32_bf16 v[108:111], v[200:203], v[166:169], v[108:111]
	v_mfma_f32_16x16x32_bf16 v[104:107], v[200:203], v[176:179], v[104:107]
	v_mfma_f32_16x16x32_bf16 v[100:103], v[208:211], v[166:169], v[100:103]
	v_mfma_f32_16x16x32_bf16 v[96:99], v[208:211], v[176:179], v[96:99]
	v_mfma_f32_16x16x32_bf16 v[124:127], v[188:191], v[172:175], v[124:127]
	v_mfma_f32_16x16x32_bf16 v[120:123], v[188:191], v[180:183], v[120:123]
	v_mfma_f32_16x16x32_bf16 v[116:119], v[196:199], v[172:175], v[116:119]
	v_mfma_f32_16x16x32_bf16 v[112:115], v[196:199], v[180:183], v[112:115]
	v_mfma_f32_16x16x32_bf16 v[108:111], v[204:207], v[172:175], v[108:111]
	v_mfma_f32_16x16x32_bf16 v[104:107], v[204:207], v[180:183], v[104:107]
	v_mfma_f32_16x16x32_bf16 v[100:103], v[212:215], v[172:175], v[100:103]
	v_mfma_f32_16x16x32_bf16 v[96:99], v[212:215], v[180:183], v[96:99]
	s_setprio 0
	s_barrier
	v_add_u32_e32 v163, s62, v155
	v_lshl_add_u64 v[240:241], v[134:135], 0, s[48:49]
	v_readfirstlane_b32 s51, v163
	v_lshl_add_u64 v[164:165], v[240:241], 0, s[20:21]
	s_mov_b32 m0, s51
	ds_read_b128 v[216:219], v161
	ds_read_b128 v[220:223], v161 offset:1024
	ds_read_b128 v[224:227], v161 offset:2048
	ds_read_b128 v[228:231], v161 offset:3072
	global_load_lds_dwordx4 v[164:165], off
	v_add_u32_e32 v164, 0x2000, v163
	v_lshl_add_u64 v[242:243], v[136:137], 0, s[48:49]
	v_readfirstlane_b32 s51, v164
	v_lshl_add_u64 v[232:233], v[242:243], 0, s[20:21]
	s_mov_b32 m0, s51
	s_nop 0
	global_load_lds_dwordx4 v[232:233], off
	s_barrier
	s_waitcnt lgkmcnt(0)
	s_setprio 0
	s_waitcnt lgkmcnt(0)
	v_mfma_f32_16x16x32_bf16 v[92:95], v[184:187], v[216:219], v[92:95]
	v_mfma_f32_16x16x32_bf16 v[88:91], v[184:187], v[224:227], v[88:91]
	v_mfma_f32_16x16x32_bf16 v[84:87], v[192:195], v[216:219], v[84:87]
	v_mfma_f32_16x16x32_bf16 v[80:83], v[192:195], v[224:227], v[80:83]
	v_mfma_f32_16x16x32_bf16 v[76:79], v[200:203], v[216:219], v[76:79]
	v_mfma_f32_16x16x32_bf16 v[72:75], v[200:203], v[224:227], v[72:75]
	v_mfma_f32_16x16x32_bf16 v[68:71], v[208:211], v[216:219], v[68:71]
	v_mfma_f32_16x16x32_bf16 v[64:67], v[208:211], v[224:227], v[64:67]
	v_mfma_f32_16x16x32_bf16 v[92:95], v[188:191], v[220:223], v[92:95]
	v_mfma_f32_16x16x32_bf16 v[88:91], v[188:191], v[228:231], v[88:91]
	v_mfma_f32_16x16x32_bf16 v[84:87], v[196:199], v[220:223], v[84:87]
	v_mfma_f32_16x16x32_bf16 v[80:83], v[196:199], v[228:231], v[80:83]
	v_mfma_f32_16x16x32_bf16 v[76:79], v[204:207], v[220:223], v[76:79]
	v_mfma_f32_16x16x32_bf16 v[72:75], v[204:207], v[228:231], v[72:75]
	v_mfma_f32_16x16x32_bf16 v[68:71], v[212:215], v[220:223], v[68:71]
	v_mfma_f32_16x16x32_bf16 v[64:67], v[212:215], v[228:231], v[64:67]
	s_setprio 0
	v_readfirstlane_b32 s51, v149
	v_add_u32_e32 v165, 0x2000, v149
	v_lshl_add_u64 v[232:233], v[236:237], 0, s[22:23]
	s_mov_b32 m0, s51
	v_readfirstlane_b32 s51, v165
	s_barrier
	ds_read_b128 v[184:187], v153 offset:16384
	ds_read_b128 v[188:191], v153 offset:17408
	ds_read_b128 v[192:195], v152 offset:16384
	ds_read_b128 v[196:199], v152 offset:17408
	ds_read_b128 v[200:203], v151 offset:16384
	ds_read_b128 v[204:207], v151 offset:17408
	ds_read_b128 v[208:211], v150 offset:16384
	ds_read_b128 v[212:215], v150 offset:17408
	global_load_lds_dwordx4 v[232:233], off
	v_lshl_add_u64 v[232:233], v[238:239], 0, s[22:23]
	s_mov_b32 m0, s51
	s_nop 0
	global_load_lds_dwordx4 v[232:233], off
	s_barrier
	s_waitcnt lgkmcnt(0)
	s_setprio 0
	s_waitcnt lgkmcnt(0)
	v_mfma_f32_16x16x32_bf16 v[60:63], v[184:187], v[166:169], v[60:63]
	v_mfma_f32_16x16x32_bf16 v[56:59], v[184:187], v[176:179], v[56:59]
	v_mfma_f32_16x16x32_bf16 v[52:55], v[192:195], v[166:169], v[52:55]
	v_mfma_f32_16x16x32_bf16 v[48:51], v[192:195], v[176:179], v[48:51]
	v_mfma_f32_16x16x32_bf16 v[44:47], v[200:203], v[166:169], v[44:47]
	v_mfma_f32_16x16x32_bf16 v[40:43], v[200:203], v[176:179], v[40:43]
	v_mfma_f32_16x16x32_bf16 v[36:39], v[208:211], v[166:169], v[36:39]
	v_mfma_f32_16x16x32_bf16 v[32:35], v[208:211], v[176:179], v[32:35]
	v_mfma_f32_16x16x32_bf16 v[60:63], v[188:191], v[172:175], v[60:63]
	v_mfma_f32_16x16x32_bf16 v[56:59], v[188:191], v[180:183], v[56:59]
	v_mfma_f32_16x16x32_bf16 v[52:55], v[196:199], v[172:175], v[52:55]
	v_mfma_f32_16x16x32_bf16 v[48:51], v[196:199], v[180:183], v[48:51]
	v_mfma_f32_16x16x32_bf16 v[44:47], v[204:207], v[172:175], v[44:47]
	v_mfma_f32_16x16x32_bf16 v[40:43], v[204:207], v[180:183], v[40:43]
	v_mfma_f32_16x16x32_bf16 v[36:39], v[212:215], v[172:175], v[36:39]
	v_mfma_f32_16x16x32_bf16 v[32:35], v[212:215], v[180:183], v[32:35]
	s_setprio 0
	s_barrier
; #define STAGE(P, BASE, LD, br, kt) do { const char* _g = (const char*)((BASE) + (size_t)(br) * (LD) + (size_t)(kt) * 64); \
;     for (int _i = 0; _i < 2; ++_i) { int _b = tidx * 16 + _i * 8192; int _r, _c; stage_rc(_b, _r, _c); \
;       __builtin_amdgcn_global_load_lds((const unsigned*)(_g + (unsigned)((_r * (LD) + _c) * 2)), (unsigned*)((char*)(P) + _b), 16, 0, 0); } } while (0)
; #define LDA(dst, b, h) for (int m = 0; m < 4; ++m) for (int k = 0; k < 2; ++k) \
;     dst[m][k] = *reinterpret_cast<const bf16x8*>((char*)SA(b, h) + lds_byte(wr * 64 + m * 16 + fr, k * 32 + fq * 8))
; #define LDB(dst, b, h) for (int n = 0; n < 2; ++n) for (int k = 0; k < 2; ++k) \
;     dst[n][k] = *reinterpret_cast<const bf16x8*>((char*)SB(b, h) + lds_byte(wc * 32 + n * 16 + fr, k * 32 + fq * 8))
; #define MMA(ai, bj, At_, Bt_) do { __builtin_amdgcn_s_setprio(1); \
;     for (int k = 0; k < 2; ++k) for (int m = 0; m < 4; ++m) for (int n = 0; n < 2; ++n) \
;       acc[ai][bj][m][n] = __builtin_amdgcn_mfma_f32_16x16x32_bf16(At_[m][k], Bt_[n][k], acc[ai][bj][m][n], 0, 0, 0); \
;     __builtin_amdgcn_s_setprio(0); } while (0)
; #define WAIT_V(n) asm volatile("s_waitcnt vmcnt(" #n ")" ::: "memory")
; #define WAIT_L(n) asm volatile("s_waitcnt lgkmcnt(" #n ")" ::: "memory")
; #define BAR __builtin_amdgcn_s_barrier()
; #define SCHED __builtin_amdgcn_sched_barrier(0)
; template <int EPI, int lda, int ldb, int N, int K>
; __device__ __forceinline__ void gemm_phase(const u16* __restrict__ A, const u16* __restrict__ Bt, const GemmEpi ep, int wv) {
;     ...
;       STAGE(SB(0, 1), Bt, ldb, bcol + HALF, t + 2);
;       WAIT_V(6); BAR; MMA(1, 1, At, B1); BAR;
;       LDB(B0, 1, 0); SCHED; LDA(At, 1, 0); STAGE(SA(0, 1), Ab, lda, brow + HALF, t + 2);
;       WAIT_L(8); BAR; WAIT_L(0); MMA(0, 0, At, B0); BAR; SCHED;
;       LDB(B1, 1, 1); STAGE(SB(1, 0), Bt, ldb, bcol, t + 3);
;       BAR; WAIT_L(0); MMA(0, 1, At, B1); BAR;
;       LDA(At, 1, 1); STAGE(SA(1, 0), Ab, lda, brow, t + 3);
	v_add_u32_e32 v166, s63, v155
	v_add_u32_e32 v167, 0x2000, v166
	v_readfirstlane_b32 s51, v166
	v_lshl_add_u64 v[168:169], v[240:241], 0, s[24:25]
	s_mov_b32 m0, s51
	v_readfirstlane_b32 s51, v167
	global_load_lds_dwordx4 v[168:169], off
	v_lshl_add_u64 v[168:169], v[242:243], 0, s[24:25]
	s_mov_b32 m0, s51
	s_nop 0
	global_load_lds_dwordx4 v[168:169], off
	s_waitcnt vmcnt(6)
	s_barrier
	s_setprio 0
	v_mfma_f32_16x16x32_bf16 v[28:31], v[184:187], v[216:219], v[28:31]
	v_mfma_f32_16x16x32_bf16 v[24:27], v[184:187], v[224:227], v[24:27]
	v_mfma_f32_16x16x32_bf16 v[20:23], v[192:195], v[216:219], v[20:23]
	v_mfma_f32_16x16x32_bf16 v[16:19], v[192:195], v[224:227], v[16:19]
	v_mfma_f32_16x16x32_bf16 v[12:15], v[200:203], v[216:219], v[12:15]
	v_mfma_f32_16x16x32_bf16 v[8:11], v[200:203], v[224:227], v[8:11]
	v_mfma_f32_16x16x32_bf16 v[4:7], v[208:211], v[216:219], v[4:7]
	v_mfma_f32_16x16x32_bf16 v[0:3], v[208:211], v[224:227], v[0:3]
	v_mfma_f32_16x16x32_bf16 v[28:31], v[188:191], v[220:223], v[28:31]
	v_mfma_f32_16x16x32_bf16 v[24:27], v[188:191], v[228:231], v[24:27]
	v_mfma_f32_16x16x32_bf16 v[20:23], v[196:199], v[220:223], v[20:23]
	v_mfma_f32_16x16x32_bf16 v[16:19], v[196:199], v[228:231], v[16:19]
	v_mfma_f32_16x16x32_bf16 v[12:15], v[204:207], v[220:223], v[12:15]
	v_mfma_f32_16x16x32_bf16 v[8:11], v[204:207], v[228:231], v[8:11]
	v_mfma_f32_16x16x32_bf16 v[4:7], v[212:215], v[220:223], v[4:7]
	v_mfma_f32_16x16x32_bf16 v[0:3], v[212:215], v[228:231], v[0:3]
	s_setprio 0
	s_barrier
	ds_read_b128 v[172:175], v156
	ds_read_b128 v[176:179], v156 offset:1024
	ds_read_b128 v[180:183], v156 offset:2048
	ds_read_b128 v[184:187], v156 offset:3072
	v_add_u32_e32 v168, 0x4000, v149
	v_add_u32_e32 v169, 0x6000, v149
	v_readfirstlane_b32 s51, v168
	v_lshl_add_u64 v[220:221], v[236:237], 0, s[26:27]
	s_mov_b32 m0, s51
	v_readfirstlane_b32 s51, v169
	ds_read_b128 v[188:191], v153 offset:32768
	ds_read_b128 v[192:195], v153 offset:33792
	ds_read_b128 v[196:199], v152 offset:32768
	ds_read_b128 v[200:203], v152 offset:33792
	ds_read_b128 v[204:207], v151 offset:32768
	ds_read_b128 v[208:211], v151 offset:33792
	ds_read_b128 v[212:215], v150 offset:32768
	ds_read_b128 v[216:219], v150 offset:33792
	global_load_lds_dwordx4 v[220:221], off
	v_lshl_add_u64 v[220:221], v[238:239], 0, s[26:27]
	s_mov_b32 m0, s51
	s_nop 0
	global_load_lds_dwordx4 v[220:221], off
	s_waitcnt lgkmcnt(8)
	s_barrier
	s_waitcnt lgkmcnt(0)
	s_setprio 0
	s_waitcnt lgkmcnt(0)
	v_mfma_f32_16x16x32_bf16 v[124:127], v[188:191], v[172:175], v[124:127]
	v_mfma_f32_16x16x32_bf16 v[120:123], v[188:191], v[180:183], v[120:123]
	v_mfma_f32_16x16x32_bf16 v[116:119], v[196:199], v[172:175], v[116:119]
	v_mfma_f32_16x16x32_bf16 v[112:115], v[196:199], v[180:183], v[112:115]
	v_mfma_f32_16x16x32_bf16 v[108:111], v[204:207], v[172:175], v[108:111]
	v_mfma_f32_16x16x32_bf16 v[104:107], v[204:207], v[180:183], v[104:107]
	v_mfma_f32_16x16x32_bf16 v[100:103], v[212:215], v[172:175], v[100:103]
	v_mfma_f32_16x16x32_bf16 v[96:99], v[212:215], v[180:183], v[96:99]
	v_mfma_f32_16x16x32_bf16 v[124:127], v[192:195], v[176:179], v[124:127]
	v_mfma_f32_16x16x32_bf16 v[120:123], v[192:195], v[184:187], v[120:123]
	v_mfma_f32_16x16x32_bf16 v[116:119], v[200:203], v[176:179], v[116:119]
	v_mfma_f32_16x16x32_bf16 v[112:115], v[200:203], v[184:187], v[112:115]
	v_mfma_f32_16x16x32_bf16 v[108:111], v[208:211], v[176:179], v[108:111]
	v_mfma_f32_16x16x32_bf16 v[104:107], v[208:211], v[184:187], v[104:107]
	v_mfma_f32_16x16x32_bf16 v[100:103], v[216:219], v[176:179], v[100:103]
	v_mfma_f32_16x16x32_bf16 v[96:99], v[216:219], v[184:187], v[96:99]
	s_setprio 0
	s_barrier
	v_readfirstlane_b32 s51, v157
	v_add_u32_e32 v246, 0x2000, v157
	v_lshl_add_u64 v[244:245], v[240:241], 0, s[36:37]
	s_mov_b32 m0, s51
	v_readfirstlane_b32 s51, v246
	ds_read_b128 v[220:223], v154
	ds_read_b128 v[224:227], v154 offset:1024
	ds_read_b128 v[228:231], v154 offset:2048
	ds_read_b128 v[232:235], v154 offset:3072
	global_load_lds_dwordx4 v[244:245], off
	v_lshl_add_u64 v[244:245], v[242:243], 0, s[36:37]
	s_mov_b32 m0, s51
	s_nop 0
	global_load_lds_dwordx4 v[244:245], off
	s_barrier
	s_waitcnt lgkmcnt(0)
	s_setprio 0
	s_waitcnt lgkmcnt(0)
	v_mfma_f32_16x16x32_bf16 v[92:95], v[188:191], v[220:223], v[92:95]
	v_mfma_f32_16x16x32_bf16 v[88:91], v[188:191], v[228:231], v[88:91]
	v_mfma_f32_16x16x32_bf16 v[84:87], v[196:199], v[220:223], v[84:87]
	v_mfma_f32_16x16x32_bf16 v[80:83], v[196:199], v[228:231], v[80:83]
	v_mfma_f32_16x16x32_bf16 v[76:79], v[204:207], v[220:223], v[76:79]
	v_mfma_f32_16x16x32_bf16 v[72:75], v[204:207], v[228:231], v[72:75]
	v_mfma_f32_16x16x32_bf16 v[68:71], v[212:215], v[220:223], v[68:71]
	v_mfma_f32_16x16x32_bf16 v[64:67], v[212:215], v[228:231], v[64:67]
	v_mfma_f32_16x16x32_bf16 v[92:95], v[192:195], v[224:227], v[92:95]
	v_mfma_f32_16x16x32_bf16 v[88:91], v[192:195], v[232:235], v[88:91]
	v_mfma_f32_16x16x32_bf16 v[84:87], v[200:203], v[224:227], v[84:87]
	v_mfma_f32_16x16x32_bf16 v[80:83], v[200:203], v[232:235], v[80:83]
	v_mfma_f32_16x16x32_bf16 v[76:79], v[208:211], v[224:227], v[76:79]
	v_mfma_f32_16x16x32_bf16 v[72:75], v[208:211], v[232:235], v[72:75]
	v_mfma_f32_16x16x32_bf16 v[68:71], v[216:219], v[224:227], v[68:71]
	v_mfma_f32_16x16x32_bf16 v[64:67], v[216:219], v[232:235], v[64:67]
	s_setprio 0
	v_readfirstlane_b32 s51, v158
	v_lshl_add_u64 v[236:237], v[236:237], 0, s[38:39]
	s_mov_b32 m0, s51
	v_readfirstlane_b32 s51, v159
	s_barrier
; #define STAGE(P, BASE, LD, br, kt) do { const char* _g = (const char*)((BASE) + (size_t)(br) * (LD) + (size_t)(kt) * 64); \
;     for (int _i = 0; _i < 2; ++_i) { int _b = tidx * 16 + _i * 8192; int _r, _c; stage_rc(_b, _r, _c); \
;       __builtin_amdgcn_global_load_lds((const unsigned*)(_g + (unsigned)((_r * (LD) + _c) * 2)), (unsigned*)((char*)(P) + _b), 16, 0, 0); } } while (0)
; #define LDA(dst, b, h) for (int m = 0; m < 4; ++m) for (int k = 0; k < 2; ++k) \
;     dst[m][k] = *reinterpret_cast<const bf16x8*>((char*)SA(b, h) + lds_byte(wr * 64 + m * 16 + fr, k * 32 + fq * 8))
; #define LDB(dst, b, h) for (int n = 0; n < 2; ++n) for (int k = 0; k < 2; ++k) \
;     dst[n][k] = *reinterpret_cast<const bf16x8*>((char*)SB(b, h) + lds_byte(wc * 32 + n * 16 + fr, k * 32 + fq * 8))
; #define MMA(ai, bj, At_, Bt_) do { __builtin_amdgcn_s_setprio(1); \
;     for (int k = 0; k < 2; ++k) for (int m = 0; m < 4; ++m) for (int n = 0; n < 2; ++n) \
;       acc[ai][bj][m][n] = __builtin_amdgcn_mfma_f32_16x16x32_bf16(At_[m][k], Bt_[n][k], acc[ai][bj][m][n], 0, 0, 0); \
;     __builtin_amdgcn_s_setprio(0); } while (0)
; #define WAIT_V(n) asm volatile("s_waitcnt vmcnt(" #n ")" ::: "memory")
; #define WAIT_L(n) asm volatile("s_waitcnt lgkmcnt(" #n ")" ::: "memory")
; #define BAR __builtin_amdgcn_s_barrier()
; #define SCHED __builtin_amdgcn_sched_barrier(0)
; template <int EPI, int lda, int ldb, int N, int K>
; __device__ __forceinline__ void gemm_phase(const u16* __restrict__ A, const u16* __restrict__ Bt, const GemmEpi ep, int wv) {
;     ...
;       LDA(At, 1, 1); STAGE(SA(1, 0), Ab, lda, brow, t + 3);
;       BAR; WAIT_L(0); MMA(1, 0, At, B0); BAR; SCHED;
;       STAGE(SB(1, 1), Bt, ldb, bcol + HALF, t + 3);
;       WAIT_V(6); BAR; MMA(1, 1, At, B1); BAR;
;     }
;     { LDB(B0, 0, 0); LDA(At, 0, 0); STAGE(SA(1, 1), Ab, lda, brow + HALF, nt - 1);
;       BAR; WAIT_L(0); MMA(0, 0, At, B0); BAR;
;       LDB(B1, 0, 1); BAR; WAIT_L(0); MMA(0, 1, At, B1); BAR;
	ds_read_b128 v[188:191], v153 offset:49152
	ds_read_b128 v[192:195], v153 offset:50176
	ds_read_b128 v[196:199], v152 offset:49152
	ds_read_b128 v[200:203], v152 offset:50176
	ds_read_b128 v[204:207], v151 offset:49152
	ds_read_b128 v[208:211], v151 offset:50176
	ds_read_b128 v[212:215], v150 offset:49152
	ds_read_b128 v[216:219], v150 offset:50176
	global_load_lds_dwordx4 v[236:237], off
	v_lshl_add_u64 v[236:237], v[238:239], 0, s[38:39]
	s_mov_b32 m0, s51
	s_nop 0
	global_load_lds_dwordx4 v[236:237], off
	s_barrier
	s_waitcnt lgkmcnt(0)
	s_setprio 0
	s_waitcnt lgkmcnt(0)
	v_mfma_f32_16x16x32_bf16 v[60:63], v[188:191], v[172:175], v[60:63]
	v_mfma_f32_16x16x32_bf16 v[56:59], v[188:191], v[180:183], v[56:59]
	v_mfma_f32_16x16x32_bf16 v[52:55], v[196:199], v[172:175], v[52:55]
	v_mfma_f32_16x16x32_bf16 v[48:51], v[196:199], v[180:183], v[48:51]
	v_mfma_f32_16x16x32_bf16 v[44:47], v[204:207], v[172:175], v[44:47]
	v_mfma_f32_16x16x32_bf16 v[40:43], v[204:207], v[180:183], v[40:43]
	v_mfma_f32_16x16x32_bf16 v[36:39], v[212:215], v[172:175], v[36:39]
	v_mfma_f32_16x16x32_bf16 v[32:35], v[212:215], v[180:183], v[32:35]
	v_mfma_f32_16x16x32_bf16 v[60:63], v[192:195], v[176:179], v[60:63]
	v_mfma_f32_16x16x32_bf16 v[56:59], v[192:195], v[184:187], v[56:59]
	v_mfma_f32_16x16x32_bf16 v[52:55], v[200:203], v[176:179], v[52:55]
	v_mfma_f32_16x16x32_bf16 v[48:51], v[200:203], v[184:187], v[48:51]
	v_mfma_f32_16x16x32_bf16 v[44:47], v[208:211], v[176:179], v[44:47]
	v_mfma_f32_16x16x32_bf16 v[40:43], v[208:211], v[184:187], v[40:43]
	v_mfma_f32_16x16x32_bf16 v[36:39], v[216:219], v[176:179], v[36:39]
	v_mfma_f32_16x16x32_bf16 v[32:35], v[216:219], v[184:187], v[32:35]
	s_setprio 0
	s_barrier
	v_readfirstlane_b32 s51, v160
	v_add_u32_e32 v174, 0x2000, v160
	v_lshl_add_u64 v[172:173], v[240:241], 0, s[42:43]
	s_mov_b32 m0, s51
	v_readfirstlane_b32 s51, v174
	global_load_lds_dwordx4 v[172:173], off
	v_lshl_add_u64 v[172:173], v[242:243], 0, s[42:43]
	s_mov_b32 m0, s51
	s_nop 0
	global_load_lds_dwordx4 v[172:173], off
	s_waitcnt vmcnt(6)
	s_barrier
	s_setprio 0
	v_mfma_f32_16x16x32_bf16 v[28:31], v[188:191], v[220:223], v[28:31]
	v_mfma_f32_16x16x32_bf16 v[24:27], v[188:191], v[228:231], v[24:27]
	v_mfma_f32_16x16x32_bf16 v[20:23], v[196:199], v[220:223], v[20:23]
	v_mfma_f32_16x16x32_bf16 v[16:19], v[196:199], v[228:231], v[16:19]
	v_mfma_f32_16x16x32_bf16 v[12:15], v[204:207], v[220:223], v[12:15]
	v_mfma_f32_16x16x32_bf16 v[8:11], v[204:207], v[228:231], v[8:11]
	v_mfma_f32_16x16x32_bf16 v[4:7], v[212:215], v[220:223], v[4:7]
	v_mfma_f32_16x16x32_bf16 v[0:3], v[212:215], v[228:231], v[0:3]
	v_mfma_f32_16x16x32_bf16 v[28:31], v[192:195], v[224:227], v[28:31]
	v_mfma_f32_16x16x32_bf16 v[24:27], v[192:195], v[232:235], v[24:27]
	v_mfma_f32_16x16x32_bf16 v[20:23], v[200:203], v[224:227], v[20:23]
	v_mfma_f32_16x16x32_bf16 v[16:19], v[200:203], v[232:235], v[16:19]
	v_mfma_f32_16x16x32_bf16 v[12:15], v[208:211], v[224:227], v[12:15]
	v_mfma_f32_16x16x32_bf16 v[8:11], v[208:211], v[232:235], v[8:11]
	v_mfma_f32_16x16x32_bf16 v[4:7], v[216:219], v[224:227], v[4:7]
	v_mfma_f32_16x16x32_bf16 v[0:3], v[216:219], v[232:235], v[0:3]
	s_setprio 0
	s_add_i32 s50, s50, 2
	s_add_u32 s48, s48, 0x100
	s_addc_u32 s49, s49, 0
	s_cmp_gt_u32 s50, 27
	s_barrier
	s_cbranch_scc0 .LBB0_340
	s_add_i32 s48, s46, 0x80
	s_mul_hi_i32 s49, s48, 0x1080
	s_mulk_i32 s48, 0x1080
	s_add_u32 s48, s31, s48
	s_addc_u32 s49, s56, s49
	v_lshl_add_u64 v[158:159], s[48:49], 0, v[128:129]
	v_readfirstlane_b32 s50, v170
	v_lshl_add_u64 v[158:159], v[158:159], 0, s[44:45]
	s_mov_b32 m0, s50
	ds_read_b128 v[134:137], v162
	ds_read_b128 v[138:141], v162 offset:1024
	ds_read_b128 v[172:175], v162 offset:2048
	ds_read_b128 v[176:179], v162 offset:3072
	ds_read_b128 v[180:183], v153
	ds_read_b128 v[184:187], v153 offset:1024
	ds_read_b128 v[188:191], v152
	ds_read_b128 v[192:195], v152 offset:1024
	ds_read_b128 v[196:199], v151
	ds_read_b128 v[200:203], v151 offset:1024
	ds_read_b128 v[204:207], v150
	ds_read_b128 v[208:211], v150 offset:1024
	global_load_lds_dwordx4 v[158:159], off
	v_lshl_add_u64 v[158:159], s[48:49], 0, v[132:133]
	v_readfirstlane_b32 s48, v171
	v_lshl_add_u64 v[158:159], v[158:159], 0, s[44:45]
	s_mov_b32 m0, s48
	s_nop 0
	global_load_lds_dwordx4 v[158:159], off
	s_barrier
	s_waitcnt lgkmcnt(0)
	s_setprio 0
	s_waitcnt lgkmcnt(0)
	v_mfma_f32_16x16x32_bf16 v[124:127], v[180:183], v[134:137], v[124:127]
	v_mfma_f32_16x16x32_bf16 v[120:123], v[180:183], v[172:175], v[120:123]
	v_mfma_f32_16x16x32_bf16 v[116:119], v[188:191], v[134:137], v[116:119]
	v_mfma_f32_16x16x32_bf16 v[112:115], v[188:191], v[172:175], v[112:115]
	v_mfma_f32_16x16x32_bf16 v[108:111], v[196:199], v[134:137], v[108:111]
	v_mfma_f32_16x16x32_bf16 v[104:107], v[196:199], v[172:175], v[104:107]
	v_mfma_f32_16x16x32_bf16 v[100:103], v[204:207], v[134:137], v[100:103]
	v_mfma_f32_16x16x32_bf16 v[96:99], v[204:207], v[172:175], v[96:99]
	v_mfma_f32_16x16x32_bf16 v[124:127], v[184:187], v[138:141], v[124:127]
	v_mfma_f32_16x16x32_bf16 v[120:123], v[184:187], v[176:179], v[120:123]
	v_mfma_f32_16x16x32_bf16 v[116:119], v[192:195], v[138:141], v[116:119]
	v_mfma_f32_16x16x32_bf16 v[112:115], v[192:195], v[176:179], v[112:115]
	v_mfma_f32_16x16x32_bf16 v[108:111], v[200:203], v[138:141], v[108:111]
	v_mfma_f32_16x16x32_bf16 v[104:107], v[200:203], v[176:179], v[104:107]
	v_mfma_f32_16x16x32_bf16 v[100:103], v[208:211], v[138:141], v[100:103]
	v_mfma_f32_16x16x32_bf16 v[96:99], v[208:211], v[176:179], v[96:99]
	s_setprio 0
	s_barrier
	ds_read_b128 v[212:215], v161
	ds_read_b128 v[216:219], v161 offset:1024
	ds_read_b128 v[220:223], v161 offset:2048
	ds_read_b128 v[158:161], v161 offset:3072
	s_barrier
; #define LDA(dst, b, h) for (int m = 0; m < 4; ++m) for (int k = 0; k < 2; ++k) \
;     dst[m][k] = *reinterpret_cast<const bf16x8*>((char*)SA(b, h) + lds_byte(wr * 64 + m * 16 + fr, k * 32 + fq * 8))
; #define LDB(dst, b, h) for (int n = 0; n < 2; ++n) for (int k = 0; k < 2; ++k) \
;     dst[n][k] = *reinterpret_cast<const bf16x8*>((char*)SB(b, h) + lds_byte(wc * 32 + n * 16 + fr, k * 32 + fq * 8))
; #define MMA(ai, bj, At_, Bt_) do { __builtin_amdgcn_s_setprio(1); \
;     for (int k = 0; k < 2; ++k) for (int m = 0; m < 4; ++m) for (int n = 0; n < 2; ++n) \
;       acc[ai][bj][m][n] = __builtin_amdgcn_mfma_f32_16x16x32_bf16(At_[m][k], Bt_[n][k], acc[ai][bj][m][n], 0, 0, 0); \
;     __builtin_amdgcn_s_setprio(0); } while (0)
; #define WAIT_V(n) asm volatile("s_waitcnt vmcnt(" #n ")" ::: "memory")
; #define WAIT_L(n) asm volatile("s_waitcnt lgkmcnt(" #n ")" ::: "memory")
; #define BAR __builtin_amdgcn_s_barrier()
; template <int EPI, int lda, int ldb, int N, int K>
; __device__ __forceinline__ void gemm_phase(const u16* __restrict__ A, const u16* __restrict__ Bt, const GemmEpi ep, int wv) {
;     ...
;       BAR; WAIT_L(0); MMA(0, 0, At, B0); BAR;
;       LDB(B1, 0, 1); BAR; WAIT_L(0); MMA(0, 1, At, B1); BAR;
;       LDA(At, 0, 1); WAIT_V(4); BAR; WAIT_L(0); MMA(1, 0, At, B0); MMA(1, 1, At, B1); BAR; }
;     { LDB(B0, 1, 0); LDA(At, 1, 0); WAIT_V(2); BAR; WAIT_L(0); MMA(0, 0, At, B0); BAR;
	s_waitcnt lgkmcnt(0)
	s_setprio 0
	s_waitcnt lgkmcnt(0)
	v_mfma_f32_16x16x32_bf16 v[92:95], v[180:183], v[212:215], v[92:95]
	v_mfma_f32_16x16x32_bf16 v[88:91], v[180:183], v[220:223], v[88:91]
	v_mfma_f32_16x16x32_bf16 v[76:79], v[196:199], v[212:215], v[76:79]
	v_mfma_f32_16x16x32_bf16 v[72:75], v[196:199], v[220:223], v[72:75]
	v_mfma_f32_16x16x32_bf16 v[68:71], v[204:207], v[212:215], v[68:71]
	v_mfma_f32_16x16x32_bf16 v[64:67], v[204:207], v[220:223], v[64:67]
	v_mfma_f32_16x16x32_bf16 v[84:87], v[188:191], v[212:215], v[84:87]
	v_mfma_f32_16x16x32_bf16 v[80:83], v[188:191], v[220:223], v[80:83]
	v_mfma_f32_16x16x32_bf16 v[92:95], v[184:187], v[216:219], v[92:95]
	v_mfma_f32_16x16x32_bf16 v[88:91], v[184:187], v[158:161], v[88:91]
	v_mfma_f32_16x16x32_bf16 v[76:79], v[200:203], v[216:219], v[76:79]
	v_mfma_f32_16x16x32_bf16 v[72:75], v[200:203], v[158:161], v[72:75]
	v_mfma_f32_16x16x32_bf16 v[68:71], v[208:211], v[216:219], v[68:71]
	v_mfma_f32_16x16x32_bf16 v[64:67], v[208:211], v[158:161], v[64:67]
	v_mfma_f32_16x16x32_bf16 v[180:183], v[192:195], v[216:219], v[84:87]
	v_mfma_f32_16x16x32_bf16 v[184:187], v[192:195], v[158:161], v[80:83]
	s_setprio 0
	s_barrier
	s_nop 0
	ds_read_b128 v[80:83], v153 offset:16384
	ds_read_b128 v[84:87], v153 offset:17408
	ds_read_b128 v[188:191], v152 offset:16384
	ds_read_b128 v[192:195], v152 offset:17408
	ds_read_b128 v[196:199], v151 offset:16384
	ds_read_b128 v[200:203], v151 offset:17408
	ds_read_b128 v[204:207], v150 offset:16384
	ds_read_b128 v[208:211], v150 offset:17408
	s_waitcnt vmcnt(4)
	s_barrier
	s_waitcnt lgkmcnt(0)
	s_setprio 0
	s_waitcnt lgkmcnt(0)
	v_mfma_f32_16x16x32_bf16 v[60:63], v[80:83], v[134:137], v[60:63]
	v_mfma_f32_16x16x32_bf16 v[44:47], v[196:199], v[134:137], v[44:47]
	v_mfma_f32_16x16x32_bf16 v[40:43], v[196:199], v[172:175], v[40:43]
	v_mfma_f32_16x16x32_bf16 v[36:39], v[204:207], v[134:137], v[36:39]
	v_mfma_f32_16x16x32_bf16 v[32:35], v[204:207], v[172:175], v[32:35]
	v_mfma_f32_16x16x32_bf16 v[56:59], v[80:83], v[172:175], v[56:59]
	v_mfma_f32_16x16x32_bf16 v[52:55], v[188:191], v[134:137], v[52:55]
	v_mfma_f32_16x16x32_bf16 v[48:51], v[188:191], v[172:175], v[48:51]
	v_mfma_f32_16x16x32_bf16 v[60:63], v[84:87], v[138:141], v[60:63]
	v_mfma_f32_16x16x32_bf16 v[44:47], v[200:203], v[138:141], v[44:47]
	v_mfma_f32_16x16x32_bf16 v[40:43], v[200:203], v[176:179], v[40:43]
	v_mfma_f32_16x16x32_bf16 v[36:39], v[208:211], v[138:141], v[36:39]
	v_mfma_f32_16x16x32_bf16 v[32:35], v[208:211], v[176:179], v[32:35]
	v_mfma_f32_16x16x32_bf16 v[134:137], v[84:87], v[176:179], v[56:59]
	v_mfma_f32_16x16x32_bf16 v[170:173], v[192:195], v[138:141], v[52:55]
	v_mfma_f32_16x16x32_bf16 v[224:227], v[192:195], v[176:179], v[48:51]
	s_setprio 0
	s_setprio 0
	v_mfma_f32_16x16x32_bf16 v[28:31], v[80:83], v[212:215], v[28:31]
	v_mfma_f32_16x16x32_bf16 v[20:23], v[188:191], v[212:215], v[20:23]
	v_mfma_f32_16x16x32_bf16 v[12:15], v[196:199], v[212:215], v[12:15]
	v_mfma_f32_16x16x32_bf16 v[4:7], v[204:207], v[212:215], v[4:7]
	v_mfma_f32_16x16x32_bf16 v[24:27], v[80:83], v[220:223], v[24:27]
	v_mfma_f32_16x16x32_bf16 v[16:19], v[188:191], v[220:223], v[16:19]
	v_mfma_f32_16x16x32_bf16 v[8:11], v[196:199], v[220:223], v[8:11]
	v_mfma_f32_16x16x32_bf16 v[0:3], v[204:207], v[220:223], v[0:3]
	v_mfma_f32_16x16x32_bf16 v[28:31], v[84:87], v[216:219], v[28:31]
	v_mfma_f32_16x16x32_bf16 v[20:23], v[192:195], v[216:219], v[20:23]
	v_mfma_f32_16x16x32_bf16 v[12:15], v[200:203], v[216:219], v[12:15]
	v_mfma_f32_16x16x32_bf16 v[4:7], v[208:211], v[216:219], v[4:7]
	v_mfma_f32_16x16x32_bf16 v[138:141], v[84:87], v[158:161], v[24:27]
	v_mfma_f32_16x16x32_bf16 v[174:177], v[192:195], v[158:161], v[16:19]
	v_mfma_f32_16x16x32_bf16 v[188:191], v[200:203], v[158:161], v[8:11]
	v_mfma_f32_16x16x32_bf16 v[158:161], v[208:211], v[158:161], v[0:3]
	s_setprio 0
	s_barrier
	s_nop 0
	ds_read_b128 v[0:3], v156
	ds_read_b128 v[8:11], v156 offset:1024
	ds_read_b128 v[16:19], v156 offset:2048
	ds_read_b128 v[192:195], v156 offset:3072
	ds_read_b128 v[24:27], v153 offset:32768
	ds_read_b128 v[56:59], v153 offset:33792
	ds_read_b128 v[196:199], v152 offset:32768
	ds_read_b128 v[200:203], v152 offset:33792
	ds_read_b128 v[204:207], v151 offset:32768
	ds_read_b128 v[208:211], v151 offset:33792
	ds_read_b128 v[212:215], v150 offset:32768
	ds_read_b128 v[216:219], v150 offset:33792
	s_waitcnt vmcnt(2)
	s_barrier
; #define LDA(dst, b, h) for (int m = 0; m < 4; ++m) for (int k = 0; k < 2; ++k) \
;     dst[m][k] = *reinterpret_cast<const bf16x8*>((char*)SA(b, h) + lds_byte(wr * 64 + m * 16 + fr, k * 32 + fq * 8))
; #define LDB(dst, b, h) for (int n = 0; n < 2; ++n) for (int k = 0; k < 2; ++k) \
;     dst[n][k] = *reinterpret_cast<const bf16x8*>((char*)SB(b, h) + lds_byte(wc * 32 + n * 16 + fr, k * 32 + fq * 8))
; #define MMA(ai, bj, At_, Bt_) do { __builtin_amdgcn_s_setprio(1); \
;     for (int k = 0; k < 2; ++k) for (int m = 0; m < 4; ++m) for (int n = 0; n < 2; ++n) \
;       acc[ai][bj][m][n] = __builtin_amdgcn_mfma_f32_16x16x32_bf16(At_[m][k], Bt_[n][k], acc[ai][bj][m][n], 0, 0, 0); \
;     __builtin_amdgcn_s_setprio(0); } while (0)
; #define WAIT_V(n) asm volatile("s_waitcnt vmcnt(" #n ")" ::: "memory")
; #define WAIT_L(n) asm volatile("s_waitcnt lgkmcnt(" #n ")" ::: "memory")
; #define BAR __builtin_amdgcn_s_barrier()
; template <int EPI, int lda, int ldb, int N, int K>
; __device__ __forceinline__ void gemm_phase(const u16* __restrict__ A, const u16* __restrict__ Bt, const GemmEpi ep, int wv) {
;     ...
;     { LDB(B0, 1, 0); LDA(At, 1, 0); WAIT_V(2); BAR; WAIT_L(0); MMA(0, 0, At, B0); BAR;
;       LDB(B1, 1, 1); WAIT_V(0); BAR; WAIT_L(0); MMA(0, 1, At, B1); BAR;
;       LDA(At, 1, 1); BAR; WAIT_L(0); MMA(1, 0, At, B0); MMA(1, 1, At, B1); BAR; }
;     if (wr == 0) BAR;
	s_waitcnt lgkmcnt(0)
	s_setprio 0
	s_waitcnt lgkmcnt(0)
	v_mfma_f32_16x16x32_bf16 v[48:51], v[24:27], v[0:3], v[124:127]
	v_mfma_f32_16x16x32_bf16 v[52:55], v[24:27], v[16:19], v[120:123]
	v_mfma_f32_16x16x32_bf16 v[80:83], v[196:199], v[0:3], v[116:119]
	v_mfma_f32_16x16x32_bf16 v[84:87], v[196:199], v[16:19], v[112:115]
	v_mfma_f32_16x16x32_bf16 v[108:111], v[204:207], v[0:3], v[108:111]
	v_mfma_f32_16x16x32_bf16 v[104:107], v[204:207], v[16:19], v[104:107]
	v_mfma_f32_16x16x32_bf16 v[112:115], v[212:215], v[0:3], v[100:103]
	v_mfma_f32_16x16x32_bf16 v[120:123], v[212:215], v[16:19], v[96:99]
	v_mfma_f32_16x16x32_bf16 v[124:127], v[56:59], v[8:11], v[48:51]
	v_mfma_f32_16x16x32_bf16 v[116:119], v[56:59], v[192:195], v[52:55]
	v_mfma_f32_16x16x32_bf16 v[100:103], v[200:203], v[8:11], v[80:83]
	v_mfma_f32_16x16x32_bf16 v[96:99], v[200:203], v[192:195], v[84:87]
	v_mfma_f32_16x16x32_bf16 v[84:87], v[208:211], v[8:11], v[108:111]
	v_mfma_f32_16x16x32_bf16 v[80:83], v[208:211], v[192:195], v[104:107]
	v_mfma_f32_16x16x32_bf16 v[52:55], v[216:219], v[8:11], v[112:115]
	v_mfma_f32_16x16x32_bf16 v[48:51], v[216:219], v[192:195], v[120:123]
	s_setprio 0
	s_barrier
	ds_read_b128 v[220:223], v154
	ds_read_b128 v[228:231], v154 offset:1024
	ds_read_b128 v[232:235], v154 offset:2048
	ds_read_b128 v[154:157], v154 offset:3072
	s_waitcnt vmcnt(0)
	s_barrier
	s_waitcnt lgkmcnt(0)
	s_setprio 0
	s_waitcnt lgkmcnt(0)
	v_mfma_f32_16x16x32_bf16 v[92:95], v[24:27], v[220:223], v[92:95]
	v_mfma_f32_16x16x32_bf16 v[24:27], v[24:27], v[232:235], v[88:91]
	v_mfma_f32_16x16x32_bf16 v[88:91], v[196:199], v[220:223], v[180:183]
	v_mfma_f32_16x16x32_bf16 v[104:107], v[196:199], v[232:235], v[184:187]
	v_mfma_f32_16x16x32_bf16 v[76:79], v[204:207], v[220:223], v[76:79]
	v_mfma_f32_16x16x32_bf16 v[72:75], v[204:207], v[232:235], v[72:75]
	v_mfma_f32_16x16x32_bf16 v[68:71], v[212:215], v[220:223], v[68:71]
	v_mfma_f32_16x16x32_bf16 v[64:67], v[212:215], v[232:235], v[64:67]
	v_mfma_f32_16x16x32_bf16 v[120:123], v[56:59], v[228:231], v[92:95]
	v_mfma_f32_16x16x32_bf16 v[112:115], v[56:59], v[154:157], v[24:27]
	v_mfma_f32_16x16x32_bf16 v[108:111], v[200:203], v[228:231], v[88:91]
	v_mfma_f32_16x16x32_bf16 v[104:107], v[200:203], v[154:157], v[104:107]
	v_mfma_f32_16x16x32_bf16 v[92:95], v[208:211], v[228:231], v[76:79]
	v_mfma_f32_16x16x32_bf16 v[88:91], v[208:211], v[154:157], v[72:75]
	v_mfma_f32_16x16x32_bf16 v[68:71], v[216:219], v[228:231], v[68:71]
	v_mfma_f32_16x16x32_bf16 v[56:59], v[216:219], v[154:157], v[64:67]
	s_setprio 0
	s_barrier
	s_nop 0
	ds_read_b128 v[64:67], v153 offset:49152
	ds_read_b128 v[178:181], v153 offset:50176
	ds_read_b128 v[76:79], v152 offset:49152
	ds_read_b128 v[182:185], v152 offset:50176
	ds_read_b128 v[196:199], v151 offset:49152
	ds_read_b128 v[200:203], v151 offset:50176
	ds_read_b128 v[204:207], v150 offset:49152
	ds_read_b128 v[150:153], v150 offset:50176
	s_barrier
	s_waitcnt lgkmcnt(0)
	s_setprio 0
	s_waitcnt lgkmcnt(0)
	v_mfma_f32_16x16x32_bf16 v[24:27], v[64:67], v[0:3], v[60:63]
	v_mfma_f32_16x16x32_bf16 v[60:63], v[64:67], v[16:19], v[134:137]
	v_mfma_f32_16x16x32_bf16 v[134:137], v[76:79], v[0:3], v[170:173]
	v_mfma_f32_16x16x32_bf16 v[170:173], v[76:79], v[16:19], v[224:227]
	v_mfma_f32_16x16x32_bf16 v[44:47], v[196:199], v[0:3], v[44:47]
	v_mfma_f32_16x16x32_bf16 v[208:211], v[196:199], v[16:19], v[40:43]
	v_mfma_f32_16x16x32_bf16 v[0:3], v[204:207], v[0:3], v[36:39]
	v_mfma_f32_16x16x32_bf16 v[36:39], v[204:207], v[16:19], v[32:35]
	v_mfma_f32_16x16x32_bf16 v[72:75], v[178:181], v[8:11], v[24:27]
	v_mfma_f32_16x16x32_bf16 v[60:63], v[178:181], v[192:195], v[60:63]
	v_mfma_f32_16x16x32_bf16 v[40:43], v[182:185], v[8:11], v[134:137]
	v_mfma_f32_16x16x32_bf16 v[32:35], v[182:185], v[192:195], v[170:173]
	v_mfma_f32_16x16x32_bf16 v[24:27], v[200:203], v[8:11], v[44:47]
	v_mfma_f32_16x16x32_bf16 v[16:19], v[200:203], v[192:195], v[208:211]
	v_mfma_f32_16x16x32_bf16 v[8:11], v[150:153], v[8:11], v[0:3]
	v_mfma_f32_16x16x32_bf16 v[0:3], v[150:153], v[192:195], v[36:39]
	s_setprio 0
	s_setprio 0
	v_mfma_f32_16x16x32_bf16 v[28:31], v[64:67], v[220:223], v[28:31]
	v_mfma_f32_16x16x32_bf16 v[36:39], v[64:67], v[232:235], v[138:141]
	v_mfma_f32_16x16x32_bf16 v[20:23], v[76:79], v[220:223], v[20:23]
	v_mfma_f32_16x16x32_bf16 v[134:137], v[76:79], v[232:235], v[174:177]
	v_mfma_f32_16x16x32_bf16 v[12:15], v[196:199], v[220:223], v[12:15]
	v_mfma_f32_16x16x32_bf16 v[138:141], v[196:199], v[232:235], v[188:191]
	v_mfma_f32_16x16x32_bf16 v[4:7], v[204:207], v[220:223], v[4:7]
	v_mfma_f32_16x16x32_bf16 v[158:161], v[204:207], v[232:235], v[158:161]
	v_mfma_f32_16x16x32_bf16 v[76:79], v[178:181], v[228:231], v[28:31]
	v_mfma_f32_16x16x32_bf16 v[64:67], v[178:181], v[154:157], v[36:39]
	v_mfma_f32_16x16x32_bf16 v[44:47], v[182:185], v[228:231], v[20:23]
	v_mfma_f32_16x16x32_bf16 v[36:39], v[182:185], v[154:157], v[134:137]
	v_mfma_f32_16x16x32_bf16 v[28:31], v[200:203], v[228:231], v[12:15]
	v_mfma_f32_16x16x32_bf16 v[20:23], v[200:203], v[154:157], v[138:141]
	v_mfma_f32_16x16x32_bf16 v[12:15], v[150:153], v[228:231], v[4:7]
	v_mfma_f32_16x16x32_bf16 v[4:7], v[150:153], v[154:157], v[158:161]
	s_setprio 0
	v_cmp_gt_u32_e32 vcc, s64, v130
	s_barrier
	s_and_saveexec_b64 s[48:49], vcc
	s_cbranch_execz .LBB0_343
	s_barrier

; #define STAGE(P, BASE, LD, br, kt) do { const char* _g = (const char*)((BASE) + (size_t)(br) * (LD) + (size_t)(kt) * 64); \
;     for (int _i = 0; _i < 2; ++_i) { int _b = tidx * 16 + _i * 8192; int _r, _c; stage_rc(_b, _r, _c); \
;       __builtin_amdgcn_global_load_lds((const unsigned*)(_g + (unsigned)((_r * (LD) + _c) * 2)), (unsigned*)((char*)(P) + _b), 16, 0, 0); } } while (0)
; #define LDA(dst, b, h) for (int m = 0; m < 4; ++m) for (int k = 0; k < 2; ++k) \
;     dst[m][k] = *reinterpret_cast<const bf16x8*>((char*)SA(b, h) + lds_byte(wr * 64 + m * 16 + fr, k * 32 + fq * 8))
; #define LDB(dst, b, h) for (int n = 0; n < 2; ++n) for (int k = 0; k < 2; ++k) \
;     dst[n][k] = *reinterpret_cast<const bf16x8*>((char*)SB(b, h) + lds_byte(wc * 32 + n * 16 + fr, k * 32 + fq * 8))
; #define MMA(ai, bj, At_, Bt_) do { __builtin_amdgcn_s_setprio(1); \
;     for (int k = 0; k < 2; ++k) for (int m = 0; m < 4; ++m) for (int n = 0; n < 2; ++n) \
;       acc[ai][bj][m][n] = __builtin_amdgcn_mfma_f32_16x16x32_bf16(At_[m][k], Bt_[n][k], acc[ai][bj][m][n], 0, 0, 0); \
;     __builtin_amdgcn_s_setprio(0); } while (0)
; #define WAIT_L(n) asm volatile("s_waitcnt lgkmcnt(" #n ")" ::: "memory")
; #define BAR __builtin_amdgcn_s_barrier()
; #define SCHED __builtin_amdgcn_sched_barrier(0)
; template <int EPI, int lda, int ldb, int N, int K>
; __device__ __forceinline__ void gemm_phase(const u16* __restrict__ A, const u16* __restrict__ Bt, const GemmEpi ep, int wv) {
;     ...
;     for (int t = 0; t < nt - 2; t += 2) {
;       LDB(B0, 0, 0); SCHED; LDA(At, 0, 0); STAGE(SA(1, 1), Ab, lda, brow + HALF, t + 1);
;       WAIT_L(8); BAR; WAIT_L(0); MMA(0, 0, At, B0); BAR; SCHED;
;       LDB(B1, 0, 1); STAGE(SB(0, 0), Bt, ldb, bcol, t + 2);
;       BAR; WAIT_L(0); MMA(0, 1, At, B1); BAR;
;       LDA(At, 0, 1); STAGE(SA(0, 0), Ab, lda, brow, t + 2);
;       BAR; WAIT_L(0); MMA(1, 0, At, B0); BAR; SCHED;
.LBB0_654:
	ds_read_b128 v[164:167], v160
	ds_read_b128 v[170:173], v160 offset:1024
	ds_read_b128 v[174:177], v160 offset:2048
	ds_read_b128 v[178:181], v160 offset:3072
	v_add_u32_e32 v168, 0xc000, v143
	v_lshl_add_u64 v[234:235], v[138:139], 0, s[52:53]
	v_readfirstlane_b32 s55, v168
	v_add_u32_e32 v169, 0xe000, v143
	v_lshl_add_u64 v[162:163], v[234:235], 0, s[20:21]
	s_mov_b32 m0, s55
	v_lshl_add_u64 v[236:237], v[140:141], 0, s[52:53]
	v_readfirstlane_b32 s55, v169
	ds_read_b128 v[182:185], v151
	ds_read_b128 v[186:189], v151 offset:1024
	ds_read_b128 v[190:193], v150
	ds_read_b128 v[194:197], v150 offset:1024
	ds_read_b128 v[198:201], v149
	ds_read_b128 v[202:205], v149 offset:1024
	ds_read_b128 v[206:209], v148
	ds_read_b128 v[210:213], v148 offset:1024
	global_load_lds_dwordx4 v[162:163], off
	v_lshl_add_u64 v[162:163], v[236:237], 0, s[20:21]
	s_mov_b32 m0, s55
	s_nop 0
	global_load_lds_dwordx4 v[162:163], off
	s_waitcnt lgkmcnt(8)
	s_barrier
	s_waitcnt lgkmcnt(0)
	s_setprio 0
	s_waitcnt lgkmcnt(0)
	v_mfma_f32_16x16x32_bf16 v[124:127], v[164:167], v[182:185], v[124:127]
	v_mfma_f32_16x16x32_bf16 v[120:123], v[174:177], v[182:185], v[120:123]
	v_mfma_f32_16x16x32_bf16 v[116:119], v[164:167], v[190:193], v[116:119]
	v_mfma_f32_16x16x32_bf16 v[112:115], v[174:177], v[190:193], v[112:115]
	v_mfma_f32_16x16x32_bf16 v[108:111], v[164:167], v[198:201], v[108:111]
	v_mfma_f32_16x16x32_bf16 v[104:107], v[174:177], v[198:201], v[104:107]
	v_mfma_f32_16x16x32_bf16 v[100:103], v[164:167], v[206:209], v[100:103]
	v_mfma_f32_16x16x32_bf16 v[96:99], v[174:177], v[206:209], v[96:99]
	v_mfma_f32_16x16x32_bf16 v[124:127], v[170:173], v[186:189], v[124:127]
	v_mfma_f32_16x16x32_bf16 v[120:123], v[178:181], v[186:189], v[120:123]
	v_mfma_f32_16x16x32_bf16 v[116:119], v[170:173], v[194:197], v[116:119]
	v_mfma_f32_16x16x32_bf16 v[112:115], v[178:181], v[194:197], v[112:115]
	v_mfma_f32_16x16x32_bf16 v[108:111], v[170:173], v[202:205], v[108:111]
	v_mfma_f32_16x16x32_bf16 v[104:107], v[178:181], v[202:205], v[104:107]
	v_mfma_f32_16x16x32_bf16 v[100:103], v[170:173], v[210:213], v[100:103]
	v_mfma_f32_16x16x32_bf16 v[96:99], v[178:181], v[210:213], v[96:99]
	s_setprio 0
	s_barrier
	v_add_u32_e32 v161, s65, v153
	v_lshl_add_u64 v[238:239], v[134:135], 0, s[52:53]
	v_readfirstlane_b32 s55, v161
	v_lshl_add_u64 v[162:163], v[238:239], 0, s[22:23]
	s_mov_b32 m0, s55
	ds_read_b128 v[214:217], v159
	ds_read_b128 v[218:221], v159 offset:1024
	ds_read_b128 v[222:225], v159 offset:2048
	ds_read_b128 v[226:229], v159 offset:3072
	global_load_lds_dwordx4 v[162:163], off
	v_add_u32_e32 v162, 0x2000, v161
	v_lshl_add_u64 v[240:241], v[136:137], 0, s[52:53]
	v_readfirstlane_b32 s55, v162
	v_lshl_add_u64 v[230:231], v[240:241], 0, s[22:23]
	s_mov_b32 m0, s55
	s_nop 0
	global_load_lds_dwordx4 v[230:231], off
	s_barrier
	s_waitcnt lgkmcnt(0)
	s_setprio 0
	s_waitcnt lgkmcnt(0)
	v_mfma_f32_16x16x32_bf16 v[92:95], v[214:217], v[182:185], v[92:95]
	v_mfma_f32_16x16x32_bf16 v[88:91], v[222:225], v[182:185], v[88:91]
	v_mfma_f32_16x16x32_bf16 v[84:87], v[214:217], v[190:193], v[84:87]
	v_mfma_f32_16x16x32_bf16 v[80:83], v[222:225], v[190:193], v[80:83]
	v_mfma_f32_16x16x32_bf16 v[76:79], v[214:217], v[198:201], v[76:79]
	v_mfma_f32_16x16x32_bf16 v[72:75], v[222:225], v[198:201], v[72:75]
	v_mfma_f32_16x16x32_bf16 v[68:71], v[214:217], v[206:209], v[68:71]
	v_mfma_f32_16x16x32_bf16 v[64:67], v[222:225], v[206:209], v[64:67]
	v_mfma_f32_16x16x32_bf16 v[92:95], v[218:221], v[186:189], v[92:95]
	v_mfma_f32_16x16x32_bf16 v[88:91], v[226:229], v[186:189], v[88:91]
	v_mfma_f32_16x16x32_bf16 v[84:87], v[218:221], v[194:197], v[84:87]
	v_mfma_f32_16x16x32_bf16 v[80:83], v[226:229], v[194:197], v[80:83]
	v_mfma_f32_16x16x32_bf16 v[76:79], v[218:221], v[202:205], v[76:79]
	v_mfma_f32_16x16x32_bf16 v[72:75], v[226:229], v[202:205], v[72:75]
	v_mfma_f32_16x16x32_bf16 v[68:71], v[218:221], v[210:213], v[68:71]
	v_mfma_f32_16x16x32_bf16 v[64:67], v[226:229], v[210:213], v[64:67]
	s_setprio 0
	v_readfirstlane_b32 s55, v143
	v_add_u32_e32 v163, 0x2000, v143
	v_lshl_add_u64 v[230:231], v[234:235], 0, s[24:25]
	s_mov_b32 m0, s55
	v_readfirstlane_b32 s55, v163
	s_barrier
	ds_read_b128 v[182:185], v151 offset:16384
	ds_read_b128 v[186:189], v151 offset:17408
	ds_read_b128 v[190:193], v150 offset:16384
	ds_read_b128 v[194:197], v150 offset:17408
	ds_read_b128 v[198:201], v149 offset:16384
	ds_read_b128 v[202:205], v149 offset:17408
	ds_read_b128 v[206:209], v148 offset:16384
	ds_read_b128 v[210:213], v148 offset:17408
	global_load_lds_dwordx4 v[230:231], off
	v_lshl_add_u64 v[230:231], v[236:237], 0, s[24:25]
	s_mov_b32 m0, s55
	s_nop 0
	global_load_lds_dwordx4 v[230:231], off
	s_barrier
	s_waitcnt lgkmcnt(0)
	s_setprio 0
	s_waitcnt lgkmcnt(0)
	v_mfma_f32_16x16x32_bf16 v[60:63], v[164:167], v[182:185], v[60:63]
	v_mfma_f32_16x16x32_bf16 v[56:59], v[174:177], v[182:185], v[56:59]
	v_mfma_f32_16x16x32_bf16 v[52:55], v[164:167], v[190:193], v[52:55]
	v_mfma_f32_16x16x32_bf16 v[48:51], v[174:177], v[190:193], v[48:51]
	v_mfma_f32_16x16x32_bf16 v[44:47], v[164:167], v[198:201], v[44:47]
	v_mfma_f32_16x16x32_bf16 v[40:43], v[174:177], v[198:201], v[40:43]
	v_mfma_f32_16x16x32_bf16 v[36:39], v[164:167], v[206:209], v[36:39]
	v_mfma_f32_16x16x32_bf16 v[32:35], v[174:177], v[206:209], v[32:35]
	v_mfma_f32_16x16x32_bf16 v[60:63], v[170:173], v[186:189], v[60:63]
	v_mfma_f32_16x16x32_bf16 v[56:59], v[178:181], v[186:189], v[56:59]
	v_mfma_f32_16x16x32_bf16 v[52:55], v[170:173], v[194:197], v[52:55]
	v_mfma_f32_16x16x32_bf16 v[48:51], v[178:181], v[194:197], v[48:51]
	v_mfma_f32_16x16x32_bf16 v[44:47], v[170:173], v[202:205], v[44:47]
	v_mfma_f32_16x16x32_bf16 v[40:43], v[178:181], v[202:205], v[40:43]
	v_mfma_f32_16x16x32_bf16 v[36:39], v[170:173], v[210:213], v[36:39]
	v_mfma_f32_16x16x32_bf16 v[32:35], v[178:181], v[210:213], v[32:35]
	s_setprio 0
	s_barrier
; #define STAGE(P, BASE, LD, br, kt) do { const char* _g = (const char*)((BASE) + (size_t)(br) * (LD) + (size_t)(kt) * 64); \
;     for (int _i = 0; _i < 2; ++_i) { int _b = tidx * 16 + _i * 8192; int _r, _c; stage_rc(_b, _r, _c); \
;       __builtin_amdgcn_global_load_lds((const unsigned*)(_g + (unsigned)((_r * (LD) + _c) * 2)), (unsigned*)((char*)(P) + _b), 16, 0, 0); } } while (0)
; #define LDA(dst, b, h) for (int m = 0; m < 4; ++m) for (int k = 0; k < 2; ++k) \
;     dst[m][k] = *reinterpret_cast<const bf16x8*>((char*)SA(b, h) + lds_byte(wr * 64 + m * 16 + fr, k * 32 + fq * 8))
; #define LDB(dst, b, h) for (int n = 0; n < 2; ++n) for (int k = 0; k < 2; ++k) \
;     dst[n][k] = *reinterpret_cast<const bf16x8*>((char*)SB(b, h) + lds_byte(wc * 32 + n * 16 + fr, k * 32 + fq * 8))
; #define MMA(ai, bj, At_, Bt_) do { __builtin_amdgcn_s_setprio(1); \
;     for (int k = 0; k < 2; ++k) for (int m = 0; m < 4; ++m) for (int n = 0; n < 2; ++n) \
;       acc[ai][bj][m][n] = __builtin_amdgcn_mfma_f32_16x16x32_bf16(At_[m][k], Bt_[n][k], acc[ai][bj][m][n], 0, 0, 0); \
;     __builtin_amdgcn_s_setprio(0); } while (0)
; #define WAIT_V(n) asm volatile("s_waitcnt vmcnt(" #n ")" ::: "memory")
; #define WAIT_L(n) asm volatile("s_waitcnt lgkmcnt(" #n ")" ::: "memory")
; #define BAR __builtin_amdgcn_s_barrier()
; #define SCHED __builtin_amdgcn_sched_barrier(0)
; template <int EPI, int lda, int ldb, int N, int K>
; __device__ __forceinline__ void gemm_phase(const u16* __restrict__ A, const u16* __restrict__ Bt, const GemmEpi ep, int wv) {
;     ...
;       STAGE(SB(0, 1), Bt, ldb, bcol + HALF, t + 2);
;       WAIT_V(6); BAR; MMA(1, 1, At, B1); BAR;
;       LDB(B0, 1, 0); SCHED; LDA(At, 1, 0); STAGE(SA(0, 1), Ab, lda, brow + HALF, t + 2);
;       WAIT_L(8); BAR; WAIT_L(0); MMA(0, 0, At, B0); BAR; SCHED;
;       LDB(B1, 1, 1); STAGE(SB(1, 0), Bt, ldb, bcol, t + 3);
;       BAR; WAIT_L(0); MMA(0, 1, At, B1); BAR;
;       LDA(At, 1, 1); STAGE(SA(1, 0), Ab, lda, brow, t + 3);
	v_add_u32_e32 v164, s66, v153
	v_add_u32_e32 v165, 0x2000, v164
	v_readfirstlane_b32 s55, v164
	v_lshl_add_u64 v[166:167], v[238:239], 0, s[26:27]
	s_mov_b32 m0, s55
	v_readfirstlane_b32 s55, v165
	global_load_lds_dwordx4 v[166:167], off
	v_lshl_add_u64 v[166:167], v[240:241], 0, s[26:27]
	s_mov_b32 m0, s55
	s_nop 0
	global_load_lds_dwordx4 v[166:167], off
	s_waitcnt vmcnt(6)
	s_barrier
	s_setprio 0
	v_mfma_f32_16x16x32_bf16 v[28:31], v[214:217], v[182:185], v[28:31]
	v_mfma_f32_16x16x32_bf16 v[24:27], v[222:225], v[182:185], v[24:27]
	v_mfma_f32_16x16x32_bf16 v[20:23], v[214:217], v[190:193], v[20:23]
	v_mfma_f32_16x16x32_bf16 v[16:19], v[222:225], v[190:193], v[16:19]
	v_mfma_f32_16x16x32_bf16 v[12:15], v[214:217], v[198:201], v[12:15]
	v_mfma_f32_16x16x32_bf16 v[8:11], v[222:225], v[198:201], v[8:11]
	v_mfma_f32_16x16x32_bf16 v[4:7], v[214:217], v[206:209], v[4:7]
	v_mfma_f32_16x16x32_bf16 v[0:3], v[222:225], v[206:209], v[0:3]
	v_mfma_f32_16x16x32_bf16 v[28:31], v[218:221], v[186:189], v[28:31]
	v_mfma_f32_16x16x32_bf16 v[24:27], v[226:229], v[186:189], v[24:27]
	v_mfma_f32_16x16x32_bf16 v[20:23], v[218:221], v[194:197], v[20:23]
	v_mfma_f32_16x16x32_bf16 v[16:19], v[226:229], v[194:197], v[16:19]
	v_mfma_f32_16x16x32_bf16 v[12:15], v[218:221], v[202:205], v[12:15]
	v_mfma_f32_16x16x32_bf16 v[8:11], v[226:229], v[202:205], v[8:11]
	v_mfma_f32_16x16x32_bf16 v[4:7], v[218:221], v[210:213], v[4:7]
	v_mfma_f32_16x16x32_bf16 v[0:3], v[226:229], v[210:213], v[0:3]
	s_setprio 0
	s_barrier
	ds_read_b128 v[170:173], v154
	ds_read_b128 v[174:177], v154 offset:1024
	ds_read_b128 v[178:181], v154 offset:2048
	ds_read_b128 v[182:185], v154 offset:3072
	v_add_u32_e32 v166, 0x4000, v143
	v_add_u32_e32 v167, 0x6000, v143
	v_readfirstlane_b32 s55, v166
	v_lshl_add_u64 v[218:219], v[234:235], 0, s[42:43]
	s_mov_b32 m0, s55
	v_readfirstlane_b32 s55, v167
	ds_read_b128 v[186:189], v151 offset:32768
	ds_read_b128 v[190:193], v151 offset:33792
	ds_read_b128 v[194:197], v150 offset:32768
	ds_read_b128 v[198:201], v150 offset:33792
	ds_read_b128 v[202:205], v149 offset:32768
	ds_read_b128 v[206:209], v149 offset:33792
	ds_read_b128 v[210:213], v148 offset:32768
	ds_read_b128 v[214:217], v148 offset:33792
	global_load_lds_dwordx4 v[218:219], off
	v_lshl_add_u64 v[218:219], v[236:237], 0, s[42:43]
	s_mov_b32 m0, s55
	s_nop 0
	global_load_lds_dwordx4 v[218:219], off
	s_waitcnt lgkmcnt(8)
	s_barrier
	s_waitcnt lgkmcnt(0)
	s_setprio 0
	s_waitcnt lgkmcnt(0)
	v_mfma_f32_16x16x32_bf16 v[124:127], v[170:173], v[186:189], v[124:127]
	v_mfma_f32_16x16x32_bf16 v[120:123], v[178:181], v[186:189], v[120:123]
	v_mfma_f32_16x16x32_bf16 v[116:119], v[170:173], v[194:197], v[116:119]
	v_mfma_f32_16x16x32_bf16 v[112:115], v[178:181], v[194:197], v[112:115]
	v_mfma_f32_16x16x32_bf16 v[108:111], v[170:173], v[202:205], v[108:111]
	v_mfma_f32_16x16x32_bf16 v[104:107], v[178:181], v[202:205], v[104:107]
	v_mfma_f32_16x16x32_bf16 v[100:103], v[170:173], v[210:213], v[100:103]
	v_mfma_f32_16x16x32_bf16 v[96:99], v[178:181], v[210:213], v[96:99]
	v_mfma_f32_16x16x32_bf16 v[124:127], v[174:177], v[190:193], v[124:127]
	v_mfma_f32_16x16x32_bf16 v[120:123], v[182:185], v[190:193], v[120:123]
	v_mfma_f32_16x16x32_bf16 v[116:119], v[174:177], v[198:201], v[116:119]
	v_mfma_f32_16x16x32_bf16 v[112:115], v[182:185], v[198:201], v[112:115]
	v_mfma_f32_16x16x32_bf16 v[108:111], v[174:177], v[206:209], v[108:111]
	v_mfma_f32_16x16x32_bf16 v[104:107], v[182:185], v[206:209], v[104:107]
	v_mfma_f32_16x16x32_bf16 v[100:103], v[174:177], v[214:217], v[100:103]
	v_mfma_f32_16x16x32_bf16 v[96:99], v[182:185], v[214:217], v[96:99]
	s_setprio 0
	s_barrier
	v_readfirstlane_b32 s55, v155
	v_add_u32_e32 v244, 0x2000, v155
	v_lshl_add_u64 v[242:243], v[238:239], 0, s[44:45]
	s_mov_b32 m0, s55
	v_readfirstlane_b32 s55, v244
	ds_read_b128 v[218:221], v152
	ds_read_b128 v[222:225], v152 offset:1024
	ds_read_b128 v[226:229], v152 offset:2048
	ds_read_b128 v[230:233], v152 offset:3072
	global_load_lds_dwordx4 v[242:243], off
	v_lshl_add_u64 v[242:243], v[240:241], 0, s[44:45]
	s_mov_b32 m0, s55
	s_nop 0
	global_load_lds_dwordx4 v[242:243], off
	s_barrier
	s_waitcnt lgkmcnt(0)
	s_setprio 0
	s_waitcnt lgkmcnt(0)
	v_mfma_f32_16x16x32_bf16 v[92:95], v[218:221], v[186:189], v[92:95]
	v_mfma_f32_16x16x32_bf16 v[88:91], v[226:229], v[186:189], v[88:91]
	v_mfma_f32_16x16x32_bf16 v[84:87], v[218:221], v[194:197], v[84:87]
	v_mfma_f32_16x16x32_bf16 v[80:83], v[226:229], v[194:197], v[80:83]
	v_mfma_f32_16x16x32_bf16 v[76:79], v[218:221], v[202:205], v[76:79]
	v_mfma_f32_16x16x32_bf16 v[72:75], v[226:229], v[202:205], v[72:75]
	v_mfma_f32_16x16x32_bf16 v[68:71], v[218:221], v[210:213], v[68:71]
	v_mfma_f32_16x16x32_bf16 v[64:67], v[226:229], v[210:213], v[64:67]
	v_mfma_f32_16x16x32_bf16 v[92:95], v[222:225], v[190:193], v[92:95]
	v_mfma_f32_16x16x32_bf16 v[88:91], v[230:233], v[190:193], v[88:91]
	v_mfma_f32_16x16x32_bf16 v[84:87], v[222:225], v[198:201], v[84:87]
	v_mfma_f32_16x16x32_bf16 v[80:83], v[230:233], v[198:201], v[80:83]
	v_mfma_f32_16x16x32_bf16 v[76:79], v[222:225], v[206:209], v[76:79]
	v_mfma_f32_16x16x32_bf16 v[72:75], v[230:233], v[206:209], v[72:75]
	v_mfma_f32_16x16x32_bf16 v[68:71], v[222:225], v[214:217], v[68:71]
	v_mfma_f32_16x16x32_bf16 v[64:67], v[230:233], v[214:217], v[64:67]
	s_setprio 0
	v_readfirstlane_b32 s55, v156
	v_lshl_add_u64 v[234:235], v[234:235], 0, s[46:47]
	s_mov_b32 m0, s55
	v_readfirstlane_b32 s55, v157
	s_barrier
; #define STAGE(P, BASE, LD, br, kt) do { const char* _g = (const char*)((BASE) + (size_t)(br) * (LD) + (size_t)(kt) * 64); \
;     for (int _i = 0; _i < 2; ++_i) { int _b = tidx * 16 + _i * 8192; int _r, _c; stage_rc(_b, _r, _c); \
;       __builtin_amdgcn_global_load_lds((const unsigned*)(_g + (unsigned)((_r * (LD) + _c) * 2)), (unsigned*)((char*)(P) + _b), 16, 0, 0); } } while (0)
; #define LDA(dst, b, h) for (int m = 0; m < 4; ++m) for (int k = 0; k < 2; ++k) \
;     dst[m][k] = *reinterpret_cast<const bf16x8*>((char*)SA(b, h) + lds_byte(wr * 64 + m * 16 + fr, k * 32 + fq * 8))
; #define LDB(dst, b, h) for (int n = 0; n < 2; ++n) for (int k = 0; k < 2; ++k) \
;     dst[n][k] = *reinterpret_cast<const bf16x8*>((char*)SB(b, h) + lds_byte(wc * 32 + n * 16 + fr, k * 32 + fq * 8))
; #define MMA(ai, bj, At_, Bt_) do { __builtin_amdgcn_s_setprio(1); \
;     for (int k = 0; k < 2; ++k) for (int m = 0; m < 4; ++m) for (int n = 0; n < 2; ++n) \
;       acc[ai][bj][m][n] = __builtin_amdgcn_mfma_f32_16x16x32_bf16(At_[m][k], Bt_[n][k], acc[ai][bj][m][n], 0, 0, 0); \
;     __builtin_amdgcn_s_setprio(0); } while (0)
; #define WAIT_V(n) asm volatile("s_waitcnt vmcnt(" #n ")" ::: "memory")
; #define WAIT_L(n) asm volatile("s_waitcnt lgkmcnt(" #n ")" ::: "memory")
; #define BAR __builtin_amdgcn_s_barrier()
; #define SCHED __builtin_amdgcn_sched_barrier(0)
; template <int EPI, int lda, int ldb, int N, int K>
; __device__ __forceinline__ void gemm_phase(const u16* __restrict__ A, const u16* __restrict__ Bt, const GemmEpi ep, int wv) {
;     ...
;       LDA(At, 1, 1); STAGE(SA(1, 0), Ab, lda, brow, t + 3);
;       BAR; WAIT_L(0); MMA(1, 0, At, B0); BAR; SCHED;
;       STAGE(SB(1, 1), Bt, ldb, bcol + HALF, t + 3);
;       WAIT_V(6); BAR; MMA(1, 1, At, B1); BAR;
;     }
;     { LDB(B0, 0, 0); LDA(At, 0, 0); STAGE(SA(1, 1), Ab, lda, brow + HALF, nt - 1);
;       BAR; WAIT_L(0); MMA(0, 0, At, B0); BAR;
;       LDB(B1, 0, 1); BAR; WAIT_L(0); MMA(0, 1, At, B1); BAR;
	ds_read_b128 v[186:189], v151 offset:49152
	ds_read_b128 v[190:193], v151 offset:50176
	ds_read_b128 v[194:197], v150 offset:49152
	ds_read_b128 v[198:201], v150 offset:50176
	ds_read_b128 v[202:205], v149 offset:49152
	ds_read_b128 v[206:209], v149 offset:50176
	ds_read_b128 v[210:213], v148 offset:49152
	ds_read_b128 v[214:217], v148 offset:50176
	global_load_lds_dwordx4 v[234:235], off
	v_lshl_add_u64 v[234:235], v[236:237], 0, s[46:47]
	s_mov_b32 m0, s55
	s_nop 0
	global_load_lds_dwordx4 v[234:235], off
	s_barrier
	s_waitcnt lgkmcnt(0)
	s_setprio 0
	s_waitcnt lgkmcnt(0)
	v_mfma_f32_16x16x32_bf16 v[60:63], v[170:173], v[186:189], v[60:63]
	v_mfma_f32_16x16x32_bf16 v[56:59], v[178:181], v[186:189], v[56:59]
	v_mfma_f32_16x16x32_bf16 v[52:55], v[170:173], v[194:197], v[52:55]
	v_mfma_f32_16x16x32_bf16 v[48:51], v[178:181], v[194:197], v[48:51]
	v_mfma_f32_16x16x32_bf16 v[44:47], v[170:173], v[202:205], v[44:47]
	v_mfma_f32_16x16x32_bf16 v[40:43], v[178:181], v[202:205], v[40:43]
	v_mfma_f32_16x16x32_bf16 v[36:39], v[170:173], v[210:213], v[36:39]
	v_mfma_f32_16x16x32_bf16 v[32:35], v[178:181], v[210:213], v[32:35]
	v_mfma_f32_16x16x32_bf16 v[60:63], v[174:177], v[190:193], v[60:63]
	v_mfma_f32_16x16x32_bf16 v[56:59], v[182:185], v[190:193], v[56:59]
	v_mfma_f32_16x16x32_bf16 v[52:55], v[174:177], v[198:201], v[52:55]
	v_mfma_f32_16x16x32_bf16 v[48:51], v[182:185], v[198:201], v[48:51]
	v_mfma_f32_16x16x32_bf16 v[44:47], v[174:177], v[206:209], v[44:47]
	v_mfma_f32_16x16x32_bf16 v[40:43], v[182:185], v[206:209], v[40:43]
	v_mfma_f32_16x16x32_bf16 v[36:39], v[174:177], v[214:217], v[36:39]
	v_mfma_f32_16x16x32_bf16 v[32:35], v[182:185], v[214:217], v[32:35]
	s_setprio 0
	s_barrier
	v_readfirstlane_b32 s55, v158
	v_add_u32_e32 v172, 0x2000, v158
	v_lshl_add_u64 v[170:171], v[238:239], 0, s[48:49]
	s_mov_b32 m0, s55
	v_readfirstlane_b32 s55, v172
	global_load_lds_dwordx4 v[170:171], off
	v_lshl_add_u64 v[170:171], v[240:241], 0, s[48:49]
	s_mov_b32 m0, s55
	s_nop 0
	global_load_lds_dwordx4 v[170:171], off
	s_waitcnt vmcnt(6)
	s_barrier
	s_setprio 0
	v_mfma_f32_16x16x32_bf16 v[28:31], v[218:221], v[186:189], v[28:31]
	v_mfma_f32_16x16x32_bf16 v[24:27], v[226:229], v[186:189], v[24:27]
	v_mfma_f32_16x16x32_bf16 v[20:23], v[218:221], v[194:197], v[20:23]
	v_mfma_f32_16x16x32_bf16 v[16:19], v[226:229], v[194:197], v[16:19]
	v_mfma_f32_16x16x32_bf16 v[12:15], v[218:221], v[202:205], v[12:15]
	v_mfma_f32_16x16x32_bf16 v[8:11], v[226:229], v[202:205], v[8:11]
	v_mfma_f32_16x16x32_bf16 v[4:7], v[218:221], v[210:213], v[4:7]
	v_mfma_f32_16x16x32_bf16 v[0:3], v[226:229], v[210:213], v[0:3]
	v_mfma_f32_16x16x32_bf16 v[28:31], v[222:225], v[190:193], v[28:31]
	v_mfma_f32_16x16x32_bf16 v[24:27], v[230:233], v[190:193], v[24:27]
	v_mfma_f32_16x16x32_bf16 v[20:23], v[222:225], v[198:201], v[20:23]
	v_mfma_f32_16x16x32_bf16 v[16:19], v[230:233], v[198:201], v[16:19]
	v_mfma_f32_16x16x32_bf16 v[12:15], v[222:225], v[206:209], v[12:15]
	v_mfma_f32_16x16x32_bf16 v[8:11], v[230:233], v[206:209], v[8:11]
	v_mfma_f32_16x16x32_bf16 v[4:7], v[222:225], v[214:217], v[4:7]
	v_mfma_f32_16x16x32_bf16 v[0:3], v[230:233], v[214:217], v[0:3]
	s_setprio 0
	s_add_i32 s54, s54, 2
	s_add_u32 s52, s52, 0x100
	s_addc_u32 s53, s53, 0
	s_cmp_gt_u32 s54, 27
	s_barrier
	s_cbranch_scc0 .LBB0_654
	s_lshl_b64 s[52:53], s[16:17], 12
	s_add_u32 s52, s14, s52
	s_addc_u32 s53, s15, s53
	s_add_u32 s52, s52, 0x80000
	s_addc_u32 s53, s53, 0
	v_lshl_add_u64 v[156:157], s[52:53], 0, v[128:129]
	v_readfirstlane_b32 s54, v168
	v_lshl_add_u64 v[156:157], v[156:157], 0, s[50:51]
	s_mov_b32 m0, s54
	ds_read_b128 v[134:137], v160
	ds_read_b128 v[138:141], v160 offset:1024
	ds_read_b128 v[170:173], v160 offset:2048
	ds_read_b128 v[174:177], v160 offset:3072
	ds_read_b128 v[178:181], v151
	ds_read_b128 v[182:185], v151 offset:1024
	ds_read_b128 v[186:189], v150
	ds_read_b128 v[190:193], v150 offset:1024
	ds_read_b128 v[194:197], v149
	ds_read_b128 v[198:201], v149 offset:1024
	ds_read_b128 v[202:205], v148
	ds_read_b128 v[206:209], v148 offset:1024
	global_load_lds_dwordx4 v[156:157], off
	v_lshl_add_u64 v[156:157], s[52:53], 0, v[132:133]
	v_readfirstlane_b32 s52, v169
	v_lshl_add_u64 v[156:157], v[156:157], 0, s[50:51]
	s_mov_b32 m0, s52
	s_nop 0
	global_load_lds_dwordx4 v[156:157], off
	s_barrier
	s_waitcnt lgkmcnt(0)
	s_setprio 0
	s_waitcnt lgkmcnt(0)
	v_mfma_f32_16x16x32_bf16 v[124:127], v[134:137], v[178:181], v[124:127]
	v_mfma_f32_16x16x32_bf16 v[120:123], v[170:173], v[178:181], v[120:123]
	v_mfma_f32_16x16x32_bf16 v[116:119], v[134:137], v[186:189], v[116:119]
	v_mfma_f32_16x16x32_bf16 v[112:115], v[170:173], v[186:189], v[112:115]
	v_mfma_f32_16x16x32_bf16 v[108:111], v[134:137], v[194:197], v[108:111]
	v_mfma_f32_16x16x32_bf16 v[104:107], v[170:173], v[194:197], v[104:107]
	v_mfma_f32_16x16x32_bf16 v[100:103], v[134:137], v[202:205], v[100:103]
	v_mfma_f32_16x16x32_bf16 v[96:99], v[170:173], v[202:205], v[96:99]
	v_mfma_f32_16x16x32_bf16 v[124:127], v[138:141], v[182:185], v[124:127]
	v_mfma_f32_16x16x32_bf16 v[120:123], v[174:177], v[182:185], v[120:123]
	v_mfma_f32_16x16x32_bf16 v[116:119], v[138:141], v[190:193], v[116:119]
	v_mfma_f32_16x16x32_bf16 v[112:115], v[174:177], v[190:193], v[112:115]
	v_mfma_f32_16x16x32_bf16 v[108:111], v[138:141], v[198:201], v[108:111]
	v_mfma_f32_16x16x32_bf16 v[104:107], v[174:177], v[198:201], v[104:107]
	v_mfma_f32_16x16x32_bf16 v[100:103], v[138:141], v[206:209], v[100:103]
	v_mfma_f32_16x16x32_bf16 v[96:99], v[174:177], v[206:209], v[96:99]
	s_setprio 0
	s_barrier
; #define LDA(dst, b, h) for (int m = 0; m < 4; ++m) for (int k = 0; k < 2; ++k) \
;     dst[m][k] = *reinterpret_cast<const bf16x8*>((char*)SA(b, h) + lds_byte(wr * 64 + m * 16 + fr, k * 32 + fq * 8))
; #define LDB(dst, b, h) for (int n = 0; n < 2; ++n) for (int k = 0; k < 2; ++k) \
;     dst[n][k] = *reinterpret_cast<const bf16x8*>((char*)SB(b, h) + lds_byte(wc * 32 + n * 16 + fr, k * 32 + fq * 8))
; #define MMA(ai, bj, At_, Bt_) do { __builtin_amdgcn_s_setprio(1); \
;     for (int k = 0; k < 2; ++k) for (int m = 0; m < 4; ++m) for (int n = 0; n < 2; ++n) \
;       acc[ai][bj][m][n] = __builtin_amdgcn_mfma_f32_16x16x32_bf16(At_[m][k], Bt_[n][k], acc[ai][bj][m][n], 0, 0, 0); \
;     __builtin_amdgcn_s_setprio(0); } while (0)
; #define WAIT_V(n) asm volatile("s_waitcnt vmcnt(" #n ")" ::: "memory")
; #define WAIT_L(n) asm volatile("s_waitcnt lgkmcnt(" #n ")" ::: "memory")
; #define BAR __builtin_amdgcn_s_barrier()
; template <int EPI, int lda, int ldb, int N, int K>
; __device__ __forceinline__ void gemm_phase(const u16* __restrict__ A, const u16* __restrict__ Bt, const GemmEpi ep, int wv) {
;     ...
;       LDB(B1, 0, 1); BAR; WAIT_L(0); MMA(0, 1, At, B1); BAR;
;       LDA(At, 0, 1); WAIT_V(4); BAR; WAIT_L(0); MMA(1, 0, At, B0); MMA(1, 1, At, B1); BAR; }
;     { LDB(B0, 1, 0); LDA(At, 1, 0); WAIT_V(2); BAR; WAIT_L(0); MMA(0, 0, At, B0); BAR;
	ds_read_b128 v[210:213], v159
	ds_read_b128 v[214:217], v159 offset:1024
	ds_read_b128 v[218:221], v159 offset:2048
	ds_read_b128 v[156:159], v159 offset:3072
	s_barrier
	s_waitcnt lgkmcnt(0)
	s_setprio 0
	s_waitcnt lgkmcnt(0)
	v_mfma_f32_16x16x32_bf16 v[92:95], v[210:213], v[178:181], v[92:95]
	v_mfma_f32_16x16x32_bf16 v[88:91], v[218:221], v[178:181], v[88:91]
	v_mfma_f32_16x16x32_bf16 v[76:79], v[210:213], v[194:197], v[76:79]
	v_mfma_f32_16x16x32_bf16 v[72:75], v[218:221], v[194:197], v[72:75]
	v_mfma_f32_16x16x32_bf16 v[84:87], v[210:213], v[186:189], v[84:87]
	v_mfma_f32_16x16x32_bf16 v[80:83], v[218:221], v[186:189], v[80:83]
	v_mfma_f32_16x16x32_bf16 v[68:71], v[210:213], v[202:205], v[68:71]
	v_mfma_f32_16x16x32_bf16 v[64:67], v[218:221], v[202:205], v[64:67]
	v_mfma_f32_16x16x32_bf16 v[92:95], v[214:217], v[182:185], v[92:95]
	v_mfma_f32_16x16x32_bf16 v[88:91], v[156:159], v[182:185], v[88:91]
	v_mfma_f32_16x16x32_bf16 v[76:79], v[214:217], v[198:201], v[76:79]
	v_mfma_f32_16x16x32_bf16 v[72:75], v[156:159], v[198:201], v[72:75]
	v_mfma_f32_16x16x32_bf16 v[178:181], v[214:217], v[190:193], v[84:87]
	v_mfma_f32_16x16x32_bf16 v[182:185], v[156:159], v[190:193], v[80:83]
	v_mfma_f32_16x16x32_bf16 v[186:189], v[214:217], v[206:209], v[68:71]
	v_mfma_f32_16x16x32_bf16 v[190:193], v[156:159], v[206:209], v[64:67]
	s_setprio 0
	s_barrier
	s_nop 0
	ds_read_b128 v[64:67], v151 offset:16384
	ds_read_b128 v[68:71], v151 offset:17408
	ds_read_b128 v[80:83], v150 offset:16384
	ds_read_b128 v[84:87], v150 offset:17408
	ds_read_b128 v[194:197], v149 offset:16384
	ds_read_b128 v[198:201], v149 offset:17408
	ds_read_b128 v[202:205], v148 offset:16384
	ds_read_b128 v[206:209], v148 offset:17408
	s_waitcnt vmcnt(4)
	s_barrier
	s_waitcnt lgkmcnt(0)
	s_setprio 0
	s_waitcnt lgkmcnt(0)
	v_mfma_f32_16x16x32_bf16 v[60:63], v[134:137], v[64:67], v[60:63]
	v_mfma_f32_16x16x32_bf16 v[56:59], v[170:173], v[64:67], v[56:59]
	v_mfma_f32_16x16x32_bf16 v[52:55], v[134:137], v[80:83], v[52:55]
	v_mfma_f32_16x16x32_bf16 v[48:51], v[170:173], v[80:83], v[48:51]
	v_mfma_f32_16x16x32_bf16 v[44:47], v[134:137], v[194:197], v[44:47]
	v_mfma_f32_16x16x32_bf16 v[40:43], v[170:173], v[194:197], v[40:43]
	v_mfma_f32_16x16x32_bf16 v[36:39], v[134:137], v[202:205], v[36:39]
	v_mfma_f32_16x16x32_bf16 v[32:35], v[170:173], v[202:205], v[32:35]
	v_mfma_f32_16x16x32_bf16 v[60:63], v[138:141], v[68:71], v[60:63]
	v_mfma_f32_16x16x32_bf16 v[56:59], v[174:177], v[68:71], v[56:59]
	v_mfma_f32_16x16x32_bf16 v[52:55], v[138:141], v[84:87], v[52:55]
	v_mfma_f32_16x16x32_bf16 v[48:51], v[174:177], v[84:87], v[48:51]
	v_mfma_f32_16x16x32_bf16 v[44:47], v[138:141], v[198:201], v[44:47]
	v_mfma_f32_16x16x32_bf16 v[40:43], v[174:177], v[198:201], v[40:43]
	v_mfma_f32_16x16x32_bf16 v[36:39], v[138:141], v[206:209], v[36:39]
	v_mfma_f32_16x16x32_bf16 v[32:35], v[174:177], v[206:209], v[32:35]
	s_setprio 0
	s_setprio 0
	v_mfma_f32_16x16x32_bf16 v[28:31], v[210:213], v[64:67], v[28:31]
	v_mfma_f32_16x16x32_bf16 v[20:23], v[210:213], v[80:83], v[20:23]
	v_mfma_f32_16x16x32_bf16 v[12:15], v[210:213], v[194:197], v[12:15]
	v_mfma_f32_16x16x32_bf16 v[4:7], v[210:213], v[202:205], v[4:7]
	v_mfma_f32_16x16x32_bf16 v[24:27], v[218:221], v[64:67], v[24:27]
	v_mfma_f32_16x16x32_bf16 v[16:19], v[218:221], v[80:83], v[16:19]
	v_mfma_f32_16x16x32_bf16 v[8:11], v[218:221], v[194:197], v[8:11]
	v_mfma_f32_16x16x32_bf16 v[0:3], v[218:221], v[202:205], v[0:3]
	v_mfma_f32_16x16x32_bf16 v[28:31], v[214:217], v[68:71], v[28:31]
	v_mfma_f32_16x16x32_bf16 v[20:23], v[214:217], v[84:87], v[20:23]
	v_mfma_f32_16x16x32_bf16 v[12:15], v[214:217], v[198:201], v[12:15]
	v_mfma_f32_16x16x32_bf16 v[4:7], v[214:217], v[206:209], v[4:7]
	v_mfma_f32_16x16x32_bf16 v[134:137], v[156:159], v[68:71], v[24:27]
	v_mfma_f32_16x16x32_bf16 v[138:141], v[156:159], v[84:87], v[16:19]
	v_mfma_f32_16x16x32_bf16 v[168:171], v[156:159], v[198:201], v[8:11]
	v_mfma_f32_16x16x32_bf16 v[156:159], v[156:159], v[206:209], v[0:3]
	s_setprio 0
	s_barrier
	s_nop 0
	ds_read_b128 v[0:3], v154
	ds_read_b128 v[8:11], v154 offset:1024
	ds_read_b128 v[16:19], v154 offset:2048
	ds_read_b128 v[172:175], v154 offset:3072
	ds_read_b128 v[24:27], v151 offset:32768
	ds_read_b128 v[194:197], v151 offset:33792
	ds_read_b128 v[198:201], v150 offset:32768
	ds_read_b128 v[202:205], v150 offset:33792
	ds_read_b128 v[206:209], v149 offset:32768
	ds_read_b128 v[210:213], v149 offset:33792
	ds_read_b128 v[214:217], v148 offset:32768
	ds_read_b128 v[218:221], v148 offset:33792
	s_waitcnt vmcnt(2)
	s_barrier
; #define LDA(dst, b, h) for (int m = 0; m < 4; ++m) for (int k = 0; k < 2; ++k) \
;     dst[m][k] = *reinterpret_cast<const bf16x8*>((char*)SA(b, h) + lds_byte(wr * 64 + m * 16 + fr, k * 32 + fq * 8))
; #define LDB(dst, b, h) for (int n = 0; n < 2; ++n) for (int k = 0; k < 2; ++k) \
;     dst[n][k] = *reinterpret_cast<const bf16x8*>((char*)SB(b, h) + lds_byte(wc * 32 + n * 16 + fr, k * 32 + fq * 8))
; #define MMA(ai, bj, At_, Bt_) do { __builtin_amdgcn_s_setprio(1); \
;     for (int k = 0; k < 2; ++k) for (int m = 0; m < 4; ++m) for (int n = 0; n < 2; ++n) \
;       acc[ai][bj][m][n] = __builtin_amdgcn_mfma_f32_16x16x32_bf16(At_[m][k], Bt_[n][k], acc[ai][bj][m][n], 0, 0, 0); \
;     __builtin_amdgcn_s_setprio(0); } while (0)
; #define WAIT_V(n) asm volatile("s_waitcnt vmcnt(" #n ")" ::: "memory")
; #define WAIT_L(n) asm volatile("s_waitcnt lgkmcnt(" #n ")" ::: "memory")
; #define BAR __builtin_amdgcn_s_barrier()
; template <int EPI, int lda, int ldb, int N, int K>
; __device__ __forceinline__ void gemm_phase(const u16* __restrict__ A, const u16* __restrict__ Bt, const GemmEpi ep, int wv) {
;     ...
;     { LDB(B0, 1, 0); LDA(At, 1, 0); WAIT_V(2); BAR; WAIT_L(0); MMA(0, 0, At, B0); BAR;
;       LDB(B1, 1, 1); WAIT_V(0); BAR; WAIT_L(0); MMA(0, 1, At, B1); BAR;
;       LDA(At, 1, 1); BAR; WAIT_L(0); MMA(1, 0, At, B0); MMA(1, 1, At, B1); BAR; }
;     if (wr == 0) BAR;
	s_waitcnt lgkmcnt(0)
	s_setprio 0
	s_waitcnt lgkmcnt(0)
	v_mfma_f32_16x16x32_bf16 v[64:67], v[0:3], v[24:27], v[124:127]
	v_mfma_f32_16x16x32_bf16 v[68:71], v[16:19], v[24:27], v[120:123]
	v_mfma_f32_16x16x32_bf16 v[80:83], v[0:3], v[198:201], v[116:119]
	v_mfma_f32_16x16x32_bf16 v[84:87], v[16:19], v[198:201], v[112:115]
	v_mfma_f32_16x16x32_bf16 v[108:111], v[0:3], v[206:209], v[108:111]
	v_mfma_f32_16x16x32_bf16 v[104:107], v[16:19], v[206:209], v[104:107]
	v_mfma_f32_16x16x32_bf16 v[120:123], v[0:3], v[214:217], v[100:103]
	v_mfma_f32_16x16x32_bf16 v[124:127], v[16:19], v[214:217], v[96:99]
	v_mfma_f32_16x16x32_bf16 v[116:119], v[8:11], v[194:197], v[64:67]
	v_mfma_f32_16x16x32_bf16 v[112:115], v[172:175], v[194:197], v[68:71]
	v_mfma_f32_16x16x32_bf16 v[100:103], v[8:11], v[202:205], v[80:83]
	v_mfma_f32_16x16x32_bf16 v[96:99], v[172:175], v[202:205], v[84:87]
	v_mfma_f32_16x16x32_bf16 v[84:87], v[8:11], v[210:213], v[108:111]
	v_mfma_f32_16x16x32_bf16 v[80:83], v[172:175], v[210:213], v[104:107]
	v_mfma_f32_16x16x32_bf16 v[68:71], v[8:11], v[218:221], v[120:123]
	v_mfma_f32_16x16x32_bf16 v[64:67], v[172:175], v[218:221], v[124:127]
	s_setprio 0
	s_barrier
	ds_read_b128 v[222:225], v152
	ds_read_b128 v[226:229], v152 offset:1024
	ds_read_b128 v[230:233], v152 offset:2048
	ds_read_b128 v[152:155], v152 offset:3072
	s_waitcnt vmcnt(0)
	s_barrier
	s_waitcnt lgkmcnt(0)
	s_setprio 0
	s_waitcnt lgkmcnt(0)
	v_mfma_f32_16x16x32_bf16 v[92:95], v[222:225], v[24:27], v[92:95]
	v_mfma_f32_16x16x32_bf16 v[24:27], v[230:233], v[24:27], v[88:91]
	v_mfma_f32_16x16x32_bf16 v[88:91], v[222:225], v[198:201], v[178:181]
	v_mfma_f32_16x16x32_bf16 v[104:107], v[230:233], v[198:201], v[182:185]
	v_mfma_f32_16x16x32_bf16 v[76:79], v[222:225], v[206:209], v[76:79]
	v_mfma_f32_16x16x32_bf16 v[72:75], v[230:233], v[206:209], v[72:75]
	v_mfma_f32_16x16x32_bf16 v[176:179], v[222:225], v[214:217], v[186:189]
	v_mfma_f32_16x16x32_bf16 v[180:183], v[230:233], v[214:217], v[190:193]
	v_mfma_f32_16x16x32_bf16 v[124:127], v[226:229], v[194:197], v[92:95]
	v_mfma_f32_16x16x32_bf16 v[120:123], v[152:155], v[194:197], v[24:27]
	v_mfma_f32_16x16x32_bf16 v[108:111], v[226:229], v[202:205], v[88:91]
	v_mfma_f32_16x16x32_bf16 v[104:107], v[152:155], v[202:205], v[104:107]
	v_mfma_f32_16x16x32_bf16 v[92:95], v[226:229], v[210:213], v[76:79]
	v_mfma_f32_16x16x32_bf16 v[88:91], v[152:155], v[210:213], v[72:75]
	v_mfma_f32_16x16x32_bf16 v[76:79], v[226:229], v[218:221], v[176:179]
	v_mfma_f32_16x16x32_bf16 v[72:75], v[152:155], v[218:221], v[180:183]
	s_setprio 0
	s_barrier
	ds_read_b128 v[176:179], v151 offset:49152
	ds_read_b128 v[180:183], v151 offset:50176
	ds_read_b128 v[184:187], v150 offset:49152
	ds_read_b128 v[188:191], v150 offset:50176
	ds_read_b128 v[192:195], v149 offset:49152
	ds_read_b128 v[196:199], v149 offset:50176
	ds_read_b128 v[200:203], v148 offset:49152
	ds_read_b128 v[148:151], v148 offset:50176
	s_barrier
	s_waitcnt lgkmcnt(0)
	s_setprio 0
	s_waitcnt lgkmcnt(0)
	v_mfma_f32_16x16x32_bf16 v[24:27], v[0:3], v[176:179], v[60:63]
	v_mfma_f32_16x16x32_bf16 v[60:63], v[16:19], v[176:179], v[56:59]
	v_mfma_f32_16x16x32_bf16 v[52:55], v[0:3], v[184:187], v[52:55]
	v_mfma_f32_16x16x32_bf16 v[204:207], v[16:19], v[184:187], v[48:51]
	v_mfma_f32_16x16x32_bf16 v[44:47], v[0:3], v[192:195], v[44:47]
	v_mfma_f32_16x16x32_bf16 v[208:211], v[16:19], v[192:195], v[40:43]
	v_mfma_f32_16x16x32_bf16 v[0:3], v[0:3], v[200:203], v[36:39]
	v_mfma_f32_16x16x32_bf16 v[36:39], v[16:19], v[200:203], v[32:35]
	v_mfma_f32_16x16x32_bf16 v[56:59], v[8:11], v[180:183], v[24:27]
	v_mfma_f32_16x16x32_bf16 v[48:51], v[172:175], v[180:183], v[60:63]
	v_mfma_f32_16x16x32_bf16 v[40:43], v[8:11], v[188:191], v[52:55]
	v_mfma_f32_16x16x32_bf16 v[32:35], v[172:175], v[188:191], v[204:207]
	v_mfma_f32_16x16x32_bf16 v[24:27], v[8:11], v[196:199], v[44:47]
	v_mfma_f32_16x16x32_bf16 v[16:19], v[172:175], v[196:199], v[208:211]
	v_mfma_f32_16x16x32_bf16 v[8:11], v[8:11], v[148:151], v[0:3]
	v_mfma_f32_16x16x32_bf16 v[0:3], v[172:175], v[148:151], v[36:39]
	s_setprio 0
	s_setprio 0
	v_mfma_f32_16x16x32_bf16 v[28:31], v[222:225], v[176:179], v[28:31]
	v_mfma_f32_16x16x32_bf16 v[36:39], v[230:233], v[176:179], v[134:137]
	v_mfma_f32_16x16x32_bf16 v[20:23], v[222:225], v[184:187], v[20:23]
	v_mfma_f32_16x16x32_bf16 v[134:137], v[230:233], v[184:187], v[138:141]
	v_mfma_f32_16x16x32_bf16 v[12:15], v[222:225], v[192:195], v[12:15]
	v_mfma_f32_16x16x32_bf16 v[138:141], v[230:233], v[192:195], v[168:171]
	v_mfma_f32_16x16x32_bf16 v[4:7], v[222:225], v[200:203], v[4:7]
	v_mfma_f32_16x16x32_bf16 v[156:159], v[230:233], v[200:203], v[156:159]
	v_mfma_f32_16x16x32_bf16 v[60:63], v[226:229], v[180:183], v[28:31]
	v_mfma_f32_16x16x32_bf16 v[52:55], v[152:155], v[180:183], v[36:39]
	v_mfma_f32_16x16x32_bf16 v[44:47], v[226:229], v[188:191], v[20:23]
	v_mfma_f32_16x16x32_bf16 v[36:39], v[152:155], v[188:191], v[134:137]
	v_mfma_f32_16x16x32_bf16 v[28:31], v[226:229], v[196:199], v[12:15]
	v_mfma_f32_16x16x32_bf16 v[20:23], v[152:155], v[196:199], v[138:141]
	v_mfma_f32_16x16x32_bf16 v[12:15], v[226:229], v[148:151], v[4:7]
	v_mfma_f32_16x16x32_bf16 v[4:7], v[152:155], v[148:151], v[156:159]
	s_setprio 0
	v_cmp_gt_u32_e32 vcc, s70, v130
	s_barrier
	s_and_saveexec_b64 s[52:53], vcc
	s_cbranch_execz .LBB0_657
	s_barrier

; #define STAGE(P, BASE, LD, br, kt) do { const char* _g = (const char*)((BASE) + (size_t)(br) * (LD) + (size_t)(kt) * 64); \
;     for (int _i = 0; _i < 2; ++_i) { int _b = tidx * 16 + _i * 8192; int _r, _c; stage_rc(_b, _r, _c); \
;       __builtin_amdgcn_global_load_lds((const unsigned*)(_g + (unsigned)((_r * (LD) + _c) * 2)), (unsigned*)((char*)(P) + _b), 16, 0, 0); } } while (0)
; #define LDA(dst, b, h) for (int m = 0; m < 4; ++m) for (int k = 0; k < 2; ++k) \
;     dst[m][k] = *reinterpret_cast<const bf16x8*>((char*)SA(b, h) + lds_byte(wr * 64 + m * 16 + fr, k * 32 + fq * 8))
; #define LDB(dst, b, h) for (int n = 0; n < 2; ++n) for (int k = 0; k < 2; ++k) \
;     dst[n][k] = *reinterpret_cast<const bf16x8*>((char*)SB(b, h) + lds_byte(wc * 32 + n * 16 + fr, k * 32 + fq * 8))
; #define MMA(ai, bj, At_, Bt_) do { __builtin_amdgcn_s_setprio(1); \
;     for (int k = 0; k < 2; ++k) for (int m = 0; m < 4; ++m) for (int n = 0; n < 2; ++n) \
;       acc[ai][bj][m][n] = __builtin_amdgcn_mfma_f32_16x16x32_bf16(At_[m][k], Bt_[n][k], acc[ai][bj][m][n], 0, 0, 0); \
;     __builtin_amdgcn_s_setprio(0); } while (0)
; #define WAIT_L(n) asm volatile("s_waitcnt lgkmcnt(" #n ")" ::: "memory")
; #define BAR __builtin_amdgcn_s_barrier()
; #define SCHED __builtin_amdgcn_sched_barrier(0)
; template <int EPI, int lda, int ldb, int N, int K>
; __device__ __forceinline__ void gemm_phase(const u16* __restrict__ A, const u16* __restrict__ Bt, const GemmEpi ep, int wv) {
;     ...
;     for (int t = 0; t < nt - 2; t += 2) {
;       LDB(B0, 0, 0); SCHED; LDA(At, 0, 0); STAGE(SA(1, 1), Ab, lda, brow + HALF, t + 1);
;       WAIT_L(8); BAR; WAIT_L(0); MMA(0, 0, At, B0); BAR; SCHED;
;       LDB(B1, 0, 1); STAGE(SB(0, 0), Bt, ldb, bcol, t + 2);
;       BAR; WAIT_L(0); MMA(0, 1, At, B1); BAR;
;       LDA(At, 0, 1); STAGE(SA(0, 0), Ab, lda, brow, t + 2);
;       BAR; WAIT_L(0); MMA(1, 0, At, B0); BAR; SCHED;
.LBB0_770:
	ds_read_b128 v[172:175], v161
	ds_read_b128 v[176:179], v161 offset:1024
	ds_read_b128 v[180:183], v161 offset:2048
	ds_read_b128 v[184:187], v161 offset:3072
	v_add_u32_e32 v169, 0xc000, v148
	v_lshl_add_u64 v[236:237], v[136:137], 0, s[50:51]
	v_readfirstlane_b32 s53, v169
	v_add_u32_e32 v170, 0xe000, v148
	v_lshl_add_u64 v[162:163], v[236:237], 0, s[18:19]
	s_mov_b32 m0, s53
	v_lshl_add_u64 v[238:239], v[134:135], 0, s[50:51]
	v_readfirstlane_b32 s53, v170
	ds_read_b128 v[164:167], v152
	ds_read_b128 v[188:191], v152 offset:1024
	ds_read_b128 v[192:195], v151
	ds_read_b128 v[196:199], v151 offset:1024
	ds_read_b128 v[200:203], v150
	ds_read_b128 v[204:207], v150 offset:1024
	ds_read_b128 v[208:211], v149
	ds_read_b128 v[212:215], v149 offset:1024
	global_load_lds_dwordx4 v[162:163], off
	v_lshl_add_u64 v[162:163], v[238:239], 0, s[18:19]
	s_mov_b32 m0, s53
	s_nop 0
	global_load_lds_dwordx4 v[162:163], off
	s_waitcnt lgkmcnt(8)
	s_barrier
	s_waitcnt lgkmcnt(0)
	s_setprio 0
	s_waitcnt lgkmcnt(0)
	v_mfma_f32_16x16x32_bf16 v[124:127], v[172:175], v[164:167], v[124:127]
	v_mfma_f32_16x16x32_bf16 v[120:123], v[180:183], v[164:167], v[120:123]
	v_mfma_f32_16x16x32_bf16 v[116:119], v[172:175], v[192:195], v[116:119]
	v_mfma_f32_16x16x32_bf16 v[112:115], v[180:183], v[192:195], v[112:115]
	v_mfma_f32_16x16x32_bf16 v[108:111], v[172:175], v[200:203], v[108:111]
	v_mfma_f32_16x16x32_bf16 v[104:107], v[180:183], v[200:203], v[104:107]
	v_mfma_f32_16x16x32_bf16 v[100:103], v[172:175], v[208:211], v[100:103]
	v_mfma_f32_16x16x32_bf16 v[96:99], v[180:183], v[208:211], v[96:99]
	v_mfma_f32_16x16x32_bf16 v[124:127], v[176:179], v[188:191], v[124:127]
	v_mfma_f32_16x16x32_bf16 v[120:123], v[184:187], v[188:191], v[120:123]
	v_mfma_f32_16x16x32_bf16 v[116:119], v[176:179], v[196:199], v[116:119]
	v_mfma_f32_16x16x32_bf16 v[112:115], v[184:187], v[196:199], v[112:115]
	v_mfma_f32_16x16x32_bf16 v[108:111], v[176:179], v[204:207], v[108:111]
	v_mfma_f32_16x16x32_bf16 v[104:107], v[184:187], v[204:207], v[104:107]
	v_mfma_f32_16x16x32_bf16 v[100:103], v[176:179], v[212:215], v[100:103]
	v_mfma_f32_16x16x32_bf16 v[96:99], v[184:187], v[212:215], v[96:99]
	s_setprio 0
	s_barrier
	v_add_u32_e32 v162, s64, v153
	v_lshl_add_u64 v[240:241], v[140:141], 0, s[50:51]
	v_readfirstlane_b32 s53, v162
	v_add_u32_e32 v163, 0x2000, v162
	v_lshl_add_u64 v[232:233], v[240:241], 0, s[20:21]
	s_mov_b32 m0, s53
	v_lshl_add_u64 v[242:243], v[138:139], 0, s[50:51]
	v_readfirstlane_b32 s53, v163
	ds_read_b128 v[216:219], v160
	ds_read_b128 v[220:223], v160 offset:1024
	ds_read_b128 v[224:227], v160 offset:2048
	ds_read_b128 v[228:231], v160 offset:3072
	global_load_lds_dwordx4 v[232:233], off
	v_lshl_add_u64 v[232:233], v[242:243], 0, s[20:21]
	s_mov_b32 m0, s53
	s_nop 0
	global_load_lds_dwordx4 v[232:233], off
	s_barrier
	s_waitcnt lgkmcnt(0)
	s_setprio 0
	s_waitcnt lgkmcnt(0)
	v_mfma_f32_16x16x32_bf16 v[92:95], v[216:219], v[164:167], v[92:95]
	v_mfma_f32_16x16x32_bf16 v[88:91], v[224:227], v[164:167], v[88:91]
	v_mfma_f32_16x16x32_bf16 v[84:87], v[216:219], v[192:195], v[84:87]
	v_mfma_f32_16x16x32_bf16 v[80:83], v[224:227], v[192:195], v[80:83]
	v_mfma_f32_16x16x32_bf16 v[76:79], v[216:219], v[200:203], v[76:79]
	v_mfma_f32_16x16x32_bf16 v[72:75], v[224:227], v[200:203], v[72:75]
	v_mfma_f32_16x16x32_bf16 v[68:71], v[216:219], v[208:211], v[68:71]
	v_mfma_f32_16x16x32_bf16 v[64:67], v[224:227], v[208:211], v[64:67]
	v_mfma_f32_16x16x32_bf16 v[92:95], v[220:223], v[188:191], v[92:95]
	v_mfma_f32_16x16x32_bf16 v[88:91], v[228:231], v[188:191], v[88:91]
	v_mfma_f32_16x16x32_bf16 v[84:87], v[220:223], v[196:199], v[84:87]
	v_mfma_f32_16x16x32_bf16 v[80:83], v[228:231], v[196:199], v[80:83]
	v_mfma_f32_16x16x32_bf16 v[76:79], v[220:223], v[204:207], v[76:79]
	v_mfma_f32_16x16x32_bf16 v[72:75], v[228:231], v[204:207], v[72:75]
	v_mfma_f32_16x16x32_bf16 v[68:71], v[220:223], v[212:215], v[68:71]
	v_mfma_f32_16x16x32_bf16 v[64:67], v[228:231], v[212:215], v[64:67]
	s_setprio 0
	v_readfirstlane_b32 s53, v148
	v_lshl_add_u64 v[164:165], v[236:237], 0, s[22:23]
	s_mov_b32 m0, s53
	s_barrier
	ds_read_b128 v[188:191], v152 offset:16384
	ds_read_b128 v[192:195], v152 offset:17408
	ds_read_b128 v[196:199], v151 offset:16384
	ds_read_b128 v[200:203], v151 offset:17408
	ds_read_b128 v[204:207], v150 offset:16384
	ds_read_b128 v[208:211], v150 offset:17408
	ds_read_b128 v[212:215], v149 offset:16384
	ds_read_b128 v[232:235], v149 offset:17408
	global_load_lds_dwordx4 v[164:165], off
	v_add_u32_e32 v164, 0x2000, v148
	v_lshl_add_u64 v[166:167], v[238:239], 0, s[22:23]
	v_readfirstlane_b32 s53, v164
	s_mov_b32 m0, s53
	s_nop 0
	global_load_lds_dwordx4 v[166:167], off
	s_barrier
	s_waitcnt lgkmcnt(0)
	s_setprio 0
	s_waitcnt lgkmcnt(0)
	v_mfma_f32_16x16x32_bf16 v[60:63], v[172:175], v[188:191], v[60:63]
	v_mfma_f32_16x16x32_bf16 v[56:59], v[180:183], v[188:191], v[56:59]
	v_mfma_f32_16x16x32_bf16 v[52:55], v[172:175], v[196:199], v[52:55]
	v_mfma_f32_16x16x32_bf16 v[48:51], v[180:183], v[196:199], v[48:51]
	v_mfma_f32_16x16x32_bf16 v[44:47], v[172:175], v[204:207], v[44:47]
	v_mfma_f32_16x16x32_bf16 v[40:43], v[180:183], v[204:207], v[40:43]
	v_mfma_f32_16x16x32_bf16 v[36:39], v[172:175], v[212:215], v[36:39]
	v_mfma_f32_16x16x32_bf16 v[32:35], v[180:183], v[212:215], v[32:35]
	v_mfma_f32_16x16x32_bf16 v[60:63], v[176:179], v[192:195], v[60:63]
	v_mfma_f32_16x16x32_bf16 v[56:59], v[184:187], v[192:195], v[56:59]
	v_mfma_f32_16x16x32_bf16 v[52:55], v[176:179], v[200:203], v[52:55]
	v_mfma_f32_16x16x32_bf16 v[48:51], v[184:187], v[200:203], v[48:51]
	v_mfma_f32_16x16x32_bf16 v[44:47], v[176:179], v[208:211], v[44:47]
	v_mfma_f32_16x16x32_bf16 v[40:43], v[184:187], v[208:211], v[40:43]
	v_mfma_f32_16x16x32_bf16 v[36:39], v[176:179], v[232:235], v[36:39]
	v_mfma_f32_16x16x32_bf16 v[32:35], v[184:187], v[232:235], v[32:35]
	s_setprio 0
	s_barrier
; #define STAGE(P, BASE, LD, br, kt) do { const char* _g = (const char*)((BASE) + (size_t)(br) * (LD) + (size_t)(kt) * 64); \
;     for (int _i = 0; _i < 2; ++_i) { int _b = tidx * 16 + _i * 8192; int _r, _c; stage_rc(_b, _r, _c); \
;       __builtin_amdgcn_global_load_lds((const unsigned*)(_g + (unsigned)((_r * (LD) + _c) * 2)), (unsigned*)((char*)(P) + _b), 16, 0, 0); } } while (0)
; #define LDA(dst, b, h) for (int m = 0; m < 4; ++m) for (int k = 0; k < 2; ++k) \
;     dst[m][k] = *reinterpret_cast<const bf16x8*>((char*)SA(b, h) + lds_byte(wr * 64 + m * 16 + fr, k * 32 + fq * 8))
; #define LDB(dst, b, h) for (int n = 0; n < 2; ++n) for (int k = 0; k < 2; ++k) \
;     dst[n][k] = *reinterpret_cast<const bf16x8*>((char*)SB(b, h) + lds_byte(wc * 32 + n * 16 + fr, k * 32 + fq * 8))
; #define MMA(ai, bj, At_, Bt_) do { __builtin_amdgcn_s_setprio(1); \
;     for (int k = 0; k < 2; ++k) for (int m = 0; m < 4; ++m) for (int n = 0; n < 2; ++n) \
;       acc[ai][bj][m][n] = __builtin_amdgcn_mfma_f32_16x16x32_bf16(At_[m][k], Bt_[n][k], acc[ai][bj][m][n], 0, 0, 0); \
;     __builtin_amdgcn_s_setprio(0); } while (0)
; #define WAIT_V(n) asm volatile("s_waitcnt vmcnt(" #n ")" ::: "memory")
; #define WAIT_L(n) asm volatile("s_waitcnt lgkmcnt(" #n ")" ::: "memory")
; #define BAR __builtin_amdgcn_s_barrier()
; #define SCHED __builtin_amdgcn_sched_barrier(0)
; template <int EPI, int lda, int ldb, int N, int K>
; __device__ __forceinline__ void gemm_phase(const u16* __restrict__ A, const u16* __restrict__ Bt, const GemmEpi ep, int wv) {
;     ...
;       STAGE(SB(0, 1), Bt, ldb, bcol + HALF, t + 2);
;       WAIT_V(6); BAR; MMA(1, 1, At, B1); BAR;
;       LDB(B0, 1, 0); SCHED; LDA(At, 1, 0); STAGE(SA(0, 1), Ab, lda, brow + HALF, t + 2);
;       WAIT_L(8); BAR; WAIT_L(0); MMA(0, 0, At, B0); BAR; SCHED;
;       LDB(B1, 1, 1); STAGE(SB(1, 0), Bt, ldb, bcol, t + 3);
;       BAR; WAIT_L(0); MMA(0, 1, At, B1); BAR;
;       LDA(At, 1, 1); STAGE(SA(1, 0), Ab, lda, brow, t + 3);
	v_add_u32_e32 v165, s65, v153
	v_lshl_add_u64 v[166:167], v[240:241], 0, s[24:25]
	v_readfirstlane_b32 s53, v165
	s_mov_b32 m0, s53
	v_lshl_add_u64 v[172:173], v[242:243], 0, s[24:25]
	global_load_lds_dwordx4 v[166:167], off
	v_add_u32_e32 v166, 0x2000, v165
	s_nop 0
	v_readfirstlane_b32 s53, v166
	s_mov_b32 m0, s53
	s_nop 0
	global_load_lds_dwordx4 v[172:173], off
	s_waitcnt vmcnt(6)
	s_barrier
	s_setprio 0
	v_mfma_f32_16x16x32_bf16 v[28:31], v[216:219], v[188:191], v[28:31]
	v_mfma_f32_16x16x32_bf16 v[24:27], v[224:227], v[188:191], v[24:27]
	v_mfma_f32_16x16x32_bf16 v[20:23], v[216:219], v[196:199], v[20:23]
	v_mfma_f32_16x16x32_bf16 v[16:19], v[224:227], v[196:199], v[16:19]
	v_mfma_f32_16x16x32_bf16 v[12:15], v[216:219], v[204:207], v[12:15]
	v_mfma_f32_16x16x32_bf16 v[8:11], v[224:227], v[204:207], v[8:11]
	v_mfma_f32_16x16x32_bf16 v[4:7], v[216:219], v[212:215], v[4:7]
	v_mfma_f32_16x16x32_bf16 v[0:3], v[224:227], v[212:215], v[0:3]
	v_mfma_f32_16x16x32_bf16 v[28:31], v[220:223], v[192:195], v[28:31]
	v_mfma_f32_16x16x32_bf16 v[24:27], v[228:231], v[192:195], v[24:27]
	v_mfma_f32_16x16x32_bf16 v[20:23], v[220:223], v[200:203], v[20:23]
	v_mfma_f32_16x16x32_bf16 v[16:19], v[228:231], v[200:203], v[16:19]
	v_mfma_f32_16x16x32_bf16 v[12:15], v[220:223], v[208:211], v[12:15]
	v_mfma_f32_16x16x32_bf16 v[8:11], v[228:231], v[208:211], v[8:11]
	v_mfma_f32_16x16x32_bf16 v[4:7], v[220:223], v[232:235], v[4:7]
	v_mfma_f32_16x16x32_bf16 v[0:3], v[228:231], v[232:235], v[0:3]
	s_setprio 0
	s_barrier
	ds_read_b128 v[172:175], v156
	ds_read_b128 v[176:179], v156 offset:1024
	ds_read_b128 v[180:183], v156 offset:2048
	ds_read_b128 v[184:187], v156 offset:3072
	v_add_u32_e32 v167, 0x4000, v148
	v_add_u32_e32 v168, 0x6000, v148
	v_readfirstlane_b32 s53, v167
	v_lshl_add_u64 v[220:221], v[236:237], 0, s[26:27]
	s_mov_b32 m0, s53
	v_readfirstlane_b32 s53, v168
	ds_read_b128 v[188:191], v152 offset:32768
	ds_read_b128 v[192:195], v152 offset:33792
	ds_read_b128 v[196:199], v151 offset:32768
	ds_read_b128 v[200:203], v151 offset:33792
	ds_read_b128 v[204:207], v150 offset:32768
	ds_read_b128 v[208:211], v150 offset:33792
	ds_read_b128 v[212:215], v149 offset:32768
	ds_read_b128 v[216:219], v149 offset:33792
	global_load_lds_dwordx4 v[220:221], off
	v_lshl_add_u64 v[220:221], v[238:239], 0, s[26:27]
	s_mov_b32 m0, s53
	s_nop 0
	global_load_lds_dwordx4 v[220:221], off
	s_waitcnt lgkmcnt(8)
	s_barrier
	s_waitcnt lgkmcnt(0)
	s_setprio 0
	s_waitcnt lgkmcnt(0)
	v_mfma_f32_16x16x32_bf16 v[124:127], v[172:175], v[188:191], v[124:127]
	v_mfma_f32_16x16x32_bf16 v[120:123], v[180:183], v[188:191], v[120:123]
	v_mfma_f32_16x16x32_bf16 v[116:119], v[172:175], v[196:199], v[116:119]
	v_mfma_f32_16x16x32_bf16 v[112:115], v[180:183], v[196:199], v[112:115]
	v_mfma_f32_16x16x32_bf16 v[108:111], v[172:175], v[204:207], v[108:111]
	v_mfma_f32_16x16x32_bf16 v[104:107], v[180:183], v[204:207], v[104:107]
	v_mfma_f32_16x16x32_bf16 v[100:103], v[172:175], v[212:215], v[100:103]
	v_mfma_f32_16x16x32_bf16 v[96:99], v[180:183], v[212:215], v[96:99]
	v_mfma_f32_16x16x32_bf16 v[124:127], v[176:179], v[192:195], v[124:127]
	v_mfma_f32_16x16x32_bf16 v[120:123], v[184:187], v[192:195], v[120:123]
	v_mfma_f32_16x16x32_bf16 v[116:119], v[176:179], v[200:203], v[116:119]
	v_mfma_f32_16x16x32_bf16 v[112:115], v[184:187], v[200:203], v[112:115]
	v_mfma_f32_16x16x32_bf16 v[108:111], v[176:179], v[208:211], v[108:111]
	v_mfma_f32_16x16x32_bf16 v[104:107], v[184:187], v[208:211], v[104:107]
	v_mfma_f32_16x16x32_bf16 v[100:103], v[176:179], v[216:219], v[100:103]
	v_mfma_f32_16x16x32_bf16 v[96:99], v[184:187], v[216:219], v[96:99]
	s_setprio 0
	s_barrier
	v_readfirstlane_b32 s53, v155
	v_add_u32_e32 v171, 0x2000, v155
	v_lshl_add_u64 v[244:245], v[240:241], 0, s[40:41]
	s_mov_b32 m0, s53
	v_readfirstlane_b32 s53, v171
	ds_read_b128 v[220:223], v154
	ds_read_b128 v[224:227], v154 offset:1024
	ds_read_b128 v[228:231], v154 offset:2048
	ds_read_b128 v[232:235], v154 offset:3072
	global_load_lds_dwordx4 v[244:245], off
	v_lshl_add_u64 v[244:245], v[242:243], 0, s[40:41]
	s_mov_b32 m0, s53
	s_nop 0
	global_load_lds_dwordx4 v[244:245], off
	s_barrier
	s_waitcnt lgkmcnt(0)
	s_setprio 0
	s_waitcnt lgkmcnt(0)
	v_mfma_f32_16x16x32_bf16 v[92:95], v[220:223], v[188:191], v[92:95]
	v_mfma_f32_16x16x32_bf16 v[88:91], v[228:231], v[188:191], v[88:91]
	v_mfma_f32_16x16x32_bf16 v[84:87], v[220:223], v[196:199], v[84:87]
	v_mfma_f32_16x16x32_bf16 v[80:83], v[228:231], v[196:199], v[80:83]
	v_mfma_f32_16x16x32_bf16 v[76:79], v[220:223], v[204:207], v[76:79]
	v_mfma_f32_16x16x32_bf16 v[72:75], v[228:231], v[204:207], v[72:75]
	v_mfma_f32_16x16x32_bf16 v[68:71], v[220:223], v[212:215], v[68:71]
	v_mfma_f32_16x16x32_bf16 v[64:67], v[228:231], v[212:215], v[64:67]
	v_mfma_f32_16x16x32_bf16 v[92:95], v[224:227], v[192:195], v[92:95]
	v_mfma_f32_16x16x32_bf16 v[88:91], v[232:235], v[192:195], v[88:91]
	v_mfma_f32_16x16x32_bf16 v[84:87], v[224:227], v[200:203], v[84:87]
	v_mfma_f32_16x16x32_bf16 v[80:83], v[232:235], v[200:203], v[80:83]
	v_mfma_f32_16x16x32_bf16 v[76:79], v[224:227], v[208:211], v[76:79]
	v_mfma_f32_16x16x32_bf16 v[72:75], v[232:235], v[208:211], v[72:75]
	v_mfma_f32_16x16x32_bf16 v[68:71], v[224:227], v[216:219], v[68:71]
	v_mfma_f32_16x16x32_bf16 v[64:67], v[232:235], v[216:219], v[64:67]
	s_setprio 0
	v_readfirstlane_b32 s53, v157
	v_lshl_add_u64 v[236:237], v[236:237], 0, s[42:43]
	s_mov_b32 m0, s53
	v_readfirstlane_b32 s53, v158
	s_barrier
; #define STAGE(P, BASE, LD, br, kt) do { const char* _g = (const char*)((BASE) + (size_t)(br) * (LD) + (size_t)(kt) * 64); \
;     for (int _i = 0; _i < 2; ++_i) { int _b = tidx * 16 + _i * 8192; int _r, _c; stage_rc(_b, _r, _c); \
;       __builtin_amdgcn_global_load_lds((const unsigned*)(_g + (unsigned)((_r * (LD) + _c) * 2)), (unsigned*)((char*)(P) + _b), 16, 0, 0); } } while (0)
; #define LDA(dst, b, h) for (int m = 0; m < 4; ++m) for (int k = 0; k < 2; ++k) \
;     dst[m][k] = *reinterpret_cast<const bf16x8*>((char*)SA(b, h) + lds_byte(wr * 64 + m * 16 + fr, k * 32 + fq * 8))
; #define LDB(dst, b, h) for (int n = 0; n < 2; ++n) for (int k = 0; k < 2; ++k) \
;     dst[n][k] = *reinterpret_cast<const bf16x8*>((char*)SB(b, h) + lds_byte(wc * 32 + n * 16 + fr, k * 32 + fq * 8))
; #define MMA(ai, bj, At_, Bt_) do { __builtin_amdgcn_s_setprio(1); \
;     for (int k = 0; k < 2; ++k) for (int m = 0; m < 4; ++m) for (int n = 0; n < 2; ++n) \
;       acc[ai][bj][m][n] = __builtin_amdgcn_mfma_f32_16x16x32_bf16(At_[m][k], Bt_[n][k], acc[ai][bj][m][n], 0, 0, 0); \
;     __builtin_amdgcn_s_setprio(0); } while (0)
; #define WAIT_V(n) asm volatile("s_waitcnt vmcnt(" #n ")" ::: "memory")
; #define WAIT_L(n) asm volatile("s_waitcnt lgkmcnt(" #n ")" ::: "memory")
; #define BAR __builtin_amdgcn_s_barrier()
; #define SCHED __builtin_amdgcn_sched_barrier(0)
; template <int EPI, int lda, int ldb, int N, int K>
; __device__ __forceinline__ void gemm_phase(const u16* __restrict__ A, const u16* __restrict__ Bt, const GemmEpi ep, int wv) {
;     ...
;       LDA(At, 1, 1); STAGE(SA(1, 0), Ab, lda, brow, t + 3);
;       BAR; WAIT_L(0); MMA(1, 0, At, B0); BAR; SCHED;
;       STAGE(SB(1, 1), Bt, ldb, bcol + HALF, t + 3);
;       WAIT_V(6); BAR; MMA(1, 1, At, B1); BAR;
;     }
;     { LDB(B0, 0, 0); LDA(At, 0, 0); STAGE(SA(1, 1), Ab, lda, brow + HALF, nt - 1);
;       BAR; WAIT_L(0); MMA(0, 0, At, B0); BAR;
;       LDB(B1, 0, 1); BAR; WAIT_L(0); MMA(0, 1, At, B1); BAR;
	ds_read_b128 v[188:191], v152 offset:49152
	ds_read_b128 v[192:195], v152 offset:50176
	ds_read_b128 v[196:199], v151 offset:49152
	ds_read_b128 v[200:203], v151 offset:50176
	ds_read_b128 v[204:207], v150 offset:49152
	ds_read_b128 v[208:211], v150 offset:50176
	ds_read_b128 v[212:215], v149 offset:49152
	ds_read_b128 v[216:219], v149 offset:50176
	global_load_lds_dwordx4 v[236:237], off
	v_lshl_add_u64 v[236:237], v[238:239], 0, s[42:43]
	s_mov_b32 m0, s53
	s_nop 0
	global_load_lds_dwordx4 v[236:237], off
	s_barrier
	s_waitcnt lgkmcnt(0)
	s_setprio 0
	s_waitcnt lgkmcnt(0)
	v_mfma_f32_16x16x32_bf16 v[60:63], v[172:175], v[188:191], v[60:63]
	v_mfma_f32_16x16x32_bf16 v[56:59], v[180:183], v[188:191], v[56:59]
	v_mfma_f32_16x16x32_bf16 v[52:55], v[172:175], v[196:199], v[52:55]
	v_mfma_f32_16x16x32_bf16 v[48:51], v[180:183], v[196:199], v[48:51]
	v_mfma_f32_16x16x32_bf16 v[44:47], v[172:175], v[204:207], v[44:47]
	v_mfma_f32_16x16x32_bf16 v[40:43], v[180:183], v[204:207], v[40:43]
	v_mfma_f32_16x16x32_bf16 v[36:39], v[172:175], v[212:215], v[36:39]
	v_mfma_f32_16x16x32_bf16 v[32:35], v[180:183], v[212:215], v[32:35]
	v_mfma_f32_16x16x32_bf16 v[60:63], v[176:179], v[192:195], v[60:63]
	v_mfma_f32_16x16x32_bf16 v[56:59], v[184:187], v[192:195], v[56:59]
	v_mfma_f32_16x16x32_bf16 v[52:55], v[176:179], v[200:203], v[52:55]
	v_mfma_f32_16x16x32_bf16 v[48:51], v[184:187], v[200:203], v[48:51]
	v_mfma_f32_16x16x32_bf16 v[44:47], v[176:179], v[208:211], v[44:47]
	v_mfma_f32_16x16x32_bf16 v[40:43], v[184:187], v[208:211], v[40:43]
	v_mfma_f32_16x16x32_bf16 v[36:39], v[176:179], v[216:219], v[36:39]
	v_mfma_f32_16x16x32_bf16 v[32:35], v[184:187], v[216:219], v[32:35]
	s_setprio 0
	s_barrier
	v_readfirstlane_b32 s53, v159
	v_add_u32_e32 v171, 0x2000, v159
	v_lshl_add_u64 v[172:173], v[240:241], 0, s[44:45]
	s_mov_b32 m0, s53
	v_readfirstlane_b32 s53, v171
	global_load_lds_dwordx4 v[172:173], off
	v_lshl_add_u64 v[172:173], v[242:243], 0, s[44:45]
	s_mov_b32 m0, s53
	s_nop 0
	global_load_lds_dwordx4 v[172:173], off
	s_waitcnt vmcnt(6)
	s_barrier
	s_setprio 0
	v_mfma_f32_16x16x32_bf16 v[28:31], v[220:223], v[188:191], v[28:31]
	v_mfma_f32_16x16x32_bf16 v[24:27], v[228:231], v[188:191], v[24:27]
	v_mfma_f32_16x16x32_bf16 v[20:23], v[220:223], v[196:199], v[20:23]
	v_mfma_f32_16x16x32_bf16 v[16:19], v[228:231], v[196:199], v[16:19]
	v_mfma_f32_16x16x32_bf16 v[12:15], v[220:223], v[204:207], v[12:15]
	v_mfma_f32_16x16x32_bf16 v[8:11], v[228:231], v[204:207], v[8:11]
	v_mfma_f32_16x16x32_bf16 v[4:7], v[220:223], v[212:215], v[4:7]
	v_mfma_f32_16x16x32_bf16 v[0:3], v[228:231], v[212:215], v[0:3]
	v_mfma_f32_16x16x32_bf16 v[28:31], v[224:227], v[192:195], v[28:31]
	v_mfma_f32_16x16x32_bf16 v[24:27], v[232:235], v[192:195], v[24:27]
	v_mfma_f32_16x16x32_bf16 v[20:23], v[224:227], v[200:203], v[20:23]
	v_mfma_f32_16x16x32_bf16 v[16:19], v[232:235], v[200:203], v[16:19]
	v_mfma_f32_16x16x32_bf16 v[12:15], v[224:227], v[208:211], v[12:15]
	v_mfma_f32_16x16x32_bf16 v[8:11], v[232:235], v[208:211], v[8:11]
	v_mfma_f32_16x16x32_bf16 v[4:7], v[224:227], v[216:219], v[4:7]
	v_mfma_f32_16x16x32_bf16 v[0:3], v[232:235], v[216:219], v[0:3]
	s_setprio 0
	s_add_i32 s52, s52, 2
	s_add_u32 s50, s50, 0x100
	s_addc_u32 s51, s51, 0
	s_cmp_gt_u32 s52, 27
	s_barrier
	s_cbranch_scc0 .LBB0_770
	s_add_i32 s50, s48, 0x80
	s_mul_hi_i32 s51, s50, 0x1080
	s_mulk_i32 s50, 0x1080
	s_add_u32 s50, s61, s50
	s_addc_u32 s51, s62, s51
	v_lshl_add_u64 v[158:159], s[50:51], 0, v[128:129]
	v_readfirstlane_b32 s52, v169
	v_lshl_add_u64 v[158:159], v[158:159], 0, s[46:47]
	s_mov_b32 m0, s52
	ds_read_b128 v[134:137], v161
	ds_read_b128 v[138:141], v161 offset:1024
	ds_read_b128 v[172:175], v161 offset:2048
	ds_read_b128 v[176:179], v161 offset:3072
	ds_read_b128 v[180:183], v152
	ds_read_b128 v[184:187], v152 offset:1024
	ds_read_b128 v[188:191], v151
	ds_read_b128 v[192:195], v151 offset:1024
	ds_read_b128 v[196:199], v150
	ds_read_b128 v[200:203], v150 offset:1024
	ds_read_b128 v[204:207], v149
	ds_read_b128 v[208:211], v149 offset:1024
	global_load_lds_dwordx4 v[158:159], off
	v_lshl_add_u64 v[158:159], s[50:51], 0, v[132:133]
	v_readfirstlane_b32 s50, v170
	v_lshl_add_u64 v[158:159], v[158:159], 0, s[46:47]
	s_mov_b32 m0, s50
	s_nop 0
	global_load_lds_dwordx4 v[158:159], off
	s_barrier
	s_waitcnt lgkmcnt(0)
	s_setprio 0
	s_waitcnt lgkmcnt(0)
	v_mfma_f32_16x16x32_bf16 v[124:127], v[134:137], v[180:183], v[124:127]
	v_mfma_f32_16x16x32_bf16 v[120:123], v[172:175], v[180:183], v[120:123]
	v_mfma_f32_16x16x32_bf16 v[116:119], v[134:137], v[188:191], v[116:119]
	v_mfma_f32_16x16x32_bf16 v[112:115], v[172:175], v[188:191], v[112:115]
	v_mfma_f32_16x16x32_bf16 v[108:111], v[134:137], v[196:199], v[108:111]
	v_mfma_f32_16x16x32_bf16 v[104:107], v[172:175], v[196:199], v[104:107]
	v_mfma_f32_16x16x32_bf16 v[100:103], v[134:137], v[204:207], v[100:103]
	v_mfma_f32_16x16x32_bf16 v[96:99], v[172:175], v[204:207], v[96:99]
	v_mfma_f32_16x16x32_bf16 v[124:127], v[138:141], v[184:187], v[124:127]
	v_mfma_f32_16x16x32_bf16 v[120:123], v[176:179], v[184:187], v[120:123]
	v_mfma_f32_16x16x32_bf16 v[116:119], v[138:141], v[192:195], v[116:119]
	v_mfma_f32_16x16x32_bf16 v[112:115], v[176:179], v[192:195], v[112:115]
	v_mfma_f32_16x16x32_bf16 v[108:111], v[138:141], v[200:203], v[108:111]
	v_mfma_f32_16x16x32_bf16 v[104:107], v[176:179], v[200:203], v[104:107]
	v_mfma_f32_16x16x32_bf16 v[100:103], v[138:141], v[208:211], v[100:103]
	v_mfma_f32_16x16x32_bf16 v[96:99], v[176:179], v[208:211], v[96:99]
	s_setprio 0
	s_barrier
	ds_read_b128 v[212:215], v160
	ds_read_b128 v[216:219], v160 offset:1024
	ds_read_b128 v[220:223], v160 offset:2048
	ds_read_b128 v[158:161], v160 offset:3072
	s_barrier
; #define LDA(dst, b, h) for (int m = 0; m < 4; ++m) for (int k = 0; k < 2; ++k) \
;     dst[m][k] = *reinterpret_cast<const bf16x8*>((char*)SA(b, h) + lds_byte(wr * 64 + m * 16 + fr, k * 32 + fq * 8))
; #define LDB(dst, b, h) for (int n = 0; n < 2; ++n) for (int k = 0; k < 2; ++k) \
;     dst[n][k] = *reinterpret_cast<const bf16x8*>((char*)SB(b, h) + lds_byte(wc * 32 + n * 16 + fr, k * 32 + fq * 8))
; #define MMA(ai, bj, At_, Bt_) do { __builtin_amdgcn_s_setprio(1); \
;     for (int k = 0; k < 2; ++k) for (int m = 0; m < 4; ++m) for (int n = 0; n < 2; ++n) \
;       acc[ai][bj][m][n] = __builtin_amdgcn_mfma_f32_16x16x32_bf16(At_[m][k], Bt_[n][k], acc[ai][bj][m][n], 0, 0, 0); \
;     __builtin_amdgcn_s_setprio(0); } while (0)
; #define WAIT_V(n) asm volatile("s_waitcnt vmcnt(" #n ")" ::: "memory")
; #define WAIT_L(n) asm volatile("s_waitcnt lgkmcnt(" #n ")" ::: "memory")
; #define BAR __builtin_amdgcn_s_barrier()
; template <int EPI, int lda, int ldb, int N, int K>
; __device__ __forceinline__ void gemm_phase(const u16* __restrict__ A, const u16* __restrict__ Bt, const GemmEpi ep, int wv) {
;     ...
;       LDB(B1, 0, 1); BAR; WAIT_L(0); MMA(0, 1, At, B1); BAR;
;       LDA(At, 0, 1); WAIT_V(4); BAR; WAIT_L(0); MMA(1, 0, At, B0); MMA(1, 1, At, B1); BAR; }
;     { LDB(B0, 1, 0); LDA(At, 1, 0); WAIT_V(2); BAR; WAIT_L(0); MMA(0, 0, At, B0); BAR;
	s_waitcnt lgkmcnt(0)
	s_setprio 0
	s_waitcnt lgkmcnt(0)
	v_mfma_f32_16x16x32_bf16 v[92:95], v[212:215], v[180:183], v[92:95]
	v_mfma_f32_16x16x32_bf16 v[88:91], v[220:223], v[180:183], v[88:91]
	v_mfma_f32_16x16x32_bf16 v[76:79], v[212:215], v[196:199], v[76:79]
	v_mfma_f32_16x16x32_bf16 v[72:75], v[220:223], v[196:199], v[72:75]
	v_mfma_f32_16x16x32_bf16 v[84:87], v[212:215], v[188:191], v[84:87]
	v_mfma_f32_16x16x32_bf16 v[80:83], v[220:223], v[188:191], v[80:83]
	v_mfma_f32_16x16x32_bf16 v[68:71], v[212:215], v[204:207], v[68:71]
	v_mfma_f32_16x16x32_bf16 v[64:67], v[220:223], v[204:207], v[64:67]
	v_mfma_f32_16x16x32_bf16 v[92:95], v[216:219], v[184:187], v[92:95]
	v_mfma_f32_16x16x32_bf16 v[88:91], v[158:161], v[184:187], v[88:91]
	v_mfma_f32_16x16x32_bf16 v[76:79], v[216:219], v[200:203], v[76:79]
	v_mfma_f32_16x16x32_bf16 v[72:75], v[158:161], v[200:203], v[72:75]
	v_mfma_f32_16x16x32_bf16 v[180:183], v[216:219], v[192:195], v[84:87]
	v_mfma_f32_16x16x32_bf16 v[184:187], v[158:161], v[192:195], v[80:83]
	v_mfma_f32_16x16x32_bf16 v[188:191], v[216:219], v[208:211], v[68:71]
	v_mfma_f32_16x16x32_bf16 v[192:195], v[158:161], v[208:211], v[64:67]
	s_setprio 0
	s_barrier
	s_nop 0
	ds_read_b128 v[64:67], v152 offset:16384
	ds_read_b128 v[68:71], v152 offset:17408
	ds_read_b128 v[80:83], v151 offset:16384
	ds_read_b128 v[84:87], v151 offset:17408
	ds_read_b128 v[196:199], v150 offset:16384
	ds_read_b128 v[200:203], v150 offset:17408
	ds_read_b128 v[204:207], v149 offset:16384
	ds_read_b128 v[208:211], v149 offset:17408
	s_waitcnt vmcnt(4)
	s_barrier
	s_waitcnt lgkmcnt(0)
	s_setprio 0
	s_waitcnt lgkmcnt(0)
	v_mfma_f32_16x16x32_bf16 v[60:63], v[134:137], v[64:67], v[60:63]
	v_mfma_f32_16x16x32_bf16 v[56:59], v[172:175], v[64:67], v[56:59]
	v_mfma_f32_16x16x32_bf16 v[52:55], v[134:137], v[80:83], v[52:55]
	v_mfma_f32_16x16x32_bf16 v[48:51], v[172:175], v[80:83], v[48:51]
	v_mfma_f32_16x16x32_bf16 v[44:47], v[134:137], v[196:199], v[44:47]
	v_mfma_f32_16x16x32_bf16 v[40:43], v[172:175], v[196:199], v[40:43]
	v_mfma_f32_16x16x32_bf16 v[36:39], v[134:137], v[204:207], v[36:39]
	v_mfma_f32_16x16x32_bf16 v[32:35], v[172:175], v[204:207], v[32:35]
	v_mfma_f32_16x16x32_bf16 v[60:63], v[138:141], v[68:71], v[60:63]
	v_mfma_f32_16x16x32_bf16 v[56:59], v[176:179], v[68:71], v[56:59]
	v_mfma_f32_16x16x32_bf16 v[52:55], v[138:141], v[84:87], v[52:55]
	v_mfma_f32_16x16x32_bf16 v[48:51], v[176:179], v[84:87], v[48:51]
	v_mfma_f32_16x16x32_bf16 v[44:47], v[138:141], v[200:203], v[44:47]
	v_mfma_f32_16x16x32_bf16 v[40:43], v[176:179], v[200:203], v[40:43]
	v_mfma_f32_16x16x32_bf16 v[36:39], v[138:141], v[208:211], v[36:39]
	v_mfma_f32_16x16x32_bf16 v[32:35], v[176:179], v[208:211], v[32:35]
	s_setprio 0
	s_setprio 0
	v_mfma_f32_16x16x32_bf16 v[28:31], v[212:215], v[64:67], v[28:31]
	v_mfma_f32_16x16x32_bf16 v[24:27], v[220:223], v[64:67], v[24:27]
	v_mfma_f32_16x16x32_bf16 v[12:15], v[212:215], v[196:199], v[12:15]
	v_mfma_f32_16x16x32_bf16 v[8:11], v[220:223], v[196:199], v[8:11]
	v_mfma_f32_16x16x32_bf16 v[20:23], v[212:215], v[80:83], v[20:23]
	v_mfma_f32_16x16x32_bf16 v[16:19], v[220:223], v[80:83], v[16:19]
	v_mfma_f32_16x16x32_bf16 v[4:7], v[212:215], v[204:207], v[4:7]
	v_mfma_f32_16x16x32_bf16 v[0:3], v[220:223], v[204:207], v[0:3]
	v_mfma_f32_16x16x32_bf16 v[28:31], v[216:219], v[68:71], v[28:31]
	v_mfma_f32_16x16x32_bf16 v[24:27], v[158:161], v[68:71], v[24:27]
	v_mfma_f32_16x16x32_bf16 v[12:15], v[216:219], v[200:203], v[12:15]
	v_mfma_f32_16x16x32_bf16 v[8:11], v[158:161], v[200:203], v[8:11]
	v_mfma_f32_16x16x32_bf16 v[134:137], v[216:219], v[84:87], v[20:23]
	v_mfma_f32_16x16x32_bf16 v[138:141], v[158:161], v[84:87], v[16:19]
	v_mfma_f32_16x16x32_bf16 v[170:173], v[216:219], v[208:211], v[4:7]
	v_mfma_f32_16x16x32_bf16 v[158:161], v[158:161], v[208:211], v[0:3]
	s_setprio 0
	s_barrier
	s_nop 0
	ds_read_b128 v[0:3], v156
	ds_read_b128 v[4:7], v156 offset:1024
	ds_read_b128 v[16:19], v156 offset:2048
	ds_read_b128 v[174:177], v156 offset:3072
	ds_read_b128 v[20:23], v152 offset:32768
	ds_read_b128 v[196:199], v152 offset:33792
	ds_read_b128 v[200:203], v151 offset:32768
	ds_read_b128 v[204:207], v151 offset:33792
	ds_read_b128 v[208:211], v150 offset:32768
	ds_read_b128 v[212:215], v150 offset:33792
	ds_read_b128 v[216:219], v149 offset:32768
	ds_read_b128 v[220:223], v149 offset:33792
	s_waitcnt vmcnt(2)
	s_barrier
; #define LDA(dst, b, h) for (int m = 0; m < 4; ++m) for (int k = 0; k < 2; ++k) \
;     dst[m][k] = *reinterpret_cast<const bf16x8*>((char*)SA(b, h) + lds_byte(wr * 64 + m * 16 + fr, k * 32 + fq * 8))
; #define LDB(dst, b, h) for (int n = 0; n < 2; ++n) for (int k = 0; k < 2; ++k) \
;     dst[n][k] = *reinterpret_cast<const bf16x8*>((char*)SB(b, h) + lds_byte(wc * 32 + n * 16 + fr, k * 32 + fq * 8))
; #define MMA(ai, bj, At_, Bt_) do { __builtin_amdgcn_s_setprio(1); \
;     for (int k = 0; k < 2; ++k) for (int m = 0; m < 4; ++m) for (int n = 0; n < 2; ++n) \
;       acc[ai][bj][m][n] = __builtin_amdgcn_mfma_f32_16x16x32_bf16(At_[m][k], Bt_[n][k], acc[ai][bj][m][n], 0, 0, 0); \
;     __builtin_amdgcn_s_setprio(0); } while (0)
; #define WAIT_V(n) asm volatile("s_waitcnt vmcnt(" #n ")" ::: "memory")
; #define WAIT_L(n) asm volatile("s_waitcnt lgkmcnt(" #n ")" ::: "memory")
; #define BAR __builtin_amdgcn_s_barrier()
; template <int EPI, int lda, int ldb, int N, int K>
; __device__ __forceinline__ void gemm_phase(const u16* __restrict__ A, const u16* __restrict__ Bt, const GemmEpi ep, int wv) {
;     ...
;     { LDB(B0, 1, 0); LDA(At, 1, 0); WAIT_V(2); BAR; WAIT_L(0); MMA(0, 0, At, B0); BAR;
;       LDB(B1, 1, 1); WAIT_V(0); BAR; WAIT_L(0); MMA(0, 1, At, B1); BAR;
;       LDA(At, 1, 1); BAR; WAIT_L(0); MMA(1, 0, At, B0); MMA(1, 1, At, B1); BAR; }
;     if (wr == 0) BAR;
	s_waitcnt lgkmcnt(0)
	s_setprio 0
	s_waitcnt lgkmcnt(0)
	v_mfma_f32_16x16x32_bf16 v[64:67], v[0:3], v[20:23], v[124:127]
	v_mfma_f32_16x16x32_bf16 v[68:71], v[16:19], v[20:23], v[120:123]
	v_mfma_f32_16x16x32_bf16 v[80:83], v[0:3], v[200:203], v[116:119]
	v_mfma_f32_16x16x32_bf16 v[84:87], v[16:19], v[200:203], v[112:115]
	v_mfma_f32_16x16x32_bf16 v[108:111], v[0:3], v[208:211], v[108:111]
	v_mfma_f32_16x16x32_bf16 v[104:107], v[16:19], v[208:211], v[104:107]
	v_mfma_f32_16x16x32_bf16 v[120:123], v[0:3], v[216:219], v[100:103]
	v_mfma_f32_16x16x32_bf16 v[124:127], v[16:19], v[216:219], v[96:99]
	v_mfma_f32_16x16x32_bf16 v[116:119], v[4:7], v[196:199], v[64:67]
	v_mfma_f32_16x16x32_bf16 v[112:115], v[174:177], v[196:199], v[68:71]
	v_mfma_f32_16x16x32_bf16 v[100:103], v[4:7], v[204:207], v[80:83]
	v_mfma_f32_16x16x32_bf16 v[96:99], v[174:177], v[204:207], v[84:87]
	v_mfma_f32_16x16x32_bf16 v[84:87], v[4:7], v[212:215], v[108:111]
	v_mfma_f32_16x16x32_bf16 v[80:83], v[174:177], v[212:215], v[104:107]
	v_mfma_f32_16x16x32_bf16 v[68:71], v[4:7], v[220:223], v[120:123]
	v_mfma_f32_16x16x32_bf16 v[64:67], v[174:177], v[220:223], v[124:127]
	s_setprio 0
	s_barrier
	ds_read_b128 v[224:227], v154
	ds_read_b128 v[228:231], v154 offset:1024
	ds_read_b128 v[232:235], v154 offset:2048
	ds_read_b128 v[154:157], v154 offset:3072
	s_waitcnt vmcnt(0)
	s_barrier
	s_waitcnt lgkmcnt(0)
	s_setprio 0
	s_waitcnt lgkmcnt(0)
	v_mfma_f32_16x16x32_bf16 v[92:95], v[224:227], v[20:23], v[92:95]
	v_mfma_f32_16x16x32_bf16 v[20:23], v[232:235], v[20:23], v[88:91]
	v_mfma_f32_16x16x32_bf16 v[88:91], v[224:227], v[200:203], v[180:183]
	v_mfma_f32_16x16x32_bf16 v[104:107], v[232:235], v[200:203], v[184:187]
	v_mfma_f32_16x16x32_bf16 v[76:79], v[224:227], v[208:211], v[76:79]
	v_mfma_f32_16x16x32_bf16 v[72:75], v[232:235], v[208:211], v[72:75]
	v_mfma_f32_16x16x32_bf16 v[178:181], v[224:227], v[216:219], v[188:191]
	v_mfma_f32_16x16x32_bf16 v[182:185], v[232:235], v[216:219], v[192:195]
	v_mfma_f32_16x16x32_bf16 v[124:127], v[228:231], v[196:199], v[92:95]
	v_mfma_f32_16x16x32_bf16 v[120:123], v[154:157], v[196:199], v[20:23]
	v_mfma_f32_16x16x32_bf16 v[108:111], v[228:231], v[204:207], v[88:91]
	v_mfma_f32_16x16x32_bf16 v[104:107], v[154:157], v[204:207], v[104:107]
	v_mfma_f32_16x16x32_bf16 v[92:95], v[228:231], v[212:215], v[76:79]
	v_mfma_f32_16x16x32_bf16 v[88:91], v[154:157], v[212:215], v[72:75]
	v_mfma_f32_16x16x32_bf16 v[76:79], v[228:231], v[220:223], v[178:181]
	v_mfma_f32_16x16x32_bf16 v[72:75], v[154:157], v[220:223], v[182:185]
	s_setprio 0
	s_barrier
	ds_read_b128 v[178:181], v152 offset:49152
	ds_read_b128 v[182:185], v152 offset:50176
	ds_read_b128 v[186:189], v151 offset:49152
	ds_read_b128 v[190:193], v151 offset:50176
	ds_read_b128 v[194:197], v150 offset:49152
	ds_read_b128 v[150:153], v150 offset:50176
	ds_read_b128 v[198:201], v149 offset:49152
	ds_read_b128 v[202:205], v149 offset:50176
	s_barrier
	s_waitcnt lgkmcnt(0)
	s_setprio 0
	s_waitcnt lgkmcnt(0)
	v_mfma_f32_16x16x32_bf16 v[20:23], v[0:3], v[178:181], v[60:63]
	v_mfma_f32_16x16x32_bf16 v[56:59], v[16:19], v[178:181], v[56:59]
	v_mfma_f32_16x16x32_bf16 v[60:63], v[0:3], v[186:189], v[52:55]
	v_mfma_f32_16x16x32_bf16 v[206:209], v[16:19], v[186:189], v[48:51]
	v_mfma_f32_16x16x32_bf16 v[44:47], v[0:3], v[194:197], v[44:47]
	v_mfma_f32_16x16x32_bf16 v[40:43], v[16:19], v[194:197], v[40:43]
	v_mfma_f32_16x16x32_bf16 v[0:3], v[0:3], v[198:201], v[36:39]
	v_mfma_f32_16x16x32_bf16 v[210:213], v[16:19], v[198:201], v[32:35]
	v_mfma_f32_16x16x32_bf16 v[52:55], v[4:7], v[182:185], v[20:23]
	v_mfma_f32_16x16x32_bf16 v[48:51], v[174:177], v[182:185], v[56:59]
	v_mfma_f32_16x16x32_bf16 v[36:39], v[4:7], v[190:193], v[60:63]
	v_mfma_f32_16x16x32_bf16 v[32:35], v[174:177], v[190:193], v[206:209]
	v_mfma_f32_16x16x32_bf16 v[20:23], v[4:7], v[150:153], v[44:47]
	v_mfma_f32_16x16x32_bf16 v[16:19], v[174:177], v[150:153], v[40:43]
	v_mfma_f32_16x16x32_bf16 v[4:7], v[4:7], v[202:205], v[0:3]
	v_mfma_f32_16x16x32_bf16 v[0:3], v[174:177], v[202:205], v[210:213]
	s_setprio 0
	s_setprio 0
	v_mfma_f32_16x16x32_bf16 v[28:31], v[224:227], v[178:181], v[28:31]
	v_mfma_f32_16x16x32_bf16 v[24:27], v[232:235], v[178:181], v[24:27]
	v_mfma_f32_16x16x32_bf16 v[40:43], v[224:227], v[186:189], v[134:137]
	v_mfma_f32_16x16x32_bf16 v[134:137], v[232:235], v[186:189], v[138:141]
	v_mfma_f32_16x16x32_bf16 v[12:15], v[224:227], v[194:197], v[12:15]
	v_mfma_f32_16x16x32_bf16 v[8:11], v[232:235], v[194:197], v[8:11]
	v_mfma_f32_16x16x32_bf16 v[138:141], v[224:227], v[198:201], v[170:173]
	v_mfma_f32_16x16x32_bf16 v[158:161], v[232:235], v[198:201], v[158:161]
	v_mfma_f32_16x16x32_bf16 v[60:63], v[228:231], v[182:185], v[28:31]
	v_mfma_f32_16x16x32_bf16 v[56:59], v[154:157], v[182:185], v[24:27]
	v_mfma_f32_16x16x32_bf16 v[44:47], v[228:231], v[190:193], v[40:43]
	v_mfma_f32_16x16x32_bf16 v[40:43], v[154:157], v[190:193], v[134:137]
	v_mfma_f32_16x16x32_bf16 v[28:31], v[228:231], v[150:153], v[12:15]
	v_mfma_f32_16x16x32_bf16 v[24:27], v[154:157], v[150:153], v[8:11]
	v_mfma_f32_16x16x32_bf16 v[12:15], v[228:231], v[202:205], v[138:141]
	v_mfma_f32_16x16x32_bf16 v[8:11], v[154:157], v[202:205], v[158:161]
	s_setprio 0
	v_cmp_gt_u32_e32 vcc, s66, v130
	s_barrier
	s_and_saveexec_b64 s[50:51], vcc
	s_cbranch_execz .LBB0_773
	s_barrier

; #define STAGE(P, BASE, LD, br, kt) do { const char* _g = (const char*)((BASE) + (size_t)(br) * (LD) + (size_t)(kt) * 64); \
;     for (int _i = 0; _i < 2; ++_i) { int _b = tidx * 16 + _i * 8192; int _r, _c; stage_rc(_b, _r, _c); \
;       __builtin_amdgcn_global_load_lds((const unsigned*)(_g + (unsigned)((_r * (LD) + _c) * 2)), (unsigned*)((char*)(P) + _b), 16, 0, 0); } } while (0)
; #define LDA(dst, b, h) for (int m = 0; m < 4; ++m) for (int k = 0; k < 2; ++k) \
;     dst[m][k] = *reinterpret_cast<const bf16x8*>((char*)SA(b, h) + lds_byte(wr * 64 + m * 16 + fr, k * 32 + fq * 8))
; #define LDB(dst, b, h) for (int n = 0; n < 2; ++n) for (int k = 0; k < 2; ++k) \
;     dst[n][k] = *reinterpret_cast<const bf16x8*>((char*)SB(b, h) + lds_byte(wc * 32 + n * 16 + fr, k * 32 + fq * 8))
; #define MMA(ai, bj, At_, Bt_) do { __builtin_amdgcn_s_setprio(1); \
;     for (int k = 0; k < 2; ++k) for (int m = 0; m < 4; ++m) for (int n = 0; n < 2; ++n) \
;       acc[ai][bj][m][n] = __builtin_amdgcn_mfma_f32_16x16x32_bf16(At_[m][k], Bt_[n][k], acc[ai][bj][m][n], 0, 0, 0); \
;     __builtin_amdgcn_s_setprio(0); } while (0)
; #define WAIT_L(n) asm volatile("s_waitcnt lgkmcnt(" #n ")" ::: "memory")
; #define BAR __builtin_amdgcn_s_barrier()
; #define SCHED __builtin_amdgcn_sched_barrier(0)
; template <int EPI, int lda, int ldb, int N, int K>
; __device__ __forceinline__ void gemm_phase(const u16* __restrict__ A, const u16* __restrict__ Bt, const GemmEpi ep, int wv) {
;     ...
;       LDB(B0, 0, 0); SCHED; LDA(At, 0, 0); STAGE(SA(1, 1), Ab, lda, brow + HALF, t + 1);
;       WAIT_L(8); BAR; WAIT_L(0); MMA(0, 0, At, B0); BAR; SCHED;
;       LDB(B1, 0, 1); STAGE(SB(0, 0), Bt, ldb, bcol, t + 2);
;       BAR; WAIT_L(0); MMA(0, 1, At, B1); BAR;
;       LDA(At, 0, 1); STAGE(SA(0, 0), Ab, lda, brow, t + 2);
;       BAR; WAIT_L(0); MMA(1, 0, At, B0); BAR; SCHED;
.LBB0_838:
	ds_read_b128 v[168:171], v164
	ds_read_b128 v[174:177], v164 offset:1024
	ds_read_b128 v[178:181], v164 offset:2048
	ds_read_b128 v[182:185], v164 offset:3072
	v_add_u32_e32 v172, 0xc000, v147
	v_lshl_add_u64 v[238:239], v[136:137], 0, s[50:51]
	v_readfirstlane_b32 s73, v172
	v_add_u32_e32 v173, 0xe000, v147
	v_lshl_add_u64 v[166:167], v[238:239], 0, s[22:23]
	s_mov_b32 m0, s73
	v_lshl_add_u64 v[240:241], v[134:135], 0, s[50:51]
	v_readfirstlane_b32 s73, v173
	ds_read_b128 v[186:189], v155
	ds_read_b128 v[190:193], v155 offset:1024
	ds_read_b128 v[194:197], v154
	ds_read_b128 v[198:201], v154 offset:1024
	ds_read_b128 v[202:205], v153
	ds_read_b128 v[206:209], v153 offset:1024
	ds_read_b128 v[210:213], v152
	ds_read_b128 v[214:217], v152 offset:1024
	global_load_lds_dwordx4 v[166:167], off
	v_lshl_add_u64 v[166:167], v[240:241], 0, s[22:23]
	s_mov_b32 m0, s73
	s_nop 0
	global_load_lds_dwordx4 v[166:167], off
	s_waitcnt lgkmcnt(8)
	s_barrier
	s_waitcnt lgkmcnt(0)
	s_setprio 0
	s_waitcnt lgkmcnt(0)
	v_mfma_f32_16x16x32_bf16 v[124:127], v[168:171], v[186:189], v[124:127]
	v_mfma_f32_16x16x32_bf16 v[120:123], v[178:181], v[186:189], v[120:123]
	v_mfma_f32_16x16x32_bf16 v[116:119], v[168:171], v[194:197], v[116:119]
	v_mfma_f32_16x16x32_bf16 v[112:115], v[178:181], v[194:197], v[112:115]
	v_mfma_f32_16x16x32_bf16 v[108:111], v[168:171], v[202:205], v[108:111]
	v_mfma_f32_16x16x32_bf16 v[104:107], v[178:181], v[202:205], v[104:107]
	v_mfma_f32_16x16x32_bf16 v[100:103], v[168:171], v[210:213], v[100:103]
	v_mfma_f32_16x16x32_bf16 v[96:99], v[178:181], v[210:213], v[96:99]
	v_mfma_f32_16x16x32_bf16 v[124:127], v[174:177], v[190:193], v[124:127]
	v_mfma_f32_16x16x32_bf16 v[120:123], v[182:185], v[190:193], v[120:123]
	v_mfma_f32_16x16x32_bf16 v[116:119], v[174:177], v[198:201], v[116:119]
	v_mfma_f32_16x16x32_bf16 v[112:115], v[182:185], v[198:201], v[112:115]
	v_mfma_f32_16x16x32_bf16 v[108:111], v[174:177], v[206:209], v[108:111]
	v_mfma_f32_16x16x32_bf16 v[104:107], v[182:185], v[206:209], v[104:107]
	v_mfma_f32_16x16x32_bf16 v[100:103], v[174:177], v[214:217], v[100:103]
	v_mfma_f32_16x16x32_bf16 v[96:99], v[182:185], v[214:217], v[96:99]
	s_setprio 0
	s_barrier
	v_add_u32_e32 v165, s63, v156
	v_lshl_add_u64 v[242:243], v[144:145], 0, s[50:51]
	v_readfirstlane_b32 s73, v165
	v_lshl_add_u64 v[166:167], v[242:243], 0, s[24:25]
	s_mov_b32 m0, s73
	ds_read_b128 v[218:221], v163
	ds_read_b128 v[222:225], v163 offset:1024
	ds_read_b128 v[226:229], v163 offset:2048
	ds_read_b128 v[230:233], v163 offset:3072
	global_load_lds_dwordx4 v[166:167], off
	v_add_u32_e32 v166, 0x2000, v165
	v_lshl_add_u64 v[244:245], v[142:143], 0, s[50:51]
	v_readfirstlane_b32 s73, v166
	v_lshl_add_u64 v[234:235], v[244:245], 0, s[24:25]
	s_mov_b32 m0, s73
	s_nop 0
	global_load_lds_dwordx4 v[234:235], off
	s_barrier
	s_waitcnt lgkmcnt(0)
	s_setprio 0
	s_waitcnt lgkmcnt(0)
	v_mfma_f32_16x16x32_bf16 v[92:95], v[218:221], v[186:189], v[92:95]
	v_mfma_f32_16x16x32_bf16 v[88:91], v[226:229], v[186:189], v[88:91]
	v_mfma_f32_16x16x32_bf16 v[84:87], v[218:221], v[194:197], v[84:87]
	v_mfma_f32_16x16x32_bf16 v[80:83], v[226:229], v[194:197], v[80:83]
	v_mfma_f32_16x16x32_bf16 v[76:79], v[218:221], v[202:205], v[76:79]
	v_mfma_f32_16x16x32_bf16 v[72:75], v[226:229], v[202:205], v[72:75]
	v_mfma_f32_16x16x32_bf16 v[68:71], v[218:221], v[210:213], v[68:71]
	v_mfma_f32_16x16x32_bf16 v[64:67], v[226:229], v[210:213], v[64:67]
	v_mfma_f32_16x16x32_bf16 v[92:95], v[222:225], v[190:193], v[92:95]
	v_mfma_f32_16x16x32_bf16 v[88:91], v[230:233], v[190:193], v[88:91]
	v_mfma_f32_16x16x32_bf16 v[84:87], v[222:225], v[198:201], v[84:87]
	v_mfma_f32_16x16x32_bf16 v[80:83], v[230:233], v[198:201], v[80:83]
	v_mfma_f32_16x16x32_bf16 v[76:79], v[222:225], v[206:209], v[76:79]
	v_mfma_f32_16x16x32_bf16 v[72:75], v[230:233], v[206:209], v[72:75]
	v_mfma_f32_16x16x32_bf16 v[68:71], v[222:225], v[214:217], v[68:71]
	v_mfma_f32_16x16x32_bf16 v[64:67], v[230:233], v[214:217], v[64:67]
	s_setprio 0
	v_readfirstlane_b32 s73, v147
	v_add_u32_e32 v167, 0x2000, v147
	v_lshl_add_u64 v[234:235], v[238:239], 0, s[26:27]
	s_mov_b32 m0, s73
	v_readfirstlane_b32 s73, v167
	s_barrier
	ds_read_b128 v[186:189], v155 offset:16384
	ds_read_b128 v[190:193], v155 offset:17408
	ds_read_b128 v[194:197], v154 offset:16384
	ds_read_b128 v[198:201], v154 offset:17408
	ds_read_b128 v[202:205], v153 offset:16384
	ds_read_b128 v[206:209], v153 offset:17408
	ds_read_b128 v[210:213], v152 offset:16384
	ds_read_b128 v[214:217], v152 offset:17408
	global_load_lds_dwordx4 v[234:235], off
	v_lshl_add_u64 v[234:235], v[240:241], 0, s[26:27]
	s_mov_b32 m0, s73
	s_nop 0
	global_load_lds_dwordx4 v[234:235], off
	s_barrier
	s_waitcnt lgkmcnt(0)
	s_setprio 0
	s_waitcnt lgkmcnt(0)
	v_mfma_f32_16x16x32_bf16 v[60:63], v[168:171], v[186:189], v[60:63]
	v_mfma_f32_16x16x32_bf16 v[56:59], v[178:181], v[186:189], v[56:59]
	v_mfma_f32_16x16x32_bf16 v[52:55], v[168:171], v[194:197], v[52:55]
	v_mfma_f32_16x16x32_bf16 v[48:51], v[178:181], v[194:197], v[48:51]
	v_mfma_f32_16x16x32_bf16 v[44:47], v[168:171], v[202:205], v[44:47]
	v_mfma_f32_16x16x32_bf16 v[40:43], v[178:181], v[202:205], v[40:43]
	v_mfma_f32_16x16x32_bf16 v[36:39], v[168:171], v[210:213], v[36:39]
	v_mfma_f32_16x16x32_bf16 v[32:35], v[178:181], v[210:213], v[32:35]
	v_mfma_f32_16x16x32_bf16 v[60:63], v[174:177], v[190:193], v[60:63]
	v_mfma_f32_16x16x32_bf16 v[56:59], v[182:185], v[190:193], v[56:59]
	v_mfma_f32_16x16x32_bf16 v[52:55], v[174:177], v[198:201], v[52:55]
	v_mfma_f32_16x16x32_bf16 v[48:51], v[182:185], v[198:201], v[48:51]
	v_mfma_f32_16x16x32_bf16 v[44:47], v[174:177], v[206:209], v[44:47]
	v_mfma_f32_16x16x32_bf16 v[40:43], v[182:185], v[206:209], v[40:43]
	v_mfma_f32_16x16x32_bf16 v[36:39], v[174:177], v[214:217], v[36:39]
	v_mfma_f32_16x16x32_bf16 v[32:35], v[182:185], v[214:217], v[32:35]
	s_setprio 0
	s_barrier
; #define STAGE(P, BASE, LD, br, kt) do { const char* _g = (const char*)((BASE) + (size_t)(br) * (LD) + (size_t)(kt) * 64); \
;     for (int _i = 0; _i < 2; ++_i) { int _b = tidx * 16 + _i * 8192; int _r, _c; stage_rc(_b, _r, _c); \
;       __builtin_amdgcn_global_load_lds((const unsigned*)(_g + (unsigned)((_r * (LD) + _c) * 2)), (unsigned*)((char*)(P) + _b), 16, 0, 0); } } while (0)
; #define LDA(dst, b, h) for (int m = 0; m < 4; ++m) for (int k = 0; k < 2; ++k) \
;     dst[m][k] = *reinterpret_cast<const bf16x8*>((char*)SA(b, h) + lds_byte(wr * 64 + m * 16 + fr, k * 32 + fq * 8))
; #define LDB(dst, b, h) for (int n = 0; n < 2; ++n) for (int k = 0; k < 2; ++k) \
;     dst[n][k] = *reinterpret_cast<const bf16x8*>((char*)SB(b, h) + lds_byte(wc * 32 + n * 16 + fr, k * 32 + fq * 8))
; #define MMA(ai, bj, At_, Bt_) do { __builtin_amdgcn_s_setprio(1); \
;     for (int k = 0; k < 2; ++k) for (int m = 0; m < 4; ++m) for (int n = 0; n < 2; ++n) \
;       acc[ai][bj][m][n] = __builtin_amdgcn_mfma_f32_16x16x32_bf16(At_[m][k], Bt_[n][k], acc[ai][bj][m][n], 0, 0, 0); \
;     __builtin_amdgcn_s_setprio(0); } while (0)
; #define WAIT_V(n) asm volatile("s_waitcnt vmcnt(" #n ")" ::: "memory")
; #define WAIT_L(n) asm volatile("s_waitcnt lgkmcnt(" #n ")" ::: "memory")
; #define BAR __builtin_amdgcn_s_barrier()
; #define SCHED __builtin_amdgcn_sched_barrier(0)
; template <int EPI, int lda, int ldb, int N, int K>
; __device__ __forceinline__ void gemm_phase(const u16* __restrict__ A, const u16* __restrict__ Bt, const GemmEpi ep, int wv) {
;     ...
;       STAGE(SB(0, 1), Bt, ldb, bcol + HALF, t + 2);
;       WAIT_V(6); BAR; MMA(1, 1, At, B1); BAR;
;       LDB(B0, 1, 0); SCHED; LDA(At, 1, 0); STAGE(SA(0, 1), Ab, lda, brow + HALF, t + 2);
;       WAIT_L(8); BAR; WAIT_L(0); MMA(0, 0, At, B0); BAR; SCHED;
;       LDB(B1, 1, 1); STAGE(SB(1, 0), Bt, ldb, bcol, t + 3);
;       BAR; WAIT_L(0); MMA(0, 1, At, B1); BAR;
;       LDA(At, 1, 1); STAGE(SA(1, 0), Ab, lda, brow, t + 3);
	v_add_u32_e32 v168, s64, v156
	v_lshl_add_u64 v[246:247], v[140:141], 0, s[50:51]
	v_readfirstlane_b32 s73, v168
	v_add_u32_e32 v169, 0x2000, v168
	v_lshl_add_u64 v[170:171], v[246:247], 0, s[40:41]
	s_mov_b32 m0, s73
	v_lshl_add_u64 v[248:249], v[138:139], 0, s[50:51]
	v_readfirstlane_b32 s73, v169
	global_load_lds_dwordx4 v[170:171], off
	v_lshl_add_u64 v[170:171], v[248:249], 0, s[40:41]
	s_mov_b32 m0, s73
	s_nop 0
	global_load_lds_dwordx4 v[170:171], off
	s_waitcnt vmcnt(6)
	s_barrier
	s_setprio 0
	v_mfma_f32_16x16x32_bf16 v[28:31], v[218:221], v[186:189], v[28:31]
	v_mfma_f32_16x16x32_bf16 v[24:27], v[226:229], v[186:189], v[24:27]
	v_mfma_f32_16x16x32_bf16 v[20:23], v[218:221], v[194:197], v[20:23]
	v_mfma_f32_16x16x32_bf16 v[16:19], v[226:229], v[194:197], v[16:19]
	v_mfma_f32_16x16x32_bf16 v[12:15], v[218:221], v[202:205], v[12:15]
	v_mfma_f32_16x16x32_bf16 v[8:11], v[226:229], v[202:205], v[8:11]
	v_mfma_f32_16x16x32_bf16 v[4:7], v[218:221], v[210:213], v[4:7]
	v_mfma_f32_16x16x32_bf16 v[0:3], v[226:229], v[210:213], v[0:3]
	v_mfma_f32_16x16x32_bf16 v[28:31], v[222:225], v[190:193], v[28:31]
	v_mfma_f32_16x16x32_bf16 v[24:27], v[230:233], v[190:193], v[24:27]
	v_mfma_f32_16x16x32_bf16 v[20:23], v[222:225], v[198:201], v[20:23]
	v_mfma_f32_16x16x32_bf16 v[16:19], v[230:233], v[198:201], v[16:19]
	v_mfma_f32_16x16x32_bf16 v[12:15], v[222:225], v[206:209], v[12:15]
	v_mfma_f32_16x16x32_bf16 v[8:11], v[230:233], v[206:209], v[8:11]
	v_mfma_f32_16x16x32_bf16 v[4:7], v[222:225], v[214:217], v[4:7]
	v_mfma_f32_16x16x32_bf16 v[0:3], v[230:233], v[214:217], v[0:3]
	s_setprio 0
	s_barrier
	ds_read_b128 v[174:177], v159
	ds_read_b128 v[178:181], v159 offset:1024
	ds_read_b128 v[182:185], v159 offset:2048
	ds_read_b128 v[186:189], v159 offset:3072
	v_add_u32_e32 v170, 0x4000, v147
	v_add_u32_e32 v171, 0x6000, v147
	v_readfirstlane_b32 s73, v170
	v_lshl_add_u64 v[222:223], v[238:239], 0, s[42:43]
	s_mov_b32 m0, s73
	v_readfirstlane_b32 s73, v171
	ds_read_b128 v[190:193], v155 offset:32768
	ds_read_b128 v[194:197], v155 offset:33792
	ds_read_b128 v[198:201], v154 offset:32768
	ds_read_b128 v[202:205], v154 offset:33792
	ds_read_b128 v[206:209], v153 offset:32768
	ds_read_b128 v[210:213], v153 offset:33792
	ds_read_b128 v[214:217], v152 offset:32768
	ds_read_b128 v[218:221], v152 offset:33792
	global_load_lds_dwordx4 v[222:223], off
	v_lshl_add_u64 v[222:223], v[240:241], 0, s[42:43]
	s_mov_b32 m0, s73
	s_nop 0
	global_load_lds_dwordx4 v[222:223], off
	s_waitcnt lgkmcnt(8)
	s_barrier
	s_waitcnt lgkmcnt(0)
	s_setprio 0
	s_waitcnt lgkmcnt(0)
	v_mfma_f32_16x16x32_bf16 v[124:127], v[174:177], v[190:193], v[124:127]
	v_mfma_f32_16x16x32_bf16 v[120:123], v[182:185], v[190:193], v[120:123]
	v_mfma_f32_16x16x32_bf16 v[116:119], v[174:177], v[198:201], v[116:119]
	v_mfma_f32_16x16x32_bf16 v[112:115], v[182:185], v[198:201], v[112:115]
	v_mfma_f32_16x16x32_bf16 v[108:111], v[174:177], v[206:209], v[108:111]
	v_mfma_f32_16x16x32_bf16 v[104:107], v[182:185], v[206:209], v[104:107]
	v_mfma_f32_16x16x32_bf16 v[100:103], v[174:177], v[214:217], v[100:103]
	v_mfma_f32_16x16x32_bf16 v[96:99], v[182:185], v[214:217], v[96:99]
	v_mfma_f32_16x16x32_bf16 v[124:127], v[178:181], v[194:197], v[124:127]
	v_mfma_f32_16x16x32_bf16 v[120:123], v[186:189], v[194:197], v[120:123]
	v_mfma_f32_16x16x32_bf16 v[116:119], v[178:181], v[202:205], v[116:119]
	v_mfma_f32_16x16x32_bf16 v[112:115], v[186:189], v[202:205], v[112:115]
	v_mfma_f32_16x16x32_bf16 v[108:111], v[178:181], v[210:213], v[108:111]
	v_mfma_f32_16x16x32_bf16 v[104:107], v[186:189], v[210:213], v[104:107]
	v_mfma_f32_16x16x32_bf16 v[100:103], v[178:181], v[218:221], v[100:103]
	v_mfma_f32_16x16x32_bf16 v[96:99], v[186:189], v[218:221], v[96:99]
	s_setprio 0
	s_barrier
	v_readfirstlane_b32 s73, v158
	v_lshl_add_u64 v[242:243], v[242:243], 0, s[44:45]
	s_mov_b32 m0, s73
	ds_read_b128 v[222:225], v157
	ds_read_b128 v[226:229], v157 offset:1024
	ds_read_b128 v[230:233], v157 offset:2048
	ds_read_b128 v[234:237], v157 offset:3072
	global_load_lds_dwordx4 v[242:243], off
	v_lshl_add_u64 v[242:243], v[244:245], 0, s[44:45]
	v_add_u32_e32 v244, 0x2000, v158
	s_nop 0
	v_readfirstlane_b32 s73, v244
	s_mov_b32 m0, s73
	s_nop 0
	global_load_lds_dwordx4 v[242:243], off
	s_barrier
	s_waitcnt lgkmcnt(0)
	s_setprio 0
	s_waitcnt lgkmcnt(0)
	v_mfma_f32_16x16x32_bf16 v[92:95], v[222:225], v[190:193], v[92:95]
	v_mfma_f32_16x16x32_bf16 v[88:91], v[230:233], v[190:193], v[88:91]
	v_mfma_f32_16x16x32_bf16 v[84:87], v[222:225], v[198:201], v[84:87]
	v_mfma_f32_16x16x32_bf16 v[80:83], v[230:233], v[198:201], v[80:83]
	v_mfma_f32_16x16x32_bf16 v[76:79], v[222:225], v[206:209], v[76:79]
	v_mfma_f32_16x16x32_bf16 v[72:75], v[230:233], v[206:209], v[72:75]
	v_mfma_f32_16x16x32_bf16 v[68:71], v[222:225], v[214:217], v[68:71]
	v_mfma_f32_16x16x32_bf16 v[64:67], v[230:233], v[214:217], v[64:67]
	v_mfma_f32_16x16x32_bf16 v[92:95], v[226:229], v[194:197], v[92:95]
	v_mfma_f32_16x16x32_bf16 v[88:91], v[234:237], v[194:197], v[88:91]
	v_mfma_f32_16x16x32_bf16 v[84:87], v[226:229], v[202:205], v[84:87]
	v_mfma_f32_16x16x32_bf16 v[80:83], v[234:237], v[202:205], v[80:83]
	v_mfma_f32_16x16x32_bf16 v[76:79], v[226:229], v[210:213], v[76:79]
	v_mfma_f32_16x16x32_bf16 v[72:75], v[234:237], v[210:213], v[72:75]
	v_mfma_f32_16x16x32_bf16 v[68:71], v[226:229], v[218:221], v[68:71]
	v_mfma_f32_16x16x32_bf16 v[64:67], v[234:237], v[218:221], v[64:67]
	s_setprio 0
	v_readfirstlane_b32 s73, v160
	v_lshl_add_u64 v[238:239], v[238:239], 0, s[46:47]
	s_mov_b32 m0, s73
	v_readfirstlane_b32 s73, v161
	s_barrier
; #define STAGE(P, BASE, LD, br, kt) do { const char* _g = (const char*)((BASE) + (size_t)(br) * (LD) + (size_t)(kt) * 64); \
;     for (int _i = 0; _i < 2; ++_i) { int _b = tidx * 16 + _i * 8192; int _r, _c; stage_rc(_b, _r, _c); \
;       __builtin_amdgcn_global_load_lds((const unsigned*)(_g + (unsigned)((_r * (LD) + _c) * 2)), (unsigned*)((char*)(P) + _b), 16, 0, 0); } } while (0)
; #define LDA(dst, b, h) for (int m = 0; m < 4; ++m) for (int k = 0; k < 2; ++k) \
;     dst[m][k] = *reinterpret_cast<const bf16x8*>((char*)SA(b, h) + lds_byte(wr * 64 + m * 16 + fr, k * 32 + fq * 8))
; #define LDB(dst, b, h) for (int n = 0; n < 2; ++n) for (int k = 0; k < 2; ++k) \
;     dst[n][k] = *reinterpret_cast<const bf16x8*>((char*)SB(b, h) + lds_byte(wc * 32 + n * 16 + fr, k * 32 + fq * 8))
; #define MMA(ai, bj, At_, Bt_) do { __builtin_amdgcn_s_setprio(1); \
;     for (int k = 0; k < 2; ++k) for (int m = 0; m < 4; ++m) for (int n = 0; n < 2; ++n) \
;       acc[ai][bj][m][n] = __builtin_amdgcn_mfma_f32_16x16x32_bf16(At_[m][k], Bt_[n][k], acc[ai][bj][m][n], 0, 0, 0); \
;     __builtin_amdgcn_s_setprio(0); } while (0)
; #define WAIT_V(n) asm volatile("s_waitcnt vmcnt(" #n ")" ::: "memory")
; #define WAIT_L(n) asm volatile("s_waitcnt lgkmcnt(" #n ")" ::: "memory")
; #define BAR __builtin_amdgcn_s_barrier()
; #define SCHED __builtin_amdgcn_sched_barrier(0)
; template <int EPI, int lda, int ldb, int N, int K>
; __device__ __forceinline__ void gemm_phase(const u16* __restrict__ A, const u16* __restrict__ Bt, const GemmEpi ep, int wv) {
;     ...
;       LDA(At, 1, 1); STAGE(SA(1, 0), Ab, lda, brow, t + 3);
;       BAR; WAIT_L(0); MMA(1, 0, At, B0); BAR; SCHED;
;       STAGE(SB(1, 1), Bt, ldb, bcol + HALF, t + 3);
;       WAIT_V(6); BAR; MMA(1, 1, At, B1); BAR;
;     }
;     { LDB(B0, 0, 0); LDA(At, 0, 0); STAGE(SA(1, 1), Ab, lda, brow + HALF, nt - 1);
;       BAR; WAIT_L(0); MMA(0, 0, At, B0); BAR;
;       LDB(B1, 0, 1); BAR; WAIT_L(0); MMA(0, 1, At, B1); BAR;
	ds_read_b128 v[190:193], v155 offset:49152
	ds_read_b128 v[194:197], v155 offset:50176
	ds_read_b128 v[198:201], v154 offset:49152
	ds_read_b128 v[202:205], v154 offset:50176
	ds_read_b128 v[206:209], v153 offset:49152
	ds_read_b128 v[210:213], v153 offset:50176
	ds_read_b128 v[214:217], v152 offset:49152
	ds_read_b128 v[218:221], v152 offset:50176
	global_load_lds_dwordx4 v[238:239], off
	v_lshl_add_u64 v[238:239], v[240:241], 0, s[46:47]
	s_mov_b32 m0, s73
	s_nop 0
	global_load_lds_dwordx4 v[238:239], off
	s_barrier
	s_waitcnt lgkmcnt(0)
	s_setprio 0
	s_waitcnt lgkmcnt(0)
	v_mfma_f32_16x16x32_bf16 v[60:63], v[174:177], v[190:193], v[60:63]
	v_mfma_f32_16x16x32_bf16 v[56:59], v[182:185], v[190:193], v[56:59]
	v_mfma_f32_16x16x32_bf16 v[52:55], v[174:177], v[198:201], v[52:55]
	v_mfma_f32_16x16x32_bf16 v[48:51], v[182:185], v[198:201], v[48:51]
	v_mfma_f32_16x16x32_bf16 v[44:47], v[174:177], v[206:209], v[44:47]
	v_mfma_f32_16x16x32_bf16 v[40:43], v[182:185], v[206:209], v[40:43]
	v_mfma_f32_16x16x32_bf16 v[36:39], v[174:177], v[214:217], v[36:39]
	v_mfma_f32_16x16x32_bf16 v[32:35], v[182:185], v[214:217], v[32:35]
	v_mfma_f32_16x16x32_bf16 v[60:63], v[178:181], v[194:197], v[60:63]
	v_mfma_f32_16x16x32_bf16 v[56:59], v[186:189], v[194:197], v[56:59]
	v_mfma_f32_16x16x32_bf16 v[52:55], v[178:181], v[202:205], v[52:55]
	v_mfma_f32_16x16x32_bf16 v[48:51], v[186:189], v[202:205], v[48:51]
	v_mfma_f32_16x16x32_bf16 v[44:47], v[178:181], v[210:213], v[44:47]
	v_mfma_f32_16x16x32_bf16 v[40:43], v[186:189], v[210:213], v[40:43]
	v_mfma_f32_16x16x32_bf16 v[36:39], v[178:181], v[218:221], v[36:39]
	v_mfma_f32_16x16x32_bf16 v[32:35], v[186:189], v[218:221], v[32:35]
	s_setprio 0
	s_barrier
	v_readfirstlane_b32 s73, v162
	v_add_u32_e32 v176, 0x2000, v162
	v_lshl_add_u64 v[174:175], v[246:247], 0, s[48:49]
	s_mov_b32 m0, s73
	v_readfirstlane_b32 s73, v176
	global_load_lds_dwordx4 v[174:175], off
	v_lshl_add_u64 v[174:175], v[248:249], 0, s[48:49]
	s_mov_b32 m0, s73
	s_nop 0
	global_load_lds_dwordx4 v[174:175], off
	s_waitcnt vmcnt(6)
	s_barrier
	s_setprio 0
	v_mfma_f32_16x16x32_bf16 v[28:31], v[222:225], v[190:193], v[28:31]
	v_mfma_f32_16x16x32_bf16 v[24:27], v[230:233], v[190:193], v[24:27]
	v_mfma_f32_16x16x32_bf16 v[20:23], v[222:225], v[198:201], v[20:23]
	v_mfma_f32_16x16x32_bf16 v[16:19], v[230:233], v[198:201], v[16:19]
	v_mfma_f32_16x16x32_bf16 v[12:15], v[222:225], v[206:209], v[12:15]
	v_mfma_f32_16x16x32_bf16 v[8:11], v[230:233], v[206:209], v[8:11]
	v_mfma_f32_16x16x32_bf16 v[4:7], v[222:225], v[214:217], v[4:7]
	v_mfma_f32_16x16x32_bf16 v[0:3], v[230:233], v[214:217], v[0:3]
	v_mfma_f32_16x16x32_bf16 v[28:31], v[226:229], v[194:197], v[28:31]
	v_mfma_f32_16x16x32_bf16 v[24:27], v[234:237], v[194:197], v[24:27]
	v_mfma_f32_16x16x32_bf16 v[20:23], v[226:229], v[202:205], v[20:23]
	v_mfma_f32_16x16x32_bf16 v[16:19], v[234:237], v[202:205], v[16:19]
	v_mfma_f32_16x16x32_bf16 v[12:15], v[226:229], v[210:213], v[12:15]
	v_mfma_f32_16x16x32_bf16 v[8:11], v[234:237], v[210:213], v[8:11]
	v_mfma_f32_16x16x32_bf16 v[4:7], v[226:229], v[218:221], v[4:7]
	v_mfma_f32_16x16x32_bf16 v[0:3], v[234:237], v[218:221], v[0:3]
	s_setprio 0
	s_add_i32 s72, s72, 2
	s_add_u32 s50, s50, 0x100
	s_addc_u32 s51, s51, 0
	s_cmpk_gt_u32 s72, 0x51
	s_barrier
	s_cbranch_scc0 .LBB0_838
	s_add_i32 s50, s18, 0x80
	s_mul_hi_i32 s51, s50, 0x2b00
	s_mulk_i32 s50, 0x2b00
	s_add_u32 s50, s56, s50
	s_addc_u32 s51, s57, s51
	s_add_u32 s50, s50, 0x2a80
	s_addc_u32 s51, s51, 0
	v_readfirstlane_b32 s72, v172
	v_lshl_add_u64 v[160:161], s[50:51], 0, v[128:129]
	s_mov_b32 m0, s72
	ds_read_b128 v[134:137], v164
	ds_read_b128 v[138:141], v164 offset:1024
	ds_read_b128 v[142:145], v164 offset:2048
	ds_read_b128 v[174:177], v164 offset:3072
	ds_read_b128 v[178:181], v155
	ds_read_b128 v[182:185], v155 offset:1024
	ds_read_b128 v[186:189], v154
	ds_read_b128 v[190:193], v154 offset:1024
	ds_read_b128 v[194:197], v153
	ds_read_b128 v[198:201], v153 offset:1024
	ds_read_b128 v[202:205], v152
	ds_read_b128 v[206:209], v152 offset:1024
	global_load_lds_dwordx4 v[160:161], off
	v_lshl_add_u64 v[160:161], s[50:51], 0, v[132:133]
	v_readfirstlane_b32 s50, v173
	s_mov_b32 m0, s50
	s_nop 0
	global_load_lds_dwordx4 v[160:161], off
	s_barrier
	s_waitcnt lgkmcnt(0)
	s_setprio 0
	s_waitcnt lgkmcnt(0)
	v_mfma_f32_16x16x32_bf16 v[124:127], v[134:137], v[178:181], v[124:127]
	v_mfma_f32_16x16x32_bf16 v[120:123], v[142:145], v[178:181], v[120:123]
	v_mfma_f32_16x16x32_bf16 v[116:119], v[134:137], v[186:189], v[116:119]
	v_mfma_f32_16x16x32_bf16 v[112:115], v[142:145], v[186:189], v[112:115]
	v_mfma_f32_16x16x32_bf16 v[108:111], v[134:137], v[194:197], v[108:111]
	v_mfma_f32_16x16x32_bf16 v[104:107], v[142:145], v[194:197], v[104:107]
	v_mfma_f32_16x16x32_bf16 v[100:103], v[134:137], v[202:205], v[100:103]
	v_mfma_f32_16x16x32_bf16 v[96:99], v[142:145], v[202:205], v[96:99]
	v_mfma_f32_16x16x32_bf16 v[124:127], v[138:141], v[182:185], v[124:127]
	v_mfma_f32_16x16x32_bf16 v[120:123], v[174:177], v[182:185], v[120:123]
	v_mfma_f32_16x16x32_bf16 v[116:119], v[138:141], v[190:193], v[116:119]
	v_mfma_f32_16x16x32_bf16 v[112:115], v[174:177], v[190:193], v[112:115]
	v_mfma_f32_16x16x32_bf16 v[108:111], v[138:141], v[198:201], v[108:111]
	v_mfma_f32_16x16x32_bf16 v[104:107], v[174:177], v[198:201], v[104:107]
	v_mfma_f32_16x16x32_bf16 v[100:103], v[138:141], v[206:209], v[100:103]
	v_mfma_f32_16x16x32_bf16 v[96:99], v[174:177], v[206:209], v[96:99]
	s_setprio 0
	s_barrier
	ds_read_b128 v[210:213], v163
	ds_read_b128 v[214:217], v163 offset:1024
	ds_read_b128 v[218:221], v163 offset:2048
	ds_read_b128 v[160:163], v163 offset:3072
	s_barrier
; #define LDA(dst, b, h) for (int m = 0; m < 4; ++m) for (int k = 0; k < 2; ++k) \
;     dst[m][k] = *reinterpret_cast<const bf16x8*>((char*)SA(b, h) + lds_byte(wr * 64 + m * 16 + fr, k * 32 + fq * 8))
; #define LDB(dst, b, h) for (int n = 0; n < 2; ++n) for (int k = 0; k < 2; ++k) \
;     dst[n][k] = *reinterpret_cast<const bf16x8*>((char*)SB(b, h) + lds_byte(wc * 32 + n * 16 + fr, k * 32 + fq * 8))
; #define MMA(ai, bj, At_, Bt_) do { __builtin_amdgcn_s_setprio(1); \
;     for (int k = 0; k < 2; ++k) for (int m = 0; m < 4; ++m) for (int n = 0; n < 2; ++n) \
;       acc[ai][bj][m][n] = __builtin_amdgcn_mfma_f32_16x16x32_bf16(At_[m][k], Bt_[n][k], acc[ai][bj][m][n], 0, 0, 0); \
;     __builtin_amdgcn_s_setprio(0); } while (0)
; #define WAIT_V(n) asm volatile("s_waitcnt vmcnt(" #n ")" ::: "memory")
; #define WAIT_L(n) asm volatile("s_waitcnt lgkmcnt(" #n ")" ::: "memory")
; #define BAR __builtin_amdgcn_s_barrier()
; template <int EPI, int lda, int ldb, int N, int K>
; __device__ __forceinline__ void gemm_phase(const u16* __restrict__ A, const u16* __restrict__ Bt, const GemmEpi ep, int wv) {
;     ...
;       LDB(B1, 0, 1); BAR; WAIT_L(0); MMA(0, 1, At, B1); BAR;
;       LDA(At, 0, 1); WAIT_V(4); BAR; WAIT_L(0); MMA(1, 0, At, B0); MMA(1, 1, At, B1); BAR; }
;     { LDB(B0, 1, 0); LDA(At, 1, 0); WAIT_V(2); BAR; WAIT_L(0); MMA(0, 0, At, B0); BAR;
	s_waitcnt lgkmcnt(0)
	s_setprio 0
	s_waitcnt lgkmcnt(0)
	v_mfma_f32_16x16x32_bf16 v[92:95], v[210:213], v[178:181], v[92:95]
	v_mfma_f32_16x16x32_bf16 v[88:91], v[218:221], v[178:181], v[88:91]
	v_mfma_f32_16x16x32_bf16 v[76:79], v[210:213], v[194:197], v[76:79]
	v_mfma_f32_16x16x32_bf16 v[72:75], v[218:221], v[194:197], v[72:75]
	v_mfma_f32_16x16x32_bf16 v[84:87], v[210:213], v[186:189], v[84:87]
	v_mfma_f32_16x16x32_bf16 v[80:83], v[218:221], v[186:189], v[80:83]
	v_mfma_f32_16x16x32_bf16 v[68:71], v[210:213], v[202:205], v[68:71]
	v_mfma_f32_16x16x32_bf16 v[64:67], v[218:221], v[202:205], v[64:67]
	v_mfma_f32_16x16x32_bf16 v[92:95], v[214:217], v[182:185], v[92:95]
	v_mfma_f32_16x16x32_bf16 v[88:91], v[160:163], v[182:185], v[88:91]
	v_mfma_f32_16x16x32_bf16 v[76:79], v[214:217], v[198:201], v[76:79]
	v_mfma_f32_16x16x32_bf16 v[72:75], v[160:163], v[198:201], v[72:75]
	v_mfma_f32_16x16x32_bf16 v[178:181], v[214:217], v[190:193], v[84:87]
	v_mfma_f32_16x16x32_bf16 v[182:185], v[160:163], v[190:193], v[80:83]
	v_mfma_f32_16x16x32_bf16 v[186:189], v[214:217], v[206:209], v[68:71]
	v_mfma_f32_16x16x32_bf16 v[190:193], v[160:163], v[206:209], v[64:67]
	s_setprio 0
	s_barrier
	s_nop 0
	ds_read_b128 v[64:67], v155 offset:16384
	ds_read_b128 v[68:71], v155 offset:17408
	ds_read_b128 v[80:83], v154 offset:16384
	ds_read_b128 v[84:87], v154 offset:17408
	ds_read_b128 v[194:197], v153 offset:16384
	ds_read_b128 v[198:201], v153 offset:17408
	ds_read_b128 v[202:205], v152 offset:16384
	ds_read_b128 v[206:209], v152 offset:17408
	s_waitcnt vmcnt(4)
	s_barrier
	s_waitcnt lgkmcnt(0)
	s_setprio 0
	s_waitcnt lgkmcnt(0)
	v_mfma_f32_16x16x32_bf16 v[60:63], v[134:137], v[64:67], v[60:63]
	v_mfma_f32_16x16x32_bf16 v[56:59], v[142:145], v[64:67], v[56:59]
	v_mfma_f32_16x16x32_bf16 v[52:55], v[134:137], v[80:83], v[52:55]
	v_mfma_f32_16x16x32_bf16 v[48:51], v[142:145], v[80:83], v[48:51]
	v_mfma_f32_16x16x32_bf16 v[44:47], v[134:137], v[194:197], v[44:47]
	v_mfma_f32_16x16x32_bf16 v[40:43], v[142:145], v[194:197], v[40:43]
	v_mfma_f32_16x16x32_bf16 v[36:39], v[134:137], v[202:205], v[36:39]
	v_mfma_f32_16x16x32_bf16 v[32:35], v[142:145], v[202:205], v[32:35]
	v_mfma_f32_16x16x32_bf16 v[60:63], v[138:141], v[68:71], v[60:63]
	v_mfma_f32_16x16x32_bf16 v[56:59], v[174:177], v[68:71], v[56:59]
	v_mfma_f32_16x16x32_bf16 v[52:55], v[138:141], v[84:87], v[52:55]
	v_mfma_f32_16x16x32_bf16 v[48:51], v[174:177], v[84:87], v[48:51]
	v_mfma_f32_16x16x32_bf16 v[44:47], v[138:141], v[198:201], v[44:47]
	v_mfma_f32_16x16x32_bf16 v[40:43], v[174:177], v[198:201], v[40:43]
	v_mfma_f32_16x16x32_bf16 v[36:39], v[138:141], v[206:209], v[36:39]
	v_mfma_f32_16x16x32_bf16 v[32:35], v[174:177], v[206:209], v[32:35]
	s_setprio 0
	s_setprio 0
	v_mfma_f32_16x16x32_bf16 v[28:31], v[210:213], v[64:67], v[28:31]
	v_mfma_f32_16x16x32_bf16 v[16:19], v[218:221], v[80:83], v[16:19]
	v_mfma_f32_16x16x32_bf16 v[12:15], v[210:213], v[194:197], v[12:15]
	v_mfma_f32_16x16x32_bf16 v[0:3], v[218:221], v[202:205], v[0:3]
	v_mfma_f32_16x16x32_bf16 v[24:27], v[218:221], v[64:67], v[24:27]
	v_mfma_f32_16x16x32_bf16 v[20:23], v[210:213], v[80:83], v[20:23]
	v_mfma_f32_16x16x32_bf16 v[8:11], v[218:221], v[194:197], v[8:11]
	v_mfma_f32_16x16x32_bf16 v[4:7], v[210:213], v[202:205], v[4:7]
	v_mfma_f32_16x16x32_bf16 v[28:31], v[214:217], v[68:71], v[28:31]
	v_mfma_f32_16x16x32_bf16 v[16:19], v[160:163], v[84:87], v[16:19]
	v_mfma_f32_16x16x32_bf16 v[12:15], v[214:217], v[198:201], v[12:15]
	v_mfma_f32_16x16x32_bf16 v[0:3], v[160:163], v[206:209], v[0:3]
	v_mfma_f32_16x16x32_bf16 v[134:137], v[160:163], v[68:71], v[24:27]
	v_mfma_f32_16x16x32_bf16 v[138:141], v[214:217], v[84:87], v[20:23]
	v_mfma_f32_16x16x32_bf16 v[142:145], v[160:163], v[198:201], v[8:11]
	v_mfma_f32_16x16x32_bf16 v[172:175], v[214:217], v[206:209], v[4:7]
	s_setprio 0
	s_barrier
	s_nop 0
	ds_read_b128 v[4:7], v159
	ds_read_b128 v[8:11], v159 offset:1024
	ds_read_b128 v[20:23], v159 offset:2048
	ds_read_b128 v[158:161], v159 offset:3072
	ds_read_b128 v[24:27], v155 offset:32768
	ds_read_b128 v[194:197], v155 offset:33792
	ds_read_b128 v[198:201], v154 offset:32768
	ds_read_b128 v[202:205], v154 offset:33792
	ds_read_b128 v[206:209], v153 offset:32768
	ds_read_b128 v[210:213], v153 offset:33792
	ds_read_b128 v[214:217], v152 offset:32768
	ds_read_b128 v[218:221], v152 offset:33792
	s_waitcnt vmcnt(2)
	s_barrier
; #define LDA(dst, b, h) for (int m = 0; m < 4; ++m) for (int k = 0; k < 2; ++k) \
;     dst[m][k] = *reinterpret_cast<const bf16x8*>((char*)SA(b, h) + lds_byte(wr * 64 + m * 16 + fr, k * 32 + fq * 8))
; #define LDB(dst, b, h) for (int n = 0; n < 2; ++n) for (int k = 0; k < 2; ++k) \
;     dst[n][k] = *reinterpret_cast<const bf16x8*>((char*)SB(b, h) + lds_byte(wc * 32 + n * 16 + fr, k * 32 + fq * 8))
; #define MMA(ai, bj, At_, Bt_) do { __builtin_amdgcn_s_setprio(1); \
;     for (int k = 0; k < 2; ++k) for (int m = 0; m < 4; ++m) for (int n = 0; n < 2; ++n) \
;       acc[ai][bj][m][n] = __builtin_amdgcn_mfma_f32_16x16x32_bf16(At_[m][k], Bt_[n][k], acc[ai][bj][m][n], 0, 0, 0); \
;     __builtin_amdgcn_s_setprio(0); } while (0)
; #define WAIT_V(n) asm volatile("s_waitcnt vmcnt(" #n ")" ::: "memory")
; #define WAIT_L(n) asm volatile("s_waitcnt lgkmcnt(" #n ")" ::: "memory")
; #define BAR __builtin_amdgcn_s_barrier()
; template <int EPI, int lda, int ldb, int N, int K>
; __device__ __forceinline__ void gemm_phase(const u16* __restrict__ A, const u16* __restrict__ Bt, const GemmEpi ep, int wv) {
;     ...
;     { LDB(B0, 1, 0); LDA(At, 1, 0); WAIT_V(2); BAR; WAIT_L(0); MMA(0, 0, At, B0); BAR;
;       LDB(B1, 1, 1); WAIT_V(0); BAR; WAIT_L(0); MMA(0, 1, At, B1); BAR;
;       LDA(At, 1, 1); BAR; WAIT_L(0); MMA(1, 0, At, B0); MMA(1, 1, At, B1); BAR; }
;     if (wr == 0) BAR;
	s_waitcnt lgkmcnt(0)
	s_setprio 0
	s_waitcnt lgkmcnt(0)
	v_mfma_f32_16x16x32_bf16 v[64:67], v[4:7], v[24:27], v[124:127]
	v_mfma_f32_16x16x32_bf16 v[68:71], v[20:23], v[24:27], v[120:123]
	v_mfma_f32_16x16x32_bf16 v[80:83], v[4:7], v[198:201], v[116:119]
	v_mfma_f32_16x16x32_bf16 v[84:87], v[20:23], v[198:201], v[112:115]
	v_mfma_f32_16x16x32_bf16 v[108:111], v[4:7], v[206:209], v[108:111]
	v_mfma_f32_16x16x32_bf16 v[104:107], v[20:23], v[206:209], v[104:107]
	v_mfma_f32_16x16x32_bf16 v[120:123], v[4:7], v[214:217], v[100:103]
	v_mfma_f32_16x16x32_bf16 v[124:127], v[20:23], v[214:217], v[96:99]
	v_mfma_f32_16x16x32_bf16 v[116:119], v[8:11], v[194:197], v[64:67]
	v_mfma_f32_16x16x32_bf16 v[112:115], v[158:161], v[194:197], v[68:71]
	v_mfma_f32_16x16x32_bf16 v[100:103], v[8:11], v[202:205], v[80:83]
	v_mfma_f32_16x16x32_bf16 v[96:99], v[158:161], v[202:205], v[84:87]
	v_mfma_f32_16x16x32_bf16 v[84:87], v[8:11], v[210:213], v[108:111]
	v_mfma_f32_16x16x32_bf16 v[80:83], v[158:161], v[210:213], v[104:107]
	v_mfma_f32_16x16x32_bf16 v[68:71], v[8:11], v[218:221], v[120:123]
	v_mfma_f32_16x16x32_bf16 v[64:67], v[158:161], v[218:221], v[124:127]
	s_setprio 0
	s_barrier
	ds_read_b128 v[222:225], v157
	ds_read_b128 v[226:229], v157 offset:1024
	ds_read_b128 v[230:233], v157 offset:2048
	ds_read_b128 v[234:237], v157 offset:3072
	s_waitcnt vmcnt(0)
	s_barrier
	s_waitcnt lgkmcnt(0)
	s_setprio 0
	s_waitcnt lgkmcnt(0)
	v_mfma_f32_16x16x32_bf16 v[92:95], v[222:225], v[24:27], v[92:95]
	v_mfma_f32_16x16x32_bf16 v[24:27], v[230:233], v[24:27], v[88:91]
	v_mfma_f32_16x16x32_bf16 v[88:91], v[222:225], v[198:201], v[178:181]
	v_mfma_f32_16x16x32_bf16 v[104:107], v[230:233], v[198:201], v[182:185]
	v_mfma_f32_16x16x32_bf16 v[76:79], v[222:225], v[206:209], v[76:79]
	v_mfma_f32_16x16x32_bf16 v[72:75], v[230:233], v[206:209], v[72:75]
	v_mfma_f32_16x16x32_bf16 v[176:179], v[222:225], v[214:217], v[186:189]
	v_mfma_f32_16x16x32_bf16 v[180:183], v[230:233], v[214:217], v[190:193]
	v_mfma_f32_16x16x32_bf16 v[124:127], v[226:229], v[194:197], v[92:95]
	v_mfma_f32_16x16x32_bf16 v[120:123], v[234:237], v[194:197], v[24:27]
	v_mfma_f32_16x16x32_bf16 v[108:111], v[226:229], v[202:205], v[88:91]
	v_mfma_f32_16x16x32_bf16 v[104:107], v[234:237], v[202:205], v[104:107]
	v_mfma_f32_16x16x32_bf16 v[92:95], v[226:229], v[210:213], v[76:79]
	v_mfma_f32_16x16x32_bf16 v[88:91], v[234:237], v[210:213], v[72:75]
	v_mfma_f32_16x16x32_bf16 v[76:79], v[226:229], v[218:221], v[176:179]
	v_mfma_f32_16x16x32_bf16 v[72:75], v[234:237], v[218:221], v[180:183]
	s_setprio 0
	s_barrier
	ds_read_b128 v[176:179], v155 offset:49152
	ds_read_b128 v[180:183], v155 offset:50176
	ds_read_b128 v[184:187], v154 offset:49152
	ds_read_b128 v[154:157], v154 offset:50176
	ds_read_b128 v[188:191], v153 offset:49152
	ds_read_b128 v[192:195], v153 offset:50176
	ds_read_b128 v[196:199], v152 offset:49152
	ds_read_b128 v[200:203], v152 offset:50176
	s_barrier
	s_waitcnt lgkmcnt(0)
	s_setprio 0
	s_waitcnt lgkmcnt(0)
	v_mfma_f32_16x16x32_bf16 v[24:27], v[4:7], v[176:179], v[60:63]
	v_mfma_f32_16x16x32_bf16 v[60:63], v[20:23], v[176:179], v[56:59]
	v_mfma_f32_16x16x32_bf16 v[204:207], v[4:7], v[184:187], v[52:55]
	v_mfma_f32_16x16x32_bf16 v[48:51], v[20:23], v[184:187], v[48:51]
	v_mfma_f32_16x16x32_bf16 v[44:47], v[4:7], v[188:191], v[44:47]
	v_mfma_f32_16x16x32_bf16 v[208:211], v[20:23], v[188:191], v[40:43]
	v_mfma_f32_16x16x32_bf16 v[4:7], v[4:7], v[196:199], v[36:39]
	v_mfma_f32_16x16x32_bf16 v[32:35], v[20:23], v[196:199], v[32:35]
	v_mfma_f32_16x16x32_bf16 v[56:59], v[8:11], v[180:183], v[24:27]
	v_mfma_f32_16x16x32_bf16 v[52:55], v[158:161], v[180:183], v[60:63]
	v_mfma_f32_16x16x32_bf16 v[40:43], v[8:11], v[154:157], v[204:207]
	v_mfma_f32_16x16x32_bf16 v[36:39], v[158:161], v[154:157], v[48:51]
	v_mfma_f32_16x16x32_bf16 v[24:27], v[8:11], v[192:195], v[44:47]
	v_mfma_f32_16x16x32_bf16 v[20:23], v[158:161], v[192:195], v[208:211]
	v_mfma_f32_16x16x32_bf16 v[8:11], v[8:11], v[200:203], v[4:7]
	v_mfma_f32_16x16x32_bf16 v[4:7], v[158:161], v[200:203], v[32:35]
	s_setprio 0
	s_setprio 0
	v_mfma_f32_16x16x32_bf16 v[28:31], v[222:225], v[176:179], v[28:31]
	v_mfma_f32_16x16x32_bf16 v[32:35], v[230:233], v[176:179], v[134:137]
	v_mfma_f32_16x16x32_bf16 v[44:47], v[222:225], v[184:187], v[138:141]
	v_mfma_f32_16x16x32_bf16 v[16:19], v[230:233], v[184:187], v[16:19]
	v_mfma_f32_16x16x32_bf16 v[12:15], v[222:225], v[188:191], v[12:15]
	v_mfma_f32_16x16x32_bf16 v[134:137], v[230:233], v[188:191], v[142:145]
	v_mfma_f32_16x16x32_bf16 v[138:141], v[222:225], v[196:199], v[172:175]
	v_mfma_f32_16x16x32_bf16 v[0:3], v[230:233], v[196:199], v[0:3]
	v_mfma_f32_16x16x32_bf16 v[60:63], v[226:229], v[180:183], v[28:31]
	v_mfma_f32_16x16x32_bf16 v[48:51], v[234:237], v[180:183], v[32:35]
	v_mfma_f32_16x16x32_bf16 v[44:47], v[226:229], v[154:157], v[44:47]
	v_mfma_f32_16x16x32_bf16 v[32:35], v[234:237], v[154:157], v[16:19]
	v_mfma_f32_16x16x32_bf16 v[28:31], v[226:229], v[192:195], v[12:15]
	v_mfma_f32_16x16x32_bf16 v[16:19], v[234:237], v[192:195], v[134:137]
	v_mfma_f32_16x16x32_bf16 v[12:15], v[226:229], v[200:203], v[138:141]
	v_mfma_f32_16x16x32_bf16 v[0:3], v[234:237], v[200:203], v[0:3]
	s_setprio 0
	v_cmp_gt_u32_e32 vcc, s69, v130
	s_barrier
	s_and_saveexec_b64 s[50:51], vcc
	s_cbranch_execz .LBB0_841
	s_barrier

; #define STAGE(P, BASE, LD, br, kt) do { const char* _g = (const char*)((BASE) + (size_t)(br) * (LD) + (size_t)(kt) * 64); \
;     for (int _i = 0; _i < 2; ++_i) { int _b = tidx * 16 + _i * 8192; int _r, _c; stage_rc(_b, _r, _c); \
;       __builtin_amdgcn_global_load_lds((const unsigned*)(_g + (unsigned)((_r * (LD) + _c) * 2)), (unsigned*)((char*)(P) + _b), 16, 0, 0); } } while (0)
; #define LDA(dst, b, h) for (int m = 0; m < 4; ++m) for (int k = 0; k < 2; ++k) \
;     dst[m][k] = *reinterpret_cast<const bf16x8*>((char*)SA(b, h) + lds_byte(wr * 64 + m * 16 + fr, k * 32 + fq * 8))
; #define LDB(dst, b, h) for (int n = 0; n < 2; ++n) for (int k = 0; k < 2; ++k) \
;     dst[n][k] = *reinterpret_cast<const bf16x8*>((char*)SB(b, h) + lds_byte(wc * 32 + n * 16 + fr, k * 32 + fq * 8))
; #define MMA(ai, bj, At_, Bt_) do { __builtin_amdgcn_s_setprio(1); \
;     for (int k = 0; k < 2; ++k) for (int m = 0; m < 4; ++m) for (int n = 0; n < 2; ++n) \
;       acc[ai][bj][m][n] = __builtin_amdgcn_mfma_f32_16x16x32_bf16(At_[m][k], Bt_[n][k], acc[ai][bj][m][n], 0, 0, 0); \
;     __builtin_amdgcn_s_setprio(0); } while (0)
; #define WAIT_L(n) asm volatile("s_waitcnt lgkmcnt(" #n ")" ::: "memory")
; #define BAR __builtin_amdgcn_s_barrier()
; #define SCHED __builtin_amdgcn_sched_barrier(0)
; template <int EPI, int lda, int ldb, int N, int K>
; __device__ __forceinline__ void gemm_phase(const u16* __restrict__ A, const u16* __restrict__ Bt, const GemmEpi ep, int wv) {
;     ...
;       LDB(B0, 0, 0); SCHED; LDA(At, 0, 0); STAGE(SA(1, 1), Ab, lda, brow + HALF, t + 1);
;       WAIT_L(8); BAR; WAIT_L(0); MMA(0, 0, At, B0); BAR; SCHED;
;       LDB(B1, 0, 1); STAGE(SB(0, 0), Bt, ldb, bcol, t + 2);
;       BAR; WAIT_L(0); MMA(0, 1, At, B1); BAR;
;       LDA(At, 0, 1); STAGE(SA(0, 0), Ab, lda, brow, t + 2);
;       BAR; WAIT_L(0); MMA(1, 0, At, B0); BAR; SCHED;
.LBB0_1147:
	ds_read_b128 v[172:175], v161
	ds_read_b128 v[176:179], v161 offset:1024
	ds_read_b128 v[180:183], v161 offset:2048
	ds_read_b128 v[184:187], v161 offset:3072
	v_add_u32_e32 v169, 0xc000, v148
	v_lshl_add_u64 v[236:237], v[138:139], 0, s[60:61]
	v_readfirstlane_b32 s63, v169
	v_add_u32_e32 v170, 0xe000, v148
	v_lshl_add_u64 v[162:163], v[236:237], 0, s[22:23]
	s_mov_b32 m0, s63
	v_lshl_add_u64 v[238:239], v[140:141], 0, s[60:61]
	v_readfirstlane_b32 s63, v170
	ds_read_b128 v[164:167], v152
	ds_read_b128 v[188:191], v152 offset:1024
	ds_read_b128 v[192:195], v151
	ds_read_b128 v[196:199], v151 offset:1024
	ds_read_b128 v[200:203], v150
	ds_read_b128 v[204:207], v150 offset:1024
	ds_read_b128 v[208:211], v149
	ds_read_b128 v[212:215], v149 offset:1024
	global_load_lds_dwordx4 v[162:163], off
	v_lshl_add_u64 v[162:163], v[238:239], 0, s[22:23]
	s_mov_b32 m0, s63
	s_nop 0
	global_load_lds_dwordx4 v[162:163], off
	s_waitcnt lgkmcnt(8)
	s_barrier
	s_waitcnt lgkmcnt(0)
	s_setprio 0
	s_waitcnt lgkmcnt(0)
	v_mfma_f32_16x16x32_bf16 v[124:127], v[164:167], v[172:175], v[124:127]
	v_mfma_f32_16x16x32_bf16 v[120:123], v[164:167], v[180:183], v[120:123]
	v_mfma_f32_16x16x32_bf16 v[116:119], v[192:195], v[172:175], v[116:119]
	v_mfma_f32_16x16x32_bf16 v[112:115], v[192:195], v[180:183], v[112:115]
	v_mfma_f32_16x16x32_bf16 v[108:111], v[200:203], v[172:175], v[108:111]
	v_mfma_f32_16x16x32_bf16 v[104:107], v[200:203], v[180:183], v[104:107]
	v_mfma_f32_16x16x32_bf16 v[100:103], v[208:211], v[172:175], v[100:103]
	v_mfma_f32_16x16x32_bf16 v[96:99], v[208:211], v[180:183], v[96:99]
	v_mfma_f32_16x16x32_bf16 v[124:127], v[188:191], v[176:179], v[124:127]
	v_mfma_f32_16x16x32_bf16 v[120:123], v[188:191], v[184:187], v[120:123]
	v_mfma_f32_16x16x32_bf16 v[116:119], v[196:199], v[176:179], v[116:119]
	v_mfma_f32_16x16x32_bf16 v[112:115], v[196:199], v[184:187], v[112:115]
	v_mfma_f32_16x16x32_bf16 v[108:111], v[204:207], v[176:179], v[108:111]
	v_mfma_f32_16x16x32_bf16 v[104:107], v[204:207], v[184:187], v[104:107]
	v_mfma_f32_16x16x32_bf16 v[100:103], v[212:215], v[176:179], v[100:103]
	v_mfma_f32_16x16x32_bf16 v[96:99], v[212:215], v[184:187], v[96:99]
	s_setprio 0
	s_barrier
	v_add_u32_e32 v162, s75, v154
	v_lshl_add_u64 v[240:241], v[134:135], 0, s[60:61]
	v_readfirstlane_b32 s63, v162
	v_add_u32_e32 v163, 0x2000, v162
	v_lshl_add_u64 v[232:233], v[240:241], 0, s[24:25]
	s_mov_b32 m0, s63
	v_lshl_add_u64 v[242:243], v[136:137], 0, s[60:61]
	v_readfirstlane_b32 s63, v163
	ds_read_b128 v[216:219], v160
	ds_read_b128 v[220:223], v160 offset:1024
	ds_read_b128 v[224:227], v160 offset:2048
	ds_read_b128 v[228:231], v160 offset:3072
	global_load_lds_dwordx4 v[232:233], off
	v_lshl_add_u64 v[232:233], v[242:243], 0, s[24:25]
	s_mov_b32 m0, s63
	s_nop 0
	global_load_lds_dwordx4 v[232:233], off
	s_barrier
	s_waitcnt lgkmcnt(0)
	s_setprio 0
	s_waitcnt lgkmcnt(0)
	v_mfma_f32_16x16x32_bf16 v[92:95], v[164:167], v[216:219], v[92:95]
	v_mfma_f32_16x16x32_bf16 v[88:91], v[164:167], v[224:227], v[88:91]
	v_mfma_f32_16x16x32_bf16 v[84:87], v[192:195], v[216:219], v[84:87]
	v_mfma_f32_16x16x32_bf16 v[80:83], v[192:195], v[224:227], v[80:83]
	v_mfma_f32_16x16x32_bf16 v[76:79], v[200:203], v[216:219], v[76:79]
	v_mfma_f32_16x16x32_bf16 v[72:75], v[200:203], v[224:227], v[72:75]
	v_mfma_f32_16x16x32_bf16 v[68:71], v[208:211], v[216:219], v[68:71]
	v_mfma_f32_16x16x32_bf16 v[64:67], v[208:211], v[224:227], v[64:67]
	v_mfma_f32_16x16x32_bf16 v[92:95], v[188:191], v[220:223], v[92:95]
	v_mfma_f32_16x16x32_bf16 v[88:91], v[188:191], v[228:231], v[88:91]
	v_mfma_f32_16x16x32_bf16 v[84:87], v[196:199], v[220:223], v[84:87]
	v_mfma_f32_16x16x32_bf16 v[80:83], v[196:199], v[228:231], v[80:83]
	v_mfma_f32_16x16x32_bf16 v[76:79], v[204:207], v[220:223], v[76:79]
	v_mfma_f32_16x16x32_bf16 v[72:75], v[204:207], v[228:231], v[72:75]
	v_mfma_f32_16x16x32_bf16 v[68:71], v[212:215], v[220:223], v[68:71]
	v_mfma_f32_16x16x32_bf16 v[64:67], v[212:215], v[228:231], v[64:67]
	s_setprio 0
	v_readfirstlane_b32 s63, v148
	v_lshl_add_u64 v[164:165], v[236:237], 0, s[26:27]
	s_mov_b32 m0, s63
	s_barrier
	ds_read_b128 v[188:191], v152 offset:16384
	ds_read_b128 v[192:195], v152 offset:17408
	ds_read_b128 v[196:199], v151 offset:16384
	ds_read_b128 v[200:203], v151 offset:17408
	ds_read_b128 v[204:207], v150 offset:16384
	ds_read_b128 v[208:211], v150 offset:17408
	ds_read_b128 v[212:215], v149 offset:16384
	ds_read_b128 v[232:235], v149 offset:17408
	global_load_lds_dwordx4 v[164:165], off
	v_add_u32_e32 v164, 0x2000, v148
	v_lshl_add_u64 v[166:167], v[238:239], 0, s[26:27]
	v_readfirstlane_b32 s63, v164
	s_mov_b32 m0, s63
	s_nop 0
	global_load_lds_dwordx4 v[166:167], off
	s_barrier
	s_waitcnt lgkmcnt(0)
	s_setprio 0
	s_waitcnt lgkmcnt(0)
	v_mfma_f32_16x16x32_bf16 v[60:63], v[188:191], v[172:175], v[60:63]
	v_mfma_f32_16x16x32_bf16 v[56:59], v[188:191], v[180:183], v[56:59]
	v_mfma_f32_16x16x32_bf16 v[52:55], v[196:199], v[172:175], v[52:55]
	v_mfma_f32_16x16x32_bf16 v[48:51], v[196:199], v[180:183], v[48:51]
	v_mfma_f32_16x16x32_bf16 v[44:47], v[204:207], v[172:175], v[44:47]
	v_mfma_f32_16x16x32_bf16 v[40:43], v[204:207], v[180:183], v[40:43]
	v_mfma_f32_16x16x32_bf16 v[36:39], v[212:215], v[172:175], v[36:39]
	v_mfma_f32_16x16x32_bf16 v[32:35], v[212:215], v[180:183], v[32:35]
	v_mfma_f32_16x16x32_bf16 v[60:63], v[192:195], v[176:179], v[60:63]
	v_mfma_f32_16x16x32_bf16 v[56:59], v[192:195], v[184:187], v[56:59]
	v_mfma_f32_16x16x32_bf16 v[52:55], v[200:203], v[176:179], v[52:55]
	v_mfma_f32_16x16x32_bf16 v[48:51], v[200:203], v[184:187], v[48:51]
	v_mfma_f32_16x16x32_bf16 v[44:47], v[208:211], v[176:179], v[44:47]
	v_mfma_f32_16x16x32_bf16 v[40:43], v[208:211], v[184:187], v[40:43]
	v_mfma_f32_16x16x32_bf16 v[36:39], v[232:235], v[176:179], v[36:39]
	v_mfma_f32_16x16x32_bf16 v[32:35], v[232:235], v[184:187], v[32:35]
	s_setprio 0
	s_barrier
; #define STAGE(P, BASE, LD, br, kt) do { const char* _g = (const char*)((BASE) + (size_t)(br) * (LD) + (size_t)(kt) * 64); \
;     for (int _i = 0; _i < 2; ++_i) { int _b = tidx * 16 + _i * 8192; int _r, _c; stage_rc(_b, _r, _c); \
;       __builtin_amdgcn_global_load_lds((const unsigned*)(_g + (unsigned)((_r * (LD) + _c) * 2)), (unsigned*)((char*)(P) + _b), 16, 0, 0); } } while (0)
; #define LDA(dst, b, h) for (int m = 0; m < 4; ++m) for (int k = 0; k < 2; ++k) \
;     dst[m][k] = *reinterpret_cast<const bf16x8*>((char*)SA(b, h) + lds_byte(wr * 64 + m * 16 + fr, k * 32 + fq * 8))
; #define LDB(dst, b, h) for (int n = 0; n < 2; ++n) for (int k = 0; k < 2; ++k) \
;     dst[n][k] = *reinterpret_cast<const bf16x8*>((char*)SB(b, h) + lds_byte(wc * 32 + n * 16 + fr, k * 32 + fq * 8))
; #define MMA(ai, bj, At_, Bt_) do { __builtin_amdgcn_s_setprio(1); \
;     for (int k = 0; k < 2; ++k) for (int m = 0; m < 4; ++m) for (int n = 0; n < 2; ++n) \
;       acc[ai][bj][m][n] = __builtin_amdgcn_mfma_f32_16x16x32_bf16(At_[m][k], Bt_[n][k], acc[ai][bj][m][n], 0, 0, 0); \
;     __builtin_amdgcn_s_setprio(0); } while (0)
; #define WAIT_V(n) asm volatile("s_waitcnt vmcnt(" #n ")" ::: "memory")
; #define WAIT_L(n) asm volatile("s_waitcnt lgkmcnt(" #n ")" ::: "memory")
; #define BAR __builtin_amdgcn_s_barrier()
; #define SCHED __builtin_amdgcn_sched_barrier(0)
; template <int EPI, int lda, int ldb, int N, int K>
; __device__ __forceinline__ void gemm_phase(const u16* __restrict__ A, const u16* __restrict__ Bt, const GemmEpi ep, int wv) {
;     ...
;       STAGE(SB(0, 1), Bt, ldb, bcol + HALF, t + 2);
;       WAIT_V(6); BAR; MMA(1, 1, At, B1); BAR;
;       LDB(B0, 1, 0); SCHED; LDA(At, 1, 0); STAGE(SA(0, 1), Ab, lda, brow + HALF, t + 2);
;       WAIT_L(8); BAR; WAIT_L(0); MMA(0, 0, At, B0); BAR; SCHED;
;       LDB(B1, 1, 1); STAGE(SB(1, 0), Bt, ldb, bcol, t + 3);
;       BAR; WAIT_L(0); MMA(0, 1, At, B1); BAR;
;       LDA(At, 1, 1); STAGE(SA(1, 0), Ab, lda, brow, t + 3);
	v_add_u32_e32 v165, s76, v154
	v_lshl_add_u64 v[166:167], v[240:241], 0, s[40:41]
	v_readfirstlane_b32 s63, v165
	s_mov_b32 m0, s63
	v_lshl_add_u64 v[172:173], v[242:243], 0, s[40:41]
	global_load_lds_dwordx4 v[166:167], off
	v_add_u32_e32 v166, 0x2000, v165
	s_nop 0
	v_readfirstlane_b32 s63, v166
	s_mov_b32 m0, s63
	s_nop 0
	global_load_lds_dwordx4 v[172:173], off
	s_waitcnt vmcnt(6)
	s_barrier
	s_setprio 0
	v_mfma_f32_16x16x32_bf16 v[28:31], v[188:191], v[216:219], v[28:31]
	v_mfma_f32_16x16x32_bf16 v[24:27], v[188:191], v[224:227], v[24:27]
	v_mfma_f32_16x16x32_bf16 v[20:23], v[196:199], v[216:219], v[20:23]
	v_mfma_f32_16x16x32_bf16 v[16:19], v[196:199], v[224:227], v[16:19]
	v_mfma_f32_16x16x32_bf16 v[12:15], v[204:207], v[216:219], v[12:15]
	v_mfma_f32_16x16x32_bf16 v[8:11], v[204:207], v[224:227], v[8:11]
	v_mfma_f32_16x16x32_bf16 v[4:7], v[212:215], v[216:219], v[4:7]
	v_mfma_f32_16x16x32_bf16 v[0:3], v[212:215], v[224:227], v[0:3]
	v_mfma_f32_16x16x32_bf16 v[28:31], v[192:195], v[220:223], v[28:31]
	v_mfma_f32_16x16x32_bf16 v[24:27], v[192:195], v[228:231], v[24:27]
	v_mfma_f32_16x16x32_bf16 v[20:23], v[200:203], v[220:223], v[20:23]
	v_mfma_f32_16x16x32_bf16 v[16:19], v[200:203], v[228:231], v[16:19]
	v_mfma_f32_16x16x32_bf16 v[12:15], v[208:211], v[220:223], v[12:15]
	v_mfma_f32_16x16x32_bf16 v[8:11], v[208:211], v[228:231], v[8:11]
	v_mfma_f32_16x16x32_bf16 v[4:7], v[232:235], v[220:223], v[4:7]
	v_mfma_f32_16x16x32_bf16 v[0:3], v[232:235], v[228:231], v[0:3]
	s_setprio 0
	s_barrier
	ds_read_b128 v[172:175], v155
	ds_read_b128 v[176:179], v155 offset:1024
	ds_read_b128 v[180:183], v155 offset:2048
	ds_read_b128 v[184:187], v155 offset:3072
	v_add_u32_e32 v167, 0x4000, v148
	v_add_u32_e32 v168, 0x6000, v148
	v_readfirstlane_b32 s63, v167
	v_lshl_add_u64 v[220:221], v[236:237], 0, s[42:43]
	s_mov_b32 m0, s63
	v_readfirstlane_b32 s63, v168
	ds_read_b128 v[188:191], v152 offset:32768
	ds_read_b128 v[192:195], v152 offset:33792
	ds_read_b128 v[196:199], v151 offset:32768
	ds_read_b128 v[200:203], v151 offset:33792
	ds_read_b128 v[204:207], v150 offset:32768
	ds_read_b128 v[208:211], v150 offset:33792
	ds_read_b128 v[212:215], v149 offset:32768
	ds_read_b128 v[216:219], v149 offset:33792
	global_load_lds_dwordx4 v[220:221], off
	v_lshl_add_u64 v[220:221], v[238:239], 0, s[42:43]
	s_mov_b32 m0, s63
	s_nop 0
	global_load_lds_dwordx4 v[220:221], off
	s_waitcnt lgkmcnt(8)
	s_barrier
	s_waitcnt lgkmcnt(0)
	s_setprio 0
	s_waitcnt lgkmcnt(0)
	v_mfma_f32_16x16x32_bf16 v[124:127], v[188:191], v[172:175], v[124:127]
	v_mfma_f32_16x16x32_bf16 v[120:123], v[188:191], v[180:183], v[120:123]
	v_mfma_f32_16x16x32_bf16 v[116:119], v[196:199], v[172:175], v[116:119]
	v_mfma_f32_16x16x32_bf16 v[112:115], v[196:199], v[180:183], v[112:115]
	v_mfma_f32_16x16x32_bf16 v[108:111], v[204:207], v[172:175], v[108:111]
	v_mfma_f32_16x16x32_bf16 v[104:107], v[204:207], v[180:183], v[104:107]
	v_mfma_f32_16x16x32_bf16 v[100:103], v[212:215], v[172:175], v[100:103]
	v_mfma_f32_16x16x32_bf16 v[96:99], v[212:215], v[180:183], v[96:99]
	v_mfma_f32_16x16x32_bf16 v[124:127], v[192:195], v[176:179], v[124:127]
	v_mfma_f32_16x16x32_bf16 v[120:123], v[192:195], v[184:187], v[120:123]
	v_mfma_f32_16x16x32_bf16 v[116:119], v[200:203], v[176:179], v[116:119]
	v_mfma_f32_16x16x32_bf16 v[112:115], v[200:203], v[184:187], v[112:115]
	v_mfma_f32_16x16x32_bf16 v[108:111], v[208:211], v[176:179], v[108:111]
	v_mfma_f32_16x16x32_bf16 v[104:107], v[208:211], v[184:187], v[104:107]
	v_mfma_f32_16x16x32_bf16 v[100:103], v[216:219], v[176:179], v[100:103]
	v_mfma_f32_16x16x32_bf16 v[96:99], v[216:219], v[184:187], v[96:99]
	s_setprio 0
	s_barrier
	v_readfirstlane_b32 s63, v156
	v_add_u32_e32 v171, 0x2000, v156
	v_lshl_add_u64 v[244:245], v[240:241], 0, s[44:45]
	s_mov_b32 m0, s63
	v_readfirstlane_b32 s63, v171
	ds_read_b128 v[220:223], v153
	ds_read_b128 v[224:227], v153 offset:1024
	ds_read_b128 v[228:231], v153 offset:2048
	ds_read_b128 v[232:235], v153 offset:3072
	global_load_lds_dwordx4 v[244:245], off
	v_lshl_add_u64 v[244:245], v[242:243], 0, s[44:45]
	s_mov_b32 m0, s63
	s_nop 0
	global_load_lds_dwordx4 v[244:245], off
	s_barrier
	s_waitcnt lgkmcnt(0)
	s_setprio 0
	s_waitcnt lgkmcnt(0)
	v_mfma_f32_16x16x32_bf16 v[92:95], v[188:191], v[220:223], v[92:95]
	v_mfma_f32_16x16x32_bf16 v[88:91], v[188:191], v[228:231], v[88:91]
	v_mfma_f32_16x16x32_bf16 v[84:87], v[196:199], v[220:223], v[84:87]
	v_mfma_f32_16x16x32_bf16 v[80:83], v[196:199], v[228:231], v[80:83]
	v_mfma_f32_16x16x32_bf16 v[76:79], v[204:207], v[220:223], v[76:79]
	v_mfma_f32_16x16x32_bf16 v[72:75], v[204:207], v[228:231], v[72:75]
	v_mfma_f32_16x16x32_bf16 v[68:71], v[212:215], v[220:223], v[68:71]
	v_mfma_f32_16x16x32_bf16 v[64:67], v[212:215], v[228:231], v[64:67]
	v_mfma_f32_16x16x32_bf16 v[92:95], v[192:195], v[224:227], v[92:95]
	v_mfma_f32_16x16x32_bf16 v[88:91], v[192:195], v[232:235], v[88:91]
	v_mfma_f32_16x16x32_bf16 v[84:87], v[200:203], v[224:227], v[84:87]
	v_mfma_f32_16x16x32_bf16 v[80:83], v[200:203], v[232:235], v[80:83]
	v_mfma_f32_16x16x32_bf16 v[76:79], v[208:211], v[224:227], v[76:79]
	v_mfma_f32_16x16x32_bf16 v[72:75], v[208:211], v[232:235], v[72:75]
	v_mfma_f32_16x16x32_bf16 v[68:71], v[216:219], v[224:227], v[68:71]
	v_mfma_f32_16x16x32_bf16 v[64:67], v[216:219], v[232:235], v[64:67]
	s_setprio 0
	v_readfirstlane_b32 s63, v157
	v_lshl_add_u64 v[236:237], v[236:237], 0, s[46:47]
	s_mov_b32 m0, s63
	v_readfirstlane_b32 s63, v158
	s_barrier
; #define STAGE(P, BASE, LD, br, kt) do { const char* _g = (const char*)((BASE) + (size_t)(br) * (LD) + (size_t)(kt) * 64); \
;     for (int _i = 0; _i < 2; ++_i) { int _b = tidx * 16 + _i * 8192; int _r, _c; stage_rc(_b, _r, _c); \
;       __builtin_amdgcn_global_load_lds((const unsigned*)(_g + (unsigned)((_r * (LD) + _c) * 2)), (unsigned*)((char*)(P) + _b), 16, 0, 0); } } while (0)
; #define LDA(dst, b, h) for (int m = 0; m < 4; ++m) for (int k = 0; k < 2; ++k) \
;     dst[m][k] = *reinterpret_cast<const bf16x8*>((char*)SA(b, h) + lds_byte(wr * 64 + m * 16 + fr, k * 32 + fq * 8))
; #define LDB(dst, b, h) for (int n = 0; n < 2; ++n) for (int k = 0; k < 2; ++k) \
;     dst[n][k] = *reinterpret_cast<const bf16x8*>((char*)SB(b, h) + lds_byte(wc * 32 + n * 16 + fr, k * 32 + fq * 8))
; #define MMA(ai, bj, At_, Bt_) do { __builtin_amdgcn_s_setprio(1); \
;     for (int k = 0; k < 2; ++k) for (int m = 0; m < 4; ++m) for (int n = 0; n < 2; ++n) \
;       acc[ai][bj][m][n] = __builtin_amdgcn_mfma_f32_16x16x32_bf16(At_[m][k], Bt_[n][k], acc[ai][bj][m][n], 0, 0, 0); \
;     __builtin_amdgcn_s_setprio(0); } while (0)
; #define WAIT_V(n) asm volatile("s_waitcnt vmcnt(" #n ")" ::: "memory")
; #define WAIT_L(n) asm volatile("s_waitcnt lgkmcnt(" #n ")" ::: "memory")
; #define BAR __builtin_amdgcn_s_barrier()
; #define SCHED __builtin_amdgcn_sched_barrier(0)
; template <int EPI, int lda, int ldb, int N, int K>
; __device__ __forceinline__ void gemm_phase(const u16* __restrict__ A, const u16* __restrict__ Bt, const GemmEpi ep, int wv) {
;     ...
;       LDA(At, 1, 1); STAGE(SA(1, 0), Ab, lda, brow, t + 3);
;       BAR; WAIT_L(0); MMA(1, 0, At, B0); BAR; SCHED;
;       STAGE(SB(1, 1), Bt, ldb, bcol + HALF, t + 3);
;       WAIT_V(6); BAR; MMA(1, 1, At, B1); BAR;
;     }
;     { LDB(B0, 0, 0); LDA(At, 0, 0); STAGE(SA(1, 1), Ab, lda, brow + HALF, nt - 1);
;       BAR; WAIT_L(0); MMA(0, 0, At, B0); BAR;
;       LDB(B1, 0, 1); BAR; WAIT_L(0); MMA(0, 1, At, B1); BAR;
	ds_read_b128 v[188:191], v152 offset:49152
	ds_read_b128 v[192:195], v152 offset:50176
	ds_read_b128 v[196:199], v151 offset:49152
	ds_read_b128 v[200:203], v151 offset:50176
	ds_read_b128 v[204:207], v150 offset:49152
	ds_read_b128 v[208:211], v150 offset:50176
	ds_read_b128 v[212:215], v149 offset:49152
	ds_read_b128 v[216:219], v149 offset:50176
	global_load_lds_dwordx4 v[236:237], off
	v_lshl_add_u64 v[236:237], v[238:239], 0, s[46:47]
	s_mov_b32 m0, s63
	s_nop 0
	global_load_lds_dwordx4 v[236:237], off
	s_barrier
	s_waitcnt lgkmcnt(0)
	s_setprio 0
	s_waitcnt lgkmcnt(0)
	v_mfma_f32_16x16x32_bf16 v[60:63], v[188:191], v[172:175], v[60:63]
	v_mfma_f32_16x16x32_bf16 v[56:59], v[188:191], v[180:183], v[56:59]
	v_mfma_f32_16x16x32_bf16 v[52:55], v[196:199], v[172:175], v[52:55]
	v_mfma_f32_16x16x32_bf16 v[48:51], v[196:199], v[180:183], v[48:51]
	v_mfma_f32_16x16x32_bf16 v[44:47], v[204:207], v[172:175], v[44:47]
	v_mfma_f32_16x16x32_bf16 v[40:43], v[204:207], v[180:183], v[40:43]
	v_mfma_f32_16x16x32_bf16 v[36:39], v[212:215], v[172:175], v[36:39]
	v_mfma_f32_16x16x32_bf16 v[32:35], v[212:215], v[180:183], v[32:35]
	v_mfma_f32_16x16x32_bf16 v[60:63], v[192:195], v[176:179], v[60:63]
	v_mfma_f32_16x16x32_bf16 v[56:59], v[192:195], v[184:187], v[56:59]
	v_mfma_f32_16x16x32_bf16 v[52:55], v[200:203], v[176:179], v[52:55]
	v_mfma_f32_16x16x32_bf16 v[48:51], v[200:203], v[184:187], v[48:51]
	v_mfma_f32_16x16x32_bf16 v[44:47], v[208:211], v[176:179], v[44:47]
	v_mfma_f32_16x16x32_bf16 v[40:43], v[208:211], v[184:187], v[40:43]
	v_mfma_f32_16x16x32_bf16 v[36:39], v[216:219], v[176:179], v[36:39]
	v_mfma_f32_16x16x32_bf16 v[32:35], v[216:219], v[184:187], v[32:35]
	s_setprio 0
	s_barrier
	v_readfirstlane_b32 s63, v159
	v_add_u32_e32 v171, 0x2000, v159
	v_lshl_add_u64 v[172:173], v[240:241], 0, s[48:49]
	s_mov_b32 m0, s63
	v_readfirstlane_b32 s63, v171
	global_load_lds_dwordx4 v[172:173], off
	v_lshl_add_u64 v[172:173], v[242:243], 0, s[48:49]
	s_mov_b32 m0, s63
	s_nop 0
	global_load_lds_dwordx4 v[172:173], off
	s_waitcnt vmcnt(6)
	s_barrier
	s_setprio 0
	v_mfma_f32_16x16x32_bf16 v[28:31], v[188:191], v[220:223], v[28:31]
	v_mfma_f32_16x16x32_bf16 v[24:27], v[188:191], v[228:231], v[24:27]
	v_mfma_f32_16x16x32_bf16 v[20:23], v[196:199], v[220:223], v[20:23]
	v_mfma_f32_16x16x32_bf16 v[16:19], v[196:199], v[228:231], v[16:19]
	v_mfma_f32_16x16x32_bf16 v[12:15], v[204:207], v[220:223], v[12:15]
	v_mfma_f32_16x16x32_bf16 v[8:11], v[204:207], v[228:231], v[8:11]
	v_mfma_f32_16x16x32_bf16 v[4:7], v[212:215], v[220:223], v[4:7]
	v_mfma_f32_16x16x32_bf16 v[0:3], v[212:215], v[228:231], v[0:3]
	v_mfma_f32_16x16x32_bf16 v[28:31], v[192:195], v[224:227], v[28:31]
	v_mfma_f32_16x16x32_bf16 v[24:27], v[192:195], v[232:235], v[24:27]
	v_mfma_f32_16x16x32_bf16 v[20:23], v[200:203], v[224:227], v[20:23]
	v_mfma_f32_16x16x32_bf16 v[16:19], v[200:203], v[232:235], v[16:19]
	v_mfma_f32_16x16x32_bf16 v[12:15], v[208:211], v[224:227], v[12:15]
	v_mfma_f32_16x16x32_bf16 v[8:11], v[208:211], v[232:235], v[8:11]
	v_mfma_f32_16x16x32_bf16 v[4:7], v[216:219], v[224:227], v[4:7]
	v_mfma_f32_16x16x32_bf16 v[0:3], v[216:219], v[232:235], v[0:3]
	s_setprio 0
	s_add_i32 s62, s62, 2
	s_add_u32 s60, s60, 0x100
	s_addc_u32 s61, s61, 0
	s_cmp_gt_u32 s62, 27
	s_barrier
	s_cbranch_scc0 .LBB0_1147
	s_add_i32 s60, s58, 0x80
	s_mul_hi_i32 s61, s60, 0x1080
	s_mulk_i32 s60, 0x1080
	s_add_u32 s60, s69, s60
	s_addc_u32 s61, s70, s61
	v_lshl_add_u64 v[208:209], s[60:61], 0, v[128:129]
	v_readfirstlane_b32 s62, v169
	v_lshl_add_u64 v[208:209], v[208:209], 0, s[50:51]
	s_mov_b32 m0, s62
	ds_read_b128 v[134:137], v161
	ds_read_b128 v[138:141], v161 offset:1024
	ds_read_b128 v[156:159], v161 offset:2048
	ds_read_b128 v[172:175], v161 offset:3072
	ds_read_b128 v[176:179], v152
	ds_read_b128 v[180:183], v152 offset:1024
	ds_read_b128 v[184:187], v151
	ds_read_b128 v[188:191], v151 offset:1024
	ds_read_b128 v[192:195], v150
	ds_read_b128 v[196:199], v150 offset:1024
	ds_read_b128 v[200:203], v149
	ds_read_b128 v[204:207], v149 offset:1024
	global_load_lds_dwordx4 v[208:209], off
	v_lshl_add_u64 v[208:209], s[60:61], 0, v[132:133]
	v_readfirstlane_b32 s60, v170
	v_lshl_add_u64 v[208:209], v[208:209], 0, s[50:51]
	s_mov_b32 m0, s60
	s_nop 0
	global_load_lds_dwordx4 v[208:209], off
	s_barrier
	s_waitcnt lgkmcnt(0)
	s_setprio 0
	s_waitcnt lgkmcnt(0)
	v_mfma_f32_16x16x32_bf16 v[124:127], v[176:179], v[134:137], v[124:127]
	v_mfma_f32_16x16x32_bf16 v[120:123], v[176:179], v[156:159], v[120:123]
	v_mfma_f32_16x16x32_bf16 v[116:119], v[184:187], v[134:137], v[116:119]
	v_mfma_f32_16x16x32_bf16 v[112:115], v[184:187], v[156:159], v[112:115]
	v_mfma_f32_16x16x32_bf16 v[108:111], v[192:195], v[134:137], v[108:111]
	v_mfma_f32_16x16x32_bf16 v[104:107], v[192:195], v[156:159], v[104:107]
	v_mfma_f32_16x16x32_bf16 v[100:103], v[200:203], v[134:137], v[100:103]
	v_mfma_f32_16x16x32_bf16 v[96:99], v[200:203], v[156:159], v[96:99]
	v_mfma_f32_16x16x32_bf16 v[124:127], v[180:183], v[138:141], v[124:127]
	v_mfma_f32_16x16x32_bf16 v[120:123], v[180:183], v[172:175], v[120:123]
	v_mfma_f32_16x16x32_bf16 v[116:119], v[188:191], v[138:141], v[116:119]
	v_mfma_f32_16x16x32_bf16 v[112:115], v[188:191], v[172:175], v[112:115]
	v_mfma_f32_16x16x32_bf16 v[108:111], v[196:199], v[138:141], v[108:111]
	v_mfma_f32_16x16x32_bf16 v[104:107], v[196:199], v[172:175], v[104:107]
	v_mfma_f32_16x16x32_bf16 v[100:103], v[204:207], v[138:141], v[100:103]
	v_mfma_f32_16x16x32_bf16 v[96:99], v[204:207], v[172:175], v[96:99]
	s_setprio 0
	s_barrier
	ds_read_b128 v[208:211], v160
	ds_read_b128 v[212:215], v160 offset:1024
	ds_read_b128 v[216:219], v160 offset:2048
	ds_read_b128 v[220:223], v160 offset:3072
	s_barrier
; #define LDA(dst, b, h) for (int m = 0; m < 4; ++m) for (int k = 0; k < 2; ++k) \
;     dst[m][k] = *reinterpret_cast<const bf16x8*>((char*)SA(b, h) + lds_byte(wr * 64 + m * 16 + fr, k * 32 + fq * 8))
; #define LDB(dst, b, h) for (int n = 0; n < 2; ++n) for (int k = 0; k < 2; ++k) \
;     dst[n][k] = *reinterpret_cast<const bf16x8*>((char*)SB(b, h) + lds_byte(wc * 32 + n * 16 + fr, k * 32 + fq * 8))
; #define MMA(ai, bj, At_, Bt_) do { __builtin_amdgcn_s_setprio(1); \
;     for (int k = 0; k < 2; ++k) for (int m = 0; m < 4; ++m) for (int n = 0; n < 2; ++n) \
;       acc[ai][bj][m][n] = __builtin_amdgcn_mfma_f32_16x16x32_bf16(At_[m][k], Bt_[n][k], acc[ai][bj][m][n], 0, 0, 0); \
;     __builtin_amdgcn_s_setprio(0); } while (0)
; #define WAIT_V(n) asm volatile("s_waitcnt vmcnt(" #n ")" ::: "memory")
; #define WAIT_L(n) asm volatile("s_waitcnt lgkmcnt(" #n ")" ::: "memory")
; #define BAR __builtin_amdgcn_s_barrier()
; template <int EPI, int lda, int ldb, int N, int K>
; __device__ __forceinline__ void gemm_phase(const u16* __restrict__ A, const u16* __restrict__ Bt, const GemmEpi ep, int wv) {
;     ...
;       LDB(B1, 0, 1); BAR; WAIT_L(0); MMA(0, 1, At, B1); BAR;
;       LDA(At, 0, 1); WAIT_V(4); BAR; WAIT_L(0); MMA(1, 0, At, B0); MMA(1, 1, At, B1); BAR; }
;     { LDB(B0, 1, 0); LDA(At, 1, 0); WAIT_V(2); BAR; WAIT_L(0); MMA(0, 0, At, B0); BAR;
	s_waitcnt lgkmcnt(0)
	s_setprio 0
	s_waitcnt lgkmcnt(0)
	v_mfma_f32_16x16x32_bf16 v[92:95], v[176:179], v[208:211], v[92:95]
	v_mfma_f32_16x16x32_bf16 v[88:91], v[176:179], v[216:219], v[88:91]
	v_mfma_f32_16x16x32_bf16 v[76:79], v[192:195], v[208:211], v[76:79]
	v_mfma_f32_16x16x32_bf16 v[72:75], v[192:195], v[216:219], v[72:75]
	v_mfma_f32_16x16x32_bf16 v[84:87], v[184:187], v[208:211], v[84:87]
	v_mfma_f32_16x16x32_bf16 v[80:83], v[184:187], v[216:219], v[80:83]
	v_mfma_f32_16x16x32_bf16 v[68:71], v[200:203], v[208:211], v[68:71]
	v_mfma_f32_16x16x32_bf16 v[64:67], v[200:203], v[216:219], v[64:67]
	v_mfma_f32_16x16x32_bf16 v[92:95], v[180:183], v[212:215], v[92:95]
	v_mfma_f32_16x16x32_bf16 v[88:91], v[180:183], v[220:223], v[88:91]
	v_mfma_f32_16x16x32_bf16 v[76:79], v[196:199], v[212:215], v[76:79]
	v_mfma_f32_16x16x32_bf16 v[72:75], v[196:199], v[220:223], v[72:75]
	v_mfma_f32_16x16x32_bf16 v[176:179], v[188:191], v[212:215], v[84:87]
	v_mfma_f32_16x16x32_bf16 v[180:183], v[188:191], v[220:223], v[80:83]
	v_mfma_f32_16x16x32_bf16 v[184:187], v[204:207], v[212:215], v[68:71]
	v_mfma_f32_16x16x32_bf16 v[188:191], v[204:207], v[220:223], v[64:67]
	s_setprio 0
	s_barrier
	s_nop 0
	ds_read_b128 v[64:67], v152 offset:16384
	ds_read_b128 v[68:71], v152 offset:17408
	ds_read_b128 v[80:83], v151 offset:16384
	ds_read_b128 v[84:87], v151 offset:17408
	ds_read_b128 v[192:195], v150 offset:16384
	ds_read_b128 v[196:199], v150 offset:17408
	ds_read_b128 v[200:203], v149 offset:16384
	ds_read_b128 v[204:207], v149 offset:17408
	s_waitcnt vmcnt(4)
	s_barrier
	s_waitcnt lgkmcnt(0)
	s_setprio 0
	s_waitcnt lgkmcnt(0)
	v_mfma_f32_16x16x32_bf16 v[60:63], v[64:67], v[134:137], v[60:63]
	v_mfma_f32_16x16x32_bf16 v[56:59], v[64:67], v[156:159], v[56:59]
	v_mfma_f32_16x16x32_bf16 v[52:55], v[80:83], v[134:137], v[52:55]
	v_mfma_f32_16x16x32_bf16 v[48:51], v[80:83], v[156:159], v[48:51]
	v_mfma_f32_16x16x32_bf16 v[44:47], v[192:195], v[134:137], v[44:47]
	v_mfma_f32_16x16x32_bf16 v[40:43], v[192:195], v[156:159], v[40:43]
	v_mfma_f32_16x16x32_bf16 v[36:39], v[200:203], v[134:137], v[36:39]
	v_mfma_f32_16x16x32_bf16 v[32:35], v[200:203], v[156:159], v[32:35]
	v_mfma_f32_16x16x32_bf16 v[60:63], v[68:71], v[138:141], v[60:63]
	v_mfma_f32_16x16x32_bf16 v[56:59], v[68:71], v[172:175], v[56:59]
	v_mfma_f32_16x16x32_bf16 v[52:55], v[84:87], v[138:141], v[52:55]
	v_mfma_f32_16x16x32_bf16 v[48:51], v[84:87], v[172:175], v[48:51]
	v_mfma_f32_16x16x32_bf16 v[44:47], v[196:199], v[138:141], v[44:47]
	v_mfma_f32_16x16x32_bf16 v[40:43], v[196:199], v[172:175], v[40:43]
	v_mfma_f32_16x16x32_bf16 v[36:39], v[204:207], v[138:141], v[36:39]
	v_mfma_f32_16x16x32_bf16 v[32:35], v[204:207], v[172:175], v[32:35]
	s_setprio 0
	s_setprio 0
	v_mfma_f32_16x16x32_bf16 v[28:31], v[64:67], v[208:211], v[28:31]
	v_mfma_f32_16x16x32_bf16 v[24:27], v[64:67], v[216:219], v[24:27]
	v_mfma_f32_16x16x32_bf16 v[12:15], v[192:195], v[208:211], v[12:15]
	v_mfma_f32_16x16x32_bf16 v[8:11], v[192:195], v[216:219], v[8:11]
	v_mfma_f32_16x16x32_bf16 v[20:23], v[80:83], v[208:211], v[20:23]
	v_mfma_f32_16x16x32_bf16 v[16:19], v[80:83], v[216:219], v[16:19]
	v_mfma_f32_16x16x32_bf16 v[4:7], v[200:203], v[208:211], v[4:7]
	v_mfma_f32_16x16x32_bf16 v[0:3], v[200:203], v[216:219], v[0:3]
	v_mfma_f32_16x16x32_bf16 v[28:31], v[68:71], v[212:215], v[28:31]
	v_mfma_f32_16x16x32_bf16 v[24:27], v[68:71], v[220:223], v[24:27]
	v_mfma_f32_16x16x32_bf16 v[12:15], v[196:199], v[212:215], v[12:15]
	v_mfma_f32_16x16x32_bf16 v[8:11], v[196:199], v[220:223], v[8:11]
	v_mfma_f32_16x16x32_bf16 v[134:137], v[84:87], v[212:215], v[20:23]
	v_mfma_f32_16x16x32_bf16 v[138:141], v[84:87], v[220:223], v[16:19]
	v_mfma_f32_16x16x32_bf16 v[156:159], v[204:207], v[212:215], v[4:7]
	v_mfma_f32_16x16x32_bf16 v[170:173], v[204:207], v[220:223], v[0:3]
	s_setprio 0
	s_barrier
	s_nop 0
	ds_read_b128 v[0:3], v155
	ds_read_b128 v[4:7], v155 offset:1024
	ds_read_b128 v[16:19], v155 offset:2048
	ds_read_b128 v[192:195], v155 offset:3072
	ds_read_b128 v[20:23], v152 offset:32768
	ds_read_b128 v[196:199], v152 offset:33792
	ds_read_b128 v[200:203], v151 offset:32768
	ds_read_b128 v[204:207], v151 offset:33792
	ds_read_b128 v[208:211], v150 offset:32768
	ds_read_b128 v[212:215], v150 offset:33792
	ds_read_b128 v[216:219], v149 offset:32768
	ds_read_b128 v[220:223], v149 offset:33792
	s_waitcnt vmcnt(2)
	s_barrier
; #define LDA(dst, b, h) for (int m = 0; m < 4; ++m) for (int k = 0; k < 2; ++k) \
;     dst[m][k] = *reinterpret_cast<const bf16x8*>((char*)SA(b, h) + lds_byte(wr * 64 + m * 16 + fr, k * 32 + fq * 8))
; #define LDB(dst, b, h) for (int n = 0; n < 2; ++n) for (int k = 0; k < 2; ++k) \
;     dst[n][k] = *reinterpret_cast<const bf16x8*>((char*)SB(b, h) + lds_byte(wc * 32 + n * 16 + fr, k * 32 + fq * 8))
; #define MMA(ai, bj, At_, Bt_) do { __builtin_amdgcn_s_setprio(1); \
;     for (int k = 0; k < 2; ++k) for (int m = 0; m < 4; ++m) for (int n = 0; n < 2; ++n) \
;       acc[ai][bj][m][n] = __builtin_amdgcn_mfma_f32_16x16x32_bf16(At_[m][k], Bt_[n][k], acc[ai][bj][m][n], 0, 0, 0); \
;     __builtin_amdgcn_s_setprio(0); } while (0)
; #define WAIT_V(n) asm volatile("s_waitcnt vmcnt(" #n ")" ::: "memory")
; #define WAIT_L(n) asm volatile("s_waitcnt lgkmcnt(" #n ")" ::: "memory")
; #define BAR __builtin_amdgcn_s_barrier()
; template <int EPI, int lda, int ldb, int N, int K>
; __device__ __forceinline__ void gemm_phase(const u16* __restrict__ A, const u16* __restrict__ Bt, const GemmEpi ep, int wv) {
;     ...
;     { LDB(B0, 1, 0); LDA(At, 1, 0); WAIT_V(2); BAR; WAIT_L(0); MMA(0, 0, At, B0); BAR;
;       LDB(B1, 1, 1); WAIT_V(0); BAR; WAIT_L(0); MMA(0, 1, At, B1); BAR;
;       LDA(At, 1, 1); BAR; WAIT_L(0); MMA(1, 0, At, B0); MMA(1, 1, At, B1); BAR; }
;     if (wr == 0) BAR;
	s_waitcnt lgkmcnt(0)
	s_setprio 0
	s_waitcnt lgkmcnt(0)
	v_mfma_f32_16x16x32_bf16 v[64:67], v[20:23], v[0:3], v[124:127]
	v_mfma_f32_16x16x32_bf16 v[68:71], v[20:23], v[16:19], v[120:123]
	v_mfma_f32_16x16x32_bf16 v[80:83], v[200:203], v[0:3], v[116:119]
	v_mfma_f32_16x16x32_bf16 v[84:87], v[200:203], v[16:19], v[112:115]
	v_mfma_f32_16x16x32_bf16 v[108:111], v[208:211], v[0:3], v[108:111]
	v_mfma_f32_16x16x32_bf16 v[104:107], v[208:211], v[16:19], v[104:107]
	v_mfma_f32_16x16x32_bf16 v[120:123], v[216:219], v[0:3], v[100:103]
	v_mfma_f32_16x16x32_bf16 v[124:127], v[216:219], v[16:19], v[96:99]
	v_mfma_f32_16x16x32_bf16 v[116:119], v[196:199], v[4:7], v[64:67]
	v_mfma_f32_16x16x32_bf16 v[112:115], v[196:199], v[192:195], v[68:71]
	v_mfma_f32_16x16x32_bf16 v[100:103], v[204:207], v[4:7], v[80:83]
	v_mfma_f32_16x16x32_bf16 v[96:99], v[204:207], v[192:195], v[84:87]
	v_mfma_f32_16x16x32_bf16 v[84:87], v[212:215], v[4:7], v[108:111]
	v_mfma_f32_16x16x32_bf16 v[80:83], v[212:215], v[192:195], v[104:107]
	v_mfma_f32_16x16x32_bf16 v[68:71], v[220:223], v[4:7], v[120:123]
	v_mfma_f32_16x16x32_bf16 v[64:67], v[220:223], v[192:195], v[124:127]
	s_setprio 0
	s_barrier
	ds_read_b128 v[224:227], v153
	ds_read_b128 v[228:231], v153 offset:1024
	ds_read_b128 v[232:235], v153 offset:2048
	ds_read_b128 v[236:239], v153 offset:3072
	s_waitcnt vmcnt(0)
	s_barrier
	s_waitcnt lgkmcnt(0)
	s_setprio 0
	s_waitcnt lgkmcnt(0)
	v_mfma_f32_16x16x32_bf16 v[92:95], v[20:23], v[224:227], v[92:95]
	v_mfma_f32_16x16x32_bf16 v[20:23], v[20:23], v[232:235], v[88:91]
	v_mfma_f32_16x16x32_bf16 v[88:91], v[200:203], v[224:227], v[176:179]
	v_mfma_f32_16x16x32_bf16 v[104:107], v[200:203], v[232:235], v[180:183]
	v_mfma_f32_16x16x32_bf16 v[76:79], v[208:211], v[224:227], v[76:79]
	v_mfma_f32_16x16x32_bf16 v[72:75], v[208:211], v[232:235], v[72:75]
	v_mfma_f32_16x16x32_bf16 v[174:177], v[216:219], v[224:227], v[184:187]
	v_mfma_f32_16x16x32_bf16 v[178:181], v[216:219], v[232:235], v[188:191]
	v_mfma_f32_16x16x32_bf16 v[124:127], v[196:199], v[228:231], v[92:95]
	v_mfma_f32_16x16x32_bf16 v[120:123], v[196:199], v[236:239], v[20:23]
	v_mfma_f32_16x16x32_bf16 v[108:111], v[204:207], v[228:231], v[88:91]
	v_mfma_f32_16x16x32_bf16 v[104:107], v[204:207], v[236:239], v[104:107]
	v_mfma_f32_16x16x32_bf16 v[92:95], v[212:215], v[228:231], v[76:79]
	v_mfma_f32_16x16x32_bf16 v[88:91], v[212:215], v[236:239], v[72:75]
	v_mfma_f32_16x16x32_bf16 v[76:79], v[220:223], v[228:231], v[174:177]
	v_mfma_f32_16x16x32_bf16 v[72:75], v[220:223], v[236:239], v[178:181]
	s_setprio 0
	s_barrier
	ds_read_b128 v[174:177], v152 offset:49152
	ds_read_b128 v[152:155], v152 offset:50176
	ds_read_b128 v[178:181], v151 offset:49152
	ds_read_b128 v[182:185], v151 offset:50176
	ds_read_b128 v[186:189], v150 offset:49152
	ds_read_b128 v[196:199], v150 offset:50176
	ds_read_b128 v[200:203], v149 offset:49152
	ds_read_b128 v[204:207], v149 offset:50176
	s_barrier
	s_waitcnt lgkmcnt(0)
	s_setprio 0
	s_waitcnt lgkmcnt(0)
	v_mfma_f32_16x16x32_bf16 v[20:23], v[174:177], v[0:3], v[60:63]
	v_mfma_f32_16x16x32_bf16 v[56:59], v[174:177], v[16:19], v[56:59]
	v_mfma_f32_16x16x32_bf16 v[60:63], v[178:181], v[0:3], v[52:55]
	v_mfma_f32_16x16x32_bf16 v[208:211], v[178:181], v[16:19], v[48:51]
	v_mfma_f32_16x16x32_bf16 v[44:47], v[186:189], v[0:3], v[44:47]
	v_mfma_f32_16x16x32_bf16 v[40:43], v[186:189], v[16:19], v[40:43]
	v_mfma_f32_16x16x32_bf16 v[0:3], v[200:203], v[0:3], v[36:39]
	v_mfma_f32_16x16x32_bf16 v[212:215], v[200:203], v[16:19], v[32:35]
	v_mfma_f32_16x16x32_bf16 v[52:55], v[152:155], v[4:7], v[20:23]
	v_mfma_f32_16x16x32_bf16 v[48:51], v[152:155], v[192:195], v[56:59]
	v_mfma_f32_16x16x32_bf16 v[36:39], v[182:185], v[4:7], v[60:63]
	v_mfma_f32_16x16x32_bf16 v[32:35], v[182:185], v[192:195], v[208:211]
	v_mfma_f32_16x16x32_bf16 v[20:23], v[196:199], v[4:7], v[44:47]
	v_mfma_f32_16x16x32_bf16 v[16:19], v[196:199], v[192:195], v[40:43]
	v_mfma_f32_16x16x32_bf16 v[4:7], v[204:207], v[4:7], v[0:3]
	v_mfma_f32_16x16x32_bf16 v[0:3], v[204:207], v[192:195], v[212:215]
	s_setprio 0
	s_setprio 0
	v_mfma_f32_16x16x32_bf16 v[28:31], v[174:177], v[224:227], v[28:31]
	v_mfma_f32_16x16x32_bf16 v[24:27], v[174:177], v[232:235], v[24:27]
	v_mfma_f32_16x16x32_bf16 v[40:43], v[178:181], v[224:227], v[134:137]
	v_mfma_f32_16x16x32_bf16 v[134:137], v[178:181], v[232:235], v[138:141]
	v_mfma_f32_16x16x32_bf16 v[12:15], v[186:189], v[224:227], v[12:15]
	v_mfma_f32_16x16x32_bf16 v[8:11], v[186:189], v[232:235], v[8:11]
	v_mfma_f32_16x16x32_bf16 v[138:141], v[200:203], v[224:227], v[156:159]
	v_mfma_f32_16x16x32_bf16 v[156:159], v[200:203], v[232:235], v[170:173]
	v_mfma_f32_16x16x32_bf16 v[60:63], v[152:155], v[228:231], v[28:31]
	v_mfma_f32_16x16x32_bf16 v[56:59], v[152:155], v[236:239], v[24:27]
	v_mfma_f32_16x16x32_bf16 v[44:47], v[182:185], v[228:231], v[40:43]
	v_mfma_f32_16x16x32_bf16 v[40:43], v[182:185], v[236:239], v[134:137]
	v_mfma_f32_16x16x32_bf16 v[28:31], v[196:199], v[228:231], v[12:15]
	v_mfma_f32_16x16x32_bf16 v[24:27], v[196:199], v[236:239], v[8:11]
	v_mfma_f32_16x16x32_bf16 v[12:15], v[204:207], v[228:231], v[138:141]
	v_mfma_f32_16x16x32_bf16 v[8:11], v[204:207], v[236:239], v[156:159]
	s_setprio 0
	v_cmp_gt_u32_e32 vcc, s80, v130
	s_barrier
	s_and_saveexec_b64 s[60:61], vcc
	s_cbranch_execz .LBB0_1150
	s_barrier

; #define STAGE(P, BASE, LD, br, kt) do { const char* _g = (const char*)((BASE) + (size_t)(br) * (LD) + (size_t)(kt) * 64); \
;     for (int _i = 0; _i < 2; ++_i) { int _b = tidx * 16 + _i * 8192; int _r, _c; stage_rc(_b, _r, _c); \
;       __builtin_amdgcn_global_load_lds((const unsigned*)(_g + (unsigned)((_r * (LD) + _c) * 2)), (unsigned*)((char*)(P) + _b), 16, 0, 0); } } while (0)
; #define LDA(dst, b, h) for (int m = 0; m < 4; ++m) for (int k = 0; k < 2; ++k) \
;     dst[m][k] = *reinterpret_cast<const bf16x8*>((char*)SA(b, h) + lds_byte(wr * 64 + m * 16 + fr, k * 32 + fq * 8))
; #define LDB(dst, b, h) for (int n = 0; n < 2; ++n) for (int k = 0; k < 2; ++k) \
;     dst[n][k] = *reinterpret_cast<const bf16x8*>((char*)SB(b, h) + lds_byte(wc * 32 + n * 16 + fr, k * 32 + fq * 8))
; #define MMA(ai, bj, At_, Bt_) do { __builtin_amdgcn_s_setprio(1); \
;     for (int k = 0; k < 2; ++k) for (int m = 0; m < 4; ++m) for (int n = 0; n < 2; ++n) \
;       acc[ai][bj][m][n] = __builtin_amdgcn_mfma_f32_16x16x32_bf16(At_[m][k], Bt_[n][k], acc[ai][bj][m][n], 0, 0, 0); \
;     __builtin_amdgcn_s_setprio(0); } while (0)
; #define WAIT_V(n) asm volatile("s_waitcnt vmcnt(" #n ")" ::: "memory")
; #define WAIT_L(n) asm volatile("s_waitcnt lgkmcnt(" #n ")" ::: "memory")
; #define BAR __builtin_amdgcn_s_barrier()
; #define SCHED __builtin_amdgcn_sched_barrier(0)
; template <int EPI, int lda, int ldb, int N, int K>
; __device__ __forceinline__ void gemm_phase(const u16* __restrict__ A, const u16* __restrict__ Bt, const GemmEpi ep, int wv) {
;     ...
;     if (wr == 1) BAR;
;     WAIT_V(4); BAR;
;     STAGE(SB(1, 0), Bt, ldb, bcol, 1); STAGE(SA(1, 0), Ab, lda, brow, 1); STAGE(SB(1, 1), Bt, ldb, bcol + HALF, 1);
;     WAIT_V(6); BAR;
;     for (int t = 0; t < nt - 2; t += 2) {
;       LDB(B0, 0, 0); SCHED; LDA(At, 0, 0); STAGE(SA(1, 1), Ab, lda, brow + HALF, t + 1);
;       WAIT_L(8); BAR; WAIT_L(0); MMA(0, 0, At, B0); BAR; SCHED;
;       LDB(B1, 0, 1); STAGE(SB(0, 0), Bt, ldb, bcol, t + 2);
;       BAR; WAIT_L(0); MMA(0, 1, At, B1); BAR;
;       LDA(At, 0, 1); STAGE(SA(0, 0), Ab, lda, brow, t + 2);
.LBB0_1248:
	s_or_b64 exec, exec, s[54:55]
	v_mov_b32_e32 v1, v129
	v_add_u32_e32 v7, s60, v6
	v_lshl_add_u64 v[12:13], s[46:47], 0, v[128:129]
	v_lshl_add_u64 v[14:15], s[46:47], 0, v[0:1]
	v_lshl_add_u64 v[2:3], s[52:53], 0, v[128:129]
	v_lshl_add_u64 v[0:1], s[52:53], 0, v[0:1]
	v_readfirstlane_b32 s53, v7
	v_add_u32_e32 v7, 0x2000, v7
	v_mov_b32_e32 v5, v129
	v_mov_b32_e32 v17, v129
	v_lshl_add_u64 v[26:27], v[12:13], 0, s[40:41]
	s_mov_b32 m0, s53
	v_readfirstlane_b32 s52, v7
	v_add_u32_e32 v7, 0x8000, v23
	v_lshl_add_u64 v[8:9], s[50:51], 0, v[4:5]
	v_lshl_add_u64 v[10:11], s[50:51], 0, v[16:17]
	s_waitcnt vmcnt(4)
	s_barrier
	global_load_lds_dwordx4 v[26:27], off
	v_lshl_add_u64 v[26:27], v[14:15], 0, s[40:41]
	s_mov_b32 m0, s52
	v_readfirstlane_b32 s51, v7
	v_add_u32_e32 v7, 0xa000, v23
	global_load_lds_dwordx4 v[26:27], off
	v_lshl_add_u64 v[26:27], v[8:9], 0, s[40:41]
	s_mov_b32 m0, s51
	v_readfirstlane_b32 s50, v7
	v_add_u32_e32 v25, s61, v6
	global_load_lds_dwordx4 v[26:27], off
	v_lshl_add_u64 v[26:27], v[10:11], 0, s[40:41]
	s_mov_b32 m0, s50
	v_readfirstlane_b32 s13, v25
	v_add_u32_e32 v25, 0x2000, v25
	global_load_lds_dwordx4 v[26:27], off
	v_lshl_add_u64 v[26:27], v[2:3], 0, s[40:41]
	s_mov_b32 m0, s13
	v_readfirstlane_b32 s11, v25
	global_load_lds_dwordx4 v[26:27], off
	v_lshl_add_u64 v[6:7], v[0:1], 0, s[40:41]
	s_mov_b32 m0, s11
	v_and_b32_e32 v132, 15, v20
	global_load_lds_dwordx4 v[6:7], off
	v_bfe_u32 v128, v20, 4, 2
	v_lshlrev_b32_e32 v7, 2, v20
	v_bfe_u32 v131, v130, 6, 2
	v_lshlrev_b32_e32 v25, 4, v128
	v_lshlrev_b32_e32 v6, 6, v132
	v_and_b32_e32 v50, 32, v7
	v_lshlrev_b32_e32 v126, 12, v131
	v_bitop3_b32 v127, v25, v50, v6 bitop3:0x36
	v_add3_u32 v133, s58, v127, v126
	s_waitcnt vmcnt(6)
	s_barrier
	ds_read_b128 v[26:29], v133
	ds_read_b128 v[30:33], v133 offset:1024
	ds_read_b128 v[34:37], v133 offset:2048
	ds_read_b128 v[38:41], v133 offset:3072
	v_lshl_add_u64 v[6:7], s[48:49], 0, v[4:5]
	v_lshl_add_u64 v[4:5], s[48:49], 0, v[16:17]
	v_lshlrev_b32_e32 v17, 6, v20
	v_and_b32_e32 v17, 0x3c0, v17
	v_add_u32_e32 v20, 0xc000, v23
	v_lshlrev_b32_e32 v16, 13, v143
	v_bitop3_b32 v17, v17, v50, v25 bitop3:0x36
	v_readfirstlane_b32 s47, v20
	v_add_u32_e32 v20, 0xe000, v23
	v_add3_u32 v228, 0, v127, v16
	v_add3_u32 v229, 0, v17, v16
	v_lshl_add_u64 v[16:17], v[6:7], 0, s[40:41]
	s_mov_b32 m0, s47
	v_readfirstlane_b32 s46, v20
	ds_read_b128 v[42:45], v228
	ds_read_b128 v[46:49], v228 offset:1024
	ds_read_b128 v[50:53], v229 offset:2048
	ds_read_b128 v[54:57], v229 offset:3072
	ds_read_b128 v[58:61], v229 offset:4096
	ds_read_b128 v[62:65], v229 offset:5120
	ds_read_b128 v[66:69], v229 offset:6144
	ds_read_b128 v[70:73], v229 offset:7168
	global_load_lds_dwordx4 v[16:17], off
	v_lshl_add_u64 v[16:17], v[4:5], 0, s[40:41]
	s_mov_b32 m0, s46
	s_nop 0
	global_load_lds_dwordx4 v[16:17], off
	s_waitcnt lgkmcnt(8)
	s_barrier
	s_waitcnt lgkmcnt(0)
	s_setprio 0
	s_waitcnt lgkmcnt(0)
	v_mfma_f32_16x16x32_bf16 v[74:77], v[42:45], v[26:29], 0
	v_mfma_f32_16x16x32_bf16 v[78:81], v[42:45], v[34:37], 0
	v_mfma_f32_16x16x32_bf16 v[82:85], v[50:53], v[26:29], 0
	v_mfma_f32_16x16x32_bf16 v[86:89], v[50:53], v[34:37], 0
	v_mfma_f32_16x16x32_bf16 v[90:93], v[58:61], v[26:29], 0
	v_mfma_f32_16x16x32_bf16 v[94:97], v[58:61], v[34:37], 0
	v_mfma_f32_16x16x32_bf16 v[98:101], v[66:69], v[26:29], 0
	v_mfma_f32_16x16x32_bf16 v[102:105], v[66:69], v[34:37], 0
	v_mfma_f32_16x16x32_bf16 v[74:77], v[46:49], v[30:33], v[74:77]
	v_mfma_f32_16x16x32_bf16 v[78:81], v[46:49], v[38:41], v[78:81]
	v_mfma_f32_16x16x32_bf16 v[82:85], v[54:57], v[30:33], v[82:85]
	v_mfma_f32_16x16x32_bf16 v[86:89], v[54:57], v[38:41], v[86:89]
	v_mfma_f32_16x16x32_bf16 v[90:93], v[62:65], v[30:33], v[90:93]
	v_mfma_f32_16x16x32_bf16 v[94:97], v[62:65], v[38:41], v[94:97]
	v_mfma_f32_16x16x32_bf16 v[98:101], v[70:73], v[30:33], v[98:101]
	v_mfma_f32_16x16x32_bf16 v[102:105], v[70:73], v[38:41], v[102:105]
	s_setprio 0
	s_barrier
	v_readfirstlane_b32 s48, v21
	v_add_u32_e32 v20, 0x2000, v21
	v_add3_u32 v224, s59, v127, v126
	v_lshl_add_u64 v[16:17], v[12:13], 0, s[42:43]
	s_mov_b32 m0, s48
	v_readfirstlane_b32 s48, v20
	ds_read_b128 v[106:109], v224
	ds_read_b128 v[110:113], v224 offset:1024
	ds_read_b128 v[114:117], v224 offset:2048
	ds_read_b128 v[118:121], v224 offset:3072
	global_load_lds_dwordx4 v[16:17], off
	v_lshl_add_u64 v[16:17], v[14:15], 0, s[42:43]
	s_mov_b32 m0, s48
	s_nop 0
	global_load_lds_dwordx4 v[16:17], off
	s_barrier
	s_waitcnt lgkmcnt(0)
	s_setprio 0
	s_waitcnt lgkmcnt(0)
	v_mfma_f32_16x16x32_bf16 v[122:125], v[42:45], v[106:109], 0
	v_mfma_f32_16x16x32_bf16 v[42:45], v[42:45], v[114:117], 0
	v_mfma_f32_16x16x32_bf16 v[134:137], v[50:53], v[106:109], 0
	v_mfma_f32_16x16x32_bf16 v[50:53], v[50:53], v[114:117], 0
	v_mfma_f32_16x16x32_bf16 v[144:147], v[58:61], v[106:109], 0
	v_mfma_f32_16x16x32_bf16 v[58:61], v[58:61], v[114:117], 0
	v_mfma_f32_16x16x32_bf16 v[148:151], v[66:69], v[106:109], 0
	v_mfma_f32_16x16x32_bf16 v[66:69], v[66:69], v[114:117], 0
	v_mfma_f32_16x16x32_bf16 v[122:125], v[46:49], v[110:113], v[122:125]
	v_mfma_f32_16x16x32_bf16 v[42:45], v[46:49], v[118:121], v[42:45]
	v_mfma_f32_16x16x32_bf16 v[46:49], v[54:57], v[110:113], v[134:137]
	v_mfma_f32_16x16x32_bf16 v[50:53], v[54:57], v[118:121], v[50:53]
	v_mfma_f32_16x16x32_bf16 v[54:57], v[62:65], v[110:113], v[144:147]
	v_mfma_f32_16x16x32_bf16 v[58:61], v[62:65], v[118:121], v[58:61]
	v_mfma_f32_16x16x32_bf16 v[62:65], v[70:73], v[110:113], v[148:151]
	v_mfma_f32_16x16x32_bf16 v[66:69], v[70:73], v[118:121], v[66:69]
	s_setprio 0
	v_readfirstlane_b32 s48, v23
	v_lshl_add_u64 v[16:17], v[8:9], 0, s[42:43]
	s_mov_b32 m0, s48
	v_readfirstlane_b32 s48, v24
	s_barrier
; #define STAGE(P, BASE, LD, br, kt) do { const char* _g = (const char*)((BASE) + (size_t)(br) * (LD) + (size_t)(kt) * 64); \
;     for (int _i = 0; _i < 2; ++_i) { int _b = tidx * 16 + _i * 8192; int _r, _c; stage_rc(_b, _r, _c); \
;       __builtin_amdgcn_global_load_lds((const unsigned*)(_g + (unsigned)((_r * (LD) + _c) * 2)), (unsigned*)((char*)(P) + _b), 16, 0, 0); } } while (0)
; #define LDA(dst, b, h) for (int m = 0; m < 4; ++m) for (int k = 0; k < 2; ++k) \
;     dst[m][k] = *reinterpret_cast<const bf16x8*>((char*)SA(b, h) + lds_byte(wr * 64 + m * 16 + fr, k * 32 + fq * 8))
; #define LDB(dst, b, h) for (int n = 0; n < 2; ++n) for (int k = 0; k < 2; ++k) \
;     dst[n][k] = *reinterpret_cast<const bf16x8*>((char*)SB(b, h) + lds_byte(wc * 32 + n * 16 + fr, k * 32 + fq * 8))
; #define MMA(ai, bj, At_, Bt_) do { __builtin_amdgcn_s_setprio(1); \
;     for (int k = 0; k < 2; ++k) for (int m = 0; m < 4; ++m) for (int n = 0; n < 2; ++n) \
;       acc[ai][bj][m][n] = __builtin_amdgcn_mfma_f32_16x16x32_bf16(At_[m][k], Bt_[n][k], acc[ai][bj][m][n], 0, 0, 0); \
;     __builtin_amdgcn_s_setprio(0); } while (0)
; #define WAIT_V(n) asm volatile("s_waitcnt vmcnt(" #n ")" ::: "memory")
; #define WAIT_L(n) asm volatile("s_waitcnt lgkmcnt(" #n ")" ::: "memory")
; #define BAR __builtin_amdgcn_s_barrier()
; #define SCHED __builtin_amdgcn_sched_barrier(0)
; template <int EPI, int lda, int ldb, int N, int K>
; __device__ __forceinline__ void gemm_phase(const u16* __restrict__ A, const u16* __restrict__ Bt, const GemmEpi ep, int wv) {
;     ...
;       LDA(At, 0, 1); STAGE(SA(0, 0), Ab, lda, brow, t + 2);
;       BAR; WAIT_L(0); MMA(1, 0, At, B0); BAR; SCHED;
;       STAGE(SB(0, 1), Bt, ldb, bcol + HALF, t + 2);
;       WAIT_V(6); BAR; MMA(1, 1, At, B1); BAR;
;       LDB(B0, 1, 0); SCHED; LDA(At, 1, 0); STAGE(SA(0, 1), Ab, lda, brow + HALF, t + 2);
;       WAIT_L(8); BAR; WAIT_L(0); MMA(0, 0, At, B0); BAR; SCHED;
;       LDB(B1, 1, 1); STAGE(SB(1, 0), Bt, ldb, bcol, t + 3);
	ds_read_b128 v[70:73], v228 offset:16384
	ds_read_b128 v[134:137], v228 offset:17408
	ds_read_b128 v[144:147], v229 offset:18432
	ds_read_b128 v[148:151], v229 offset:19456
	ds_read_b128 v[152:155], v229 offset:20480
	ds_read_b128 v[156:159], v229 offset:21504
	ds_read_b128 v[160:163], v229 offset:22528
	ds_read_b128 v[164:167], v229 offset:23552
	global_load_lds_dwordx4 v[16:17], off
	v_lshl_add_u64 v[16:17], v[10:11], 0, s[42:43]
	s_mov_b32 m0, s48
	s_nop 0
	global_load_lds_dwordx4 v[16:17], off
	s_barrier
	s_waitcnt lgkmcnt(0)
	s_setprio 0
	s_waitcnt lgkmcnt(0)
	v_mfma_f32_16x16x32_bf16 v[168:171], v[70:73], v[26:29], 0
	v_mfma_f32_16x16x32_bf16 v[172:175], v[70:73], v[34:37], 0
	v_mfma_f32_16x16x32_bf16 v[176:179], v[144:147], v[26:29], 0
	v_mfma_f32_16x16x32_bf16 v[180:183], v[144:147], v[34:37], 0
	v_mfma_f32_16x16x32_bf16 v[184:187], v[152:155], v[26:29], 0
	v_mfma_f32_16x16x32_bf16 v[188:191], v[152:155], v[34:37], 0
	v_mfma_f32_16x16x32_bf16 v[24:27], v[160:163], v[26:29], 0
	v_mfma_f32_16x16x32_bf16 v[34:37], v[160:163], v[34:37], 0
	v_mfma_f32_16x16x32_bf16 v[168:171], v[134:137], v[30:33], v[168:171]
	v_mfma_f32_16x16x32_bf16 v[176:179], v[148:151], v[30:33], v[176:179]
	v_mfma_f32_16x16x32_bf16 v[184:187], v[156:159], v[30:33], v[184:187]
	v_mfma_f32_16x16x32_bf16 v[24:27], v[164:167], v[30:33], v[24:27]
	v_mfma_f32_16x16x32_bf16 v[28:31], v[164:167], v[38:41], v[34:37]
	v_mfma_f32_16x16x32_bf16 v[172:175], v[134:137], v[38:41], v[172:175]
	v_mfma_f32_16x16x32_bf16 v[180:183], v[148:151], v[38:41], v[180:183]
	v_mfma_f32_16x16x32_bf16 v[188:191], v[156:159], v[38:41], v[188:191]
	s_setprio 0
	s_barrier
	v_readfirstlane_b32 s48, v22
	v_add_u32_e32 v20, 0x2000, v22
	v_lshl_add_u64 v[16:17], v[2:3], 0, s[42:43]
	s_mov_b32 m0, s48
	v_readfirstlane_b32 s48, v20
	global_load_lds_dwordx4 v[16:17], off
	v_lshl_add_u64 v[16:17], v[0:1], 0, s[42:43]
	s_mov_b32 m0, s48
	s_nop 0
	global_load_lds_dwordx4 v[16:17], off
	s_waitcnt vmcnt(6)
	s_barrier
	s_setprio 0
	v_mfma_f32_16x16x32_bf16 v[20:23], v[70:73], v[106:109], 0
	v_mfma_f32_16x16x32_bf16 v[32:35], v[70:73], v[114:117], 0
	v_mfma_f32_16x16x32_bf16 v[36:39], v[144:147], v[106:109], 0
	v_mfma_f32_16x16x32_bf16 v[70:73], v[144:147], v[114:117], 0
	v_mfma_f32_16x16x32_bf16 v[144:147], v[152:155], v[106:109], 0
	v_mfma_f32_16x16x32_bf16 v[152:155], v[152:155], v[114:117], 0
	v_mfma_f32_16x16x32_bf16 v[106:109], v[160:163], v[106:109], 0
	v_mfma_f32_16x16x32_bf16 v[114:117], v[160:163], v[114:117], 0
	v_mfma_f32_16x16x32_bf16 v[20:23], v[134:137], v[110:113], v[20:23]
	v_mfma_f32_16x16x32_bf16 v[32:35], v[134:137], v[118:121], v[32:35]
	v_mfma_f32_16x16x32_bf16 v[36:39], v[148:151], v[110:113], v[36:39]
	v_mfma_f32_16x16x32_bf16 v[70:73], v[148:151], v[118:121], v[70:73]
	v_mfma_f32_16x16x32_bf16 v[134:137], v[156:159], v[110:113], v[144:147]
	v_mfma_f32_16x16x32_bf16 v[106:109], v[164:167], v[110:113], v[106:109]
	v_mfma_f32_16x16x32_bf16 v[110:113], v[164:167], v[118:121], v[114:117]
	v_mfma_f32_16x16x32_bf16 v[144:147], v[156:159], v[118:121], v[152:155]
	s_setprio 0
	v_add3_u32 v225, s60, v127, v126
	s_barrier
	ds_read_b128 v[114:117], v225
	ds_read_b128 v[118:121], v225 offset:1024
	ds_read_b128 v[148:151], v225 offset:2048
	ds_read_b128 v[152:155], v225 offset:3072
	v_readfirstlane_b32 s48, v18
	v_lshl_add_u64 v[16:17], v[6:7], 0, s[42:43]
	s_mov_b32 m0, s48
	v_readfirstlane_b32 s48, v19
	ds_read_b128 v[156:159], v228 offset:32768
	ds_read_b128 v[160:163], v228 offset:33792
	ds_read_b128 v[164:167], v229 offset:34816
	ds_read_b128 v[192:195], v229 offset:35840
	ds_read_b128 v[196:199], v229 offset:36864
	ds_read_b128 v[200:203], v229 offset:37888
	ds_read_b128 v[204:207], v229 offset:38912
	ds_read_b128 v[208:211], v229 offset:39936
	global_load_lds_dwordx4 v[16:17], off
	v_lshl_add_u64 v[16:17], v[4:5], 0, s[42:43]
	s_mov_b32 m0, s48
	s_nop 0
	global_load_lds_dwordx4 v[16:17], off
	s_waitcnt lgkmcnt(8)
	s_barrier
	s_waitcnt lgkmcnt(0)
	s_setprio 0
	s_waitcnt lgkmcnt(0)
	v_mfma_f32_16x16x32_bf16 v[16:19], v[156:159], v[114:117], v[74:77]
	v_mfma_f32_16x16x32_bf16 v[74:77], v[156:159], v[148:151], v[78:81]
	v_mfma_f32_16x16x32_bf16 v[78:81], v[164:167], v[114:117], v[82:85]
	v_mfma_f32_16x16x32_bf16 v[82:85], v[164:167], v[148:151], v[86:89]
	v_mfma_f32_16x16x32_bf16 v[86:89], v[196:199], v[114:117], v[90:93]
	v_mfma_f32_16x16x32_bf16 v[90:93], v[196:199], v[148:151], v[94:97]
	v_mfma_f32_16x16x32_bf16 v[94:97], v[204:207], v[114:117], v[98:101]
	v_mfma_f32_16x16x32_bf16 v[98:101], v[204:207], v[148:151], v[102:105]
	v_mfma_f32_16x16x32_bf16 v[16:19], v[160:163], v[118:121], v[16:19]
	v_mfma_f32_16x16x32_bf16 v[74:77], v[160:163], v[152:155], v[74:77]
	v_mfma_f32_16x16x32_bf16 v[78:81], v[192:195], v[118:121], v[78:81]
	v_mfma_f32_16x16x32_bf16 v[82:85], v[192:195], v[152:155], v[82:85]
	v_mfma_f32_16x16x32_bf16 v[86:89], v[200:203], v[118:121], v[86:89]
	v_mfma_f32_16x16x32_bf16 v[90:93], v[200:203], v[152:155], v[90:93]
	v_mfma_f32_16x16x32_bf16 v[94:97], v[208:211], v[118:121], v[94:97]
	v_mfma_f32_16x16x32_bf16 v[98:101], v[208:211], v[152:155], v[98:101]
	s_setprio 0
	s_barrier
	s_mov_b32 m0, s53
	v_add3_u32 v226, s61, v127, v126
	v_lshl_add_u64 v[12:13], v[12:13], 0, s[44:45]
	ds_read_b128 v[102:105], v226
	ds_read_b128 v[212:215], v226 offset:1024
	ds_read_b128 v[216:219], v226 offset:2048
	ds_read_b128 v[220:223], v226 offset:3072
	global_load_lds_dwordx4 v[12:13], off
	v_lshl_add_u64 v[12:13], v[14:15], 0, s[44:45]
	s_mov_b32 m0, s52
	s_nop 0
	global_load_lds_dwordx4 v[12:13], off
	s_barrier
; #define STAGE(P, BASE, LD, br, kt) do { const char* _g = (const char*)((BASE) + (size_t)(br) * (LD) + (size_t)(kt) * 64); \
;     for (int _i = 0; _i < 2; ++_i) { int _b = tidx * 16 + _i * 8192; int _r, _c; stage_rc(_b, _r, _c); \
;       __builtin_amdgcn_global_load_lds((const unsigned*)(_g + (unsigned)((_r * (LD) + _c) * 2)), (unsigned*)((char*)(P) + _b), 16, 0, 0); } } while (0)
; #define LDA(dst, b, h) for (int m = 0; m < 4; ++m) for (int k = 0; k < 2; ++k) \
;     dst[m][k] = *reinterpret_cast<const bf16x8*>((char*)SA(b, h) + lds_byte(wr * 64 + m * 16 + fr, k * 32 + fq * 8))
; #define LDB(dst, b, h) for (int n = 0; n < 2; ++n) for (int k = 0; k < 2; ++k) \
;     dst[n][k] = *reinterpret_cast<const bf16x8*>((char*)SB(b, h) + lds_byte(wc * 32 + n * 16 + fr, k * 32 + fq * 8))
; #define MMA(ai, bj, At_, Bt_) do { __builtin_amdgcn_s_setprio(1); \
;     for (int k = 0; k < 2; ++k) for (int m = 0; m < 4; ++m) for (int n = 0; n < 2; ++n) \
;       acc[ai][bj][m][n] = __builtin_amdgcn_mfma_f32_16x16x32_bf16(At_[m][k], Bt_[n][k], acc[ai][bj][m][n], 0, 0, 0); \
;     __builtin_amdgcn_s_setprio(0); } while (0)
; #define WAIT_V(n) asm volatile("s_waitcnt vmcnt(" #n ")" ::: "memory")
; #define WAIT_L(n) asm volatile("s_waitcnt lgkmcnt(" #n ")" ::: "memory")
; #define BAR __builtin_amdgcn_s_barrier()
; #define SCHED __builtin_amdgcn_sched_barrier(0)
; template <int EPI, int lda, int ldb, int N, int K>
; __device__ __forceinline__ void gemm_phase(const u16* __restrict__ A, const u16* __restrict__ Bt, const GemmEpi ep, int wv) {
;     ...
;       BAR; WAIT_L(0); MMA(0, 1, At, B1); BAR;
;       LDA(At, 1, 1); STAGE(SA(1, 0), Ab, lda, brow, t + 3);
;       BAR; WAIT_L(0); MMA(1, 0, At, B0); BAR; SCHED;
;       STAGE(SB(1, 1), Bt, ldb, bcol + HALF, t + 3);
;       WAIT_V(6); BAR; MMA(1, 1, At, B1); BAR;
;     }
;     { LDB(B0, 0, 0); LDA(At, 0, 0); STAGE(SA(1, 1), Ab, lda, brow + HALF, nt - 1);
	s_waitcnt lgkmcnt(0)
	s_setprio 0
	s_waitcnt lgkmcnt(0)
	v_mfma_f32_16x16x32_bf16 v[12:15], v[156:159], v[102:105], v[122:125]
	v_mfma_f32_16x16x32_bf16 v[40:43], v[156:159], v[216:219], v[42:45]
	v_mfma_f32_16x16x32_bf16 v[44:47], v[164:167], v[102:105], v[46:49]
	v_mfma_f32_16x16x32_bf16 v[48:51], v[164:167], v[216:219], v[50:53]
	v_mfma_f32_16x16x32_bf16 v[52:55], v[196:199], v[102:105], v[54:57]
	v_mfma_f32_16x16x32_bf16 v[56:59], v[196:199], v[216:219], v[58:61]
	v_mfma_f32_16x16x32_bf16 v[60:63], v[204:207], v[102:105], v[62:65]
	v_mfma_f32_16x16x32_bf16 v[64:67], v[204:207], v[216:219], v[66:69]
	v_mfma_f32_16x16x32_bf16 v[12:15], v[160:163], v[212:215], v[12:15]
	v_mfma_f32_16x16x32_bf16 v[40:43], v[160:163], v[220:223], v[40:43]
	v_mfma_f32_16x16x32_bf16 v[44:47], v[192:195], v[212:215], v[44:47]
	v_mfma_f32_16x16x32_bf16 v[48:51], v[192:195], v[220:223], v[48:51]
	v_mfma_f32_16x16x32_bf16 v[52:55], v[200:203], v[212:215], v[52:55]
	v_mfma_f32_16x16x32_bf16 v[56:59], v[200:203], v[220:223], v[56:59]
	v_mfma_f32_16x16x32_bf16 v[60:63], v[208:211], v[212:215], v[60:63]
	v_mfma_f32_16x16x32_bf16 v[64:67], v[208:211], v[220:223], v[64:67]
	s_setprio 0
	s_mov_b32 m0, s51
	v_lshl_add_u64 v[8:9], v[8:9], 0, s[44:45]
	s_barrier
	ds_read_b128 v[122:125], v228 offset:49152
	ds_read_b128 v[156:159], v228 offset:50176
	ds_read_b128 v[160:163], v229 offset:51200
	ds_read_b128 v[164:167], v229 offset:52224
	ds_read_b128 v[192:195], v229 offset:53248
	ds_read_b128 v[196:199], v229 offset:54272
	ds_read_b128 v[200:203], v229 offset:55296
	ds_read_b128 v[204:207], v229 offset:56320
	global_load_lds_dwordx4 v[8:9], off
	v_lshl_add_u64 v[8:9], v[10:11], 0, s[44:45]
	s_mov_b32 m0, s50
	s_nop 0
	global_load_lds_dwordx4 v[8:9], off
	s_barrier
	s_waitcnt lgkmcnt(0)
	s_setprio 0
	s_waitcnt lgkmcnt(0)
	v_mfma_f32_16x16x32_bf16 v[8:11], v[122:125], v[114:117], v[168:171]
	v_mfma_f32_16x16x32_bf16 v[168:171], v[122:125], v[148:151], v[172:175]
	v_mfma_f32_16x16x32_bf16 v[24:27], v[200:203], v[114:117], v[24:27]
	v_mfma_f32_16x16x32_bf16 v[28:31], v[200:203], v[148:151], v[28:31]
	v_mfma_f32_16x16x32_bf16 v[172:175], v[160:163], v[114:117], v[176:179]
	v_mfma_f32_16x16x32_bf16 v[176:179], v[160:163], v[148:151], v[180:183]
	v_mfma_f32_16x16x32_bf16 v[180:183], v[192:195], v[114:117], v[184:187]
	v_mfma_f32_16x16x32_bf16 v[184:187], v[192:195], v[148:151], v[188:191]
	v_mfma_f32_16x16x32_bf16 v[8:11], v[156:159], v[118:121], v[8:11]
	v_mfma_f32_16x16x32_bf16 v[114:117], v[156:159], v[152:155], v[168:171]
	v_mfma_f32_16x16x32_bf16 v[24:27], v[204:207], v[118:121], v[24:27]
	v_mfma_f32_16x16x32_bf16 v[28:31], v[204:207], v[152:155], v[28:31]
	v_mfma_f32_16x16x32_bf16 v[148:151], v[164:167], v[118:121], v[172:175]
	v_mfma_f32_16x16x32_bf16 v[168:171], v[164:167], v[152:155], v[176:179]
	v_mfma_f32_16x16x32_bf16 v[172:175], v[196:199], v[118:121], v[180:183]
	v_mfma_f32_16x16x32_bf16 v[176:179], v[196:199], v[152:155], v[184:187]
	s_setprio 0
	s_barrier
	s_mov_b32 m0, s13
	v_lshl_add_u64 v[2:3], v[2:3], 0, s[44:45]
	global_load_lds_dwordx4 v[2:3], off
	v_lshl_add_u64 v[0:1], v[0:1], 0, s[44:45]
	s_mov_b32 m0, s11
	s_nop 0
	global_load_lds_dwordx4 v[0:1], off
	s_waitcnt vmcnt(6)
	s_barrier
	s_setprio 0
	v_mfma_f32_16x16x32_bf16 v[0:3], v[122:125], v[102:105], v[20:23]
	v_mfma_f32_16x16x32_bf16 v[20:23], v[122:125], v[216:219], v[32:35]
	v_mfma_f32_16x16x32_bf16 v[32:35], v[160:163], v[102:105], v[36:39]
	v_mfma_f32_16x16x32_bf16 v[36:39], v[160:163], v[216:219], v[70:73]
	v_mfma_f32_16x16x32_bf16 v[68:71], v[192:195], v[102:105], v[134:137]
	v_mfma_f32_16x16x32_bf16 v[118:121], v[192:195], v[216:219], v[144:147]
	v_mfma_f32_16x16x32_bf16 v[102:105], v[200:203], v[102:105], v[106:109]
	v_mfma_f32_16x16x32_bf16 v[106:109], v[200:203], v[216:219], v[110:113]
	v_mfma_f32_16x16x32_bf16 v[0:3], v[156:159], v[212:215], v[0:3]
	v_mfma_f32_16x16x32_bf16 v[20:23], v[156:159], v[220:223], v[20:23]
	v_mfma_f32_16x16x32_bf16 v[32:35], v[164:167], v[212:215], v[32:35]
	v_mfma_f32_16x16x32_bf16 v[36:39], v[164:167], v[220:223], v[36:39]
	v_mfma_f32_16x16x32_bf16 v[68:71], v[196:199], v[212:215], v[68:71]
	v_mfma_f32_16x16x32_bf16 v[110:113], v[196:199], v[220:223], v[118:121]
	v_mfma_f32_16x16x32_bf16 v[102:105], v[204:207], v[212:215], v[102:105]
	v_mfma_f32_16x16x32_bf16 v[106:109], v[204:207], v[220:223], v[106:109]
	s_setprio 0
	s_mov_b32 m0, s47
	v_lshl_add_u64 v[6:7], v[6:7], 0, s[44:45]
	s_barrier
	ds_read_b128 v[118:121], v133
	ds_read_b128 v[122:125], v133 offset:1024
	ds_read_b128 v[134:137], v133 offset:2048
	ds_read_b128 v[144:147], v133 offset:3072
	ds_read_b128 v[152:155], v228
	ds_read_b128 v[156:159], v228 offset:1024
	ds_read_b128 v[160:163], v229 offset:2048
	ds_read_b128 v[164:167], v229 offset:3072
	ds_read_b128 v[180:183], v229 offset:4096
	ds_read_b128 v[184:187], v229 offset:5120
	ds_read_b128 v[188:191], v229 offset:6144
	ds_read_b128 v[192:195], v229 offset:7168
	global_load_lds_dwordx4 v[6:7], off
	v_lshl_add_u64 v[4:5], v[4:5], 0, s[44:45]
	s_mov_b32 m0, s46
	s_nop 0
	global_load_lds_dwordx4 v[4:5], off
	s_barrier
; #define LDA(dst, b, h) for (int m = 0; m < 4; ++m) for (int k = 0; k < 2; ++k) \
;     dst[m][k] = *reinterpret_cast<const bf16x8*>((char*)SA(b, h) + lds_byte(wr * 64 + m * 16 + fr, k * 32 + fq * 8))
; #define LDB(dst, b, h) for (int n = 0; n < 2; ++n) for (int k = 0; k < 2; ++k) \
;     dst[n][k] = *reinterpret_cast<const bf16x8*>((char*)SB(b, h) + lds_byte(wc * 32 + n * 16 + fr, k * 32 + fq * 8))
; #define MMA(ai, bj, At_, Bt_) do { __builtin_amdgcn_s_setprio(1); \
;     for (int k = 0; k < 2; ++k) for (int m = 0; m < 4; ++m) for (int n = 0; n < 2; ++n) \
;       acc[ai][bj][m][n] = __builtin_amdgcn_mfma_f32_16x16x32_bf16(At_[m][k], Bt_[n][k], acc[ai][bj][m][n], 0, 0, 0); \
;     __builtin_amdgcn_s_setprio(0); } while (0)
; #define WAIT_V(n) asm volatile("s_waitcnt vmcnt(" #n ")" ::: "memory")
; #define WAIT_L(n) asm volatile("s_waitcnt lgkmcnt(" #n ")" ::: "memory")
; #define BAR __builtin_amdgcn_s_barrier()
; template <int EPI, int lda, int ldb, int N, int K>
; __device__ __forceinline__ void gemm_phase(const u16* __restrict__ A, const u16* __restrict__ Bt, const GemmEpi ep, int wv) {
;     ...
;       BAR; WAIT_L(0); MMA(0, 0, At, B0); BAR;
;       LDB(B1, 0, 1); BAR; WAIT_L(0); MMA(0, 1, At, B1); BAR;
;       LDA(At, 0, 1); WAIT_V(4); BAR; WAIT_L(0); MMA(1, 0, At, B0); MMA(1, 1, At, B1); BAR; }
;     { LDB(B0, 1, 0); LDA(At, 1, 0); WAIT_V(2); BAR; WAIT_L(0); MMA(0, 0, At, B0); BAR;
	s_waitcnt lgkmcnt(0)
	s_setprio 0
	s_waitcnt lgkmcnt(0)
	v_mfma_f32_16x16x32_bf16 v[4:7], v[152:155], v[118:121], v[16:19]
	v_mfma_f32_16x16x32_bf16 v[16:19], v[152:155], v[134:137], v[74:77]
	v_mfma_f32_16x16x32_bf16 v[72:75], v[160:163], v[118:121], v[78:81]
	v_mfma_f32_16x16x32_bf16 v[76:79], v[160:163], v[134:137], v[82:85]
	v_mfma_f32_16x16x32_bf16 v[80:83], v[180:183], v[118:121], v[86:89]
	v_mfma_f32_16x16x32_bf16 v[84:87], v[180:183], v[134:137], v[90:93]
	v_mfma_f32_16x16x32_bf16 v[88:91], v[188:191], v[118:121], v[94:97]
	v_mfma_f32_16x16x32_bf16 v[92:95], v[188:191], v[134:137], v[98:101]
	v_mfma_f32_16x16x32_bf16 v[4:7], v[156:159], v[122:125], v[4:7]
	v_mfma_f32_16x16x32_bf16 v[16:19], v[156:159], v[144:147], v[16:19]
	v_mfma_f32_16x16x32_bf16 v[72:75], v[164:167], v[122:125], v[72:75]
	v_mfma_f32_16x16x32_bf16 v[76:79], v[164:167], v[144:147], v[76:79]
	v_mfma_f32_16x16x32_bf16 v[80:83], v[184:187], v[122:125], v[80:83]
	v_mfma_f32_16x16x32_bf16 v[84:87], v[184:187], v[144:147], v[84:87]
	v_mfma_f32_16x16x32_bf16 v[88:91], v[192:195], v[122:125], v[88:91]
	v_mfma_f32_16x16x32_bf16 v[92:95], v[192:195], v[144:147], v[92:95]
	s_setprio 0
	s_barrier
	ds_read_b128 v[96:99], v224
	ds_read_b128 v[196:199], v224 offset:1024
	ds_read_b128 v[200:203], v224 offset:2048
	ds_read_b128 v[204:207], v224 offset:3072
	s_barrier
	s_waitcnt lgkmcnt(0)
	s_setprio 0
	s_waitcnt lgkmcnt(0)
	v_mfma_f32_16x16x32_bf16 v[12:15], v[152:155], v[96:99], v[12:15]
	v_mfma_f32_16x16x32_bf16 v[40:43], v[152:155], v[200:203], v[40:43]
	v_mfma_f32_16x16x32_bf16 v[52:55], v[180:183], v[96:99], v[52:55]
	v_mfma_f32_16x16x32_bf16 v[56:59], v[180:183], v[200:203], v[56:59]
	v_mfma_f32_16x16x32_bf16 v[64:67], v[188:191], v[200:203], v[64:67]
	v_mfma_f32_16x16x32_bf16 v[44:47], v[160:163], v[96:99], v[44:47]
	v_mfma_f32_16x16x32_bf16 v[48:51], v[160:163], v[200:203], v[48:51]
	v_mfma_f32_16x16x32_bf16 v[60:63], v[188:191], v[96:99], v[60:63]
	v_mfma_f32_16x16x32_bf16 v[12:15], v[156:159], v[196:199], v[12:15]
	v_mfma_f32_16x16x32_bf16 v[40:43], v[156:159], v[204:207], v[40:43]
	v_mfma_f32_16x16x32_bf16 v[52:55], v[184:187], v[196:199], v[52:55]
	v_mfma_f32_16x16x32_bf16 v[56:59], v[184:187], v[204:207], v[56:59]
	v_mfma_f32_16x16x32_bf16 v[64:67], v[192:195], v[204:207], v[64:67]
	v_mfma_f32_16x16x32_bf16 v[152:155], v[164:167], v[196:199], v[44:47]
	v_mfma_f32_16x16x32_bf16 v[156:159], v[164:167], v[204:207], v[48:51]
	v_mfma_f32_16x16x32_bf16 v[160:163], v[192:195], v[196:199], v[60:63]
	s_setprio 0
	s_barrier
	ds_read_b128 v[44:47], v228 offset:16384
	ds_read_b128 v[48:51], v228 offset:17408
	ds_read_b128 v[60:63], v229 offset:18432
	ds_read_b128 v[164:167], v229 offset:19456
	ds_read_b128 v[180:183], v229 offset:20480
	ds_read_b128 v[184:187], v229 offset:21504
	ds_read_b128 v[188:191], v229 offset:22528
	ds_read_b128 v[192:195], v229 offset:23552
	s_waitcnt vmcnt(4)
	s_barrier
	s_waitcnt lgkmcnt(0)
	s_setprio 0
	s_waitcnt lgkmcnt(0)
	v_mfma_f32_16x16x32_bf16 v[8:11], v[44:47], v[118:121], v[8:11]
	v_mfma_f32_16x16x32_bf16 v[24:27], v[188:191], v[118:121], v[24:27]
	v_mfma_f32_16x16x32_bf16 v[28:31], v[188:191], v[134:137], v[28:31]
	v_mfma_f32_16x16x32_bf16 v[114:117], v[44:47], v[134:137], v[114:117]
	v_mfma_f32_16x16x32_bf16 v[148:151], v[60:63], v[118:121], v[148:151]
	v_mfma_f32_16x16x32_bf16 v[168:171], v[60:63], v[134:137], v[168:171]
	v_mfma_f32_16x16x32_bf16 v[172:175], v[180:183], v[118:121], v[172:175]
	v_mfma_f32_16x16x32_bf16 v[176:179], v[180:183], v[134:137], v[176:179]
	v_mfma_f32_16x16x32_bf16 v[8:11], v[48:51], v[122:125], v[8:11]
	v_mfma_f32_16x16x32_bf16 v[24:27], v[192:195], v[122:125], v[24:27]
	v_mfma_f32_16x16x32_bf16 v[28:31], v[192:195], v[144:147], v[28:31]
	v_mfma_f32_16x16x32_bf16 v[134:137], v[48:51], v[144:147], v[114:117]
	v_mfma_f32_16x16x32_bf16 v[148:151], v[164:167], v[122:125], v[148:151]
	v_mfma_f32_16x16x32_bf16 v[168:171], v[164:167], v[144:147], v[168:171]
	v_mfma_f32_16x16x32_bf16 v[172:175], v[184:187], v[122:125], v[172:175]
	v_mfma_f32_16x16x32_bf16 v[176:179], v[184:187], v[144:147], v[176:179]
	s_setprio 0
	s_setprio 0
	v_mfma_f32_16x16x32_bf16 v[0:3], v[44:47], v[96:99], v[0:3]
	v_mfma_f32_16x16x32_bf16 v[20:23], v[44:47], v[200:203], v[20:23]
	v_mfma_f32_16x16x32_bf16 v[44:47], v[180:183], v[96:99], v[68:71]
	v_mfma_f32_16x16x32_bf16 v[68:71], v[188:191], v[96:99], v[102:105]
	v_mfma_f32_16x16x32_bf16 v[32:35], v[60:63], v[96:99], v[32:35]
	v_mfma_f32_16x16x32_bf16 v[36:39], v[60:63], v[200:203], v[36:39]
	v_mfma_f32_16x16x32_bf16 v[60:63], v[180:183], v[200:203], v[110:113]
	v_mfma_f32_16x16x32_bf16 v[96:99], v[188:191], v[200:203], v[106:109]
	v_mfma_f32_16x16x32_bf16 v[20:23], v[48:51], v[204:207], v[20:23]
	v_mfma_f32_16x16x32_bf16 v[68:71], v[192:195], v[196:199], v[68:71]
	v_mfma_f32_16x16x32_bf16 v[144:147], v[48:51], v[196:199], v[0:3]
	v_mfma_f32_16x16x32_bf16 v[180:183], v[164:167], v[196:199], v[32:35]
	v_mfma_f32_16x16x32_bf16 v[164:167], v[164:167], v[204:207], v[36:39]
	v_mfma_f32_16x16x32_bf16 v[188:191], v[184:187], v[196:199], v[44:47]
	v_mfma_f32_16x16x32_bf16 v[184:187], v[184:187], v[204:207], v[60:63]
	v_mfma_f32_16x16x32_bf16 v[192:195], v[192:195], v[204:207], v[96:99]
	s_setprio 0
	s_barrier
	ds_read_b128 v[0:3], v225
	ds_read_b128 v[196:199], v225 offset:1024
	ds_read_b128 v[200:203], v225 offset:2048
	ds_read_b128 v[204:207], v225 offset:3072
	ds_read_b128 v[36:39], v228 offset:32768
	ds_read_b128 v[100:103], v228 offset:33792
	ds_read_b128 v[108:111], v229 offset:34816
	ds_read_b128 v[208:211], v229 offset:35840
	ds_read_b128 v[116:119], v229 offset:36864
	ds_read_b128 v[212:215], v229 offset:37888
	ds_read_b128 v[124:127], v229 offset:38912
	ds_read_b128 v[216:219], v229 offset:39936
	s_waitcnt vmcnt(2)
	s_barrier
; #define LDA(dst, b, h) for (int m = 0; m < 4; ++m) for (int k = 0; k < 2; ++k) \
;     dst[m][k] = *reinterpret_cast<const bf16x8*>((char*)SA(b, h) + lds_byte(wr * 64 + m * 16 + fr, k * 32 + fq * 8))
; #define LDB(dst, b, h) for (int n = 0; n < 2; ++n) for (int k = 0; k < 2; ++k) \
;     dst[n][k] = *reinterpret_cast<const bf16x8*>((char*)SB(b, h) + lds_byte(wc * 32 + n * 16 + fr, k * 32 + fq * 8))
; #define MMA(ai, bj, At_, Bt_) do { __builtin_amdgcn_s_setprio(1); \
;     for (int k = 0; k < 2; ++k) for (int m = 0; m < 4; ++m) for (int n = 0; n < 2; ++n) \
;       acc[ai][bj][m][n] = __builtin_amdgcn_mfma_f32_16x16x32_bf16(At_[m][k], Bt_[n][k], acc[ai][bj][m][n], 0, 0, 0); \
;     __builtin_amdgcn_s_setprio(0); } while (0)
; #define WAIT_V(n) asm volatile("s_waitcnt vmcnt(" #n ")" ::: "memory")
; #define WAIT_L(n) asm volatile("s_waitcnt lgkmcnt(" #n ")" ::: "memory")
; #define BAR __builtin_amdgcn_s_barrier()
; template <int EPI, int lda, int ldb, int N, int K>
; __device__ __forceinline__ void gemm_phase(const u16* __restrict__ A, const u16* __restrict__ Bt, const GemmEpi ep, int wv) {
;     ...
;     { LDB(B0, 1, 0); LDA(At, 1, 0); WAIT_V(2); BAR; WAIT_L(0); MMA(0, 0, At, B0); BAR;
;       LDB(B1, 1, 1); WAIT_V(0); BAR; WAIT_L(0); MMA(0, 1, At, B1); BAR;
;       LDA(At, 1, 1); BAR; WAIT_L(0); MMA(1, 0, At, B0); MMA(1, 1, At, B1); BAR; }
;     if (wr == 0) BAR;
	s_waitcnt lgkmcnt(0)
	s_setprio 0
	s_waitcnt lgkmcnt(0)
	v_mfma_f32_16x16x32_bf16 v[4:7], v[36:39], v[0:3], v[4:7]
	v_mfma_f32_16x16x32_bf16 v[16:19], v[36:39], v[200:203], v[16:19]
	v_mfma_f32_16x16x32_bf16 v[32:35], v[108:111], v[0:3], v[72:75]
	v_mfma_f32_16x16x32_bf16 v[44:47], v[108:111], v[200:203], v[76:79]
	v_mfma_f32_16x16x32_bf16 v[72:75], v[116:119], v[0:3], v[80:83]
	v_mfma_f32_16x16x32_bf16 v[76:79], v[116:119], v[200:203], v[84:87]
	v_mfma_f32_16x16x32_bf16 v[80:83], v[124:127], v[0:3], v[88:91]
	v_mfma_f32_16x16x32_bf16 v[84:87], v[124:127], v[200:203], v[92:95]
	v_mfma_f32_16x16x32_bf16 v[120:123], v[100:103], v[196:199], v[4:7]
	v_mfma_f32_16x16x32_bf16 v[60:63], v[100:103], v[204:207], v[16:19]
	v_mfma_f32_16x16x32_bf16 v[112:115], v[208:211], v[196:199], v[32:35]
	v_mfma_f32_16x16x32_bf16 v[48:51], v[208:211], v[204:207], v[44:47]
	v_mfma_f32_16x16x32_bf16 v[104:107], v[212:215], v[196:199], v[72:75]
	v_mfma_f32_16x16x32_bf16 v[44:47], v[212:215], v[204:207], v[76:79]
	v_mfma_f32_16x16x32_bf16 v[96:99], v[216:219], v[196:199], v[80:83]
	v_mfma_f32_16x16x32_bf16 v[32:35], v[216:219], v[204:207], v[84:87]
	s_setprio 0
	s_barrier
	ds_read_b128 v[4:7], v226
	ds_read_b128 v[220:223], v226 offset:1024
	ds_read_b128 v[76:79], v226 offset:2048
	ds_read_b128 v[224:227], v226 offset:3072
	s_waitcnt vmcnt(0)
	s_barrier
	s_waitcnt lgkmcnt(0)
	s_setprio 0
	s_waitcnt lgkmcnt(0)
	v_mfma_f32_16x16x32_bf16 v[12:15], v[36:39], v[4:7], v[12:15]
	v_mfma_f32_16x16x32_bf16 v[16:19], v[36:39], v[76:79], v[40:43]
	v_mfma_f32_16x16x32_bf16 v[36:39], v[108:111], v[4:7], v[152:155]
	v_mfma_f32_16x16x32_bf16 v[40:43], v[108:111], v[76:79], v[156:159]
	v_mfma_f32_16x16x32_bf16 v[72:75], v[116:119], v[4:7], v[52:55]
	v_mfma_f32_16x16x32_bf16 v[80:83], v[116:119], v[76:79], v[56:59]
	v_mfma_f32_16x16x32_bf16 v[84:87], v[124:127], v[4:7], v[160:163]
	v_mfma_f32_16x16x32_bf16 v[64:67], v[124:127], v[76:79], v[64:67]
	v_mfma_f32_16x16x32_bf16 v[124:127], v[100:103], v[220:223], v[12:15]
	v_mfma_f32_16x16x32_bf16 v[56:59], v[100:103], v[224:227], v[16:19]
	v_mfma_f32_16x16x32_bf16 v[116:119], v[208:211], v[220:223], v[36:39]
	v_mfma_f32_16x16x32_bf16 v[52:55], v[208:211], v[224:227], v[40:43]
	v_mfma_f32_16x16x32_bf16 v[108:111], v[212:215], v[220:223], v[72:75]
	v_mfma_f32_16x16x32_bf16 v[40:43], v[212:215], v[224:227], v[80:83]
	v_mfma_f32_16x16x32_bf16 v[100:103], v[216:219], v[220:223], v[84:87]
	v_mfma_f32_16x16x32_bf16 v[36:39], v[216:219], v[224:227], v[64:67]
	s_setprio 0
	s_barrier
	ds_read_b128 v[84:87], v228 offset:49152
	ds_read_b128 v[152:155], v228 offset:50176
	ds_read_b128 v[92:95], v229 offset:51200
	ds_read_b128 v[156:159], v229 offset:52224
	ds_read_b128 v[160:163], v229 offset:53248
	ds_read_b128 v[208:211], v229 offset:54272
	ds_read_b128 v[212:215], v229 offset:55296
	ds_read_b128 v[216:219], v229 offset:56320
	s_barrier
	s_waitcnt lgkmcnt(0)
	s_setprio 0
	s_waitcnt lgkmcnt(0)
	v_mfma_f32_16x16x32_bf16 v[8:11], v[84:87], v[0:3], v[8:11]
	v_mfma_f32_16x16x32_bf16 v[12:15], v[84:87], v[200:203], v[134:137]
	v_mfma_f32_16x16x32_bf16 v[16:19], v[92:95], v[0:3], v[148:151]
	v_mfma_f32_16x16x32_bf16 v[64:67], v[92:95], v[200:203], v[168:171]
	v_mfma_f32_16x16x32_bf16 v[72:75], v[160:163], v[0:3], v[172:175]
	v_mfma_f32_16x16x32_bf16 v[134:137], v[160:163], v[200:203], v[176:179]
	v_mfma_f32_16x16x32_bf16 v[0:3], v[212:215], v[0:3], v[24:27]
	v_mfma_f32_16x16x32_bf16 v[24:27], v[212:215], v[200:203], v[28:31]
	v_mfma_f32_16x16x32_bf16 v[88:91], v[152:155], v[196:199], v[8:11]
	v_mfma_f32_16x16x32_bf16 v[28:31], v[152:155], v[204:207], v[12:15]
	v_mfma_f32_16x16x32_bf16 v[80:83], v[156:159], v[196:199], v[16:19]
	v_mfma_f32_16x16x32_bf16 v[16:19], v[156:159], v[204:207], v[64:67]
	v_mfma_f32_16x16x32_bf16 v[72:75], v[208:211], v[196:199], v[72:75]
	v_mfma_f32_16x16x32_bf16 v[12:15], v[208:211], v[204:207], v[134:137]
	v_mfma_f32_16x16x32_bf16 v[64:67], v[216:219], v[196:199], v[0:3]
	v_mfma_f32_16x16x32_bf16 v[0:3], v[216:219], v[204:207], v[24:27]
	s_setprio 0
	s_setprio 0
	v_mfma_f32_16x16x32_bf16 v[8:11], v[84:87], v[4:7], v[144:147]
	v_mfma_f32_16x16x32_bf16 v[20:23], v[84:87], v[76:79], v[20:23]
	v_mfma_f32_16x16x32_bf16 v[84:87], v[92:95], v[4:7], v[180:183]
	v_mfma_f32_16x16x32_bf16 v[134:137], v[92:95], v[76:79], v[164:167]
	v_mfma_f32_16x16x32_bf16 v[144:147], v[160:163], v[4:7], v[188:191]
	v_mfma_f32_16x16x32_bf16 v[148:151], v[160:163], v[76:79], v[184:187]
	v_mfma_f32_16x16x32_bf16 v[4:7], v[212:215], v[4:7], v[68:71]
	v_mfma_f32_16x16x32_bf16 v[160:163], v[212:215], v[76:79], v[192:195]
	v_mfma_f32_16x16x32_bf16 v[92:95], v[152:155], v[220:223], v[8:11]
	v_mfma_f32_16x16x32_bf16 v[24:27], v[152:155], v[224:227], v[20:23]
	v_mfma_f32_16x16x32_bf16 v[84:87], v[156:159], v[220:223], v[84:87]
	v_mfma_f32_16x16x32_bf16 v[20:23], v[156:159], v[224:227], v[134:137]
	v_mfma_f32_16x16x32_bf16 v[76:79], v[208:211], v[220:223], v[144:147]
	v_mfma_f32_16x16x32_bf16 v[8:11], v[208:211], v[224:227], v[148:151]
	v_mfma_f32_16x16x32_bf16 v[68:71], v[216:219], v[220:223], v[4:7]
	v_mfma_f32_16x16x32_bf16 v[4:7], v[216:219], v[224:227], v[160:163]
	s_setprio 0
	v_cmp_gt_u32_e32 vcc, s62, v130
	s_barrier
	s_and_saveexec_b64 s[46:47], vcc
	s_cbranch_execz .LBB0_1245
	s_barrier
	s_branch .LBB0_1245

; #define STAGE(P, BASE, LD, br, kt) do { const char* _g = (const char*)((BASE) + (size_t)(br) * (LD) + (size_t)(kt) * 64); \
;     for (int _i = 0; _i < 2; ++_i) { int _b = tidx * 16 + _i * 8192; int _r, _c; stage_rc(_b, _r, _c); \
;       __builtin_amdgcn_global_load_lds((const unsigned*)(_g + (unsigned)((_r * (LD) + _c) * 2)), (unsigned*)((char*)(P) + _b), 16, 0, 0); } } while (0)
; #define LDA(dst, b, h) for (int m = 0; m < 4; ++m) for (int k = 0; k < 2; ++k) \
;     dst[m][k] = *reinterpret_cast<const bf16x8*>((char*)SA(b, h) + lds_byte(wr * 64 + m * 16 + fr, k * 32 + fq * 8))
; #define LDB(dst, b, h) for (int n = 0; n < 2; ++n) for (int k = 0; k < 2; ++k) \
;     dst[n][k] = *reinterpret_cast<const bf16x8*>((char*)SB(b, h) + lds_byte(wc * 32 + n * 16 + fr, k * 32 + fq * 8))
; #define MMA(ai, bj, At_, Bt_) do { __builtin_amdgcn_s_setprio(1); \
;     for (int k = 0; k < 2; ++k) for (int m = 0; m < 4; ++m) for (int n = 0; n < 2; ++n) \
;       acc[ai][bj][m][n] = __builtin_amdgcn_mfma_f32_16x16x32_bf16(At_[m][k], Bt_[n][k], acc[ai][bj][m][n], 0, 0, 0); \
;     __builtin_amdgcn_s_setprio(0); } while (0)
; #define WAIT_V(n) asm volatile("s_waitcnt vmcnt(" #n ")" ::: "memory")
; #define WAIT_L(n) asm volatile("s_waitcnt lgkmcnt(" #n ")" ::: "memory")
; #define BAR __builtin_amdgcn_s_barrier()
; #define SCHED __builtin_amdgcn_sched_barrier(0)
; template <int EPI, int lda, int ldb, int N, int K>
; __device__ __forceinline__ void gemm_phase(const u16* __restrict__ A, const u16* __restrict__ Bt, const GemmEpi ep, int wv) {
;     ...
;     if (wr == 1) BAR;
;     WAIT_V(4); BAR;
;     STAGE(SB(1, 0), Bt, ldb, bcol, 1); STAGE(SA(1, 0), Ab, lda, brow, 1); STAGE(SB(1, 1), Bt, ldb, bcol + HALF, 1);
;     WAIT_V(6); BAR;
;     for (int t = 0; t < nt - 2; t += 2) {
;       LDB(B0, 0, 0); SCHED; LDA(At, 0, 0); STAGE(SA(1, 1), Ab, lda, brow + HALF, t + 1);
;       WAIT_L(8); BAR; WAIT_L(0); MMA(0, 0, At, B0); BAR; SCHED;
;       LDB(B1, 0, 1); STAGE(SB(0, 0), Bt, ldb, bcol, t + 2);
;       BAR; WAIT_L(0); MMA(0, 1, At, B1); BAR;
;       LDA(At, 0, 1); STAGE(SA(0, 0), Ab, lda, brow, t + 2);
.LBB0_1349:
	s_or_b64 exec, exec, s[54:55]
	v_mov_b32_e32 v1, v129
	v_add_u32_e32 v7, s58, v6
	v_lshl_add_u64 v[12:13], s[46:47], 0, v[128:129]
	v_lshl_add_u64 v[14:15], s[46:47], 0, v[0:1]
	v_lshl_add_u64 v[2:3], s[52:53], 0, v[128:129]
	v_lshl_add_u64 v[0:1], s[52:53], 0, v[0:1]
	v_readfirstlane_b32 s53, v7
	v_add_u32_e32 v7, 0x2000, v7
	v_mov_b32_e32 v5, v129
	v_mov_b32_e32 v17, v129
	v_lshl_add_u64 v[26:27], v[12:13], 0, s[36:37]
	s_mov_b32 m0, s53
	v_readfirstlane_b32 s52, v7
	v_add_u32_e32 v7, 0x8000, v23
	v_lshl_add_u64 v[8:9], s[50:51], 0, v[4:5]
	v_lshl_add_u64 v[10:11], s[50:51], 0, v[16:17]
	s_waitcnt vmcnt(4)
	s_barrier
	global_load_lds_dwordx4 v[26:27], off
	v_lshl_add_u64 v[26:27], v[14:15], 0, s[36:37]
	s_mov_b32 m0, s52
	v_readfirstlane_b32 s51, v7
	v_add_u32_e32 v7, 0xa000, v23
	global_load_lds_dwordx4 v[26:27], off
	v_lshl_add_u64 v[26:27], v[8:9], 0, s[36:37]
	s_mov_b32 m0, s51
	v_readfirstlane_b32 s50, v7
	v_add_u32_e32 v25, s59, v6
	global_load_lds_dwordx4 v[26:27], off
	v_lshl_add_u64 v[26:27], v[10:11], 0, s[36:37]
	s_mov_b32 m0, s50
	v_readfirstlane_b32 s11, v25
	v_add_u32_e32 v25, 0x2000, v25
	global_load_lds_dwordx4 v[26:27], off
	v_lshl_add_u64 v[26:27], v[2:3], 0, s[36:37]
	s_mov_b32 m0, s11
	v_readfirstlane_b32 s5, v25
	global_load_lds_dwordx4 v[26:27], off
	v_lshl_add_u64 v[6:7], v[0:1], 0, s[36:37]
	s_mov_b32 m0, s5
	v_and_b32_e32 v132, 15, v20
	global_load_lds_dwordx4 v[6:7], off
	v_bfe_u32 v128, v20, 4, 2
	v_lshlrev_b32_e32 v7, 2, v20
	v_bfe_u32 v131, v130, 6, 2
	v_lshlrev_b32_e32 v25, 4, v128
	v_lshlrev_b32_e32 v6, 6, v132
	v_and_b32_e32 v50, 32, v7
	v_lshlrev_b32_e32 v126, 12, v131
	v_bitop3_b32 v127, v25, v50, v6 bitop3:0x36
	v_add3_u32 v133, s56, v127, v126
	s_waitcnt vmcnt(6)
	s_barrier
	ds_read_b128 v[26:29], v133
	ds_read_b128 v[30:33], v133 offset:1024
	ds_read_b128 v[34:37], v133 offset:2048
	ds_read_b128 v[38:41], v133 offset:3072
	v_lshl_add_u64 v[6:7], s[48:49], 0, v[4:5]
	v_lshl_add_u64 v[4:5], s[48:49], 0, v[16:17]
	v_lshlrev_b32_e32 v17, 6, v20
	v_and_b32_e32 v17, 0x3c0, v17
	v_add_u32_e32 v20, 0xc000, v23
	v_lshlrev_b32_e32 v16, 13, v139
	v_bitop3_b32 v17, v17, v50, v25 bitop3:0x36
	v_readfirstlane_b32 s47, v20
	v_add_u32_e32 v20, 0xe000, v23
	v_add3_u32 v228, 0, v127, v16
	v_add3_u32 v229, 0, v17, v16
	v_lshl_add_u64 v[16:17], v[6:7], 0, s[36:37]
	s_mov_b32 m0, s47
	v_readfirstlane_b32 s46, v20
	ds_read_b128 v[42:45], v228
	ds_read_b128 v[46:49], v228 offset:1024
	ds_read_b128 v[50:53], v229 offset:2048
	ds_read_b128 v[54:57], v229 offset:3072
	ds_read_b128 v[58:61], v229 offset:4096
	ds_read_b128 v[62:65], v229 offset:5120
	ds_read_b128 v[66:69], v229 offset:6144
	ds_read_b128 v[70:73], v229 offset:7168
	global_load_lds_dwordx4 v[16:17], off
	v_lshl_add_u64 v[16:17], v[4:5], 0, s[36:37]
	s_mov_b32 m0, s46
	s_nop 0
	global_load_lds_dwordx4 v[16:17], off
	s_waitcnt lgkmcnt(8)
	s_barrier
	s_waitcnt lgkmcnt(0)
	s_setprio 0
	s_waitcnt lgkmcnt(0)
	v_mfma_f32_16x16x32_bf16 v[74:77], v[42:45], v[26:29], 0
	v_mfma_f32_16x16x32_bf16 v[78:81], v[42:45], v[34:37], 0
	v_mfma_f32_16x16x32_bf16 v[82:85], v[50:53], v[26:29], 0
	v_mfma_f32_16x16x32_bf16 v[86:89], v[50:53], v[34:37], 0
	v_mfma_f32_16x16x32_bf16 v[90:93], v[58:61], v[26:29], 0
	v_mfma_f32_16x16x32_bf16 v[94:97], v[58:61], v[34:37], 0
	v_mfma_f32_16x16x32_bf16 v[98:101], v[66:69], v[26:29], 0
	v_mfma_f32_16x16x32_bf16 v[102:105], v[66:69], v[34:37], 0
	v_mfma_f32_16x16x32_bf16 v[74:77], v[46:49], v[30:33], v[74:77]
	v_mfma_f32_16x16x32_bf16 v[78:81], v[46:49], v[38:41], v[78:81]
	v_mfma_f32_16x16x32_bf16 v[82:85], v[54:57], v[30:33], v[82:85]
	v_mfma_f32_16x16x32_bf16 v[86:89], v[54:57], v[38:41], v[86:89]
	v_mfma_f32_16x16x32_bf16 v[90:93], v[62:65], v[30:33], v[90:93]
	v_mfma_f32_16x16x32_bf16 v[94:97], v[62:65], v[38:41], v[94:97]
	v_mfma_f32_16x16x32_bf16 v[98:101], v[70:73], v[30:33], v[98:101]
	v_mfma_f32_16x16x32_bf16 v[102:105], v[70:73], v[38:41], v[102:105]
	s_setprio 0
	s_barrier
	v_readfirstlane_b32 s48, v21
	v_add_u32_e32 v20, 0x2000, v21
	v_add3_u32 v224, s57, v127, v126
	v_lshl_add_u64 v[16:17], v[12:13], 0, s[38:39]
	s_mov_b32 m0, s48
	v_readfirstlane_b32 s48, v20
	ds_read_b128 v[106:109], v224
	ds_read_b128 v[110:113], v224 offset:1024
	ds_read_b128 v[114:117], v224 offset:2048
	ds_read_b128 v[118:121], v224 offset:3072
	global_load_lds_dwordx4 v[16:17], off
	v_lshl_add_u64 v[16:17], v[14:15], 0, s[38:39]
	s_mov_b32 m0, s48
	s_nop 0
	global_load_lds_dwordx4 v[16:17], off
	s_barrier
	s_waitcnt lgkmcnt(0)
	s_setprio 0
	s_waitcnt lgkmcnt(0)
	v_mfma_f32_16x16x32_bf16 v[122:125], v[42:45], v[106:109], 0
	v_mfma_f32_16x16x32_bf16 v[42:45], v[42:45], v[114:117], 0
	v_mfma_f32_16x16x32_bf16 v[140:143], v[50:53], v[106:109], 0
	v_mfma_f32_16x16x32_bf16 v[50:53], v[50:53], v[114:117], 0
	v_mfma_f32_16x16x32_bf16 v[144:147], v[58:61], v[106:109], 0
	v_mfma_f32_16x16x32_bf16 v[58:61], v[58:61], v[114:117], 0
	v_mfma_f32_16x16x32_bf16 v[148:151], v[66:69], v[106:109], 0
	v_mfma_f32_16x16x32_bf16 v[66:69], v[66:69], v[114:117], 0
	v_mfma_f32_16x16x32_bf16 v[122:125], v[46:49], v[110:113], v[122:125]
	v_mfma_f32_16x16x32_bf16 v[42:45], v[46:49], v[118:121], v[42:45]
	v_mfma_f32_16x16x32_bf16 v[46:49], v[54:57], v[110:113], v[140:143]
	v_mfma_f32_16x16x32_bf16 v[50:53], v[54:57], v[118:121], v[50:53]
	v_mfma_f32_16x16x32_bf16 v[54:57], v[62:65], v[110:113], v[144:147]
	v_mfma_f32_16x16x32_bf16 v[58:61], v[62:65], v[118:121], v[58:61]
	v_mfma_f32_16x16x32_bf16 v[62:65], v[70:73], v[110:113], v[148:151]
	v_mfma_f32_16x16x32_bf16 v[66:69], v[70:73], v[118:121], v[66:69]
	s_setprio 0
	v_readfirstlane_b32 s48, v23
	v_lshl_add_u64 v[16:17], v[8:9], 0, s[38:39]
	s_mov_b32 m0, s48
	v_readfirstlane_b32 s48, v24
	s_barrier
; #define STAGE(P, BASE, LD, br, kt) do { const char* _g = (const char*)((BASE) + (size_t)(br) * (LD) + (size_t)(kt) * 64); \
;     for (int _i = 0; _i < 2; ++_i) { int _b = tidx * 16 + _i * 8192; int _r, _c; stage_rc(_b, _r, _c); \
;       __builtin_amdgcn_global_load_lds((const unsigned*)(_g + (unsigned)((_r * (LD) + _c) * 2)), (unsigned*)((char*)(P) + _b), 16, 0, 0); } } while (0)
; #define LDA(dst, b, h) for (int m = 0; m < 4; ++m) for (int k = 0; k < 2; ++k) \
;     dst[m][k] = *reinterpret_cast<const bf16x8*>((char*)SA(b, h) + lds_byte(wr * 64 + m * 16 + fr, k * 32 + fq * 8))
; #define LDB(dst, b, h) for (int n = 0; n < 2; ++n) for (int k = 0; k < 2; ++k) \
;     dst[n][k] = *reinterpret_cast<const bf16x8*>((char*)SB(b, h) + lds_byte(wc * 32 + n * 16 + fr, k * 32 + fq * 8))
; #define MMA(ai, bj, At_, Bt_) do { __builtin_amdgcn_s_setprio(1); \
;     for (int k = 0; k < 2; ++k) for (int m = 0; m < 4; ++m) for (int n = 0; n < 2; ++n) \
;       acc[ai][bj][m][n] = __builtin_amdgcn_mfma_f32_16x16x32_bf16(At_[m][k], Bt_[n][k], acc[ai][bj][m][n], 0, 0, 0); \
;     __builtin_amdgcn_s_setprio(0); } while (0)
; #define WAIT_V(n) asm volatile("s_waitcnt vmcnt(" #n ")" ::: "memory")
; #define WAIT_L(n) asm volatile("s_waitcnt lgkmcnt(" #n ")" ::: "memory")
; #define BAR __builtin_amdgcn_s_barrier()
; #define SCHED __builtin_amdgcn_sched_barrier(0)
; template <int EPI, int lda, int ldb, int N, int K>
; __device__ __forceinline__ void gemm_phase(const u16* __restrict__ A, const u16* __restrict__ Bt, const GemmEpi ep, int wv) {
;     ...
;       LDA(At, 0, 1); STAGE(SA(0, 0), Ab, lda, brow, t + 2);
;       BAR; WAIT_L(0); MMA(1, 0, At, B0); BAR; SCHED;
;       STAGE(SB(0, 1), Bt, ldb, bcol + HALF, t + 2);
;       WAIT_V(6); BAR; MMA(1, 1, At, B1); BAR;
;       LDB(B0, 1, 0); SCHED; LDA(At, 1, 0); STAGE(SA(0, 1), Ab, lda, brow + HALF, t + 2);
;       WAIT_L(8); BAR; WAIT_L(0); MMA(0, 0, At, B0); BAR; SCHED;
;       LDB(B1, 1, 1); STAGE(SB(1, 0), Bt, ldb, bcol, t + 3);
	ds_read_b128 v[70:73], v228 offset:16384
	ds_read_b128 v[140:143], v228 offset:17408
	ds_read_b128 v[144:147], v229 offset:18432
	ds_read_b128 v[148:151], v229 offset:19456
	ds_read_b128 v[152:155], v229 offset:20480
	ds_read_b128 v[156:159], v229 offset:21504
	ds_read_b128 v[160:163], v229 offset:22528
	ds_read_b128 v[164:167], v229 offset:23552
	global_load_lds_dwordx4 v[16:17], off
	v_lshl_add_u64 v[16:17], v[10:11], 0, s[38:39]
	s_mov_b32 m0, s48
	s_nop 0
	global_load_lds_dwordx4 v[16:17], off
	s_barrier
	s_waitcnt lgkmcnt(0)
	s_setprio 0
	s_waitcnt lgkmcnt(0)
	v_mfma_f32_16x16x32_bf16 v[168:171], v[70:73], v[26:29], 0
	v_mfma_f32_16x16x32_bf16 v[172:175], v[70:73], v[34:37], 0
	v_mfma_f32_16x16x32_bf16 v[176:179], v[144:147], v[26:29], 0
	v_mfma_f32_16x16x32_bf16 v[180:183], v[144:147], v[34:37], 0
	v_mfma_f32_16x16x32_bf16 v[184:187], v[152:155], v[26:29], 0
	v_mfma_f32_16x16x32_bf16 v[188:191], v[152:155], v[34:37], 0
	v_mfma_f32_16x16x32_bf16 v[24:27], v[160:163], v[26:29], 0
	v_mfma_f32_16x16x32_bf16 v[34:37], v[160:163], v[34:37], 0
	v_mfma_f32_16x16x32_bf16 v[168:171], v[140:143], v[30:33], v[168:171]
	v_mfma_f32_16x16x32_bf16 v[176:179], v[148:151], v[30:33], v[176:179]
	v_mfma_f32_16x16x32_bf16 v[184:187], v[156:159], v[30:33], v[184:187]
	v_mfma_f32_16x16x32_bf16 v[24:27], v[164:167], v[30:33], v[24:27]
	v_mfma_f32_16x16x32_bf16 v[28:31], v[164:167], v[38:41], v[34:37]
	v_mfma_f32_16x16x32_bf16 v[172:175], v[140:143], v[38:41], v[172:175]
	v_mfma_f32_16x16x32_bf16 v[180:183], v[148:151], v[38:41], v[180:183]
	v_mfma_f32_16x16x32_bf16 v[188:191], v[156:159], v[38:41], v[188:191]
	s_setprio 0
	s_barrier
	v_readfirstlane_b32 s48, v22
	v_add_u32_e32 v20, 0x2000, v22
	v_lshl_add_u64 v[16:17], v[2:3], 0, s[38:39]
	s_mov_b32 m0, s48
	v_readfirstlane_b32 s48, v20
	global_load_lds_dwordx4 v[16:17], off
	v_lshl_add_u64 v[16:17], v[0:1], 0, s[38:39]
	s_mov_b32 m0, s48
	s_nop 0
	global_load_lds_dwordx4 v[16:17], off
	s_waitcnt vmcnt(6)
	s_barrier
	s_setprio 0
	v_mfma_f32_16x16x32_bf16 v[20:23], v[70:73], v[106:109], 0
	v_mfma_f32_16x16x32_bf16 v[32:35], v[70:73], v[114:117], 0
	v_mfma_f32_16x16x32_bf16 v[36:39], v[144:147], v[106:109], 0
	v_mfma_f32_16x16x32_bf16 v[70:73], v[144:147], v[114:117], 0
	v_mfma_f32_16x16x32_bf16 v[144:147], v[152:155], v[106:109], 0
	v_mfma_f32_16x16x32_bf16 v[152:155], v[152:155], v[114:117], 0
	v_mfma_f32_16x16x32_bf16 v[106:109], v[160:163], v[106:109], 0
	v_mfma_f32_16x16x32_bf16 v[114:117], v[160:163], v[114:117], 0
	v_mfma_f32_16x16x32_bf16 v[20:23], v[140:143], v[110:113], v[20:23]
	v_mfma_f32_16x16x32_bf16 v[32:35], v[140:143], v[118:121], v[32:35]
	v_mfma_f32_16x16x32_bf16 v[36:39], v[148:151], v[110:113], v[36:39]
	v_mfma_f32_16x16x32_bf16 v[70:73], v[148:151], v[118:121], v[70:73]
	v_mfma_f32_16x16x32_bf16 v[140:143], v[156:159], v[110:113], v[144:147]
	v_mfma_f32_16x16x32_bf16 v[106:109], v[164:167], v[110:113], v[106:109]
	v_mfma_f32_16x16x32_bf16 v[110:113], v[164:167], v[118:121], v[114:117]
	v_mfma_f32_16x16x32_bf16 v[144:147], v[156:159], v[118:121], v[152:155]
	s_setprio 0
	v_add3_u32 v225, s58, v127, v126
	s_barrier
	ds_read_b128 v[114:117], v225
	ds_read_b128 v[118:121], v225 offset:1024
	ds_read_b128 v[148:151], v225 offset:2048
	ds_read_b128 v[152:155], v225 offset:3072
	v_readfirstlane_b32 s48, v18
	v_lshl_add_u64 v[16:17], v[6:7], 0, s[38:39]
	s_mov_b32 m0, s48
	v_readfirstlane_b32 s48, v19
	ds_read_b128 v[156:159], v228 offset:32768
	ds_read_b128 v[160:163], v228 offset:33792
	ds_read_b128 v[164:167], v229 offset:34816
	ds_read_b128 v[192:195], v229 offset:35840
	ds_read_b128 v[196:199], v229 offset:36864
	ds_read_b128 v[200:203], v229 offset:37888
	ds_read_b128 v[204:207], v229 offset:38912
	ds_read_b128 v[208:211], v229 offset:39936
	global_load_lds_dwordx4 v[16:17], off
	v_lshl_add_u64 v[16:17], v[4:5], 0, s[38:39]
	s_mov_b32 m0, s48
	s_nop 0
	global_load_lds_dwordx4 v[16:17], off
	s_waitcnt lgkmcnt(8)
	s_barrier
	s_waitcnt lgkmcnt(0)
	s_setprio 0
	s_waitcnt lgkmcnt(0)
	v_mfma_f32_16x16x32_bf16 v[16:19], v[156:159], v[114:117], v[74:77]
	v_mfma_f32_16x16x32_bf16 v[74:77], v[156:159], v[148:151], v[78:81]
	v_mfma_f32_16x16x32_bf16 v[78:81], v[164:167], v[114:117], v[82:85]
	v_mfma_f32_16x16x32_bf16 v[82:85], v[164:167], v[148:151], v[86:89]
	v_mfma_f32_16x16x32_bf16 v[86:89], v[196:199], v[114:117], v[90:93]
	v_mfma_f32_16x16x32_bf16 v[90:93], v[196:199], v[148:151], v[94:97]
	v_mfma_f32_16x16x32_bf16 v[94:97], v[204:207], v[114:117], v[98:101]
	v_mfma_f32_16x16x32_bf16 v[98:101], v[204:207], v[148:151], v[102:105]
	v_mfma_f32_16x16x32_bf16 v[16:19], v[160:163], v[118:121], v[16:19]
	v_mfma_f32_16x16x32_bf16 v[74:77], v[160:163], v[152:155], v[74:77]
	v_mfma_f32_16x16x32_bf16 v[78:81], v[192:195], v[118:121], v[78:81]
	v_mfma_f32_16x16x32_bf16 v[82:85], v[192:195], v[152:155], v[82:85]
	v_mfma_f32_16x16x32_bf16 v[86:89], v[200:203], v[118:121], v[86:89]
	v_mfma_f32_16x16x32_bf16 v[90:93], v[200:203], v[152:155], v[90:93]
	v_mfma_f32_16x16x32_bf16 v[94:97], v[208:211], v[118:121], v[94:97]
	v_mfma_f32_16x16x32_bf16 v[98:101], v[208:211], v[152:155], v[98:101]
	s_setprio 0
	s_barrier
	s_mov_b32 m0, s53
	v_add3_u32 v226, s59, v127, v126
	v_lshl_add_u64 v[12:13], v[12:13], 0, s[40:41]
	ds_read_b128 v[102:105], v226
	ds_read_b128 v[212:215], v226 offset:1024
	ds_read_b128 v[216:219], v226 offset:2048
	ds_read_b128 v[220:223], v226 offset:3072
	global_load_lds_dwordx4 v[12:13], off
	v_lshl_add_u64 v[12:13], v[14:15], 0, s[40:41]
	s_mov_b32 m0, s52
	s_nop 0
	global_load_lds_dwordx4 v[12:13], off
	s_barrier
; #define STAGE(P, BASE, LD, br, kt) do { const char* _g = (const char*)((BASE) + (size_t)(br) * (LD) + (size_t)(kt) * 64); \
;     for (int _i = 0; _i < 2; ++_i) { int _b = tidx * 16 + _i * 8192; int _r, _c; stage_rc(_b, _r, _c); \
;       __builtin_amdgcn_global_load_lds((const unsigned*)(_g + (unsigned)((_r * (LD) + _c) * 2)), (unsigned*)((char*)(P) + _b), 16, 0, 0); } } while (0)
; #define LDA(dst, b, h) for (int m = 0; m < 4; ++m) for (int k = 0; k < 2; ++k) \
;     dst[m][k] = *reinterpret_cast<const bf16x8*>((char*)SA(b, h) + lds_byte(wr * 64 + m * 16 + fr, k * 32 + fq * 8))
; #define LDB(dst, b, h) for (int n = 0; n < 2; ++n) for (int k = 0; k < 2; ++k) \
;     dst[n][k] = *reinterpret_cast<const bf16x8*>((char*)SB(b, h) + lds_byte(wc * 32 + n * 16 + fr, k * 32 + fq * 8))
; #define MMA(ai, bj, At_, Bt_) do { __builtin_amdgcn_s_setprio(1); \
;     for (int k = 0; k < 2; ++k) for (int m = 0; m < 4; ++m) for (int n = 0; n < 2; ++n) \
;       acc[ai][bj][m][n] = __builtin_amdgcn_mfma_f32_16x16x32_bf16(At_[m][k], Bt_[n][k], acc[ai][bj][m][n], 0, 0, 0); \
;     __builtin_amdgcn_s_setprio(0); } while (0)
; #define WAIT_V(n) asm volatile("s_waitcnt vmcnt(" #n ")" ::: "memory")
; #define WAIT_L(n) asm volatile("s_waitcnt lgkmcnt(" #n ")" ::: "memory")
; #define BAR __builtin_amdgcn_s_barrier()
; #define SCHED __builtin_amdgcn_sched_barrier(0)
; template <int EPI, int lda, int ldb, int N, int K>
; __device__ __forceinline__ void gemm_phase(const u16* __restrict__ A, const u16* __restrict__ Bt, const GemmEpi ep, int wv) {
;     ...
;       BAR; WAIT_L(0); MMA(0, 1, At, B1); BAR;
;       LDA(At, 1, 1); STAGE(SA(1, 0), Ab, lda, brow, t + 3);
;       BAR; WAIT_L(0); MMA(1, 0, At, B0); BAR; SCHED;
;       STAGE(SB(1, 1), Bt, ldb, bcol + HALF, t + 3);
;       WAIT_V(6); BAR; MMA(1, 1, At, B1); BAR;
;     }
;     { LDB(B0, 0, 0); LDA(At, 0, 0); STAGE(SA(1, 1), Ab, lda, brow + HALF, nt - 1);
	s_waitcnt lgkmcnt(0)
	s_setprio 0
	s_waitcnt lgkmcnt(0)
	v_mfma_f32_16x16x32_bf16 v[12:15], v[156:159], v[102:105], v[122:125]
	v_mfma_f32_16x16x32_bf16 v[40:43], v[156:159], v[216:219], v[42:45]
	v_mfma_f32_16x16x32_bf16 v[44:47], v[164:167], v[102:105], v[46:49]
	v_mfma_f32_16x16x32_bf16 v[48:51], v[164:167], v[216:219], v[50:53]
	v_mfma_f32_16x16x32_bf16 v[52:55], v[196:199], v[102:105], v[54:57]
	v_mfma_f32_16x16x32_bf16 v[56:59], v[196:199], v[216:219], v[58:61]
	v_mfma_f32_16x16x32_bf16 v[60:63], v[204:207], v[102:105], v[62:65]
	v_mfma_f32_16x16x32_bf16 v[64:67], v[204:207], v[216:219], v[66:69]
	v_mfma_f32_16x16x32_bf16 v[12:15], v[160:163], v[212:215], v[12:15]
	v_mfma_f32_16x16x32_bf16 v[40:43], v[160:163], v[220:223], v[40:43]
	v_mfma_f32_16x16x32_bf16 v[44:47], v[192:195], v[212:215], v[44:47]
	v_mfma_f32_16x16x32_bf16 v[48:51], v[192:195], v[220:223], v[48:51]
	v_mfma_f32_16x16x32_bf16 v[52:55], v[200:203], v[212:215], v[52:55]
	v_mfma_f32_16x16x32_bf16 v[56:59], v[200:203], v[220:223], v[56:59]
	v_mfma_f32_16x16x32_bf16 v[60:63], v[208:211], v[212:215], v[60:63]
	v_mfma_f32_16x16x32_bf16 v[64:67], v[208:211], v[220:223], v[64:67]
	s_setprio 0
	s_mov_b32 m0, s51
	v_lshl_add_u64 v[8:9], v[8:9], 0, s[40:41]
	s_barrier
	ds_read_b128 v[122:125], v228 offset:49152
	ds_read_b128 v[156:159], v228 offset:50176
	ds_read_b128 v[160:163], v229 offset:51200
	ds_read_b128 v[164:167], v229 offset:52224
	ds_read_b128 v[192:195], v229 offset:53248
	ds_read_b128 v[196:199], v229 offset:54272
	ds_read_b128 v[200:203], v229 offset:55296
	ds_read_b128 v[204:207], v229 offset:56320
	global_load_lds_dwordx4 v[8:9], off
	v_lshl_add_u64 v[8:9], v[10:11], 0, s[40:41]
	s_mov_b32 m0, s50
	s_nop 0
	global_load_lds_dwordx4 v[8:9], off
	s_barrier
	s_waitcnt lgkmcnt(0)
	s_setprio 0
	s_waitcnt lgkmcnt(0)
	v_mfma_f32_16x16x32_bf16 v[8:11], v[122:125], v[114:117], v[168:171]
	v_mfma_f32_16x16x32_bf16 v[168:171], v[122:125], v[148:151], v[172:175]
	v_mfma_f32_16x16x32_bf16 v[24:27], v[200:203], v[114:117], v[24:27]
	v_mfma_f32_16x16x32_bf16 v[28:31], v[200:203], v[148:151], v[28:31]
	v_mfma_f32_16x16x32_bf16 v[172:175], v[160:163], v[114:117], v[176:179]
	v_mfma_f32_16x16x32_bf16 v[176:179], v[160:163], v[148:151], v[180:183]
	v_mfma_f32_16x16x32_bf16 v[180:183], v[192:195], v[114:117], v[184:187]
	v_mfma_f32_16x16x32_bf16 v[184:187], v[192:195], v[148:151], v[188:191]
	v_mfma_f32_16x16x32_bf16 v[8:11], v[156:159], v[118:121], v[8:11]
	v_mfma_f32_16x16x32_bf16 v[114:117], v[156:159], v[152:155], v[168:171]
	v_mfma_f32_16x16x32_bf16 v[24:27], v[204:207], v[118:121], v[24:27]
	v_mfma_f32_16x16x32_bf16 v[28:31], v[204:207], v[152:155], v[28:31]
	v_mfma_f32_16x16x32_bf16 v[148:151], v[164:167], v[118:121], v[172:175]
	v_mfma_f32_16x16x32_bf16 v[168:171], v[164:167], v[152:155], v[176:179]
	v_mfma_f32_16x16x32_bf16 v[172:175], v[196:199], v[118:121], v[180:183]
	v_mfma_f32_16x16x32_bf16 v[176:179], v[196:199], v[152:155], v[184:187]
	s_setprio 0
	s_barrier
	s_mov_b32 m0, s11
	v_lshl_add_u64 v[2:3], v[2:3], 0, s[40:41]
	global_load_lds_dwordx4 v[2:3], off
	v_lshl_add_u64 v[0:1], v[0:1], 0, s[40:41]
	s_mov_b32 m0, s5
	s_nop 0
	global_load_lds_dwordx4 v[0:1], off
	s_waitcnt vmcnt(6)
	s_barrier
	s_setprio 0
	v_mfma_f32_16x16x32_bf16 v[0:3], v[122:125], v[102:105], v[20:23]
	v_mfma_f32_16x16x32_bf16 v[20:23], v[122:125], v[216:219], v[32:35]
	v_mfma_f32_16x16x32_bf16 v[32:35], v[160:163], v[102:105], v[36:39]
	v_mfma_f32_16x16x32_bf16 v[36:39], v[160:163], v[216:219], v[70:73]
	v_mfma_f32_16x16x32_bf16 v[68:71], v[192:195], v[102:105], v[140:143]
	v_mfma_f32_16x16x32_bf16 v[118:121], v[192:195], v[216:219], v[144:147]
	v_mfma_f32_16x16x32_bf16 v[102:105], v[200:203], v[102:105], v[106:109]
	v_mfma_f32_16x16x32_bf16 v[106:109], v[200:203], v[216:219], v[110:113]
	v_mfma_f32_16x16x32_bf16 v[0:3], v[156:159], v[212:215], v[0:3]
	v_mfma_f32_16x16x32_bf16 v[20:23], v[156:159], v[220:223], v[20:23]
	v_mfma_f32_16x16x32_bf16 v[32:35], v[164:167], v[212:215], v[32:35]
	v_mfma_f32_16x16x32_bf16 v[36:39], v[164:167], v[220:223], v[36:39]
	v_mfma_f32_16x16x32_bf16 v[68:71], v[196:199], v[212:215], v[68:71]
	v_mfma_f32_16x16x32_bf16 v[110:113], v[196:199], v[220:223], v[118:121]
	v_mfma_f32_16x16x32_bf16 v[102:105], v[204:207], v[212:215], v[102:105]
	v_mfma_f32_16x16x32_bf16 v[106:109], v[204:207], v[220:223], v[106:109]
	s_setprio 0
	s_mov_b32 m0, s47
	v_lshl_add_u64 v[6:7], v[6:7], 0, s[40:41]
	s_barrier
	ds_read_b128 v[118:121], v133
	ds_read_b128 v[122:125], v133 offset:1024
	ds_read_b128 v[140:143], v133 offset:2048
	ds_read_b128 v[144:147], v133 offset:3072
	ds_read_b128 v[152:155], v228
	ds_read_b128 v[156:159], v228 offset:1024
	ds_read_b128 v[160:163], v229 offset:2048
	ds_read_b128 v[164:167], v229 offset:3072
	ds_read_b128 v[180:183], v229 offset:4096
	ds_read_b128 v[184:187], v229 offset:5120
	ds_read_b128 v[188:191], v229 offset:6144
	ds_read_b128 v[192:195], v229 offset:7168
	global_load_lds_dwordx4 v[6:7], off
	v_lshl_add_u64 v[4:5], v[4:5], 0, s[40:41]
	s_mov_b32 m0, s46
	s_nop 0
	global_load_lds_dwordx4 v[4:5], off
	s_barrier
; #define LDA(dst, b, h) for (int m = 0; m < 4; ++m) for (int k = 0; k < 2; ++k) \
;     dst[m][k] = *reinterpret_cast<const bf16x8*>((char*)SA(b, h) + lds_byte(wr * 64 + m * 16 + fr, k * 32 + fq * 8))
; #define LDB(dst, b, h) for (int n = 0; n < 2; ++n) for (int k = 0; k < 2; ++k) \
;     dst[n][k] = *reinterpret_cast<const bf16x8*>((char*)SB(b, h) + lds_byte(wc * 32 + n * 16 + fr, k * 32 + fq * 8))
; #define MMA(ai, bj, At_, Bt_) do { __builtin_amdgcn_s_setprio(1); \
;     for (int k = 0; k < 2; ++k) for (int m = 0; m < 4; ++m) for (int n = 0; n < 2; ++n) \
;       acc[ai][bj][m][n] = __builtin_amdgcn_mfma_f32_16x16x32_bf16(At_[m][k], Bt_[n][k], acc[ai][bj][m][n], 0, 0, 0); \
;     __builtin_amdgcn_s_setprio(0); } while (0)
; #define WAIT_V(n) asm volatile("s_waitcnt vmcnt(" #n ")" ::: "memory")
; #define WAIT_L(n) asm volatile("s_waitcnt lgkmcnt(" #n ")" ::: "memory")
; #define BAR __builtin_amdgcn_s_barrier()
; template <int EPI, int lda, int ldb, int N, int K>
; __device__ __forceinline__ void gemm_phase(const u16* __restrict__ A, const u16* __restrict__ Bt, const GemmEpi ep, int wv) {
;     ...
;       BAR; WAIT_L(0); MMA(0, 0, At, B0); BAR;
;       LDB(B1, 0, 1); BAR; WAIT_L(0); MMA(0, 1, At, B1); BAR;
;       LDA(At, 0, 1); WAIT_V(4); BAR; WAIT_L(0); MMA(1, 0, At, B0); MMA(1, 1, At, B1); BAR; }
;     { LDB(B0, 1, 0); LDA(At, 1, 0); WAIT_V(2); BAR; WAIT_L(0); MMA(0, 0, At, B0); BAR;
	s_waitcnt lgkmcnt(0)
	s_setprio 0
	s_waitcnt lgkmcnt(0)
	v_mfma_f32_16x16x32_bf16 v[4:7], v[152:155], v[118:121], v[16:19]
	v_mfma_f32_16x16x32_bf16 v[16:19], v[152:155], v[140:143], v[74:77]
	v_mfma_f32_16x16x32_bf16 v[72:75], v[160:163], v[118:121], v[78:81]
	v_mfma_f32_16x16x32_bf16 v[76:79], v[160:163], v[140:143], v[82:85]
	v_mfma_f32_16x16x32_bf16 v[80:83], v[180:183], v[118:121], v[86:89]
	v_mfma_f32_16x16x32_bf16 v[84:87], v[180:183], v[140:143], v[90:93]
	v_mfma_f32_16x16x32_bf16 v[88:91], v[188:191], v[118:121], v[94:97]
	v_mfma_f32_16x16x32_bf16 v[92:95], v[188:191], v[140:143], v[98:101]
	v_mfma_f32_16x16x32_bf16 v[4:7], v[156:159], v[122:125], v[4:7]
	v_mfma_f32_16x16x32_bf16 v[16:19], v[156:159], v[144:147], v[16:19]
	v_mfma_f32_16x16x32_bf16 v[72:75], v[164:167], v[122:125], v[72:75]
	v_mfma_f32_16x16x32_bf16 v[76:79], v[164:167], v[144:147], v[76:79]
	v_mfma_f32_16x16x32_bf16 v[80:83], v[184:187], v[122:125], v[80:83]
	v_mfma_f32_16x16x32_bf16 v[84:87], v[184:187], v[144:147], v[84:87]
	v_mfma_f32_16x16x32_bf16 v[88:91], v[192:195], v[122:125], v[88:91]
	v_mfma_f32_16x16x32_bf16 v[92:95], v[192:195], v[144:147], v[92:95]
	s_setprio 0
	s_barrier
	ds_read_b128 v[96:99], v224
	ds_read_b128 v[196:199], v224 offset:1024
	ds_read_b128 v[200:203], v224 offset:2048
	ds_read_b128 v[204:207], v224 offset:3072
	s_barrier
	s_waitcnt lgkmcnt(0)
	s_setprio 0
	s_waitcnt lgkmcnt(0)
	v_mfma_f32_16x16x32_bf16 v[12:15], v[152:155], v[96:99], v[12:15]
	v_mfma_f32_16x16x32_bf16 v[40:43], v[152:155], v[200:203], v[40:43]
	v_mfma_f32_16x16x32_bf16 v[52:55], v[180:183], v[96:99], v[52:55]
	v_mfma_f32_16x16x32_bf16 v[56:59], v[180:183], v[200:203], v[56:59]
	v_mfma_f32_16x16x32_bf16 v[64:67], v[188:191], v[200:203], v[64:67]
	v_mfma_f32_16x16x32_bf16 v[44:47], v[160:163], v[96:99], v[44:47]
	v_mfma_f32_16x16x32_bf16 v[48:51], v[160:163], v[200:203], v[48:51]
	v_mfma_f32_16x16x32_bf16 v[60:63], v[188:191], v[96:99], v[60:63]
	v_mfma_f32_16x16x32_bf16 v[12:15], v[156:159], v[196:199], v[12:15]
	v_mfma_f32_16x16x32_bf16 v[40:43], v[156:159], v[204:207], v[40:43]
	v_mfma_f32_16x16x32_bf16 v[52:55], v[184:187], v[196:199], v[52:55]
	v_mfma_f32_16x16x32_bf16 v[56:59], v[184:187], v[204:207], v[56:59]
	v_mfma_f32_16x16x32_bf16 v[64:67], v[192:195], v[204:207], v[64:67]
	v_mfma_f32_16x16x32_bf16 v[152:155], v[164:167], v[196:199], v[44:47]
	v_mfma_f32_16x16x32_bf16 v[156:159], v[164:167], v[204:207], v[48:51]
	v_mfma_f32_16x16x32_bf16 v[160:163], v[192:195], v[196:199], v[60:63]
	s_setprio 0
	s_barrier
	ds_read_b128 v[44:47], v228 offset:16384
	ds_read_b128 v[48:51], v228 offset:17408
	ds_read_b128 v[60:63], v229 offset:18432
	ds_read_b128 v[164:167], v229 offset:19456
	ds_read_b128 v[180:183], v229 offset:20480
	ds_read_b128 v[184:187], v229 offset:21504
	ds_read_b128 v[188:191], v229 offset:22528
	ds_read_b128 v[192:195], v229 offset:23552
	s_waitcnt vmcnt(4)
	s_barrier
	s_waitcnt lgkmcnt(0)
	s_setprio 0
	s_waitcnt lgkmcnt(0)
	v_mfma_f32_16x16x32_bf16 v[8:11], v[44:47], v[118:121], v[8:11]
	v_mfma_f32_16x16x32_bf16 v[24:27], v[188:191], v[118:121], v[24:27]
	v_mfma_f32_16x16x32_bf16 v[28:31], v[188:191], v[140:143], v[28:31]
	v_mfma_f32_16x16x32_bf16 v[114:117], v[44:47], v[140:143], v[114:117]
	v_mfma_f32_16x16x32_bf16 v[148:151], v[60:63], v[118:121], v[148:151]
	v_mfma_f32_16x16x32_bf16 v[168:171], v[60:63], v[140:143], v[168:171]
	v_mfma_f32_16x16x32_bf16 v[172:175], v[180:183], v[118:121], v[172:175]
	v_mfma_f32_16x16x32_bf16 v[176:179], v[180:183], v[140:143], v[176:179]
	v_mfma_f32_16x16x32_bf16 v[8:11], v[48:51], v[122:125], v[8:11]
	v_mfma_f32_16x16x32_bf16 v[24:27], v[192:195], v[122:125], v[24:27]
	v_mfma_f32_16x16x32_bf16 v[28:31], v[192:195], v[144:147], v[28:31]
	v_mfma_f32_16x16x32_bf16 v[140:143], v[48:51], v[144:147], v[114:117]
	v_mfma_f32_16x16x32_bf16 v[148:151], v[164:167], v[122:125], v[148:151]
	v_mfma_f32_16x16x32_bf16 v[168:171], v[164:167], v[144:147], v[168:171]
	v_mfma_f32_16x16x32_bf16 v[172:175], v[184:187], v[122:125], v[172:175]
	v_mfma_f32_16x16x32_bf16 v[176:179], v[184:187], v[144:147], v[176:179]
	s_setprio 0
	s_setprio 0
	v_mfma_f32_16x16x32_bf16 v[0:3], v[44:47], v[96:99], v[0:3]
	v_mfma_f32_16x16x32_bf16 v[20:23], v[44:47], v[200:203], v[20:23]
	v_mfma_f32_16x16x32_bf16 v[44:47], v[180:183], v[96:99], v[68:71]
	v_mfma_f32_16x16x32_bf16 v[68:71], v[188:191], v[96:99], v[102:105]
	v_mfma_f32_16x16x32_bf16 v[32:35], v[60:63], v[96:99], v[32:35]
	v_mfma_f32_16x16x32_bf16 v[36:39], v[60:63], v[200:203], v[36:39]
	v_mfma_f32_16x16x32_bf16 v[60:63], v[180:183], v[200:203], v[110:113]
	v_mfma_f32_16x16x32_bf16 v[96:99], v[188:191], v[200:203], v[106:109]
	v_mfma_f32_16x16x32_bf16 v[20:23], v[48:51], v[204:207], v[20:23]
	v_mfma_f32_16x16x32_bf16 v[68:71], v[192:195], v[196:199], v[68:71]
	v_mfma_f32_16x16x32_bf16 v[144:147], v[48:51], v[196:199], v[0:3]
	v_mfma_f32_16x16x32_bf16 v[180:183], v[164:167], v[196:199], v[32:35]
	v_mfma_f32_16x16x32_bf16 v[164:167], v[164:167], v[204:207], v[36:39]
	v_mfma_f32_16x16x32_bf16 v[188:191], v[184:187], v[196:199], v[44:47]
	v_mfma_f32_16x16x32_bf16 v[184:187], v[184:187], v[204:207], v[60:63]
	v_mfma_f32_16x16x32_bf16 v[192:195], v[192:195], v[204:207], v[96:99]
	s_setprio 0
	s_barrier
	ds_read_b128 v[0:3], v225
	ds_read_b128 v[196:199], v225 offset:1024
	ds_read_b128 v[200:203], v225 offset:2048
	ds_read_b128 v[204:207], v225 offset:3072
	ds_read_b128 v[36:39], v228 offset:32768
	ds_read_b128 v[100:103], v228 offset:33792
	ds_read_b128 v[108:111], v229 offset:34816
	ds_read_b128 v[208:211], v229 offset:35840
	ds_read_b128 v[116:119], v229 offset:36864
	ds_read_b128 v[212:215], v229 offset:37888
	ds_read_b128 v[124:127], v229 offset:38912
	ds_read_b128 v[216:219], v229 offset:39936
	s_waitcnt vmcnt(2)
	s_barrier
; #define LDA(dst, b, h) for (int m = 0; m < 4; ++m) for (int k = 0; k < 2; ++k) \
;     dst[m][k] = *reinterpret_cast<const bf16x8*>((char*)SA(b, h) + lds_byte(wr * 64 + m * 16 + fr, k * 32 + fq * 8))
; #define LDB(dst, b, h) for (int n = 0; n < 2; ++n) for (int k = 0; k < 2; ++k) \
;     dst[n][k] = *reinterpret_cast<const bf16x8*>((char*)SB(b, h) + lds_byte(wc * 32 + n * 16 + fr, k * 32 + fq * 8))
; #define MMA(ai, bj, At_, Bt_) do { __builtin_amdgcn_s_setprio(1); \
;     for (int k = 0; k < 2; ++k) for (int m = 0; m < 4; ++m) for (int n = 0; n < 2; ++n) \
;       acc[ai][bj][m][n] = __builtin_amdgcn_mfma_f32_16x16x32_bf16(At_[m][k], Bt_[n][k], acc[ai][bj][m][n], 0, 0, 0); \
;     __builtin_amdgcn_s_setprio(0); } while (0)
; #define WAIT_V(n) asm volatile("s_waitcnt vmcnt(" #n ")" ::: "memory")
; #define WAIT_L(n) asm volatile("s_waitcnt lgkmcnt(" #n ")" ::: "memory")
; #define BAR __builtin_amdgcn_s_barrier()
; template <int EPI, int lda, int ldb, int N, int K>
; __device__ __forceinline__ void gemm_phase(const u16* __restrict__ A, const u16* __restrict__ Bt, const GemmEpi ep, int wv) {
;     ...
;     { LDB(B0, 1, 0); LDA(At, 1, 0); WAIT_V(2); BAR; WAIT_L(0); MMA(0, 0, At, B0); BAR;
;       LDB(B1, 1, 1); WAIT_V(0); BAR; WAIT_L(0); MMA(0, 1, At, B1); BAR;
;       LDA(At, 1, 1); BAR; WAIT_L(0); MMA(1, 0, At, B0); MMA(1, 1, At, B1); BAR; }
;     if (wr == 0) BAR;
	s_waitcnt lgkmcnt(0)
	s_setprio 0
	s_waitcnt lgkmcnt(0)
	v_mfma_f32_16x16x32_bf16 v[4:7], v[36:39], v[0:3], v[4:7]
	v_mfma_f32_16x16x32_bf16 v[16:19], v[36:39], v[200:203], v[16:19]
	v_mfma_f32_16x16x32_bf16 v[32:35], v[108:111], v[0:3], v[72:75]
	v_mfma_f32_16x16x32_bf16 v[44:47], v[108:111], v[200:203], v[76:79]
	v_mfma_f32_16x16x32_bf16 v[72:75], v[116:119], v[0:3], v[80:83]
	v_mfma_f32_16x16x32_bf16 v[76:79], v[116:119], v[200:203], v[84:87]
	v_mfma_f32_16x16x32_bf16 v[80:83], v[124:127], v[0:3], v[88:91]
	v_mfma_f32_16x16x32_bf16 v[84:87], v[124:127], v[200:203], v[92:95]
	v_mfma_f32_16x16x32_bf16 v[120:123], v[100:103], v[196:199], v[4:7]
	v_mfma_f32_16x16x32_bf16 v[60:63], v[100:103], v[204:207], v[16:19]
	v_mfma_f32_16x16x32_bf16 v[112:115], v[208:211], v[196:199], v[32:35]
	v_mfma_f32_16x16x32_bf16 v[48:51], v[208:211], v[204:207], v[44:47]
	v_mfma_f32_16x16x32_bf16 v[104:107], v[212:215], v[196:199], v[72:75]
	v_mfma_f32_16x16x32_bf16 v[44:47], v[212:215], v[204:207], v[76:79]
	v_mfma_f32_16x16x32_bf16 v[96:99], v[216:219], v[196:199], v[80:83]
	v_mfma_f32_16x16x32_bf16 v[32:35], v[216:219], v[204:207], v[84:87]
	s_setprio 0
	s_barrier
	ds_read_b128 v[4:7], v226
	ds_read_b128 v[220:223], v226 offset:1024
	ds_read_b128 v[76:79], v226 offset:2048
	ds_read_b128 v[224:227], v226 offset:3072
	s_waitcnt vmcnt(0)
	s_barrier
	s_waitcnt lgkmcnt(0)
	s_setprio 0
	s_waitcnt lgkmcnt(0)
	v_mfma_f32_16x16x32_bf16 v[12:15], v[36:39], v[4:7], v[12:15]
	v_mfma_f32_16x16x32_bf16 v[16:19], v[36:39], v[76:79], v[40:43]
	v_mfma_f32_16x16x32_bf16 v[36:39], v[108:111], v[4:7], v[152:155]
	v_mfma_f32_16x16x32_bf16 v[40:43], v[108:111], v[76:79], v[156:159]
	v_mfma_f32_16x16x32_bf16 v[72:75], v[116:119], v[4:7], v[52:55]
	v_mfma_f32_16x16x32_bf16 v[80:83], v[116:119], v[76:79], v[56:59]
	v_mfma_f32_16x16x32_bf16 v[84:87], v[124:127], v[4:7], v[160:163]
	v_mfma_f32_16x16x32_bf16 v[64:67], v[124:127], v[76:79], v[64:67]
	v_mfma_f32_16x16x32_bf16 v[124:127], v[100:103], v[220:223], v[12:15]
	v_mfma_f32_16x16x32_bf16 v[56:59], v[100:103], v[224:227], v[16:19]
	v_mfma_f32_16x16x32_bf16 v[116:119], v[208:211], v[220:223], v[36:39]
	v_mfma_f32_16x16x32_bf16 v[52:55], v[208:211], v[224:227], v[40:43]
	v_mfma_f32_16x16x32_bf16 v[108:111], v[212:215], v[220:223], v[72:75]
	v_mfma_f32_16x16x32_bf16 v[40:43], v[212:215], v[224:227], v[80:83]
	v_mfma_f32_16x16x32_bf16 v[100:103], v[216:219], v[220:223], v[84:87]
	v_mfma_f32_16x16x32_bf16 v[36:39], v[216:219], v[224:227], v[64:67]
	s_setprio 0
	s_barrier
	ds_read_b128 v[84:87], v228 offset:49152
	ds_read_b128 v[152:155], v228 offset:50176
	ds_read_b128 v[92:95], v229 offset:51200
	ds_read_b128 v[156:159], v229 offset:52224
	ds_read_b128 v[160:163], v229 offset:53248
	ds_read_b128 v[208:211], v229 offset:54272
	ds_read_b128 v[212:215], v229 offset:55296
	ds_read_b128 v[216:219], v229 offset:56320
	s_barrier
	s_waitcnt lgkmcnt(0)
	s_setprio 0
	s_waitcnt lgkmcnt(0)
	v_mfma_f32_16x16x32_bf16 v[8:11], v[84:87], v[0:3], v[8:11]
	v_mfma_f32_16x16x32_bf16 v[12:15], v[84:87], v[200:203], v[140:143]
	v_mfma_f32_16x16x32_bf16 v[16:19], v[92:95], v[0:3], v[148:151]
	v_mfma_f32_16x16x32_bf16 v[64:67], v[92:95], v[200:203], v[168:171]
	v_mfma_f32_16x16x32_bf16 v[72:75], v[160:163], v[0:3], v[172:175]
	v_mfma_f32_16x16x32_bf16 v[140:143], v[160:163], v[200:203], v[176:179]
	v_mfma_f32_16x16x32_bf16 v[0:3], v[212:215], v[0:3], v[24:27]
	v_mfma_f32_16x16x32_bf16 v[24:27], v[212:215], v[200:203], v[28:31]
	v_mfma_f32_16x16x32_bf16 v[88:91], v[152:155], v[196:199], v[8:11]
	v_mfma_f32_16x16x32_bf16 v[28:31], v[152:155], v[204:207], v[12:15]
	v_mfma_f32_16x16x32_bf16 v[80:83], v[156:159], v[196:199], v[16:19]
	v_mfma_f32_16x16x32_bf16 v[16:19], v[156:159], v[204:207], v[64:67]
	v_mfma_f32_16x16x32_bf16 v[72:75], v[208:211], v[196:199], v[72:75]
	v_mfma_f32_16x16x32_bf16 v[12:15], v[208:211], v[204:207], v[140:143]
	v_mfma_f32_16x16x32_bf16 v[64:67], v[216:219], v[196:199], v[0:3]
	v_mfma_f32_16x16x32_bf16 v[0:3], v[216:219], v[204:207], v[24:27]
	s_setprio 0
	s_setprio 0
	v_mfma_f32_16x16x32_bf16 v[8:11], v[84:87], v[4:7], v[144:147]
	v_mfma_f32_16x16x32_bf16 v[20:23], v[84:87], v[76:79], v[20:23]
	v_mfma_f32_16x16x32_bf16 v[84:87], v[92:95], v[4:7], v[180:183]
	v_mfma_f32_16x16x32_bf16 v[140:143], v[92:95], v[76:79], v[164:167]
	v_mfma_f32_16x16x32_bf16 v[144:147], v[160:163], v[4:7], v[188:191]
	v_mfma_f32_16x16x32_bf16 v[148:151], v[160:163], v[76:79], v[184:187]
	v_mfma_f32_16x16x32_bf16 v[4:7], v[212:215], v[4:7], v[68:71]
	v_mfma_f32_16x16x32_bf16 v[160:163], v[212:215], v[76:79], v[192:195]
	v_mfma_f32_16x16x32_bf16 v[92:95], v[152:155], v[220:223], v[8:11]
	v_mfma_f32_16x16x32_bf16 v[24:27], v[152:155], v[224:227], v[20:23]
	v_mfma_f32_16x16x32_bf16 v[84:87], v[156:159], v[220:223], v[84:87]
	v_mfma_f32_16x16x32_bf16 v[20:23], v[156:159], v[224:227], v[140:143]
	v_mfma_f32_16x16x32_bf16 v[76:79], v[208:211], v[220:223], v[144:147]
	v_mfma_f32_16x16x32_bf16 v[8:11], v[208:211], v[224:227], v[148:151]
	v_mfma_f32_16x16x32_bf16 v[68:71], v[216:219], v[220:223], v[4:7]
	v_mfma_f32_16x16x32_bf16 v[4:7], v[216:219], v[224:227], v[160:163]
	s_setprio 0
	v_cmp_gt_u32_e32 vcc, s60, v130
	s_barrier
	s_and_saveexec_b64 s[46:47], vcc
	s_cbranch_execz .LBB0_1346
	s_barrier
	s_branch .LBB0_1346

; #define STAGE(P, BASE, LD, br, kt) do { const char* _g = (const char*)((BASE) + (size_t)(br) * (LD) + (size_t)(kt) * 64); \
;     for (int _i = 0; _i < 2; ++_i) { int _b = tidx * 16 + _i * 8192; int _r, _c; stage_rc(_b, _r, _c); \
;       __builtin_amdgcn_global_load_lds((const unsigned*)(_g + (unsigned)((_r * (LD) + _c) * 2)), (unsigned*)((char*)(P) + _b), 16, 0, 0); } } while (0)
; #define LDA(dst, b, h) for (int m = 0; m < 4; ++m) for (int k = 0; k < 2; ++k) \
;     dst[m][k] = *reinterpret_cast<const bf16x8*>((char*)SA(b, h) + lds_byte(wr * 64 + m * 16 + fr, k * 32 + fq * 8))
; #define LDB(dst, b, h) for (int n = 0; n < 2; ++n) for (int k = 0; k < 2; ++k) \
;     dst[n][k] = *reinterpret_cast<const bf16x8*>((char*)SB(b, h) + lds_byte(wc * 32 + n * 16 + fr, k * 32 + fq * 8))
; #define MMA(ai, bj, At_, Bt_) do { __builtin_amdgcn_s_setprio(1); \
;     for (int k = 0; k < 2; ++k) for (int m = 0; m < 4; ++m) for (int n = 0; n < 2; ++n) \
;       acc[ai][bj][m][n] = __builtin_amdgcn_mfma_f32_16x16x32_bf16(At_[m][k], Bt_[n][k], acc[ai][bj][m][n], 0, 0, 0); \
;     __builtin_amdgcn_s_setprio(0); } while (0)
; #define WAIT_L(n) asm volatile("s_waitcnt lgkmcnt(" #n ")" ::: "memory")
; #define BAR __builtin_amdgcn_s_barrier()
; #define SCHED __builtin_amdgcn_sched_barrier(0)
; template <int EPI, int lda, int ldb, int N, int K>
; __device__ __forceinline__ void gemm_phase(const u16* __restrict__ A, const u16* __restrict__ Bt, const GemmEpi ep, int wv) {
;     ...
;       LDB(B0, 0, 0); SCHED; LDA(At, 0, 0); STAGE(SA(1, 1), Ab, lda, brow + HALF, t + 1);
;       WAIT_L(8); BAR; WAIT_L(0); MMA(0, 0, At, B0); BAR; SCHED;
;       LDB(B1, 0, 1); STAGE(SB(0, 0), Bt, ldb, bcol, t + 2);
;       BAR; WAIT_L(0); MMA(0, 1, At, B1); BAR;
;       LDA(At, 0, 1); STAGE(SA(0, 0), Ab, lda, brow, t + 2);
;       BAR; WAIT_L(0); MMA(1, 0, At, B0); BAR; SCHED;
.LBB0_1448:
	ds_read_b128 v[164:167], v160
	ds_read_b128 v[170:173], v160 offset:1024
	ds_read_b128 v[174:177], v160 offset:2048
	ds_read_b128 v[178:181], v160 offset:3072
	v_add_u32_e32 v168, 0xc000, v143
	v_lshl_add_u64 v[234:235], v[138:139], 0, s[44:45]
	v_readfirstlane_b32 s47, v168
	v_add_u32_e32 v169, 0xe000, v143
	v_lshl_add_u64 v[162:163], v[234:235], 0, s[20:21]
	s_mov_b32 m0, s47
	v_lshl_add_u64 v[236:237], v[140:141], 0, s[44:45]
	v_readfirstlane_b32 s47, v169
	ds_read_b128 v[182:185], v151
	ds_read_b128 v[186:189], v151 offset:1024
	ds_read_b128 v[190:193], v150
	ds_read_b128 v[194:197], v150 offset:1024
	ds_read_b128 v[198:201], v149
	ds_read_b128 v[202:205], v149 offset:1024
	ds_read_b128 v[206:209], v148
	ds_read_b128 v[210:213], v148 offset:1024
	global_load_lds_dwordx4 v[162:163], off
	v_lshl_add_u64 v[162:163], v[236:237], 0, s[20:21]
	s_mov_b32 m0, s47
	s_nop 0
	global_load_lds_dwordx4 v[162:163], off
	s_waitcnt lgkmcnt(8)
	s_barrier
	s_waitcnt lgkmcnt(0)
	s_setprio 0
	s_waitcnt lgkmcnt(0)
	v_mfma_f32_16x16x32_bf16 v[124:127], v[164:167], v[182:185], v[124:127]
	v_mfma_f32_16x16x32_bf16 v[120:123], v[174:177], v[182:185], v[120:123]
	v_mfma_f32_16x16x32_bf16 v[116:119], v[164:167], v[190:193], v[116:119]
	v_mfma_f32_16x16x32_bf16 v[112:115], v[174:177], v[190:193], v[112:115]
	v_mfma_f32_16x16x32_bf16 v[108:111], v[164:167], v[198:201], v[108:111]
	v_mfma_f32_16x16x32_bf16 v[104:107], v[174:177], v[198:201], v[104:107]
	v_mfma_f32_16x16x32_bf16 v[100:103], v[164:167], v[206:209], v[100:103]
	v_mfma_f32_16x16x32_bf16 v[96:99], v[174:177], v[206:209], v[96:99]
	v_mfma_f32_16x16x32_bf16 v[124:127], v[170:173], v[186:189], v[124:127]
	v_mfma_f32_16x16x32_bf16 v[120:123], v[178:181], v[186:189], v[120:123]
	v_mfma_f32_16x16x32_bf16 v[116:119], v[170:173], v[194:197], v[116:119]
	v_mfma_f32_16x16x32_bf16 v[112:115], v[178:181], v[194:197], v[112:115]
	v_mfma_f32_16x16x32_bf16 v[108:111], v[170:173], v[202:205], v[108:111]
	v_mfma_f32_16x16x32_bf16 v[104:107], v[178:181], v[202:205], v[104:107]
	v_mfma_f32_16x16x32_bf16 v[100:103], v[170:173], v[210:213], v[100:103]
	v_mfma_f32_16x16x32_bf16 v[96:99], v[178:181], v[210:213], v[96:99]
	s_setprio 0
	s_barrier
	v_add_u32_e32 v161, s55, v153
	v_lshl_add_u64 v[238:239], v[134:135], 0, s[44:45]
	v_readfirstlane_b32 s47, v161
	v_lshl_add_u64 v[162:163], v[238:239], 0, s[22:23]
	s_mov_b32 m0, s47
	ds_read_b128 v[214:217], v159
	ds_read_b128 v[218:221], v159 offset:1024
	ds_read_b128 v[222:225], v159 offset:2048
	ds_read_b128 v[226:229], v159 offset:3072
	global_load_lds_dwordx4 v[162:163], off
	v_add_u32_e32 v162, 0x2000, v161
	v_lshl_add_u64 v[240:241], v[136:137], 0, s[44:45]
	v_readfirstlane_b32 s47, v162
	v_lshl_add_u64 v[230:231], v[240:241], 0, s[22:23]
	s_mov_b32 m0, s47
	s_nop 0
	global_load_lds_dwordx4 v[230:231], off
	s_barrier
	s_waitcnt lgkmcnt(0)
	s_setprio 0
	s_waitcnt lgkmcnt(0)
	v_mfma_f32_16x16x32_bf16 v[92:95], v[214:217], v[182:185], v[92:95]
	v_mfma_f32_16x16x32_bf16 v[88:91], v[222:225], v[182:185], v[88:91]
	v_mfma_f32_16x16x32_bf16 v[84:87], v[214:217], v[190:193], v[84:87]
	v_mfma_f32_16x16x32_bf16 v[80:83], v[222:225], v[190:193], v[80:83]
	v_mfma_f32_16x16x32_bf16 v[76:79], v[214:217], v[198:201], v[76:79]
	v_mfma_f32_16x16x32_bf16 v[72:75], v[222:225], v[198:201], v[72:75]
	v_mfma_f32_16x16x32_bf16 v[68:71], v[214:217], v[206:209], v[68:71]
	v_mfma_f32_16x16x32_bf16 v[64:67], v[222:225], v[206:209], v[64:67]
	v_mfma_f32_16x16x32_bf16 v[92:95], v[218:221], v[186:189], v[92:95]
	v_mfma_f32_16x16x32_bf16 v[88:91], v[226:229], v[186:189], v[88:91]
	v_mfma_f32_16x16x32_bf16 v[84:87], v[218:221], v[194:197], v[84:87]
	v_mfma_f32_16x16x32_bf16 v[80:83], v[226:229], v[194:197], v[80:83]
	v_mfma_f32_16x16x32_bf16 v[76:79], v[218:221], v[202:205], v[76:79]
	v_mfma_f32_16x16x32_bf16 v[72:75], v[226:229], v[202:205], v[72:75]
	v_mfma_f32_16x16x32_bf16 v[68:71], v[218:221], v[210:213], v[68:71]
	v_mfma_f32_16x16x32_bf16 v[64:67], v[226:229], v[210:213], v[64:67]
	s_setprio 0
	v_readfirstlane_b32 s47, v143
	v_add_u32_e32 v163, 0x2000, v143
	v_lshl_add_u64 v[230:231], v[234:235], 0, s[24:25]
	s_mov_b32 m0, s47
	v_readfirstlane_b32 s47, v163
	s_barrier
	ds_read_b128 v[182:185], v151 offset:16384
	ds_read_b128 v[186:189], v151 offset:17408
	ds_read_b128 v[190:193], v150 offset:16384
	ds_read_b128 v[194:197], v150 offset:17408
	ds_read_b128 v[198:201], v149 offset:16384
	ds_read_b128 v[202:205], v149 offset:17408
	ds_read_b128 v[206:209], v148 offset:16384
	ds_read_b128 v[210:213], v148 offset:17408
	global_load_lds_dwordx4 v[230:231], off
	v_lshl_add_u64 v[230:231], v[236:237], 0, s[24:25]
	s_mov_b32 m0, s47
	s_nop 0
	global_load_lds_dwordx4 v[230:231], off
	s_barrier
	s_waitcnt lgkmcnt(0)
	s_setprio 0
	s_waitcnt lgkmcnt(0)
	v_mfma_f32_16x16x32_bf16 v[60:63], v[164:167], v[182:185], v[60:63]
	v_mfma_f32_16x16x32_bf16 v[56:59], v[174:177], v[182:185], v[56:59]
	v_mfma_f32_16x16x32_bf16 v[52:55], v[164:167], v[190:193], v[52:55]
	v_mfma_f32_16x16x32_bf16 v[48:51], v[174:177], v[190:193], v[48:51]
	v_mfma_f32_16x16x32_bf16 v[44:47], v[164:167], v[198:201], v[44:47]
	v_mfma_f32_16x16x32_bf16 v[40:43], v[174:177], v[198:201], v[40:43]
	v_mfma_f32_16x16x32_bf16 v[36:39], v[164:167], v[206:209], v[36:39]
	v_mfma_f32_16x16x32_bf16 v[32:35], v[174:177], v[206:209], v[32:35]
	v_mfma_f32_16x16x32_bf16 v[60:63], v[170:173], v[186:189], v[60:63]
	v_mfma_f32_16x16x32_bf16 v[56:59], v[178:181], v[186:189], v[56:59]
	v_mfma_f32_16x16x32_bf16 v[52:55], v[170:173], v[194:197], v[52:55]
	v_mfma_f32_16x16x32_bf16 v[48:51], v[178:181], v[194:197], v[48:51]
	v_mfma_f32_16x16x32_bf16 v[44:47], v[170:173], v[202:205], v[44:47]
	v_mfma_f32_16x16x32_bf16 v[40:43], v[178:181], v[202:205], v[40:43]
	v_mfma_f32_16x16x32_bf16 v[36:39], v[170:173], v[210:213], v[36:39]
	v_mfma_f32_16x16x32_bf16 v[32:35], v[178:181], v[210:213], v[32:35]
	s_setprio 0
	s_barrier
; #define STAGE(P, BASE, LD, br, kt) do { const char* _g = (const char*)((BASE) + (size_t)(br) * (LD) + (size_t)(kt) * 64); \
;     for (int _i = 0; _i < 2; ++_i) { int _b = tidx * 16 + _i * 8192; int _r, _c; stage_rc(_b, _r, _c); \
;       __builtin_amdgcn_global_load_lds((const unsigned*)(_g + (unsigned)((_r * (LD) + _c) * 2)), (unsigned*)((char*)(P) + _b), 16, 0, 0); } } while (0)
; #define LDA(dst, b, h) for (int m = 0; m < 4; ++m) for (int k = 0; k < 2; ++k) \
;     dst[m][k] = *reinterpret_cast<const bf16x8*>((char*)SA(b, h) + lds_byte(wr * 64 + m * 16 + fr, k * 32 + fq * 8))
; #define LDB(dst, b, h) for (int n = 0; n < 2; ++n) for (int k = 0; k < 2; ++k) \
;     dst[n][k] = *reinterpret_cast<const bf16x8*>((char*)SB(b, h) + lds_byte(wc * 32 + n * 16 + fr, k * 32 + fq * 8))
; #define MMA(ai, bj, At_, Bt_) do { __builtin_amdgcn_s_setprio(1); \
;     for (int k = 0; k < 2; ++k) for (int m = 0; m < 4; ++m) for (int n = 0; n < 2; ++n) \
;       acc[ai][bj][m][n] = __builtin_amdgcn_mfma_f32_16x16x32_bf16(At_[m][k], Bt_[n][k], acc[ai][bj][m][n], 0, 0, 0); \
;     __builtin_amdgcn_s_setprio(0); } while (0)
; #define WAIT_V(n) asm volatile("s_waitcnt vmcnt(" #n ")" ::: "memory")
; #define WAIT_L(n) asm volatile("s_waitcnt lgkmcnt(" #n ")" ::: "memory")
; #define BAR __builtin_amdgcn_s_barrier()
; #define SCHED __builtin_amdgcn_sched_barrier(0)
; template <int EPI, int lda, int ldb, int N, int K>
; __device__ __forceinline__ void gemm_phase(const u16* __restrict__ A, const u16* __restrict__ Bt, const GemmEpi ep, int wv) {
;     ...
;       STAGE(SB(0, 1), Bt, ldb, bcol + HALF, t + 2);
;       WAIT_V(6); BAR; MMA(1, 1, At, B1); BAR;
;       LDB(B0, 1, 0); SCHED; LDA(At, 1, 0); STAGE(SA(0, 1), Ab, lda, brow + HALF, t + 2);
;       WAIT_L(8); BAR; WAIT_L(0); MMA(0, 0, At, B0); BAR; SCHED;
;       LDB(B1, 1, 1); STAGE(SB(1, 0), Bt, ldb, bcol, t + 3);
;       BAR; WAIT_L(0); MMA(0, 1, At, B1); BAR;
;       LDA(At, 1, 1); STAGE(SA(1, 0), Ab, lda, brow, t + 3);
	v_add_u32_e32 v164, s56, v153
	v_add_u32_e32 v165, 0x2000, v164
	v_readfirstlane_b32 s47, v164
	v_lshl_add_u64 v[166:167], v[238:239], 0, s[26:27]
	s_mov_b32 m0, s47
	v_readfirstlane_b32 s47, v165
	global_load_lds_dwordx4 v[166:167], off
	v_lshl_add_u64 v[166:167], v[240:241], 0, s[26:27]
	s_mov_b32 m0, s47
	s_nop 0
	global_load_lds_dwordx4 v[166:167], off
	s_waitcnt vmcnt(6)
	s_barrier
	s_setprio 0
	v_mfma_f32_16x16x32_bf16 v[28:31], v[214:217], v[182:185], v[28:31]
	v_mfma_f32_16x16x32_bf16 v[24:27], v[222:225], v[182:185], v[24:27]
	v_mfma_f32_16x16x32_bf16 v[20:23], v[214:217], v[190:193], v[20:23]
	v_mfma_f32_16x16x32_bf16 v[16:19], v[222:225], v[190:193], v[16:19]
	v_mfma_f32_16x16x32_bf16 v[12:15], v[214:217], v[198:201], v[12:15]
	v_mfma_f32_16x16x32_bf16 v[8:11], v[222:225], v[198:201], v[8:11]
	v_mfma_f32_16x16x32_bf16 v[4:7], v[214:217], v[206:209], v[4:7]
	v_mfma_f32_16x16x32_bf16 v[0:3], v[222:225], v[206:209], v[0:3]
	v_mfma_f32_16x16x32_bf16 v[28:31], v[218:221], v[186:189], v[28:31]
	v_mfma_f32_16x16x32_bf16 v[24:27], v[226:229], v[186:189], v[24:27]
	v_mfma_f32_16x16x32_bf16 v[20:23], v[218:221], v[194:197], v[20:23]
	v_mfma_f32_16x16x32_bf16 v[16:19], v[226:229], v[194:197], v[16:19]
	v_mfma_f32_16x16x32_bf16 v[12:15], v[218:221], v[202:205], v[12:15]
	v_mfma_f32_16x16x32_bf16 v[8:11], v[226:229], v[202:205], v[8:11]
	v_mfma_f32_16x16x32_bf16 v[4:7], v[218:221], v[210:213], v[4:7]
	v_mfma_f32_16x16x32_bf16 v[0:3], v[226:229], v[210:213], v[0:3]
	s_setprio 0
	s_barrier
	ds_read_b128 v[170:173], v154
	ds_read_b128 v[174:177], v154 offset:1024
	ds_read_b128 v[178:181], v154 offset:2048
	ds_read_b128 v[182:185], v154 offset:3072
	v_add_u32_e32 v166, 0x4000, v143
	v_add_u32_e32 v167, 0x6000, v143
	v_readfirstlane_b32 s47, v166
	v_lshl_add_u64 v[218:219], v[234:235], 0, s[34:35]
	s_mov_b32 m0, s47
	v_readfirstlane_b32 s47, v167
	ds_read_b128 v[186:189], v151 offset:32768
	ds_read_b128 v[190:193], v151 offset:33792
	ds_read_b128 v[194:197], v150 offset:32768
	ds_read_b128 v[198:201], v150 offset:33792
	ds_read_b128 v[202:205], v149 offset:32768
	ds_read_b128 v[206:209], v149 offset:33792
	ds_read_b128 v[210:213], v148 offset:32768
	ds_read_b128 v[214:217], v148 offset:33792
	global_load_lds_dwordx4 v[218:219], off
	v_lshl_add_u64 v[218:219], v[236:237], 0, s[34:35]
	s_mov_b32 m0, s47
	s_nop 0
	global_load_lds_dwordx4 v[218:219], off
	s_waitcnt lgkmcnt(8)
	s_barrier
	s_waitcnt lgkmcnt(0)
	s_setprio 0
	s_waitcnt lgkmcnt(0)
	v_mfma_f32_16x16x32_bf16 v[124:127], v[170:173], v[186:189], v[124:127]
	v_mfma_f32_16x16x32_bf16 v[120:123], v[178:181], v[186:189], v[120:123]
	v_mfma_f32_16x16x32_bf16 v[116:119], v[170:173], v[194:197], v[116:119]
	v_mfma_f32_16x16x32_bf16 v[112:115], v[178:181], v[194:197], v[112:115]
	v_mfma_f32_16x16x32_bf16 v[108:111], v[170:173], v[202:205], v[108:111]
	v_mfma_f32_16x16x32_bf16 v[104:107], v[178:181], v[202:205], v[104:107]
	v_mfma_f32_16x16x32_bf16 v[100:103], v[170:173], v[210:213], v[100:103]
	v_mfma_f32_16x16x32_bf16 v[96:99], v[178:181], v[210:213], v[96:99]
	v_mfma_f32_16x16x32_bf16 v[124:127], v[174:177], v[190:193], v[124:127]
	v_mfma_f32_16x16x32_bf16 v[120:123], v[182:185], v[190:193], v[120:123]
	v_mfma_f32_16x16x32_bf16 v[116:119], v[174:177], v[198:201], v[116:119]
	v_mfma_f32_16x16x32_bf16 v[112:115], v[182:185], v[198:201], v[112:115]
	v_mfma_f32_16x16x32_bf16 v[108:111], v[174:177], v[206:209], v[108:111]
	v_mfma_f32_16x16x32_bf16 v[104:107], v[182:185], v[206:209], v[104:107]
	v_mfma_f32_16x16x32_bf16 v[100:103], v[174:177], v[214:217], v[100:103]
	v_mfma_f32_16x16x32_bf16 v[96:99], v[182:185], v[214:217], v[96:99]
	s_setprio 0
	s_barrier
	v_readfirstlane_b32 s47, v155
	v_add_u32_e32 v244, 0x2000, v155
	v_lshl_add_u64 v[242:243], v[238:239], 0, s[36:37]
	s_mov_b32 m0, s47
	v_readfirstlane_b32 s47, v244
	ds_read_b128 v[218:221], v152
	ds_read_b128 v[222:225], v152 offset:1024
	ds_read_b128 v[226:229], v152 offset:2048
	ds_read_b128 v[230:233], v152 offset:3072
	global_load_lds_dwordx4 v[242:243], off
	v_lshl_add_u64 v[242:243], v[240:241], 0, s[36:37]
	s_mov_b32 m0, s47
	s_nop 0
	global_load_lds_dwordx4 v[242:243], off
	s_barrier
	s_waitcnt lgkmcnt(0)
	s_setprio 0
	s_waitcnt lgkmcnt(0)
	v_mfma_f32_16x16x32_bf16 v[92:95], v[218:221], v[186:189], v[92:95]
	v_mfma_f32_16x16x32_bf16 v[88:91], v[226:229], v[186:189], v[88:91]
	v_mfma_f32_16x16x32_bf16 v[84:87], v[218:221], v[194:197], v[84:87]
	v_mfma_f32_16x16x32_bf16 v[80:83], v[226:229], v[194:197], v[80:83]
	v_mfma_f32_16x16x32_bf16 v[76:79], v[218:221], v[202:205], v[76:79]
	v_mfma_f32_16x16x32_bf16 v[72:75], v[226:229], v[202:205], v[72:75]
	v_mfma_f32_16x16x32_bf16 v[68:71], v[218:221], v[210:213], v[68:71]
	v_mfma_f32_16x16x32_bf16 v[64:67], v[226:229], v[210:213], v[64:67]
	v_mfma_f32_16x16x32_bf16 v[92:95], v[222:225], v[190:193], v[92:95]
	v_mfma_f32_16x16x32_bf16 v[88:91], v[230:233], v[190:193], v[88:91]
	v_mfma_f32_16x16x32_bf16 v[84:87], v[222:225], v[198:201], v[84:87]
	v_mfma_f32_16x16x32_bf16 v[80:83], v[230:233], v[198:201], v[80:83]
	v_mfma_f32_16x16x32_bf16 v[76:79], v[222:225], v[206:209], v[76:79]
	v_mfma_f32_16x16x32_bf16 v[72:75], v[230:233], v[206:209], v[72:75]
	v_mfma_f32_16x16x32_bf16 v[68:71], v[222:225], v[214:217], v[68:71]
	v_mfma_f32_16x16x32_bf16 v[64:67], v[230:233], v[214:217], v[64:67]
	s_setprio 0
	v_readfirstlane_b32 s47, v156
	v_lshl_add_u64 v[234:235], v[234:235], 0, s[38:39]
	s_mov_b32 m0, s47
	v_readfirstlane_b32 s47, v157
	s_barrier
; #define STAGE(P, BASE, LD, br, kt) do { const char* _g = (const char*)((BASE) + (size_t)(br) * (LD) + (size_t)(kt) * 64); \
;     for (int _i = 0; _i < 2; ++_i) { int _b = tidx * 16 + _i * 8192; int _r, _c; stage_rc(_b, _r, _c); \
;       __builtin_amdgcn_global_load_lds((const unsigned*)(_g + (unsigned)((_r * (LD) + _c) * 2)), (unsigned*)((char*)(P) + _b), 16, 0, 0); } } while (0)
; #define LDA(dst, b, h) for (int m = 0; m < 4; ++m) for (int k = 0; k < 2; ++k) \
;     dst[m][k] = *reinterpret_cast<const bf16x8*>((char*)SA(b, h) + lds_byte(wr * 64 + m * 16 + fr, k * 32 + fq * 8))
; #define LDB(dst, b, h) for (int n = 0; n < 2; ++n) for (int k = 0; k < 2; ++k) \
;     dst[n][k] = *reinterpret_cast<const bf16x8*>((char*)SB(b, h) + lds_byte(wc * 32 + n * 16 + fr, k * 32 + fq * 8))
; #define MMA(ai, bj, At_, Bt_) do { __builtin_amdgcn_s_setprio(1); \
;     for (int k = 0; k < 2; ++k) for (int m = 0; m < 4; ++m) for (int n = 0; n < 2; ++n) \
;       acc[ai][bj][m][n] = __builtin_amdgcn_mfma_f32_16x16x32_bf16(At_[m][k], Bt_[n][k], acc[ai][bj][m][n], 0, 0, 0); \
;     __builtin_amdgcn_s_setprio(0); } while (0)
; #define WAIT_V(n) asm volatile("s_waitcnt vmcnt(" #n ")" ::: "memory")
; #define WAIT_L(n) asm volatile("s_waitcnt lgkmcnt(" #n ")" ::: "memory")
; #define BAR __builtin_amdgcn_s_barrier()
; #define SCHED __builtin_amdgcn_sched_barrier(0)
; template <int EPI, int lda, int ldb, int N, int K>
; __device__ __forceinline__ void gemm_phase(const u16* __restrict__ A, const u16* __restrict__ Bt, const GemmEpi ep, int wv) {
;     ...
;       LDA(At, 1, 1); STAGE(SA(1, 0), Ab, lda, brow, t + 3);
;       BAR; WAIT_L(0); MMA(1, 0, At, B0); BAR; SCHED;
;       STAGE(SB(1, 1), Bt, ldb, bcol + HALF, t + 3);
;       WAIT_V(6); BAR; MMA(1, 1, At, B1); BAR;
;     }
;     { LDB(B0, 0, 0); LDA(At, 0, 0); STAGE(SA(1, 1), Ab, lda, brow + HALF, nt - 1);
;       BAR; WAIT_L(0); MMA(0, 0, At, B0); BAR;
	ds_read_b128 v[186:189], v151 offset:49152
	ds_read_b128 v[190:193], v151 offset:50176
	ds_read_b128 v[194:197], v150 offset:49152
	ds_read_b128 v[198:201], v150 offset:50176
	ds_read_b128 v[202:205], v149 offset:49152
	ds_read_b128 v[206:209], v149 offset:50176
	ds_read_b128 v[210:213], v148 offset:49152
	ds_read_b128 v[214:217], v148 offset:50176
	global_load_lds_dwordx4 v[234:235], off
	v_lshl_add_u64 v[234:235], v[236:237], 0, s[38:39]
	s_mov_b32 m0, s47
	s_nop 0
	global_load_lds_dwordx4 v[234:235], off
	s_barrier
	s_waitcnt lgkmcnt(0)
	s_setprio 0
	s_waitcnt lgkmcnt(0)
	v_mfma_f32_16x16x32_bf16 v[60:63], v[170:173], v[186:189], v[60:63]
	v_mfma_f32_16x16x32_bf16 v[56:59], v[178:181], v[186:189], v[56:59]
	v_mfma_f32_16x16x32_bf16 v[52:55], v[170:173], v[194:197], v[52:55]
	v_mfma_f32_16x16x32_bf16 v[48:51], v[178:181], v[194:197], v[48:51]
	v_mfma_f32_16x16x32_bf16 v[44:47], v[170:173], v[202:205], v[44:47]
	v_mfma_f32_16x16x32_bf16 v[40:43], v[178:181], v[202:205], v[40:43]
	v_mfma_f32_16x16x32_bf16 v[36:39], v[170:173], v[210:213], v[36:39]
	v_mfma_f32_16x16x32_bf16 v[32:35], v[178:181], v[210:213], v[32:35]
	v_mfma_f32_16x16x32_bf16 v[60:63], v[174:177], v[190:193], v[60:63]
	v_mfma_f32_16x16x32_bf16 v[56:59], v[182:185], v[190:193], v[56:59]
	v_mfma_f32_16x16x32_bf16 v[52:55], v[174:177], v[198:201], v[52:55]
	v_mfma_f32_16x16x32_bf16 v[48:51], v[182:185], v[198:201], v[48:51]
	v_mfma_f32_16x16x32_bf16 v[44:47], v[174:177], v[206:209], v[44:47]
	v_mfma_f32_16x16x32_bf16 v[40:43], v[182:185], v[206:209], v[40:43]
	v_mfma_f32_16x16x32_bf16 v[36:39], v[174:177], v[214:217], v[36:39]
	v_mfma_f32_16x16x32_bf16 v[32:35], v[182:185], v[214:217], v[32:35]
	s_setprio 0
	s_barrier
	v_readfirstlane_b32 s47, v158
	v_add_u32_e32 v172, 0x2000, v158
	v_lshl_add_u64 v[170:171], v[238:239], 0, s[40:41]
	s_mov_b32 m0, s47
	v_readfirstlane_b32 s47, v172
	global_load_lds_dwordx4 v[170:171], off
	v_lshl_add_u64 v[170:171], v[240:241], 0, s[40:41]
	s_mov_b32 m0, s47
	s_nop 0
	global_load_lds_dwordx4 v[170:171], off
	s_waitcnt vmcnt(6)
	s_barrier
	s_setprio 0
	v_mfma_f32_16x16x32_bf16 v[28:31], v[218:221], v[186:189], v[28:31]
	v_mfma_f32_16x16x32_bf16 v[24:27], v[226:229], v[186:189], v[24:27]
	v_mfma_f32_16x16x32_bf16 v[20:23], v[218:221], v[194:197], v[20:23]
	v_mfma_f32_16x16x32_bf16 v[16:19], v[226:229], v[194:197], v[16:19]
	v_mfma_f32_16x16x32_bf16 v[12:15], v[218:221], v[202:205], v[12:15]
	v_mfma_f32_16x16x32_bf16 v[8:11], v[226:229], v[202:205], v[8:11]
	v_mfma_f32_16x16x32_bf16 v[4:7], v[218:221], v[210:213], v[4:7]
	v_mfma_f32_16x16x32_bf16 v[0:3], v[226:229], v[210:213], v[0:3]
	v_mfma_f32_16x16x32_bf16 v[28:31], v[222:225], v[190:193], v[28:31]
	v_mfma_f32_16x16x32_bf16 v[24:27], v[230:233], v[190:193], v[24:27]
	v_mfma_f32_16x16x32_bf16 v[20:23], v[222:225], v[198:201], v[20:23]
	v_mfma_f32_16x16x32_bf16 v[16:19], v[230:233], v[198:201], v[16:19]
	v_mfma_f32_16x16x32_bf16 v[12:15], v[222:225], v[206:209], v[12:15]
	v_mfma_f32_16x16x32_bf16 v[8:11], v[230:233], v[206:209], v[8:11]
	v_mfma_f32_16x16x32_bf16 v[4:7], v[222:225], v[214:217], v[4:7]
	v_mfma_f32_16x16x32_bf16 v[0:3], v[230:233], v[214:217], v[0:3]
	s_setprio 0
	s_add_i32 s46, s46, 2
	s_add_u32 s44, s44, 0x100
	s_addc_u32 s45, s45, 0
	s_cmp_gt_u32 s46, 27
	s_barrier
	s_cbranch_scc0 .LBB0_1448
	s_lshl_b64 s[44:45], s[16:17], 12
	s_add_u32 s44, s14, s44
	s_addc_u32 s45, s15, s45
	s_add_u32 s44, s44, 0x80000
	s_addc_u32 s45, s45, 0
	v_lshl_add_u64 v[156:157], s[44:45], 0, v[128:129]
	v_readfirstlane_b32 s46, v168
	v_lshl_add_u64 v[156:157], v[156:157], 0, s[42:43]
	s_mov_b32 m0, s46
	ds_read_b128 v[134:137], v160
	ds_read_b128 v[138:141], v160 offset:1024
	ds_read_b128 v[170:173], v160 offset:2048
	ds_read_b128 v[174:177], v160 offset:3072
	ds_read_b128 v[178:181], v151
	ds_read_b128 v[182:185], v151 offset:1024
	ds_read_b128 v[186:189], v150
	ds_read_b128 v[190:193], v150 offset:1024
	ds_read_b128 v[194:197], v149
	ds_read_b128 v[198:201], v149 offset:1024
	ds_read_b128 v[202:205], v148
	ds_read_b128 v[206:209], v148 offset:1024
	global_load_lds_dwordx4 v[156:157], off
	v_lshl_add_u64 v[156:157], s[44:45], 0, v[132:133]
	v_readfirstlane_b32 s44, v169
	v_lshl_add_u64 v[156:157], v[156:157], 0, s[42:43]
	s_mov_b32 m0, s44
	s_nop 0
	global_load_lds_dwordx4 v[156:157], off
	s_barrier
	s_waitcnt lgkmcnt(0)
	s_setprio 0
	s_waitcnt lgkmcnt(0)
	v_mfma_f32_16x16x32_bf16 v[124:127], v[134:137], v[178:181], v[124:127]
	v_mfma_f32_16x16x32_bf16 v[120:123], v[170:173], v[178:181], v[120:123]
	v_mfma_f32_16x16x32_bf16 v[116:119], v[134:137], v[186:189], v[116:119]
	v_mfma_f32_16x16x32_bf16 v[112:115], v[170:173], v[186:189], v[112:115]
	v_mfma_f32_16x16x32_bf16 v[108:111], v[134:137], v[194:197], v[108:111]
	v_mfma_f32_16x16x32_bf16 v[104:107], v[170:173], v[194:197], v[104:107]
	v_mfma_f32_16x16x32_bf16 v[100:103], v[134:137], v[202:205], v[100:103]
	v_mfma_f32_16x16x32_bf16 v[96:99], v[170:173], v[202:205], v[96:99]
	v_mfma_f32_16x16x32_bf16 v[124:127], v[138:141], v[182:185], v[124:127]
	v_mfma_f32_16x16x32_bf16 v[120:123], v[174:177], v[182:185], v[120:123]
	v_mfma_f32_16x16x32_bf16 v[116:119], v[138:141], v[190:193], v[116:119]
	v_mfma_f32_16x16x32_bf16 v[112:115], v[174:177], v[190:193], v[112:115]
	v_mfma_f32_16x16x32_bf16 v[108:111], v[138:141], v[198:201], v[108:111]
	v_mfma_f32_16x16x32_bf16 v[104:107], v[174:177], v[198:201], v[104:107]
	v_mfma_f32_16x16x32_bf16 v[100:103], v[138:141], v[206:209], v[100:103]
	v_mfma_f32_16x16x32_bf16 v[96:99], v[174:177], v[206:209], v[96:99]
	s_setprio 0
	s_barrier
; #define LDA(dst, b, h) for (int m = 0; m < 4; ++m) for (int k = 0; k < 2; ++k) \
;     dst[m][k] = *reinterpret_cast<const bf16x8*>((char*)SA(b, h) + lds_byte(wr * 64 + m * 16 + fr, k * 32 + fq * 8))
; #define LDB(dst, b, h) for (int n = 0; n < 2; ++n) for (int k = 0; k < 2; ++k) \
;     dst[n][k] = *reinterpret_cast<const bf16x8*>((char*)SB(b, h) + lds_byte(wc * 32 + n * 16 + fr, k * 32 + fq * 8))
; #define MMA(ai, bj, At_, Bt_) do { __builtin_amdgcn_s_setprio(1); \
;     for (int k = 0; k < 2; ++k) for (int m = 0; m < 4; ++m) for (int n = 0; n < 2; ++n) \
;       acc[ai][bj][m][n] = __builtin_amdgcn_mfma_f32_16x16x32_bf16(At_[m][k], Bt_[n][k], acc[ai][bj][m][n], 0, 0, 0); \
;     __builtin_amdgcn_s_setprio(0); } while (0)
; #define WAIT_V(n) asm volatile("s_waitcnt vmcnt(" #n ")" ::: "memory")
; #define WAIT_L(n) asm volatile("s_waitcnt lgkmcnt(" #n ")" ::: "memory")
; #define BAR __builtin_amdgcn_s_barrier()
; template <int EPI, int lda, int ldb, int N, int K>
; __device__ __forceinline__ void gemm_phase(const u16* __restrict__ A, const u16* __restrict__ Bt, const GemmEpi ep, int wv) {
;     ...
;       LDB(B1, 0, 1); BAR; WAIT_L(0); MMA(0, 1, At, B1); BAR;
;       LDA(At, 0, 1); WAIT_V(4); BAR; WAIT_L(0); MMA(1, 0, At, B0); MMA(1, 1, At, B1); BAR; }
;     { LDB(B0, 1, 0); LDA(At, 1, 0); WAIT_V(2); BAR; WAIT_L(0); MMA(0, 0, At, B0); BAR;
	ds_read_b128 v[210:213], v159
	ds_read_b128 v[214:217], v159 offset:1024
	ds_read_b128 v[218:221], v159 offset:2048
	ds_read_b128 v[156:159], v159 offset:3072
	s_barrier
	s_waitcnt lgkmcnt(0)
	s_setprio 0
	s_waitcnt lgkmcnt(0)
	v_mfma_f32_16x16x32_bf16 v[92:95], v[210:213], v[178:181], v[92:95]
	v_mfma_f32_16x16x32_bf16 v[88:91], v[218:221], v[178:181], v[88:91]
	v_mfma_f32_16x16x32_bf16 v[76:79], v[210:213], v[194:197], v[76:79]
	v_mfma_f32_16x16x32_bf16 v[72:75], v[218:221], v[194:197], v[72:75]
	v_mfma_f32_16x16x32_bf16 v[84:87], v[210:213], v[186:189], v[84:87]
	v_mfma_f32_16x16x32_bf16 v[80:83], v[218:221], v[186:189], v[80:83]
	v_mfma_f32_16x16x32_bf16 v[68:71], v[210:213], v[202:205], v[68:71]
	v_mfma_f32_16x16x32_bf16 v[64:67], v[218:221], v[202:205], v[64:67]
	v_mfma_f32_16x16x32_bf16 v[92:95], v[214:217], v[182:185], v[92:95]
	v_mfma_f32_16x16x32_bf16 v[88:91], v[156:159], v[182:185], v[88:91]
	v_mfma_f32_16x16x32_bf16 v[76:79], v[214:217], v[198:201], v[76:79]
	v_mfma_f32_16x16x32_bf16 v[72:75], v[156:159], v[198:201], v[72:75]
	v_mfma_f32_16x16x32_bf16 v[178:181], v[214:217], v[190:193], v[84:87]
	v_mfma_f32_16x16x32_bf16 v[182:185], v[156:159], v[190:193], v[80:83]
	v_mfma_f32_16x16x32_bf16 v[186:189], v[214:217], v[206:209], v[68:71]
	v_mfma_f32_16x16x32_bf16 v[190:193], v[156:159], v[206:209], v[64:67]
	s_setprio 0
	s_barrier
	s_nop 0
	ds_read_b128 v[64:67], v151 offset:16384
	ds_read_b128 v[68:71], v151 offset:17408
	ds_read_b128 v[80:83], v150 offset:16384
	ds_read_b128 v[84:87], v150 offset:17408
	ds_read_b128 v[194:197], v149 offset:16384
	ds_read_b128 v[198:201], v149 offset:17408
	ds_read_b128 v[202:205], v148 offset:16384
	ds_read_b128 v[206:209], v148 offset:17408
	s_waitcnt vmcnt(4)
	s_barrier
	s_waitcnt lgkmcnt(0)
	s_setprio 0
	s_waitcnt lgkmcnt(0)
	v_mfma_f32_16x16x32_bf16 v[60:63], v[134:137], v[64:67], v[60:63]
	v_mfma_f32_16x16x32_bf16 v[56:59], v[170:173], v[64:67], v[56:59]
	v_mfma_f32_16x16x32_bf16 v[52:55], v[134:137], v[80:83], v[52:55]
	v_mfma_f32_16x16x32_bf16 v[48:51], v[170:173], v[80:83], v[48:51]
	v_mfma_f32_16x16x32_bf16 v[44:47], v[134:137], v[194:197], v[44:47]
	v_mfma_f32_16x16x32_bf16 v[40:43], v[170:173], v[194:197], v[40:43]
	v_mfma_f32_16x16x32_bf16 v[36:39], v[134:137], v[202:205], v[36:39]
	v_mfma_f32_16x16x32_bf16 v[32:35], v[170:173], v[202:205], v[32:35]
	v_mfma_f32_16x16x32_bf16 v[60:63], v[138:141], v[68:71], v[60:63]
	v_mfma_f32_16x16x32_bf16 v[56:59], v[174:177], v[68:71], v[56:59]
	v_mfma_f32_16x16x32_bf16 v[52:55], v[138:141], v[84:87], v[52:55]
	v_mfma_f32_16x16x32_bf16 v[48:51], v[174:177], v[84:87], v[48:51]
	v_mfma_f32_16x16x32_bf16 v[44:47], v[138:141], v[198:201], v[44:47]
	v_mfma_f32_16x16x32_bf16 v[40:43], v[174:177], v[198:201], v[40:43]
	v_mfma_f32_16x16x32_bf16 v[36:39], v[138:141], v[206:209], v[36:39]
	v_mfma_f32_16x16x32_bf16 v[32:35], v[174:177], v[206:209], v[32:35]
	s_setprio 0
	s_setprio 0
	v_mfma_f32_16x16x32_bf16 v[28:31], v[210:213], v[64:67], v[28:31]
	v_mfma_f32_16x16x32_bf16 v[20:23], v[210:213], v[80:83], v[20:23]
	v_mfma_f32_16x16x32_bf16 v[12:15], v[210:213], v[194:197], v[12:15]
	v_mfma_f32_16x16x32_bf16 v[4:7], v[210:213], v[202:205], v[4:7]
	v_mfma_f32_16x16x32_bf16 v[24:27], v[218:221], v[64:67], v[24:27]
	v_mfma_f32_16x16x32_bf16 v[16:19], v[218:221], v[80:83], v[16:19]
	v_mfma_f32_16x16x32_bf16 v[8:11], v[218:221], v[194:197], v[8:11]
	v_mfma_f32_16x16x32_bf16 v[0:3], v[218:221], v[202:205], v[0:3]
	v_mfma_f32_16x16x32_bf16 v[28:31], v[214:217], v[68:71], v[28:31]
	v_mfma_f32_16x16x32_bf16 v[20:23], v[214:217], v[84:87], v[20:23]
	v_mfma_f32_16x16x32_bf16 v[12:15], v[214:217], v[198:201], v[12:15]
	v_mfma_f32_16x16x32_bf16 v[4:7], v[214:217], v[206:209], v[4:7]
	v_mfma_f32_16x16x32_bf16 v[134:137], v[156:159], v[68:71], v[24:27]
	v_mfma_f32_16x16x32_bf16 v[138:141], v[156:159], v[84:87], v[16:19]
	v_mfma_f32_16x16x32_bf16 v[168:171], v[156:159], v[198:201], v[8:11]
	v_mfma_f32_16x16x32_bf16 v[156:159], v[156:159], v[206:209], v[0:3]
	s_setprio 0
	s_barrier
	s_nop 0
	ds_read_b128 v[0:3], v154
	ds_read_b128 v[8:11], v154 offset:1024
	ds_read_b128 v[16:19], v154 offset:2048
	ds_read_b128 v[172:175], v154 offset:3072
	ds_read_b128 v[24:27], v151 offset:32768
	ds_read_b128 v[194:197], v151 offset:33792
	ds_read_b128 v[198:201], v150 offset:32768
	ds_read_b128 v[202:205], v150 offset:33792
	ds_read_b128 v[206:209], v149 offset:32768
	ds_read_b128 v[210:213], v149 offset:33792
	ds_read_b128 v[214:217], v148 offset:32768
	ds_read_b128 v[218:221], v148 offset:33792
	s_waitcnt vmcnt(2)
	s_barrier
; #define LDA(dst, b, h) for (int m = 0; m < 4; ++m) for (int k = 0; k < 2; ++k) \
;     dst[m][k] = *reinterpret_cast<const bf16x8*>((char*)SA(b, h) + lds_byte(wr * 64 + m * 16 + fr, k * 32 + fq * 8))
; #define LDB(dst, b, h) for (int n = 0; n < 2; ++n) for (int k = 0; k < 2; ++k) \
;     dst[n][k] = *reinterpret_cast<const bf16x8*>((char*)SB(b, h) + lds_byte(wc * 32 + n * 16 + fr, k * 32 + fq * 8))
; #define MMA(ai, bj, At_, Bt_) do { __builtin_amdgcn_s_setprio(1); \
;     for (int k = 0; k < 2; ++k) for (int m = 0; m < 4; ++m) for (int n = 0; n < 2; ++n) \
;       acc[ai][bj][m][n] = __builtin_amdgcn_mfma_f32_16x16x32_bf16(At_[m][k], Bt_[n][k], acc[ai][bj][m][n], 0, 0, 0); \
;     __builtin_amdgcn_s_setprio(0); } while (0)
; #define WAIT_V(n) asm volatile("s_waitcnt vmcnt(" #n ")" ::: "memory")
; #define WAIT_L(n) asm volatile("s_waitcnt lgkmcnt(" #n ")" ::: "memory")
; #define BAR __builtin_amdgcn_s_barrier()
; template <int EPI, int lda, int ldb, int N, int K>
; __device__ __forceinline__ void gemm_phase(const u16* __restrict__ A, const u16* __restrict__ Bt, const GemmEpi ep, int wv) {
;     ...
;     { LDB(B0, 1, 0); LDA(At, 1, 0); WAIT_V(2); BAR; WAIT_L(0); MMA(0, 0, At, B0); BAR;
;       LDB(B1, 1, 1); WAIT_V(0); BAR; WAIT_L(0); MMA(0, 1, At, B1); BAR;
;       LDA(At, 1, 1); BAR; WAIT_L(0); MMA(1, 0, At, B0); MMA(1, 1, At, B1); BAR; }
;     if (wr == 0) BAR;
	s_waitcnt lgkmcnt(0)
	s_setprio 0
	s_waitcnt lgkmcnt(0)
	v_mfma_f32_16x16x32_bf16 v[64:67], v[0:3], v[24:27], v[124:127]
	v_mfma_f32_16x16x32_bf16 v[68:71], v[16:19], v[24:27], v[120:123]
	v_mfma_f32_16x16x32_bf16 v[80:83], v[0:3], v[198:201], v[116:119]
	v_mfma_f32_16x16x32_bf16 v[84:87], v[16:19], v[198:201], v[112:115]
	v_mfma_f32_16x16x32_bf16 v[108:111], v[0:3], v[206:209], v[108:111]
	v_mfma_f32_16x16x32_bf16 v[104:107], v[16:19], v[206:209], v[104:107]
	v_mfma_f32_16x16x32_bf16 v[120:123], v[0:3], v[214:217], v[100:103]
	v_mfma_f32_16x16x32_bf16 v[124:127], v[16:19], v[214:217], v[96:99]
	v_mfma_f32_16x16x32_bf16 v[116:119], v[8:11], v[194:197], v[64:67]
	v_mfma_f32_16x16x32_bf16 v[112:115], v[172:175], v[194:197], v[68:71]
	v_mfma_f32_16x16x32_bf16 v[100:103], v[8:11], v[202:205], v[80:83]
	v_mfma_f32_16x16x32_bf16 v[96:99], v[172:175], v[202:205], v[84:87]
	v_mfma_f32_16x16x32_bf16 v[84:87], v[8:11], v[210:213], v[108:111]
	v_mfma_f32_16x16x32_bf16 v[80:83], v[172:175], v[210:213], v[104:107]
	v_mfma_f32_16x16x32_bf16 v[68:71], v[8:11], v[218:221], v[120:123]
	v_mfma_f32_16x16x32_bf16 v[64:67], v[172:175], v[218:221], v[124:127]
	s_setprio 0
	s_barrier
	ds_read_b128 v[222:225], v152
	ds_read_b128 v[226:229], v152 offset:1024
	ds_read_b128 v[230:233], v152 offset:2048
	ds_read_b128 v[152:155], v152 offset:3072
	s_waitcnt vmcnt(0)
	s_barrier
	s_waitcnt lgkmcnt(0)
	s_setprio 0
	s_waitcnt lgkmcnt(0)
	v_mfma_f32_16x16x32_bf16 v[92:95], v[222:225], v[24:27], v[92:95]
	v_mfma_f32_16x16x32_bf16 v[24:27], v[230:233], v[24:27], v[88:91]
	v_mfma_f32_16x16x32_bf16 v[88:91], v[222:225], v[198:201], v[178:181]
	v_mfma_f32_16x16x32_bf16 v[104:107], v[230:233], v[198:201], v[182:185]
	v_mfma_f32_16x16x32_bf16 v[76:79], v[222:225], v[206:209], v[76:79]
	v_mfma_f32_16x16x32_bf16 v[72:75], v[230:233], v[206:209], v[72:75]
	v_mfma_f32_16x16x32_bf16 v[176:179], v[222:225], v[214:217], v[186:189]
	v_mfma_f32_16x16x32_bf16 v[180:183], v[230:233], v[214:217], v[190:193]
	v_mfma_f32_16x16x32_bf16 v[124:127], v[226:229], v[194:197], v[92:95]
	v_mfma_f32_16x16x32_bf16 v[120:123], v[152:155], v[194:197], v[24:27]
	v_mfma_f32_16x16x32_bf16 v[108:111], v[226:229], v[202:205], v[88:91]
	v_mfma_f32_16x16x32_bf16 v[104:107], v[152:155], v[202:205], v[104:107]
	v_mfma_f32_16x16x32_bf16 v[92:95], v[226:229], v[210:213], v[76:79]
	v_mfma_f32_16x16x32_bf16 v[88:91], v[152:155], v[210:213], v[72:75]
	v_mfma_f32_16x16x32_bf16 v[76:79], v[226:229], v[218:221], v[176:179]
	v_mfma_f32_16x16x32_bf16 v[72:75], v[152:155], v[218:221], v[180:183]
	s_setprio 0
	s_barrier
	ds_read_b128 v[176:179], v151 offset:49152
	ds_read_b128 v[180:183], v151 offset:50176
	ds_read_b128 v[184:187], v150 offset:49152
	ds_read_b128 v[188:191], v150 offset:50176
	ds_read_b128 v[192:195], v149 offset:49152
	ds_read_b128 v[196:199], v149 offset:50176
	ds_read_b128 v[200:203], v148 offset:49152
	ds_read_b128 v[148:151], v148 offset:50176
	s_barrier
	s_waitcnt lgkmcnt(0)
	s_setprio 0
	s_waitcnt lgkmcnt(0)
	v_mfma_f32_16x16x32_bf16 v[24:27], v[0:3], v[176:179], v[60:63]
	v_mfma_f32_16x16x32_bf16 v[60:63], v[16:19], v[176:179], v[56:59]
	v_mfma_f32_16x16x32_bf16 v[52:55], v[0:3], v[184:187], v[52:55]
	v_mfma_f32_16x16x32_bf16 v[204:207], v[16:19], v[184:187], v[48:51]
	v_mfma_f32_16x16x32_bf16 v[44:47], v[0:3], v[192:195], v[44:47]
	v_mfma_f32_16x16x32_bf16 v[208:211], v[16:19], v[192:195], v[40:43]
	v_mfma_f32_16x16x32_bf16 v[0:3], v[0:3], v[200:203], v[36:39]
	v_mfma_f32_16x16x32_bf16 v[36:39], v[16:19], v[200:203], v[32:35]
	v_mfma_f32_16x16x32_bf16 v[56:59], v[8:11], v[180:183], v[24:27]
	v_mfma_f32_16x16x32_bf16 v[48:51], v[172:175], v[180:183], v[60:63]
	v_mfma_f32_16x16x32_bf16 v[40:43], v[8:11], v[188:191], v[52:55]
	v_mfma_f32_16x16x32_bf16 v[32:35], v[172:175], v[188:191], v[204:207]
	v_mfma_f32_16x16x32_bf16 v[24:27], v[8:11], v[196:199], v[44:47]
	v_mfma_f32_16x16x32_bf16 v[16:19], v[172:175], v[196:199], v[208:211]
	v_mfma_f32_16x16x32_bf16 v[8:11], v[8:11], v[148:151], v[0:3]
	v_mfma_f32_16x16x32_bf16 v[0:3], v[172:175], v[148:151], v[36:39]
	s_setprio 0
	s_setprio 0
	v_mfma_f32_16x16x32_bf16 v[28:31], v[222:225], v[176:179], v[28:31]
	v_mfma_f32_16x16x32_bf16 v[36:39], v[230:233], v[176:179], v[134:137]
	v_mfma_f32_16x16x32_bf16 v[20:23], v[222:225], v[184:187], v[20:23]
	v_mfma_f32_16x16x32_bf16 v[134:137], v[230:233], v[184:187], v[138:141]
	v_mfma_f32_16x16x32_bf16 v[12:15], v[222:225], v[192:195], v[12:15]
	v_mfma_f32_16x16x32_bf16 v[138:141], v[230:233], v[192:195], v[168:171]
	v_mfma_f32_16x16x32_bf16 v[4:7], v[222:225], v[200:203], v[4:7]
	v_mfma_f32_16x16x32_bf16 v[156:159], v[230:233], v[200:203], v[156:159]
	v_mfma_f32_16x16x32_bf16 v[60:63], v[226:229], v[180:183], v[28:31]
	v_mfma_f32_16x16x32_bf16 v[52:55], v[152:155], v[180:183], v[36:39]
	v_mfma_f32_16x16x32_bf16 v[44:47], v[226:229], v[188:191], v[20:23]
	v_mfma_f32_16x16x32_bf16 v[36:39], v[152:155], v[188:191], v[134:137]
	v_mfma_f32_16x16x32_bf16 v[28:31], v[226:229], v[196:199], v[12:15]
	v_mfma_f32_16x16x32_bf16 v[20:23], v[152:155], v[196:199], v[138:141]
	v_mfma_f32_16x16x32_bf16 v[12:15], v[226:229], v[148:151], v[4:7]
	v_mfma_f32_16x16x32_bf16 v[4:7], v[152:155], v[148:151], v[156:159]
	s_setprio 0
	v_cmp_gt_u32_e32 vcc, s60, v130
	s_barrier
	s_and_saveexec_b64 s[44:45], vcc
	s_cbranch_execz .LBB0_1451
	s_barrier

; #define STAGE(P, BASE, LD, br, kt) do { const char* _g = (const char*)((BASE) + (size_t)(br) * (LD) + (size_t)(kt) * 64); \
;     for (int _i = 0; _i < 2; ++_i) { int _b = tidx * 16 + _i * 8192; int _r, _c; stage_rc(_b, _r, _c); \
;       __builtin_amdgcn_global_load_lds((const unsigned*)(_g + (unsigned)((_r * (LD) + _c) * 2)), (unsigned*)((char*)(P) + _b), 16, 0, 0); } } while (0)
; #define LDA(dst, b, h) for (int m = 0; m < 4; ++m) for (int k = 0; k < 2; ++k) \
;     dst[m][k] = *reinterpret_cast<const bf16x8*>((char*)SA(b, h) + lds_byte(wr * 64 + m * 16 + fr, k * 32 + fq * 8))
; #define LDB(dst, b, h) for (int n = 0; n < 2; ++n) for (int k = 0; k < 2; ++k) \
;     dst[n][k] = *reinterpret_cast<const bf16x8*>((char*)SB(b, h) + lds_byte(wc * 32 + n * 16 + fr, k * 32 + fq * 8))
; #define MMA(ai, bj, At_, Bt_) do { __builtin_amdgcn_s_setprio(1); \
;     for (int k = 0; k < 2; ++k) for (int m = 0; m < 4; ++m) for (int n = 0; n < 2; ++n) \
;       acc[ai][bj][m][n] = __builtin_amdgcn_mfma_f32_16x16x32_bf16(At_[m][k], Bt_[n][k], acc[ai][bj][m][n], 0, 0, 0); \
;     __builtin_amdgcn_s_setprio(0); } while (0)
; #define WAIT_L(n) asm volatile("s_waitcnt lgkmcnt(" #n ")" ::: "memory")
; #define BAR __builtin_amdgcn_s_barrier()
; #define SCHED __builtin_amdgcn_sched_barrier(0)
; template <int EPI, int lda, int ldb, int N, int K>
; __device__ __forceinline__ void gemm_phase(const u16* __restrict__ A, const u16* __restrict__ Bt, const GemmEpi ep, int wv) {
;     ...
;       LDB(B0, 0, 0); SCHED; LDA(At, 0, 0); STAGE(SA(1, 1), Ab, lda, brow + HALF, t + 1);
;       WAIT_L(8); BAR; WAIT_L(0); MMA(0, 0, At, B0); BAR; SCHED;
;       LDB(B1, 0, 1); STAGE(SB(0, 0), Bt, ldb, bcol, t + 2);
;       BAR; WAIT_L(0); MMA(0, 1, At, B1); BAR;
;       LDA(At, 0, 1); STAGE(SA(0, 0), Ab, lda, brow, t + 2);
;       BAR; WAIT_L(0); MMA(1, 0, At, B0); BAR; SCHED;
.LBB0_1564:
	ds_read_b128 v[172:175], v161
	ds_read_b128 v[176:179], v161 offset:1024
	ds_read_b128 v[180:183], v161 offset:2048
	ds_read_b128 v[184:187], v161 offset:3072
	v_add_u32_e32 v169, 0xc000, v148
	v_lshl_add_u64 v[236:237], v[136:137], 0, s[40:41]
	v_readfirstlane_b32 s43, v169
	v_add_u32_e32 v170, 0xe000, v148
	v_lshl_add_u64 v[162:163], v[236:237], 0, s[14:15]
	s_mov_b32 m0, s43
	v_lshl_add_u64 v[238:239], v[134:135], 0, s[40:41]
	v_readfirstlane_b32 s43, v170
	ds_read_b128 v[164:167], v152
	ds_read_b128 v[188:191], v152 offset:1024
	ds_read_b128 v[192:195], v151
	ds_read_b128 v[196:199], v151 offset:1024
	ds_read_b128 v[200:203], v150
	ds_read_b128 v[204:207], v150 offset:1024
	ds_read_b128 v[208:211], v149
	ds_read_b128 v[212:215], v149 offset:1024
	global_load_lds_dwordx4 v[162:163], off
	v_lshl_add_u64 v[162:163], v[238:239], 0, s[14:15]
	s_mov_b32 m0, s43
	s_nop 0
	global_load_lds_dwordx4 v[162:163], off
	s_waitcnt lgkmcnt(8)
	s_barrier
	s_waitcnt lgkmcnt(0)
	s_setprio 0
	s_waitcnt lgkmcnt(0)
	v_mfma_f32_16x16x32_bf16 v[124:127], v[172:175], v[164:167], v[124:127]
	v_mfma_f32_16x16x32_bf16 v[120:123], v[180:183], v[164:167], v[120:123]
	v_mfma_f32_16x16x32_bf16 v[116:119], v[172:175], v[192:195], v[116:119]
	v_mfma_f32_16x16x32_bf16 v[112:115], v[180:183], v[192:195], v[112:115]
	v_mfma_f32_16x16x32_bf16 v[108:111], v[172:175], v[200:203], v[108:111]
	v_mfma_f32_16x16x32_bf16 v[104:107], v[180:183], v[200:203], v[104:107]
	v_mfma_f32_16x16x32_bf16 v[100:103], v[172:175], v[208:211], v[100:103]
	v_mfma_f32_16x16x32_bf16 v[96:99], v[180:183], v[208:211], v[96:99]
	v_mfma_f32_16x16x32_bf16 v[124:127], v[176:179], v[188:191], v[124:127]
	v_mfma_f32_16x16x32_bf16 v[120:123], v[184:187], v[188:191], v[120:123]
	v_mfma_f32_16x16x32_bf16 v[116:119], v[176:179], v[196:199], v[116:119]
	v_mfma_f32_16x16x32_bf16 v[112:115], v[184:187], v[196:199], v[112:115]
	v_mfma_f32_16x16x32_bf16 v[108:111], v[176:179], v[204:207], v[108:111]
	v_mfma_f32_16x16x32_bf16 v[104:107], v[184:187], v[204:207], v[104:107]
	v_mfma_f32_16x16x32_bf16 v[100:103], v[176:179], v[212:215], v[100:103]
	v_mfma_f32_16x16x32_bf16 v[96:99], v[184:187], v[212:215], v[96:99]
	s_setprio 0
	s_barrier
	v_add_u32_e32 v162, s52, v153
	v_lshl_add_u64 v[240:241], v[140:141], 0, s[40:41]
	v_readfirstlane_b32 s43, v162
	v_add_u32_e32 v163, 0x2000, v162
	v_lshl_add_u64 v[232:233], v[240:241], 0, s[16:17]
	s_mov_b32 m0, s43
	v_lshl_add_u64 v[242:243], v[138:139], 0, s[40:41]
	v_readfirstlane_b32 s43, v163
	ds_read_b128 v[216:219], v160
	ds_read_b128 v[220:223], v160 offset:1024
	ds_read_b128 v[224:227], v160 offset:2048
	ds_read_b128 v[228:231], v160 offset:3072
	global_load_lds_dwordx4 v[232:233], off
	v_lshl_add_u64 v[232:233], v[242:243], 0, s[16:17]
	s_mov_b32 m0, s43
	s_nop 0
	global_load_lds_dwordx4 v[232:233], off
	s_barrier
	s_waitcnt lgkmcnt(0)
	s_setprio 0
	s_waitcnt lgkmcnt(0)
	v_mfma_f32_16x16x32_bf16 v[92:95], v[216:219], v[164:167], v[92:95]
	v_mfma_f32_16x16x32_bf16 v[88:91], v[224:227], v[164:167], v[88:91]
	v_mfma_f32_16x16x32_bf16 v[84:87], v[216:219], v[192:195], v[84:87]
	v_mfma_f32_16x16x32_bf16 v[80:83], v[224:227], v[192:195], v[80:83]
	v_mfma_f32_16x16x32_bf16 v[76:79], v[216:219], v[200:203], v[76:79]
	v_mfma_f32_16x16x32_bf16 v[72:75], v[224:227], v[200:203], v[72:75]
	v_mfma_f32_16x16x32_bf16 v[68:71], v[216:219], v[208:211], v[68:71]
	v_mfma_f32_16x16x32_bf16 v[64:67], v[224:227], v[208:211], v[64:67]
	v_mfma_f32_16x16x32_bf16 v[92:95], v[220:223], v[188:191], v[92:95]
	v_mfma_f32_16x16x32_bf16 v[88:91], v[228:231], v[188:191], v[88:91]
	v_mfma_f32_16x16x32_bf16 v[84:87], v[220:223], v[196:199], v[84:87]
	v_mfma_f32_16x16x32_bf16 v[80:83], v[228:231], v[196:199], v[80:83]
	v_mfma_f32_16x16x32_bf16 v[76:79], v[220:223], v[204:207], v[76:79]
	v_mfma_f32_16x16x32_bf16 v[72:75], v[228:231], v[204:207], v[72:75]
	v_mfma_f32_16x16x32_bf16 v[68:71], v[220:223], v[212:215], v[68:71]
	v_mfma_f32_16x16x32_bf16 v[64:67], v[228:231], v[212:215], v[64:67]
	s_setprio 0
	v_readfirstlane_b32 s43, v148
	v_lshl_add_u64 v[164:165], v[236:237], 0, s[18:19]
	s_mov_b32 m0, s43
	s_barrier
	ds_read_b128 v[188:191], v152 offset:16384
	ds_read_b128 v[192:195], v152 offset:17408
	ds_read_b128 v[196:199], v151 offset:16384
	ds_read_b128 v[200:203], v151 offset:17408
	ds_read_b128 v[204:207], v150 offset:16384
	ds_read_b128 v[208:211], v150 offset:17408
	ds_read_b128 v[212:215], v149 offset:16384
	ds_read_b128 v[232:235], v149 offset:17408
	global_load_lds_dwordx4 v[164:165], off
	v_add_u32_e32 v164, 0x2000, v148
	v_lshl_add_u64 v[166:167], v[238:239], 0, s[18:19]
	v_readfirstlane_b32 s43, v164
	s_mov_b32 m0, s43
	s_nop 0
	global_load_lds_dwordx4 v[166:167], off
	s_barrier
	s_waitcnt lgkmcnt(0)
	s_setprio 0
	s_waitcnt lgkmcnt(0)
	v_mfma_f32_16x16x32_bf16 v[60:63], v[172:175], v[188:191], v[60:63]
	v_mfma_f32_16x16x32_bf16 v[56:59], v[180:183], v[188:191], v[56:59]
	v_mfma_f32_16x16x32_bf16 v[52:55], v[172:175], v[196:199], v[52:55]
	v_mfma_f32_16x16x32_bf16 v[48:51], v[180:183], v[196:199], v[48:51]
	v_mfma_f32_16x16x32_bf16 v[44:47], v[172:175], v[204:207], v[44:47]
	v_mfma_f32_16x16x32_bf16 v[40:43], v[180:183], v[204:207], v[40:43]
	v_mfma_f32_16x16x32_bf16 v[36:39], v[172:175], v[212:215], v[36:39]
	v_mfma_f32_16x16x32_bf16 v[32:35], v[180:183], v[212:215], v[32:35]
	v_mfma_f32_16x16x32_bf16 v[60:63], v[176:179], v[192:195], v[60:63]
	v_mfma_f32_16x16x32_bf16 v[56:59], v[184:187], v[192:195], v[56:59]
	v_mfma_f32_16x16x32_bf16 v[52:55], v[176:179], v[200:203], v[52:55]
	v_mfma_f32_16x16x32_bf16 v[48:51], v[184:187], v[200:203], v[48:51]
	v_mfma_f32_16x16x32_bf16 v[44:47], v[176:179], v[208:211], v[44:47]
	v_mfma_f32_16x16x32_bf16 v[40:43], v[184:187], v[208:211], v[40:43]
	v_mfma_f32_16x16x32_bf16 v[36:39], v[176:179], v[232:235], v[36:39]
	v_mfma_f32_16x16x32_bf16 v[32:35], v[184:187], v[232:235], v[32:35]
	s_setprio 0
	s_barrier
; #define STAGE(P, BASE, LD, br, kt) do { const char* _g = (const char*)((BASE) + (size_t)(br) * (LD) + (size_t)(kt) * 64); \
;     for (int _i = 0; _i < 2; ++_i) { int _b = tidx * 16 + _i * 8192; int _r, _c; stage_rc(_b, _r, _c); \
;       __builtin_amdgcn_global_load_lds((const unsigned*)(_g + (unsigned)((_r * (LD) + _c) * 2)), (unsigned*)((char*)(P) + _b), 16, 0, 0); } } while (0)
; #define LDA(dst, b, h) for (int m = 0; m < 4; ++m) for (int k = 0; k < 2; ++k) \
;     dst[m][k] = *reinterpret_cast<const bf16x8*>((char*)SA(b, h) + lds_byte(wr * 64 + m * 16 + fr, k * 32 + fq * 8))
; #define LDB(dst, b, h) for (int n = 0; n < 2; ++n) for (int k = 0; k < 2; ++k) \
;     dst[n][k] = *reinterpret_cast<const bf16x8*>((char*)SB(b, h) + lds_byte(wc * 32 + n * 16 + fr, k * 32 + fq * 8))
; #define MMA(ai, bj, At_, Bt_) do { __builtin_amdgcn_s_setprio(1); \
;     for (int k = 0; k < 2; ++k) for (int m = 0; m < 4; ++m) for (int n = 0; n < 2; ++n) \
;       acc[ai][bj][m][n] = __builtin_amdgcn_mfma_f32_16x16x32_bf16(At_[m][k], Bt_[n][k], acc[ai][bj][m][n], 0, 0, 0); \
;     __builtin_amdgcn_s_setprio(0); } while (0)
; #define WAIT_V(n) asm volatile("s_waitcnt vmcnt(" #n ")" ::: "memory")
; #define WAIT_L(n) asm volatile("s_waitcnt lgkmcnt(" #n ")" ::: "memory")
; #define BAR __builtin_amdgcn_s_barrier()
; #define SCHED __builtin_amdgcn_sched_barrier(0)
; template <int EPI, int lda, int ldb, int N, int K>
; __device__ __forceinline__ void gemm_phase(const u16* __restrict__ A, const u16* __restrict__ Bt, const GemmEpi ep, int wv) {
;     ...
;       STAGE(SB(0, 1), Bt, ldb, bcol + HALF, t + 2);
;       WAIT_V(6); BAR; MMA(1, 1, At, B1); BAR;
;       LDB(B0, 1, 0); SCHED; LDA(At, 1, 0); STAGE(SA(0, 1), Ab, lda, brow + HALF, t + 2);
;       WAIT_L(8); BAR; WAIT_L(0); MMA(0, 0, At, B0); BAR; SCHED;
;       LDB(B1, 1, 1); STAGE(SB(1, 0), Bt, ldb, bcol, t + 3);
;       BAR; WAIT_L(0); MMA(0, 1, At, B1); BAR;
;       LDA(At, 1, 1); STAGE(SA(1, 0), Ab, lda, brow, t + 3);
	v_add_u32_e32 v165, s53, v153
	v_lshl_add_u64 v[166:167], v[240:241], 0, s[20:21]
	v_readfirstlane_b32 s43, v165
	s_mov_b32 m0, s43
	v_lshl_add_u64 v[172:173], v[242:243], 0, s[20:21]
	global_load_lds_dwordx4 v[166:167], off
	v_add_u32_e32 v166, 0x2000, v165
	s_nop 0
	v_readfirstlane_b32 s43, v166
	s_mov_b32 m0, s43
	s_nop 0
	global_load_lds_dwordx4 v[172:173], off
	s_waitcnt vmcnt(6)
	s_barrier
	s_setprio 0
	v_mfma_f32_16x16x32_bf16 v[28:31], v[216:219], v[188:191], v[28:31]
	v_mfma_f32_16x16x32_bf16 v[24:27], v[224:227], v[188:191], v[24:27]
	v_mfma_f32_16x16x32_bf16 v[20:23], v[216:219], v[196:199], v[20:23]
	v_mfma_f32_16x16x32_bf16 v[16:19], v[224:227], v[196:199], v[16:19]
	v_mfma_f32_16x16x32_bf16 v[12:15], v[216:219], v[204:207], v[12:15]
	v_mfma_f32_16x16x32_bf16 v[8:11], v[224:227], v[204:207], v[8:11]
	v_mfma_f32_16x16x32_bf16 v[4:7], v[216:219], v[212:215], v[4:7]
	v_mfma_f32_16x16x32_bf16 v[0:3], v[224:227], v[212:215], v[0:3]
	v_mfma_f32_16x16x32_bf16 v[28:31], v[220:223], v[192:195], v[28:31]
	v_mfma_f32_16x16x32_bf16 v[24:27], v[228:231], v[192:195], v[24:27]
	v_mfma_f32_16x16x32_bf16 v[20:23], v[220:223], v[200:203], v[20:23]
	v_mfma_f32_16x16x32_bf16 v[16:19], v[228:231], v[200:203], v[16:19]
	v_mfma_f32_16x16x32_bf16 v[12:15], v[220:223], v[208:211], v[12:15]
	v_mfma_f32_16x16x32_bf16 v[8:11], v[228:231], v[208:211], v[8:11]
	v_mfma_f32_16x16x32_bf16 v[4:7], v[220:223], v[232:235], v[4:7]
	v_mfma_f32_16x16x32_bf16 v[0:3], v[228:231], v[232:235], v[0:3]
	s_setprio 0
	s_barrier
	ds_read_b128 v[172:175], v156
	ds_read_b128 v[176:179], v156 offset:1024
	ds_read_b128 v[180:183], v156 offset:2048
	ds_read_b128 v[184:187], v156 offset:3072
	v_add_u32_e32 v167, 0x4000, v148
	v_add_u32_e32 v168, 0x6000, v148
	v_readfirstlane_b32 s43, v167
	v_lshl_add_u64 v[220:221], v[236:237], 0, s[22:23]
	s_mov_b32 m0, s43
	v_readfirstlane_b32 s43, v168
	ds_read_b128 v[188:191], v152 offset:32768
	ds_read_b128 v[192:195], v152 offset:33792
	ds_read_b128 v[196:199], v151 offset:32768
	ds_read_b128 v[200:203], v151 offset:33792
	ds_read_b128 v[204:207], v150 offset:32768
	ds_read_b128 v[208:211], v150 offset:33792
	ds_read_b128 v[212:215], v149 offset:32768
	ds_read_b128 v[216:219], v149 offset:33792
	global_load_lds_dwordx4 v[220:221], off
	v_lshl_add_u64 v[220:221], v[238:239], 0, s[22:23]
	s_mov_b32 m0, s43
	s_nop 0
	global_load_lds_dwordx4 v[220:221], off
	s_waitcnt lgkmcnt(8)
	s_barrier
	s_waitcnt lgkmcnt(0)
	s_setprio 0
	s_waitcnt lgkmcnt(0)
	v_mfma_f32_16x16x32_bf16 v[124:127], v[172:175], v[188:191], v[124:127]
	v_mfma_f32_16x16x32_bf16 v[120:123], v[180:183], v[188:191], v[120:123]
	v_mfma_f32_16x16x32_bf16 v[116:119], v[172:175], v[196:199], v[116:119]
	v_mfma_f32_16x16x32_bf16 v[112:115], v[180:183], v[196:199], v[112:115]
	v_mfma_f32_16x16x32_bf16 v[108:111], v[172:175], v[204:207], v[108:111]
	v_mfma_f32_16x16x32_bf16 v[104:107], v[180:183], v[204:207], v[104:107]
	v_mfma_f32_16x16x32_bf16 v[100:103], v[172:175], v[212:215], v[100:103]
	v_mfma_f32_16x16x32_bf16 v[96:99], v[180:183], v[212:215], v[96:99]
	v_mfma_f32_16x16x32_bf16 v[124:127], v[176:179], v[192:195], v[124:127]
	v_mfma_f32_16x16x32_bf16 v[120:123], v[184:187], v[192:195], v[120:123]
	v_mfma_f32_16x16x32_bf16 v[116:119], v[176:179], v[200:203], v[116:119]
	v_mfma_f32_16x16x32_bf16 v[112:115], v[184:187], v[200:203], v[112:115]
	v_mfma_f32_16x16x32_bf16 v[108:111], v[176:179], v[208:211], v[108:111]
	v_mfma_f32_16x16x32_bf16 v[104:107], v[184:187], v[208:211], v[104:107]
	v_mfma_f32_16x16x32_bf16 v[100:103], v[176:179], v[216:219], v[100:103]
	v_mfma_f32_16x16x32_bf16 v[96:99], v[184:187], v[216:219], v[96:99]
	s_setprio 0
	s_barrier
	v_readfirstlane_b32 s43, v155
	v_add_u32_e32 v171, 0x2000, v155
	v_lshl_add_u64 v[244:245], v[240:241], 0, s[24:25]
	s_mov_b32 m0, s43
	v_readfirstlane_b32 s43, v171
	ds_read_b128 v[220:223], v154
	ds_read_b128 v[224:227], v154 offset:1024
	ds_read_b128 v[228:231], v154 offset:2048
	ds_read_b128 v[232:235], v154 offset:3072
	global_load_lds_dwordx4 v[244:245], off
	v_lshl_add_u64 v[244:245], v[242:243], 0, s[24:25]
	s_mov_b32 m0, s43
	s_nop 0
	global_load_lds_dwordx4 v[244:245], off
	s_barrier
	s_waitcnt lgkmcnt(0)
	s_setprio 0
	s_waitcnt lgkmcnt(0)
	v_mfma_f32_16x16x32_bf16 v[92:95], v[220:223], v[188:191], v[92:95]
	v_mfma_f32_16x16x32_bf16 v[88:91], v[228:231], v[188:191], v[88:91]
	v_mfma_f32_16x16x32_bf16 v[84:87], v[220:223], v[196:199], v[84:87]
	v_mfma_f32_16x16x32_bf16 v[80:83], v[228:231], v[196:199], v[80:83]
	v_mfma_f32_16x16x32_bf16 v[76:79], v[220:223], v[204:207], v[76:79]
	v_mfma_f32_16x16x32_bf16 v[72:75], v[228:231], v[204:207], v[72:75]
	v_mfma_f32_16x16x32_bf16 v[68:71], v[220:223], v[212:215], v[68:71]
	v_mfma_f32_16x16x32_bf16 v[64:67], v[228:231], v[212:215], v[64:67]
	v_mfma_f32_16x16x32_bf16 v[92:95], v[224:227], v[192:195], v[92:95]
	v_mfma_f32_16x16x32_bf16 v[88:91], v[232:235], v[192:195], v[88:91]
	v_mfma_f32_16x16x32_bf16 v[84:87], v[224:227], v[200:203], v[84:87]
	v_mfma_f32_16x16x32_bf16 v[80:83], v[232:235], v[200:203], v[80:83]
	v_mfma_f32_16x16x32_bf16 v[76:79], v[224:227], v[208:211], v[76:79]
	v_mfma_f32_16x16x32_bf16 v[72:75], v[232:235], v[208:211], v[72:75]
	v_mfma_f32_16x16x32_bf16 v[68:71], v[224:227], v[216:219], v[68:71]
	v_mfma_f32_16x16x32_bf16 v[64:67], v[232:235], v[216:219], v[64:67]
	s_setprio 0
	v_readfirstlane_b32 s43, v157
	v_lshl_add_u64 v[236:237], v[236:237], 0, s[26:27]
	s_mov_b32 m0, s43
	v_readfirstlane_b32 s43, v158
	s_barrier
; #define STAGE(P, BASE, LD, br, kt) do { const char* _g = (const char*)((BASE) + (size_t)(br) * (LD) + (size_t)(kt) * 64); \
;     for (int _i = 0; _i < 2; ++_i) { int _b = tidx * 16 + _i * 8192; int _r, _c; stage_rc(_b, _r, _c); \
;       __builtin_amdgcn_global_load_lds((const unsigned*)(_g + (unsigned)((_r * (LD) + _c) * 2)), (unsigned*)((char*)(P) + _b), 16, 0, 0); } } while (0)
; #define LDA(dst, b, h) for (int m = 0; m < 4; ++m) for (int k = 0; k < 2; ++k) \
;     dst[m][k] = *reinterpret_cast<const bf16x8*>((char*)SA(b, h) + lds_byte(wr * 64 + m * 16 + fr, k * 32 + fq * 8))
; #define LDB(dst, b, h) for (int n = 0; n < 2; ++n) for (int k = 0; k < 2; ++k) \
;     dst[n][k] = *reinterpret_cast<const bf16x8*>((char*)SB(b, h) + lds_byte(wc * 32 + n * 16 + fr, k * 32 + fq * 8))
; #define MMA(ai, bj, At_, Bt_) do { __builtin_amdgcn_s_setprio(1); \
;     for (int k = 0; k < 2; ++k) for (int m = 0; m < 4; ++m) for (int n = 0; n < 2; ++n) \
;       acc[ai][bj][m][n] = __builtin_amdgcn_mfma_f32_16x16x32_bf16(At_[m][k], Bt_[n][k], acc[ai][bj][m][n], 0, 0, 0); \
;     __builtin_amdgcn_s_setprio(0); } while (0)
; #define WAIT_V(n) asm volatile("s_waitcnt vmcnt(" #n ")" ::: "memory")
; #define WAIT_L(n) asm volatile("s_waitcnt lgkmcnt(" #n ")" ::: "memory")
; #define BAR __builtin_amdgcn_s_barrier()
; #define SCHED __builtin_amdgcn_sched_barrier(0)
; template <int EPI, int lda, int ldb, int N, int K>
; __device__ __forceinline__ void gemm_phase(const u16* __restrict__ A, const u16* __restrict__ Bt, const GemmEpi ep, int wv) {
;     ...
;       LDA(At, 1, 1); STAGE(SA(1, 0), Ab, lda, brow, t + 3);
;       BAR; WAIT_L(0); MMA(1, 0, At, B0); BAR; SCHED;
;       STAGE(SB(1, 1), Bt, ldb, bcol + HALF, t + 3);
;       WAIT_V(6); BAR; MMA(1, 1, At, B1); BAR;
;     }
;     { LDB(B0, 0, 0); LDA(At, 0, 0); STAGE(SA(1, 1), Ab, lda, brow + HALF, nt - 1);
;       BAR; WAIT_L(0); MMA(0, 0, At, B0); BAR;
;       LDB(B1, 0, 1); BAR; WAIT_L(0); MMA(0, 1, At, B1); BAR;
	ds_read_b128 v[188:191], v152 offset:49152
	ds_read_b128 v[192:195], v152 offset:50176
	ds_read_b128 v[196:199], v151 offset:49152
	ds_read_b128 v[200:203], v151 offset:50176
	ds_read_b128 v[204:207], v150 offset:49152
	ds_read_b128 v[208:211], v150 offset:50176
	ds_read_b128 v[212:215], v149 offset:49152
	ds_read_b128 v[216:219], v149 offset:50176
	global_load_lds_dwordx4 v[236:237], off
	v_lshl_add_u64 v[236:237], v[238:239], 0, s[26:27]
	s_mov_b32 m0, s43
	s_nop 0
	global_load_lds_dwordx4 v[236:237], off
	s_barrier
	s_waitcnt lgkmcnt(0)
	s_setprio 0
	s_waitcnt lgkmcnt(0)
	v_mfma_f32_16x16x32_bf16 v[60:63], v[172:175], v[188:191], v[60:63]
	v_mfma_f32_16x16x32_bf16 v[56:59], v[180:183], v[188:191], v[56:59]
	v_mfma_f32_16x16x32_bf16 v[52:55], v[172:175], v[196:199], v[52:55]
	v_mfma_f32_16x16x32_bf16 v[48:51], v[180:183], v[196:199], v[48:51]
	v_mfma_f32_16x16x32_bf16 v[44:47], v[172:175], v[204:207], v[44:47]
	v_mfma_f32_16x16x32_bf16 v[40:43], v[180:183], v[204:207], v[40:43]
	v_mfma_f32_16x16x32_bf16 v[36:39], v[172:175], v[212:215], v[36:39]
	v_mfma_f32_16x16x32_bf16 v[32:35], v[180:183], v[212:215], v[32:35]
	v_mfma_f32_16x16x32_bf16 v[60:63], v[176:179], v[192:195], v[60:63]
	v_mfma_f32_16x16x32_bf16 v[56:59], v[184:187], v[192:195], v[56:59]
	v_mfma_f32_16x16x32_bf16 v[52:55], v[176:179], v[200:203], v[52:55]
	v_mfma_f32_16x16x32_bf16 v[48:51], v[184:187], v[200:203], v[48:51]
	v_mfma_f32_16x16x32_bf16 v[44:47], v[176:179], v[208:211], v[44:47]
	v_mfma_f32_16x16x32_bf16 v[40:43], v[184:187], v[208:211], v[40:43]
	v_mfma_f32_16x16x32_bf16 v[36:39], v[176:179], v[216:219], v[36:39]
	v_mfma_f32_16x16x32_bf16 v[32:35], v[184:187], v[216:219], v[32:35]
	s_setprio 0
	s_barrier
	v_readfirstlane_b32 s43, v159
	v_add_u32_e32 v171, 0x2000, v159
	v_lshl_add_u64 v[172:173], v[240:241], 0, s[34:35]
	s_mov_b32 m0, s43
	v_readfirstlane_b32 s43, v171
	global_load_lds_dwordx4 v[172:173], off
	v_lshl_add_u64 v[172:173], v[242:243], 0, s[34:35]
	s_mov_b32 m0, s43
	s_nop 0
	global_load_lds_dwordx4 v[172:173], off
	s_waitcnt vmcnt(6)
	s_barrier
	s_setprio 0
	v_mfma_f32_16x16x32_bf16 v[28:31], v[220:223], v[188:191], v[28:31]
	v_mfma_f32_16x16x32_bf16 v[24:27], v[228:231], v[188:191], v[24:27]
	v_mfma_f32_16x16x32_bf16 v[20:23], v[220:223], v[196:199], v[20:23]
	v_mfma_f32_16x16x32_bf16 v[16:19], v[228:231], v[196:199], v[16:19]
	v_mfma_f32_16x16x32_bf16 v[12:15], v[220:223], v[204:207], v[12:15]
	v_mfma_f32_16x16x32_bf16 v[8:11], v[228:231], v[204:207], v[8:11]
	v_mfma_f32_16x16x32_bf16 v[4:7], v[220:223], v[212:215], v[4:7]
	v_mfma_f32_16x16x32_bf16 v[0:3], v[228:231], v[212:215], v[0:3]
	v_mfma_f32_16x16x32_bf16 v[28:31], v[224:227], v[192:195], v[28:31]
	v_mfma_f32_16x16x32_bf16 v[24:27], v[232:235], v[192:195], v[24:27]
	v_mfma_f32_16x16x32_bf16 v[20:23], v[224:227], v[200:203], v[20:23]
	v_mfma_f32_16x16x32_bf16 v[16:19], v[232:235], v[200:203], v[16:19]
	v_mfma_f32_16x16x32_bf16 v[12:15], v[224:227], v[208:211], v[12:15]
	v_mfma_f32_16x16x32_bf16 v[8:11], v[232:235], v[208:211], v[8:11]
	v_mfma_f32_16x16x32_bf16 v[4:7], v[224:227], v[216:219], v[4:7]
	v_mfma_f32_16x16x32_bf16 v[0:3], v[232:235], v[216:219], v[0:3]
	s_setprio 0
	s_add_i32 s42, s42, 2
	s_add_u32 s40, s40, 0x100
	s_addc_u32 s41, s41, 0
	s_cmp_gt_u32 s42, 27
	s_barrier
	s_cbranch_scc0 .LBB0_1564
	s_add_i32 s40, s38, 0x80
	s_mul_hi_i32 s41, s40, 0x1080
	s_mulk_i32 s40, 0x1080
	s_add_u32 s40, s49, s40
	s_addc_u32 s41, s50, s41
	v_lshl_add_u64 v[158:159], s[40:41], 0, v[128:129]
	v_readfirstlane_b32 s42, v169
	v_lshl_add_u64 v[158:159], v[158:159], 0, s[36:37]
	s_mov_b32 m0, s42
	ds_read_b128 v[134:137], v161
	ds_read_b128 v[138:141], v161 offset:1024
	ds_read_b128 v[172:175], v161 offset:2048
	ds_read_b128 v[176:179], v161 offset:3072
	ds_read_b128 v[180:183], v152
	ds_read_b128 v[184:187], v152 offset:1024
	ds_read_b128 v[188:191], v151
	ds_read_b128 v[192:195], v151 offset:1024
	ds_read_b128 v[196:199], v150
	ds_read_b128 v[200:203], v150 offset:1024
	ds_read_b128 v[204:207], v149
	ds_read_b128 v[208:211], v149 offset:1024
	global_load_lds_dwordx4 v[158:159], off
	v_lshl_add_u64 v[158:159], s[40:41], 0, v[132:133]
	v_readfirstlane_b32 s40, v170
	v_lshl_add_u64 v[158:159], v[158:159], 0, s[36:37]
	s_mov_b32 m0, s40
	s_nop 0
	global_load_lds_dwordx4 v[158:159], off
	s_barrier
	s_waitcnt lgkmcnt(0)
	s_setprio 0
	s_waitcnt lgkmcnt(0)
	v_mfma_f32_16x16x32_bf16 v[124:127], v[134:137], v[180:183], v[124:127]
	v_mfma_f32_16x16x32_bf16 v[120:123], v[172:175], v[180:183], v[120:123]
	v_mfma_f32_16x16x32_bf16 v[116:119], v[134:137], v[188:191], v[116:119]
	v_mfma_f32_16x16x32_bf16 v[112:115], v[172:175], v[188:191], v[112:115]
	v_mfma_f32_16x16x32_bf16 v[108:111], v[134:137], v[196:199], v[108:111]
	v_mfma_f32_16x16x32_bf16 v[104:107], v[172:175], v[196:199], v[104:107]
	v_mfma_f32_16x16x32_bf16 v[100:103], v[134:137], v[204:207], v[100:103]
	v_mfma_f32_16x16x32_bf16 v[96:99], v[172:175], v[204:207], v[96:99]
	v_mfma_f32_16x16x32_bf16 v[124:127], v[138:141], v[184:187], v[124:127]
	v_mfma_f32_16x16x32_bf16 v[120:123], v[176:179], v[184:187], v[120:123]
	v_mfma_f32_16x16x32_bf16 v[116:119], v[138:141], v[192:195], v[116:119]
	v_mfma_f32_16x16x32_bf16 v[112:115], v[176:179], v[192:195], v[112:115]
	v_mfma_f32_16x16x32_bf16 v[108:111], v[138:141], v[200:203], v[108:111]
	v_mfma_f32_16x16x32_bf16 v[104:107], v[176:179], v[200:203], v[104:107]
	v_mfma_f32_16x16x32_bf16 v[100:103], v[138:141], v[208:211], v[100:103]
	v_mfma_f32_16x16x32_bf16 v[96:99], v[176:179], v[208:211], v[96:99]
	s_setprio 0
	s_barrier
	ds_read_b128 v[212:215], v160
	ds_read_b128 v[216:219], v160 offset:1024
	ds_read_b128 v[220:223], v160 offset:2048
	ds_read_b128 v[158:161], v160 offset:3072
	s_barrier
; #define LDA(dst, b, h) for (int m = 0; m < 4; ++m) for (int k = 0; k < 2; ++k) \
;     dst[m][k] = *reinterpret_cast<const bf16x8*>((char*)SA(b, h) + lds_byte(wr * 64 + m * 16 + fr, k * 32 + fq * 8))
; #define LDB(dst, b, h) for (int n = 0; n < 2; ++n) for (int k = 0; k < 2; ++k) \
;     dst[n][k] = *reinterpret_cast<const bf16x8*>((char*)SB(b, h) + lds_byte(wc * 32 + n * 16 + fr, k * 32 + fq * 8))
; #define MMA(ai, bj, At_, Bt_) do { __builtin_amdgcn_s_setprio(1); \
;     for (int k = 0; k < 2; ++k) for (int m = 0; m < 4; ++m) for (int n = 0; n < 2; ++n) \
;       acc[ai][bj][m][n] = __builtin_amdgcn_mfma_f32_16x16x32_bf16(At_[m][k], Bt_[n][k], acc[ai][bj][m][n], 0, 0, 0); \
;     __builtin_amdgcn_s_setprio(0); } while (0)
; #define WAIT_V(n) asm volatile("s_waitcnt vmcnt(" #n ")" ::: "memory")
; #define WAIT_L(n) asm volatile("s_waitcnt lgkmcnt(" #n ")" ::: "memory")
; #define BAR __builtin_amdgcn_s_barrier()
; template <int EPI, int lda, int ldb, int N, int K>
; __device__ __forceinline__ void gemm_phase(const u16* __restrict__ A, const u16* __restrict__ Bt, const GemmEpi ep, int wv) {
;     ...
;       LDB(B1, 0, 1); BAR; WAIT_L(0); MMA(0, 1, At, B1); BAR;
;       LDA(At, 0, 1); WAIT_V(4); BAR; WAIT_L(0); MMA(1, 0, At, B0); MMA(1, 1, At, B1); BAR; }
;     { LDB(B0, 1, 0); LDA(At, 1, 0); WAIT_V(2); BAR; WAIT_L(0); MMA(0, 0, At, B0); BAR;
	s_waitcnt lgkmcnt(0)
	s_setprio 0
	s_waitcnt lgkmcnt(0)
	v_mfma_f32_16x16x32_bf16 v[92:95], v[212:215], v[180:183], v[92:95]
	v_mfma_f32_16x16x32_bf16 v[88:91], v[220:223], v[180:183], v[88:91]
	v_mfma_f32_16x16x32_bf16 v[76:79], v[212:215], v[196:199], v[76:79]
	v_mfma_f32_16x16x32_bf16 v[72:75], v[220:223], v[196:199], v[72:75]
	v_mfma_f32_16x16x32_bf16 v[84:87], v[212:215], v[188:191], v[84:87]
	v_mfma_f32_16x16x32_bf16 v[80:83], v[220:223], v[188:191], v[80:83]
	v_mfma_f32_16x16x32_bf16 v[68:71], v[212:215], v[204:207], v[68:71]
	v_mfma_f32_16x16x32_bf16 v[64:67], v[220:223], v[204:207], v[64:67]
	v_mfma_f32_16x16x32_bf16 v[92:95], v[216:219], v[184:187], v[92:95]
	v_mfma_f32_16x16x32_bf16 v[88:91], v[158:161], v[184:187], v[88:91]
	v_mfma_f32_16x16x32_bf16 v[76:79], v[216:219], v[200:203], v[76:79]
	v_mfma_f32_16x16x32_bf16 v[72:75], v[158:161], v[200:203], v[72:75]
	v_mfma_f32_16x16x32_bf16 v[180:183], v[216:219], v[192:195], v[84:87]
	v_mfma_f32_16x16x32_bf16 v[184:187], v[158:161], v[192:195], v[80:83]
	v_mfma_f32_16x16x32_bf16 v[188:191], v[216:219], v[208:211], v[68:71]
	v_mfma_f32_16x16x32_bf16 v[192:195], v[158:161], v[208:211], v[64:67]
	s_setprio 0
	s_barrier
	s_nop 0
	ds_read_b128 v[64:67], v152 offset:16384
	ds_read_b128 v[68:71], v152 offset:17408
	ds_read_b128 v[80:83], v151 offset:16384
	ds_read_b128 v[84:87], v151 offset:17408
	ds_read_b128 v[196:199], v150 offset:16384
	ds_read_b128 v[200:203], v150 offset:17408
	ds_read_b128 v[204:207], v149 offset:16384
	ds_read_b128 v[208:211], v149 offset:17408
	s_waitcnt vmcnt(4)
	s_barrier
	s_waitcnt lgkmcnt(0)
	s_setprio 0
	s_waitcnt lgkmcnt(0)
	v_mfma_f32_16x16x32_bf16 v[60:63], v[134:137], v[64:67], v[60:63]
	v_mfma_f32_16x16x32_bf16 v[56:59], v[172:175], v[64:67], v[56:59]
	v_mfma_f32_16x16x32_bf16 v[52:55], v[134:137], v[80:83], v[52:55]
	v_mfma_f32_16x16x32_bf16 v[48:51], v[172:175], v[80:83], v[48:51]
	v_mfma_f32_16x16x32_bf16 v[44:47], v[134:137], v[196:199], v[44:47]
	v_mfma_f32_16x16x32_bf16 v[40:43], v[172:175], v[196:199], v[40:43]
	v_mfma_f32_16x16x32_bf16 v[36:39], v[134:137], v[204:207], v[36:39]
	v_mfma_f32_16x16x32_bf16 v[32:35], v[172:175], v[204:207], v[32:35]
	v_mfma_f32_16x16x32_bf16 v[60:63], v[138:141], v[68:71], v[60:63]
	v_mfma_f32_16x16x32_bf16 v[56:59], v[176:179], v[68:71], v[56:59]
	v_mfma_f32_16x16x32_bf16 v[52:55], v[138:141], v[84:87], v[52:55]
	v_mfma_f32_16x16x32_bf16 v[48:51], v[176:179], v[84:87], v[48:51]
	v_mfma_f32_16x16x32_bf16 v[44:47], v[138:141], v[200:203], v[44:47]
	v_mfma_f32_16x16x32_bf16 v[40:43], v[176:179], v[200:203], v[40:43]
	v_mfma_f32_16x16x32_bf16 v[36:39], v[138:141], v[208:211], v[36:39]
	v_mfma_f32_16x16x32_bf16 v[32:35], v[176:179], v[208:211], v[32:35]
	s_setprio 0
	s_setprio 0
	v_mfma_f32_16x16x32_bf16 v[28:31], v[212:215], v[64:67], v[28:31]
	v_mfma_f32_16x16x32_bf16 v[24:27], v[220:223], v[64:67], v[24:27]
	v_mfma_f32_16x16x32_bf16 v[12:15], v[212:215], v[196:199], v[12:15]
	v_mfma_f32_16x16x32_bf16 v[8:11], v[220:223], v[196:199], v[8:11]
	v_mfma_f32_16x16x32_bf16 v[20:23], v[212:215], v[80:83], v[20:23]
	v_mfma_f32_16x16x32_bf16 v[16:19], v[220:223], v[80:83], v[16:19]
	v_mfma_f32_16x16x32_bf16 v[4:7], v[212:215], v[204:207], v[4:7]
	v_mfma_f32_16x16x32_bf16 v[0:3], v[220:223], v[204:207], v[0:3]
	v_mfma_f32_16x16x32_bf16 v[28:31], v[216:219], v[68:71], v[28:31]
	v_mfma_f32_16x16x32_bf16 v[24:27], v[158:161], v[68:71], v[24:27]
	v_mfma_f32_16x16x32_bf16 v[12:15], v[216:219], v[200:203], v[12:15]
	v_mfma_f32_16x16x32_bf16 v[8:11], v[158:161], v[200:203], v[8:11]
	v_mfma_f32_16x16x32_bf16 v[134:137], v[216:219], v[84:87], v[20:23]
	v_mfma_f32_16x16x32_bf16 v[138:141], v[158:161], v[84:87], v[16:19]
	v_mfma_f32_16x16x32_bf16 v[170:173], v[216:219], v[208:211], v[4:7]
	v_mfma_f32_16x16x32_bf16 v[158:161], v[158:161], v[208:211], v[0:3]
	s_setprio 0
	s_barrier
	s_nop 0
	ds_read_b128 v[0:3], v156
	ds_read_b128 v[4:7], v156 offset:1024
	ds_read_b128 v[16:19], v156 offset:2048
	ds_read_b128 v[174:177], v156 offset:3072
	ds_read_b128 v[20:23], v152 offset:32768
	ds_read_b128 v[196:199], v152 offset:33792
	ds_read_b128 v[200:203], v151 offset:32768
	ds_read_b128 v[204:207], v151 offset:33792
	ds_read_b128 v[208:211], v150 offset:32768
	ds_read_b128 v[212:215], v150 offset:33792
	ds_read_b128 v[216:219], v149 offset:32768
	ds_read_b128 v[220:223], v149 offset:33792
	s_waitcnt vmcnt(2)
	s_barrier
; #define LDA(dst, b, h) for (int m = 0; m < 4; ++m) for (int k = 0; k < 2; ++k) \
;     dst[m][k] = *reinterpret_cast<const bf16x8*>((char*)SA(b, h) + lds_byte(wr * 64 + m * 16 + fr, k * 32 + fq * 8))
; #define LDB(dst, b, h) for (int n = 0; n < 2; ++n) for (int k = 0; k < 2; ++k) \
;     dst[n][k] = *reinterpret_cast<const bf16x8*>((char*)SB(b, h) + lds_byte(wc * 32 + n * 16 + fr, k * 32 + fq * 8))
; #define MMA(ai, bj, At_, Bt_) do { __builtin_amdgcn_s_setprio(1); \
;     for (int k = 0; k < 2; ++k) for (int m = 0; m < 4; ++m) for (int n = 0; n < 2; ++n) \
;       acc[ai][bj][m][n] = __builtin_amdgcn_mfma_f32_16x16x32_bf16(At_[m][k], Bt_[n][k], acc[ai][bj][m][n], 0, 0, 0); \
;     __builtin_amdgcn_s_setprio(0); } while (0)
; #define WAIT_V(n) asm volatile("s_waitcnt vmcnt(" #n ")" ::: "memory")
; #define WAIT_L(n) asm volatile("s_waitcnt lgkmcnt(" #n ")" ::: "memory")
; #define BAR __builtin_amdgcn_s_barrier()
; template <int EPI, int lda, int ldb, int N, int K>
; __device__ __forceinline__ void gemm_phase(const u16* __restrict__ A, const u16* __restrict__ Bt, const GemmEpi ep, int wv) {
;     ...
;     { LDB(B0, 1, 0); LDA(At, 1, 0); WAIT_V(2); BAR; WAIT_L(0); MMA(0, 0, At, B0); BAR;
;       LDB(B1, 1, 1); WAIT_V(0); BAR; WAIT_L(0); MMA(0, 1, At, B1); BAR;
;       LDA(At, 1, 1); BAR; WAIT_L(0); MMA(1, 0, At, B0); MMA(1, 1, At, B1); BAR; }
;     if (wr == 0) BAR;
	s_waitcnt lgkmcnt(0)
	s_setprio 0
	s_waitcnt lgkmcnt(0)
	v_mfma_f32_16x16x32_bf16 v[64:67], v[0:3], v[20:23], v[124:127]
	v_mfma_f32_16x16x32_bf16 v[68:71], v[16:19], v[20:23], v[120:123]
	v_mfma_f32_16x16x32_bf16 v[80:83], v[0:3], v[200:203], v[116:119]
	v_mfma_f32_16x16x32_bf16 v[84:87], v[16:19], v[200:203], v[112:115]
	v_mfma_f32_16x16x32_bf16 v[108:111], v[0:3], v[208:211], v[108:111]
	v_mfma_f32_16x16x32_bf16 v[104:107], v[16:19], v[208:211], v[104:107]
	v_mfma_f32_16x16x32_bf16 v[120:123], v[0:3], v[216:219], v[100:103]
	v_mfma_f32_16x16x32_bf16 v[124:127], v[16:19], v[216:219], v[96:99]
	v_mfma_f32_16x16x32_bf16 v[116:119], v[4:7], v[196:199], v[64:67]
	v_mfma_f32_16x16x32_bf16 v[112:115], v[174:177], v[196:199], v[68:71]
	v_mfma_f32_16x16x32_bf16 v[100:103], v[4:7], v[204:207], v[80:83]
	v_mfma_f32_16x16x32_bf16 v[96:99], v[174:177], v[204:207], v[84:87]
	v_mfma_f32_16x16x32_bf16 v[84:87], v[4:7], v[212:215], v[108:111]
	v_mfma_f32_16x16x32_bf16 v[80:83], v[174:177], v[212:215], v[104:107]
	v_mfma_f32_16x16x32_bf16 v[68:71], v[4:7], v[220:223], v[120:123]
	v_mfma_f32_16x16x32_bf16 v[64:67], v[174:177], v[220:223], v[124:127]
	s_setprio 0
	s_barrier
	ds_read_b128 v[224:227], v154
	ds_read_b128 v[228:231], v154 offset:1024
	ds_read_b128 v[232:235], v154 offset:2048
	ds_read_b128 v[154:157], v154 offset:3072
	s_waitcnt vmcnt(0)
	s_barrier
	s_waitcnt lgkmcnt(0)
	s_setprio 0
	s_waitcnt lgkmcnt(0)
	v_mfma_f32_16x16x32_bf16 v[92:95], v[224:227], v[20:23], v[92:95]
	v_mfma_f32_16x16x32_bf16 v[20:23], v[232:235], v[20:23], v[88:91]
	v_mfma_f32_16x16x32_bf16 v[88:91], v[224:227], v[200:203], v[180:183]
	v_mfma_f32_16x16x32_bf16 v[104:107], v[232:235], v[200:203], v[184:187]
	v_mfma_f32_16x16x32_bf16 v[76:79], v[224:227], v[208:211], v[76:79]
	v_mfma_f32_16x16x32_bf16 v[72:75], v[232:235], v[208:211], v[72:75]
	v_mfma_f32_16x16x32_bf16 v[178:181], v[224:227], v[216:219], v[188:191]
	v_mfma_f32_16x16x32_bf16 v[182:185], v[232:235], v[216:219], v[192:195]
	v_mfma_f32_16x16x32_bf16 v[124:127], v[228:231], v[196:199], v[92:95]
	v_mfma_f32_16x16x32_bf16 v[120:123], v[154:157], v[196:199], v[20:23]
	v_mfma_f32_16x16x32_bf16 v[108:111], v[228:231], v[204:207], v[88:91]
	v_mfma_f32_16x16x32_bf16 v[104:107], v[154:157], v[204:207], v[104:107]
	v_mfma_f32_16x16x32_bf16 v[92:95], v[228:231], v[212:215], v[76:79]
	v_mfma_f32_16x16x32_bf16 v[88:91], v[154:157], v[212:215], v[72:75]
	v_mfma_f32_16x16x32_bf16 v[76:79], v[228:231], v[220:223], v[178:181]
	v_mfma_f32_16x16x32_bf16 v[72:75], v[154:157], v[220:223], v[182:185]
	s_setprio 0
	s_barrier
	ds_read_b128 v[178:181], v152 offset:49152
	ds_read_b128 v[182:185], v152 offset:50176
	ds_read_b128 v[186:189], v151 offset:49152
	ds_read_b128 v[190:193], v151 offset:50176
	ds_read_b128 v[194:197], v150 offset:49152
	ds_read_b128 v[150:153], v150 offset:50176
	ds_read_b128 v[198:201], v149 offset:49152
	ds_read_b128 v[202:205], v149 offset:50176
	s_barrier
	s_waitcnt lgkmcnt(0)
	s_setprio 0
	s_waitcnt lgkmcnt(0)
	v_mfma_f32_16x16x32_bf16 v[20:23], v[0:3], v[178:181], v[60:63]
	v_mfma_f32_16x16x32_bf16 v[56:59], v[16:19], v[178:181], v[56:59]
	v_mfma_f32_16x16x32_bf16 v[60:63], v[0:3], v[186:189], v[52:55]
	v_mfma_f32_16x16x32_bf16 v[206:209], v[16:19], v[186:189], v[48:51]
	v_mfma_f32_16x16x32_bf16 v[44:47], v[0:3], v[194:197], v[44:47]
	v_mfma_f32_16x16x32_bf16 v[40:43], v[16:19], v[194:197], v[40:43]
	v_mfma_f32_16x16x32_bf16 v[0:3], v[0:3], v[198:201], v[36:39]
	v_mfma_f32_16x16x32_bf16 v[210:213], v[16:19], v[198:201], v[32:35]
	v_mfma_f32_16x16x32_bf16 v[52:55], v[4:7], v[182:185], v[20:23]
	v_mfma_f32_16x16x32_bf16 v[48:51], v[174:177], v[182:185], v[56:59]
	v_mfma_f32_16x16x32_bf16 v[36:39], v[4:7], v[190:193], v[60:63]
	v_mfma_f32_16x16x32_bf16 v[32:35], v[174:177], v[190:193], v[206:209]
	v_mfma_f32_16x16x32_bf16 v[20:23], v[4:7], v[150:153], v[44:47]
	v_mfma_f32_16x16x32_bf16 v[16:19], v[174:177], v[150:153], v[40:43]
	v_mfma_f32_16x16x32_bf16 v[4:7], v[4:7], v[202:205], v[0:3]
	v_mfma_f32_16x16x32_bf16 v[0:3], v[174:177], v[202:205], v[210:213]
	s_setprio 0
	s_setprio 0
	v_mfma_f32_16x16x32_bf16 v[28:31], v[224:227], v[178:181], v[28:31]
	v_mfma_f32_16x16x32_bf16 v[24:27], v[232:235], v[178:181], v[24:27]
	v_mfma_f32_16x16x32_bf16 v[40:43], v[224:227], v[186:189], v[134:137]
	v_mfma_f32_16x16x32_bf16 v[134:137], v[232:235], v[186:189], v[138:141]
	v_mfma_f32_16x16x32_bf16 v[12:15], v[224:227], v[194:197], v[12:15]
	v_mfma_f32_16x16x32_bf16 v[8:11], v[232:235], v[194:197], v[8:11]
	v_mfma_f32_16x16x32_bf16 v[138:141], v[224:227], v[198:201], v[170:173]
	v_mfma_f32_16x16x32_bf16 v[158:161], v[232:235], v[198:201], v[158:161]
	v_mfma_f32_16x16x32_bf16 v[60:63], v[228:231], v[182:185], v[28:31]
	v_mfma_f32_16x16x32_bf16 v[56:59], v[154:157], v[182:185], v[24:27]
	v_mfma_f32_16x16x32_bf16 v[44:47], v[228:231], v[190:193], v[40:43]
	v_mfma_f32_16x16x32_bf16 v[40:43], v[154:157], v[190:193], v[134:137]
	v_mfma_f32_16x16x32_bf16 v[28:31], v[228:231], v[150:153], v[12:15]
	v_mfma_f32_16x16x32_bf16 v[24:27], v[154:157], v[150:153], v[8:11]
	v_mfma_f32_16x16x32_bf16 v[12:15], v[228:231], v[202:205], v[138:141]
	v_mfma_f32_16x16x32_bf16 v[8:11], v[154:157], v[202:205], v[158:161]
	s_setprio 0
	v_cmp_gt_u32_e32 vcc, s54, v130
	s_barrier
	s_and_saveexec_b64 s[40:41], vcc
	s_cbranch_execz .LBB0_1567
	s_barrier

; #define STAGE(P, BASE, LD, br, kt) do { const char* _g = (const char*)((BASE) + (size_t)(br) * (LD) + (size_t)(kt) * 64); \
;     for (int _i = 0; _i < 2; ++_i) { int _b = tidx * 16 + _i * 8192; int _r, _c; stage_rc(_b, _r, _c); \
;       __builtin_amdgcn_global_load_lds((const unsigned*)(_g + (unsigned)((_r * (LD) + _c) * 2)), (unsigned*)((char*)(P) + _b), 16, 0, 0); } } while (0)
; #define LDA(dst, b, h) for (int m = 0; m < 4; ++m) for (int k = 0; k < 2; ++k) \
;     dst[m][k] = *reinterpret_cast<const bf16x8*>((char*)SA(b, h) + lds_byte(wr * 64 + m * 16 + fr, k * 32 + fq * 8))
; #define LDB(dst, b, h) for (int n = 0; n < 2; ++n) for (int k = 0; k < 2; ++k) \
;     dst[n][k] = *reinterpret_cast<const bf16x8*>((char*)SB(b, h) + lds_byte(wc * 32 + n * 16 + fr, k * 32 + fq * 8))
; #define MMA(ai, bj, At_, Bt_) do { __builtin_amdgcn_s_setprio(1); \
;     for (int k = 0; k < 2; ++k) for (int m = 0; m < 4; ++m) for (int n = 0; n < 2; ++n) \
;       acc[ai][bj][m][n] = __builtin_amdgcn_mfma_f32_16x16x32_bf16(At_[m][k], Bt_[n][k], acc[ai][bj][m][n], 0, 0, 0); \
;     __builtin_amdgcn_s_setprio(0); } while (0)
; #define WAIT_L(n) asm volatile("s_waitcnt lgkmcnt(" #n ")" ::: "memory")
; #define BAR __builtin_amdgcn_s_barrier()
; #define SCHED __builtin_amdgcn_sched_barrier(0)
; template <int EPI, int lda, int ldb, int N, int K>
; __device__ __forceinline__ void gemm_phase(const u16* __restrict__ A, const u16* __restrict__ Bt, const GemmEpi ep, int wv) {
;     ...
;       LDB(B0, 0, 0); SCHED; LDA(At, 0, 0); STAGE(SA(1, 1), Ab, lda, brow + HALF, t + 1);
;       WAIT_L(8); BAR; WAIT_L(0); MMA(0, 0, At, B0); BAR; SCHED;
;       LDB(B1, 0, 1); STAGE(SB(0, 0), Bt, ldb, bcol, t + 2);
;       BAR; WAIT_L(0); MMA(0, 1, At, B1); BAR;
;       LDA(At, 0, 1); STAGE(SA(0, 0), Ab, lda, brow, t + 2);
;       BAR; WAIT_L(0); MMA(1, 0, At, B0); BAR; SCHED;
.LBB0_1624:
	ds_read_b128 v[174:177], v163
	ds_read_b128 v[178:181], v163 offset:1024
	ds_read_b128 v[182:185], v163 offset:2048
	ds_read_b128 v[186:189], v163 offset:3072
	v_add_u32_e32 v171, 0xc000, v149
	v_lshl_add_u64 v[238:239], v[134:135], 0, s[28:29]
	v_readfirstlane_b32 s50, v171
	v_add_u32_e32 v172, 0xe000, v149
	v_lshl_add_u64 v[164:165], v[238:239], 0, s[10:11]
	s_mov_b32 m0, s50
	v_lshl_add_u64 v[240:241], v[132:133], 0, s[28:29]
	v_readfirstlane_b32 s50, v172
	ds_read_b128 v[166:169], v154
	ds_read_b128 v[190:193], v154 offset:1024
	ds_read_b128 v[194:197], v153
	ds_read_b128 v[198:201], v153 offset:1024
	ds_read_b128 v[202:205], v151
	ds_read_b128 v[206:209], v151 offset:1024
	ds_read_b128 v[210:213], v150
	ds_read_b128 v[214:217], v150 offset:1024
	global_load_lds_dwordx4 v[164:165], off
	v_lshl_add_u64 v[164:165], v[240:241], 0, s[10:11]
	s_mov_b32 m0, s50
	s_nop 0
	global_load_lds_dwordx4 v[164:165], off
	s_waitcnt lgkmcnt(8)
	s_barrier
	s_waitcnt lgkmcnt(0)
	s_setprio 0
	s_waitcnt lgkmcnt(0)
	v_mfma_f32_16x16x32_bf16 v[124:127], v[166:169], v[174:177], v[124:127]
	v_mfma_f32_16x16x32_bf16 v[120:123], v[166:169], v[182:185], v[120:123]
	v_mfma_f32_16x16x32_bf16 v[116:119], v[194:197], v[174:177], v[116:119]
	v_mfma_f32_16x16x32_bf16 v[112:115], v[194:197], v[182:185], v[112:115]
	v_mfma_f32_16x16x32_bf16 v[108:111], v[202:205], v[174:177], v[108:111]
	v_mfma_f32_16x16x32_bf16 v[104:107], v[202:205], v[182:185], v[104:107]
	v_mfma_f32_16x16x32_bf16 v[100:103], v[210:213], v[174:177], v[100:103]
	v_mfma_f32_16x16x32_bf16 v[96:99], v[210:213], v[182:185], v[96:99]
	v_mfma_f32_16x16x32_bf16 v[124:127], v[190:193], v[178:181], v[124:127]
	v_mfma_f32_16x16x32_bf16 v[120:123], v[190:193], v[186:189], v[120:123]
	v_mfma_f32_16x16x32_bf16 v[116:119], v[198:201], v[178:181], v[116:119]
	v_mfma_f32_16x16x32_bf16 v[112:115], v[198:201], v[186:189], v[112:115]
	v_mfma_f32_16x16x32_bf16 v[108:111], v[206:209], v[178:181], v[108:111]
	v_mfma_f32_16x16x32_bf16 v[104:107], v[206:209], v[186:189], v[104:107]
	v_mfma_f32_16x16x32_bf16 v[100:103], v[214:217], v[178:181], v[100:103]
	v_mfma_f32_16x16x32_bf16 v[96:99], v[214:217], v[186:189], v[96:99]
	s_setprio 0
	s_barrier
	v_add_u32_e32 v164, s40, v155
	v_lshl_add_u64 v[242:243], v[142:143], 0, s[28:29]
	v_readfirstlane_b32 s50, v164
	v_add_u32_e32 v165, 0x2000, v164
	v_lshl_add_u64 v[234:235], v[242:243], 0, s[12:13]
	s_mov_b32 m0, s50
	v_lshl_add_u64 v[244:245], v[140:141], 0, s[28:29]
	v_readfirstlane_b32 s50, v165
	ds_read_b128 v[218:221], v162
	ds_read_b128 v[222:225], v162 offset:1024
	ds_read_b128 v[226:229], v162 offset:2048
	ds_read_b128 v[230:233], v162 offset:3072
	global_load_lds_dwordx4 v[234:235], off
	v_lshl_add_u64 v[234:235], v[244:245], 0, s[12:13]
	s_mov_b32 m0, s50
	s_nop 0
	global_load_lds_dwordx4 v[234:235], off
	s_barrier
	s_waitcnt lgkmcnt(0)
	s_setprio 0
	s_waitcnt lgkmcnt(0)
	v_mfma_f32_16x16x32_bf16 v[92:95], v[166:169], v[218:221], v[92:95]
	v_mfma_f32_16x16x32_bf16 v[88:91], v[166:169], v[226:229], v[88:91]
	v_mfma_f32_16x16x32_bf16 v[84:87], v[194:197], v[218:221], v[84:87]
	v_mfma_f32_16x16x32_bf16 v[80:83], v[194:197], v[226:229], v[80:83]
	v_mfma_f32_16x16x32_bf16 v[76:79], v[202:205], v[218:221], v[76:79]
	v_mfma_f32_16x16x32_bf16 v[72:75], v[202:205], v[226:229], v[72:75]
	v_mfma_f32_16x16x32_bf16 v[68:71], v[210:213], v[218:221], v[68:71]
	v_mfma_f32_16x16x32_bf16 v[64:67], v[210:213], v[226:229], v[64:67]
	v_mfma_f32_16x16x32_bf16 v[92:95], v[190:193], v[222:225], v[92:95]
	v_mfma_f32_16x16x32_bf16 v[88:91], v[190:193], v[230:233], v[88:91]
	v_mfma_f32_16x16x32_bf16 v[84:87], v[198:201], v[222:225], v[84:87]
	v_mfma_f32_16x16x32_bf16 v[80:83], v[198:201], v[230:233], v[80:83]
	v_mfma_f32_16x16x32_bf16 v[76:79], v[206:209], v[222:225], v[76:79]
	v_mfma_f32_16x16x32_bf16 v[72:75], v[206:209], v[230:233], v[72:75]
	v_mfma_f32_16x16x32_bf16 v[68:71], v[214:217], v[222:225], v[68:71]
	v_mfma_f32_16x16x32_bf16 v[64:67], v[214:217], v[230:233], v[64:67]
	s_setprio 0
	v_readfirstlane_b32 s50, v149
	v_lshl_add_u64 v[166:167], v[238:239], 0, s[14:15]
	s_mov_b32 m0, s50
	s_barrier
	ds_read_b128 v[190:193], v154 offset:16384
	ds_read_b128 v[194:197], v154 offset:17408
	ds_read_b128 v[198:201], v153 offset:16384
	ds_read_b128 v[202:205], v153 offset:17408
	ds_read_b128 v[206:209], v151 offset:16384
	ds_read_b128 v[210:213], v151 offset:17408
	ds_read_b128 v[214:217], v150 offset:16384
	ds_read_b128 v[234:237], v150 offset:17408
	global_load_lds_dwordx4 v[166:167], off
	v_add_u32_e32 v166, 0x2000, v149
	v_lshl_add_u64 v[168:169], v[240:241], 0, s[14:15]
	v_readfirstlane_b32 s50, v166
	s_mov_b32 m0, s50
	s_nop 0
	global_load_lds_dwordx4 v[168:169], off
	s_barrier
	s_waitcnt lgkmcnt(0)
	s_setprio 0
	s_waitcnt lgkmcnt(0)
	v_mfma_f32_16x16x32_bf16 v[60:63], v[190:193], v[174:177], v[60:63]
	v_mfma_f32_16x16x32_bf16 v[56:59], v[190:193], v[182:185], v[56:59]
	v_mfma_f32_16x16x32_bf16 v[52:55], v[198:201], v[174:177], v[52:55]
	v_mfma_f32_16x16x32_bf16 v[48:51], v[198:201], v[182:185], v[48:51]
	v_mfma_f32_16x16x32_bf16 v[44:47], v[206:209], v[174:177], v[44:47]
	v_mfma_f32_16x16x32_bf16 v[40:43], v[206:209], v[182:185], v[40:43]
	v_mfma_f32_16x16x32_bf16 v[36:39], v[214:217], v[174:177], v[36:39]
	v_mfma_f32_16x16x32_bf16 v[32:35], v[214:217], v[182:185], v[32:35]
	v_mfma_f32_16x16x32_bf16 v[60:63], v[194:197], v[178:181], v[60:63]
	v_mfma_f32_16x16x32_bf16 v[56:59], v[194:197], v[186:189], v[56:59]
	v_mfma_f32_16x16x32_bf16 v[52:55], v[202:205], v[178:181], v[52:55]
	v_mfma_f32_16x16x32_bf16 v[48:51], v[202:205], v[186:189], v[48:51]
	v_mfma_f32_16x16x32_bf16 v[44:47], v[210:213], v[178:181], v[44:47]
	v_mfma_f32_16x16x32_bf16 v[40:43], v[210:213], v[186:189], v[40:43]
	v_mfma_f32_16x16x32_bf16 v[36:39], v[234:237], v[178:181], v[36:39]
	v_mfma_f32_16x16x32_bf16 v[32:35], v[234:237], v[186:189], v[32:35]
	s_setprio 0
	s_barrier
; #define STAGE(P, BASE, LD, br, kt) do { const char* _g = (const char*)((BASE) + (size_t)(br) * (LD) + (size_t)(kt) * 64); \
;     for (int _i = 0; _i < 2; ++_i) { int _b = tidx * 16 + _i * 8192; int _r, _c; stage_rc(_b, _r, _c); \
;       __builtin_amdgcn_global_load_lds((const unsigned*)(_g + (unsigned)((_r * (LD) + _c) * 2)), (unsigned*)((char*)(P) + _b), 16, 0, 0); } } while (0)
; #define LDA(dst, b, h) for (int m = 0; m < 4; ++m) for (int k = 0; k < 2; ++k) \
;     dst[m][k] = *reinterpret_cast<const bf16x8*>((char*)SA(b, h) + lds_byte(wr * 64 + m * 16 + fr, k * 32 + fq * 8))
; #define LDB(dst, b, h) for (int n = 0; n < 2; ++n) for (int k = 0; k < 2; ++k) \
;     dst[n][k] = *reinterpret_cast<const bf16x8*>((char*)SB(b, h) + lds_byte(wc * 32 + n * 16 + fr, k * 32 + fq * 8))
; #define MMA(ai, bj, At_, Bt_) do { __builtin_amdgcn_s_setprio(1); \
;     for (int k = 0; k < 2; ++k) for (int m = 0; m < 4; ++m) for (int n = 0; n < 2; ++n) \
;       acc[ai][bj][m][n] = __builtin_amdgcn_mfma_f32_16x16x32_bf16(At_[m][k], Bt_[n][k], acc[ai][bj][m][n], 0, 0, 0); \
;     __builtin_amdgcn_s_setprio(0); } while (0)
; #define WAIT_V(n) asm volatile("s_waitcnt vmcnt(" #n ")" ::: "memory")
; #define WAIT_L(n) asm volatile("s_waitcnt lgkmcnt(" #n ")" ::: "memory")
; #define BAR __builtin_amdgcn_s_barrier()
; #define SCHED __builtin_amdgcn_sched_barrier(0)
; template <int EPI, int lda, int ldb, int N, int K>
; __device__ __forceinline__ void gemm_phase(const u16* __restrict__ A, const u16* __restrict__ Bt, const GemmEpi ep, int wv) {
;     ...
;       STAGE(SB(0, 1), Bt, ldb, bcol + HALF, t + 2);
;       WAIT_V(6); BAR; MMA(1, 1, At, B1); BAR;
;       LDB(B0, 1, 0); SCHED; LDA(At, 1, 0); STAGE(SA(0, 1), Ab, lda, brow + HALF, t + 2);
;       WAIT_L(8); BAR; WAIT_L(0); MMA(0, 0, At, B0); BAR; SCHED;
;       LDB(B1, 1, 1); STAGE(SB(1, 0), Bt, ldb, bcol, t + 3);
;       BAR; WAIT_L(0); MMA(0, 1, At, B1); BAR;
;       LDA(At, 1, 1); STAGE(SA(1, 0), Ab, lda, brow, t + 3);
	v_add_u32_e32 v167, s41, v155
	v_lshl_add_u64 v[246:247], v[138:139], 0, s[28:29]
	v_readfirstlane_b32 s50, v167
	v_lshl_add_u64 v[168:169], v[246:247], 0, s[16:17]
	s_mov_b32 m0, s50
	v_lshl_add_u64 v[248:249], v[136:137], 0, s[28:29]
	global_load_lds_dwordx4 v[168:169], off
	v_add_u32_e32 v168, 0x2000, v167
	v_lshl_add_u64 v[174:175], v[248:249], 0, s[16:17]
	v_readfirstlane_b32 s50, v168
	s_mov_b32 m0, s50
	s_nop 0
	global_load_lds_dwordx4 v[174:175], off
	s_waitcnt vmcnt(6)
	s_barrier
	s_setprio 0
	v_mfma_f32_16x16x32_bf16 v[28:31], v[190:193], v[218:221], v[28:31]
	v_mfma_f32_16x16x32_bf16 v[24:27], v[190:193], v[226:229], v[24:27]
	v_mfma_f32_16x16x32_bf16 v[20:23], v[198:201], v[218:221], v[20:23]
	v_mfma_f32_16x16x32_bf16 v[16:19], v[198:201], v[226:229], v[16:19]
	v_mfma_f32_16x16x32_bf16 v[12:15], v[206:209], v[218:221], v[12:15]
	v_mfma_f32_16x16x32_bf16 v[8:11], v[206:209], v[226:229], v[8:11]
	v_mfma_f32_16x16x32_bf16 v[4:7], v[214:217], v[218:221], v[4:7]
	v_mfma_f32_16x16x32_bf16 v[0:3], v[214:217], v[226:229], v[0:3]
	v_mfma_f32_16x16x32_bf16 v[28:31], v[194:197], v[222:225], v[28:31]
	v_mfma_f32_16x16x32_bf16 v[24:27], v[194:197], v[230:233], v[24:27]
	v_mfma_f32_16x16x32_bf16 v[20:23], v[202:205], v[222:225], v[20:23]
	v_mfma_f32_16x16x32_bf16 v[16:19], v[202:205], v[230:233], v[16:19]
	v_mfma_f32_16x16x32_bf16 v[12:15], v[210:213], v[222:225], v[12:15]
	v_mfma_f32_16x16x32_bf16 v[8:11], v[210:213], v[230:233], v[8:11]
	v_mfma_f32_16x16x32_bf16 v[4:7], v[234:237], v[222:225], v[4:7]
	v_mfma_f32_16x16x32_bf16 v[0:3], v[234:237], v[230:233], v[0:3]
	s_setprio 0
	s_barrier
	ds_read_b128 v[174:177], v158
	ds_read_b128 v[178:181], v158 offset:1024
	ds_read_b128 v[182:185], v158 offset:2048
	ds_read_b128 v[186:189], v158 offset:3072
	v_add_u32_e32 v169, 0x4000, v149
	v_add_u32_e32 v170, 0x6000, v149
	v_readfirstlane_b32 s50, v169
	v_lshl_add_u64 v[222:223], v[238:239], 0, s[18:19]
	s_mov_b32 m0, s50
	v_readfirstlane_b32 s50, v170
	ds_read_b128 v[190:193], v154 offset:32768
	ds_read_b128 v[194:197], v154 offset:33792
	ds_read_b128 v[198:201], v153 offset:32768
	ds_read_b128 v[202:205], v153 offset:33792
	ds_read_b128 v[206:209], v151 offset:32768
	ds_read_b128 v[210:213], v151 offset:33792
	ds_read_b128 v[214:217], v150 offset:32768
	ds_read_b128 v[218:221], v150 offset:33792
	global_load_lds_dwordx4 v[222:223], off
	v_lshl_add_u64 v[222:223], v[240:241], 0, s[18:19]
	s_mov_b32 m0, s50
	s_nop 0
	global_load_lds_dwordx4 v[222:223], off
	s_waitcnt lgkmcnt(8)
	s_barrier
	s_waitcnt lgkmcnt(0)
	s_setprio 0
	s_waitcnt lgkmcnt(0)
	v_mfma_f32_16x16x32_bf16 v[124:127], v[190:193], v[174:177], v[124:127]
	v_mfma_f32_16x16x32_bf16 v[120:123], v[190:193], v[182:185], v[120:123]
	v_mfma_f32_16x16x32_bf16 v[116:119], v[198:201], v[174:177], v[116:119]
	v_mfma_f32_16x16x32_bf16 v[112:115], v[198:201], v[182:185], v[112:115]
	v_mfma_f32_16x16x32_bf16 v[108:111], v[206:209], v[174:177], v[108:111]
	v_mfma_f32_16x16x32_bf16 v[104:107], v[206:209], v[182:185], v[104:107]
	v_mfma_f32_16x16x32_bf16 v[100:103], v[214:217], v[174:177], v[100:103]
	v_mfma_f32_16x16x32_bf16 v[96:99], v[214:217], v[182:185], v[96:99]
	v_mfma_f32_16x16x32_bf16 v[124:127], v[194:197], v[178:181], v[124:127]
	v_mfma_f32_16x16x32_bf16 v[120:123], v[194:197], v[186:189], v[120:123]
	v_mfma_f32_16x16x32_bf16 v[116:119], v[202:205], v[178:181], v[116:119]
	v_mfma_f32_16x16x32_bf16 v[112:115], v[202:205], v[186:189], v[112:115]
	v_mfma_f32_16x16x32_bf16 v[108:111], v[210:213], v[178:181], v[108:111]
	v_mfma_f32_16x16x32_bf16 v[104:107], v[210:213], v[186:189], v[104:107]
	v_mfma_f32_16x16x32_bf16 v[100:103], v[218:221], v[178:181], v[100:103]
	v_mfma_f32_16x16x32_bf16 v[96:99], v[218:221], v[186:189], v[96:99]
	s_setprio 0
	s_barrier
	v_readfirstlane_b32 s50, v157
	v_add_u32_e32 v173, 0x2000, v157
	v_lshl_add_u64 v[242:243], v[242:243], 0, s[20:21]
	s_mov_b32 m0, s50
	v_readfirstlane_b32 s50, v173
	ds_read_b128 v[222:225], v156
	ds_read_b128 v[226:229], v156 offset:1024
	ds_read_b128 v[230:233], v156 offset:2048
	ds_read_b128 v[234:237], v156 offset:3072
	global_load_lds_dwordx4 v[242:243], off
	v_lshl_add_u64 v[242:243], v[244:245], 0, s[20:21]
	s_mov_b32 m0, s50
	s_nop 0
	global_load_lds_dwordx4 v[242:243], off
	s_barrier
	s_waitcnt lgkmcnt(0)
	s_setprio 0
	s_waitcnt lgkmcnt(0)
	v_mfma_f32_16x16x32_bf16 v[92:95], v[190:193], v[222:225], v[92:95]
	v_mfma_f32_16x16x32_bf16 v[88:91], v[190:193], v[230:233], v[88:91]
	v_mfma_f32_16x16x32_bf16 v[84:87], v[198:201], v[222:225], v[84:87]
	v_mfma_f32_16x16x32_bf16 v[80:83], v[198:201], v[230:233], v[80:83]
	v_mfma_f32_16x16x32_bf16 v[76:79], v[206:209], v[222:225], v[76:79]
	v_mfma_f32_16x16x32_bf16 v[72:75], v[206:209], v[230:233], v[72:75]
	v_mfma_f32_16x16x32_bf16 v[68:71], v[214:217], v[222:225], v[68:71]
	v_mfma_f32_16x16x32_bf16 v[64:67], v[214:217], v[230:233], v[64:67]
	v_mfma_f32_16x16x32_bf16 v[92:95], v[194:197], v[226:229], v[92:95]
	v_mfma_f32_16x16x32_bf16 v[88:91], v[194:197], v[234:237], v[88:91]
	v_mfma_f32_16x16x32_bf16 v[84:87], v[202:205], v[226:229], v[84:87]
	v_mfma_f32_16x16x32_bf16 v[80:83], v[202:205], v[234:237], v[80:83]
	v_mfma_f32_16x16x32_bf16 v[76:79], v[210:213], v[226:229], v[76:79]
	v_mfma_f32_16x16x32_bf16 v[72:75], v[210:213], v[234:237], v[72:75]
	v_mfma_f32_16x16x32_bf16 v[68:71], v[218:221], v[226:229], v[68:71]
	v_mfma_f32_16x16x32_bf16 v[64:67], v[218:221], v[234:237], v[64:67]
	s_setprio 0
	v_readfirstlane_b32 s50, v159
	v_lshl_add_u64 v[238:239], v[238:239], 0, s[22:23]
	s_mov_b32 m0, s50
	v_readfirstlane_b32 s50, v160
	s_barrier
; #define STAGE(P, BASE, LD, br, kt) do { const char* _g = (const char*)((BASE) + (size_t)(br) * (LD) + (size_t)(kt) * 64); \
;     for (int _i = 0; _i < 2; ++_i) { int _b = tidx * 16 + _i * 8192; int _r, _c; stage_rc(_b, _r, _c); \
;       __builtin_amdgcn_global_load_lds((const unsigned*)(_g + (unsigned)((_r * (LD) + _c) * 2)), (unsigned*)((char*)(P) + _b), 16, 0, 0); } } while (0)
; #define LDA(dst, b, h) for (int m = 0; m < 4; ++m) for (int k = 0; k < 2; ++k) \
;     dst[m][k] = *reinterpret_cast<const bf16x8*>((char*)SA(b, h) + lds_byte(wr * 64 + m * 16 + fr, k * 32 + fq * 8))
; #define LDB(dst, b, h) for (int n = 0; n < 2; ++n) for (int k = 0; k < 2; ++k) \
;     dst[n][k] = *reinterpret_cast<const bf16x8*>((char*)SB(b, h) + lds_byte(wc * 32 + n * 16 + fr, k * 32 + fq * 8))
; #define MMA(ai, bj, At_, Bt_) do { __builtin_amdgcn_s_setprio(1); \
;     for (int k = 0; k < 2; ++k) for (int m = 0; m < 4; ++m) for (int n = 0; n < 2; ++n) \
;       acc[ai][bj][m][n] = __builtin_amdgcn_mfma_f32_16x16x32_bf16(At_[m][k], Bt_[n][k], acc[ai][bj][m][n], 0, 0, 0); \
;     __builtin_amdgcn_s_setprio(0); } while (0)
; #define WAIT_V(n) asm volatile("s_waitcnt vmcnt(" #n ")" ::: "memory")
; #define WAIT_L(n) asm volatile("s_waitcnt lgkmcnt(" #n ")" ::: "memory")
; #define BAR __builtin_amdgcn_s_barrier()
; #define SCHED __builtin_amdgcn_sched_barrier(0)
; template <int EPI, int lda, int ldb, int N, int K>
; __device__ __forceinline__ void gemm_phase(const u16* __restrict__ A, const u16* __restrict__ Bt, const GemmEpi ep, int wv) {
;     ...
;       LDA(At, 1, 1); STAGE(SA(1, 0), Ab, lda, brow, t + 3);
;       BAR; WAIT_L(0); MMA(1, 0, At, B0); BAR; SCHED;
;       STAGE(SB(1, 1), Bt, ldb, bcol + HALF, t + 3);
;       WAIT_V(6); BAR; MMA(1, 1, At, B1); BAR;
;     }
;     { LDB(B0, 0, 0); LDA(At, 0, 0); STAGE(SA(1, 1), Ab, lda, brow + HALF, nt - 1);
;       BAR; WAIT_L(0); MMA(0, 0, At, B0); BAR;
;       LDB(B1, 0, 1); BAR; WAIT_L(0); MMA(0, 1, At, B1); BAR;
	ds_read_b128 v[190:193], v154 offset:49152
	ds_read_b128 v[194:197], v154 offset:50176
	ds_read_b128 v[198:201], v153 offset:49152
	ds_read_b128 v[202:205], v153 offset:50176
	ds_read_b128 v[206:209], v151 offset:49152
	ds_read_b128 v[210:213], v151 offset:50176
	ds_read_b128 v[214:217], v150 offset:49152
	ds_read_b128 v[218:221], v150 offset:50176
	global_load_lds_dwordx4 v[238:239], off
	v_lshl_add_u64 v[238:239], v[240:241], 0, s[22:23]
	s_mov_b32 m0, s50
	s_nop 0
	global_load_lds_dwordx4 v[238:239], off
	s_barrier
	s_waitcnt lgkmcnt(0)
	s_setprio 0
	s_waitcnt lgkmcnt(0)
	v_mfma_f32_16x16x32_bf16 v[60:63], v[190:193], v[174:177], v[60:63]
	v_mfma_f32_16x16x32_bf16 v[56:59], v[190:193], v[182:185], v[56:59]
	v_mfma_f32_16x16x32_bf16 v[52:55], v[198:201], v[174:177], v[52:55]
	v_mfma_f32_16x16x32_bf16 v[48:51], v[198:201], v[182:185], v[48:51]
	v_mfma_f32_16x16x32_bf16 v[44:47], v[206:209], v[174:177], v[44:47]
	v_mfma_f32_16x16x32_bf16 v[40:43], v[206:209], v[182:185], v[40:43]
	v_mfma_f32_16x16x32_bf16 v[36:39], v[214:217], v[174:177], v[36:39]
	v_mfma_f32_16x16x32_bf16 v[32:35], v[214:217], v[182:185], v[32:35]
	v_mfma_f32_16x16x32_bf16 v[60:63], v[194:197], v[178:181], v[60:63]
	v_mfma_f32_16x16x32_bf16 v[56:59], v[194:197], v[186:189], v[56:59]
	v_mfma_f32_16x16x32_bf16 v[52:55], v[202:205], v[178:181], v[52:55]
	v_mfma_f32_16x16x32_bf16 v[48:51], v[202:205], v[186:189], v[48:51]
	v_mfma_f32_16x16x32_bf16 v[44:47], v[210:213], v[178:181], v[44:47]
	v_mfma_f32_16x16x32_bf16 v[40:43], v[210:213], v[186:189], v[40:43]
	v_mfma_f32_16x16x32_bf16 v[36:39], v[218:221], v[178:181], v[36:39]
	v_mfma_f32_16x16x32_bf16 v[32:35], v[218:221], v[186:189], v[32:35]
	s_setprio 0
	s_barrier
	v_readfirstlane_b32 s50, v161
	v_add_u32_e32 v173, 0x2000, v161
	v_lshl_add_u64 v[174:175], v[246:247], 0, s[24:25]
	s_mov_b32 m0, s50
	v_readfirstlane_b32 s50, v173
	global_load_lds_dwordx4 v[174:175], off
	v_lshl_add_u64 v[174:175], v[248:249], 0, s[24:25]
	s_mov_b32 m0, s50
	s_nop 0
	global_load_lds_dwordx4 v[174:175], off
	s_waitcnt vmcnt(6)
	s_barrier
	s_setprio 0
	v_mfma_f32_16x16x32_bf16 v[28:31], v[190:193], v[222:225], v[28:31]
	v_mfma_f32_16x16x32_bf16 v[24:27], v[190:193], v[230:233], v[24:27]
	v_mfma_f32_16x16x32_bf16 v[20:23], v[198:201], v[222:225], v[20:23]
	v_mfma_f32_16x16x32_bf16 v[16:19], v[198:201], v[230:233], v[16:19]
	v_mfma_f32_16x16x32_bf16 v[12:15], v[206:209], v[222:225], v[12:15]
	v_mfma_f32_16x16x32_bf16 v[8:11], v[206:209], v[230:233], v[8:11]
	v_mfma_f32_16x16x32_bf16 v[4:7], v[214:217], v[222:225], v[4:7]
	v_mfma_f32_16x16x32_bf16 v[0:3], v[214:217], v[230:233], v[0:3]
	v_mfma_f32_16x16x32_bf16 v[28:31], v[194:197], v[226:229], v[28:31]
	v_mfma_f32_16x16x32_bf16 v[24:27], v[194:197], v[234:237], v[24:27]
	v_mfma_f32_16x16x32_bf16 v[20:23], v[202:205], v[226:229], v[20:23]
	v_mfma_f32_16x16x32_bf16 v[16:19], v[202:205], v[234:237], v[16:19]
	v_mfma_f32_16x16x32_bf16 v[12:15], v[210:213], v[226:229], v[12:15]
	v_mfma_f32_16x16x32_bf16 v[8:11], v[210:213], v[234:237], v[8:11]
	v_mfma_f32_16x16x32_bf16 v[4:7], v[218:221], v[226:229], v[4:7]
	v_mfma_f32_16x16x32_bf16 v[0:3], v[218:221], v[234:237], v[0:3]
	s_setprio 0
	s_add_i32 s49, s49, 2
	s_add_u32 s28, s28, 0x100
	s_addc_u32 s29, s29, 0
	s_cmpk_gt_u32 s49, 0x51
	s_barrier
	s_cbranch_scc0 .LBB0_1624
	s_add_i32 s28, s48, 0x80
	s_mul_hi_i32 s29, s28, 0x2b00
	s_mulk_i32 s28, 0x2b00
	s_add_u32 s28, s34, s28
	s_addc_u32 s29, s35, s29
	s_add_u32 s28, s28, 0x2a80
	s_addc_u32 s29, s29, 0
	v_readfirstlane_b32 s49, v171
	v_lshl_add_u64 v[160:161], s[28:29], 0, v[128:129]
	s_mov_b32 m0, s49
	ds_read_b128 v[132:135], v163
	ds_read_b128 v[136:139], v163 offset:1024
	ds_read_b128 v[140:143], v163 offset:2048
	ds_read_b128 v[174:177], v163 offset:3072
	ds_read_b128 v[178:181], v154
	ds_read_b128 v[182:185], v154 offset:1024
	ds_read_b128 v[186:189], v153
	ds_read_b128 v[190:193], v153 offset:1024
	ds_read_b128 v[194:197], v151
	ds_read_b128 v[198:201], v151 offset:1024
	ds_read_b128 v[202:205], v150
	ds_read_b128 v[206:209], v150 offset:1024
	global_load_lds_dwordx4 v[160:161], off
	v_lshl_add_u64 v[160:161], s[28:29], 0, v[130:131]
	v_readfirstlane_b32 s28, v172
	s_mov_b32 m0, s28
	s_nop 0
	global_load_lds_dwordx4 v[160:161], off
	s_barrier
	s_waitcnt lgkmcnt(0)
	s_setprio 0
	s_waitcnt lgkmcnt(0)
	v_mfma_f32_16x16x32_bf16 v[124:127], v[178:181], v[132:135], v[124:127]
	v_mfma_f32_16x16x32_bf16 v[120:123], v[178:181], v[140:143], v[120:123]
	v_mfma_f32_16x16x32_bf16 v[116:119], v[186:189], v[132:135], v[116:119]
	v_mfma_f32_16x16x32_bf16 v[112:115], v[186:189], v[140:143], v[112:115]
	v_mfma_f32_16x16x32_bf16 v[108:111], v[194:197], v[132:135], v[108:111]
	v_mfma_f32_16x16x32_bf16 v[104:107], v[194:197], v[140:143], v[104:107]
	v_mfma_f32_16x16x32_bf16 v[100:103], v[202:205], v[132:135], v[100:103]
	v_mfma_f32_16x16x32_bf16 v[96:99], v[202:205], v[140:143], v[96:99]
	v_mfma_f32_16x16x32_bf16 v[124:127], v[182:185], v[136:139], v[124:127]
	v_mfma_f32_16x16x32_bf16 v[120:123], v[182:185], v[174:177], v[120:123]
	v_mfma_f32_16x16x32_bf16 v[116:119], v[190:193], v[136:139], v[116:119]
	v_mfma_f32_16x16x32_bf16 v[112:115], v[190:193], v[174:177], v[112:115]
	v_mfma_f32_16x16x32_bf16 v[108:111], v[198:201], v[136:139], v[108:111]
	v_mfma_f32_16x16x32_bf16 v[104:107], v[198:201], v[174:177], v[104:107]
	v_mfma_f32_16x16x32_bf16 v[100:103], v[206:209], v[136:139], v[100:103]
	v_mfma_f32_16x16x32_bf16 v[96:99], v[206:209], v[174:177], v[96:99]
	s_setprio 0
	s_barrier
	ds_read_b128 v[210:213], v162
	ds_read_b128 v[214:217], v162 offset:1024
	ds_read_b128 v[218:221], v162 offset:2048
	ds_read_b128 v[160:163], v162 offset:3072
	s_barrier
; #define LDA(dst, b, h) for (int m = 0; m < 4; ++m) for (int k = 0; k < 2; ++k) \
;     dst[m][k] = *reinterpret_cast<const bf16x8*>((char*)SA(b, h) + lds_byte(wr * 64 + m * 16 + fr, k * 32 + fq * 8))
; #define LDB(dst, b, h) for (int n = 0; n < 2; ++n) for (int k = 0; k < 2; ++k) \
;     dst[n][k] = *reinterpret_cast<const bf16x8*>((char*)SB(b, h) + lds_byte(wc * 32 + n * 16 + fr, k * 32 + fq * 8))
; #define MMA(ai, bj, At_, Bt_) do { __builtin_amdgcn_s_setprio(1); \
;     for (int k = 0; k < 2; ++k) for (int m = 0; m < 4; ++m) for (int n = 0; n < 2; ++n) \
;       acc[ai][bj][m][n] = __builtin_amdgcn_mfma_f32_16x16x32_bf16(At_[m][k], Bt_[n][k], acc[ai][bj][m][n], 0, 0, 0); \
;     __builtin_amdgcn_s_setprio(0); } while (0)
; #define WAIT_V(n) asm volatile("s_waitcnt vmcnt(" #n ")" ::: "memory")
; #define WAIT_L(n) asm volatile("s_waitcnt lgkmcnt(" #n ")" ::: "memory")
; #define BAR __builtin_amdgcn_s_barrier()
; template <int EPI, int lda, int ldb, int N, int K>
; __device__ __forceinline__ void gemm_phase(const u16* __restrict__ A, const u16* __restrict__ Bt, const GemmEpi ep, int wv) {
;     ...
;       LDB(B1, 0, 1); BAR; WAIT_L(0); MMA(0, 1, At, B1); BAR;
;       LDA(At, 0, 1); WAIT_V(4); BAR; WAIT_L(0); MMA(1, 0, At, B0); MMA(1, 1, At, B1); BAR; }
;     { LDB(B0, 1, 0); LDA(At, 1, 0); WAIT_V(2); BAR; WAIT_L(0); MMA(0, 0, At, B0); BAR;
	s_waitcnt lgkmcnt(0)
	s_setprio 0
	s_waitcnt lgkmcnt(0)
	v_mfma_f32_16x16x32_bf16 v[92:95], v[178:181], v[210:213], v[92:95]
	v_mfma_f32_16x16x32_bf16 v[88:91], v[178:181], v[218:221], v[88:91]
	v_mfma_f32_16x16x32_bf16 v[72:75], v[194:197], v[218:221], v[72:75]
	v_mfma_f32_16x16x32_bf16 v[68:71], v[202:205], v[210:213], v[68:71]
	v_mfma_f32_16x16x32_bf16 v[84:87], v[186:189], v[210:213], v[84:87]
	v_mfma_f32_16x16x32_bf16 v[80:83], v[186:189], v[218:221], v[80:83]
	v_mfma_f32_16x16x32_bf16 v[76:79], v[194:197], v[210:213], v[76:79]
	v_mfma_f32_16x16x32_bf16 v[64:67], v[202:205], v[218:221], v[64:67]
	v_mfma_f32_16x16x32_bf16 v[92:95], v[182:185], v[214:217], v[92:95]
	v_mfma_f32_16x16x32_bf16 v[88:91], v[182:185], v[160:163], v[88:91]
	v_mfma_f32_16x16x32_bf16 v[72:75], v[198:201], v[160:163], v[72:75]
	v_mfma_f32_16x16x32_bf16 v[68:71], v[206:209], v[214:217], v[68:71]
	v_mfma_f32_16x16x32_bf16 v[178:181], v[190:193], v[214:217], v[84:87]
	v_mfma_f32_16x16x32_bf16 v[182:185], v[190:193], v[160:163], v[80:83]
	v_mfma_f32_16x16x32_bf16 v[186:189], v[198:201], v[214:217], v[76:79]
	v_mfma_f32_16x16x32_bf16 v[190:193], v[206:209], v[160:163], v[64:67]
	s_setprio 0
	s_barrier
	s_nop 0
	ds_read_b128 v[64:67], v154 offset:16384
	ds_read_b128 v[76:79], v154 offset:17408
	ds_read_b128 v[80:83], v153 offset:16384
	ds_read_b128 v[84:87], v153 offset:17408
	ds_read_b128 v[194:197], v151 offset:16384
	ds_read_b128 v[198:201], v151 offset:17408
	ds_read_b128 v[202:205], v150 offset:16384
	ds_read_b128 v[206:209], v150 offset:17408
	s_waitcnt vmcnt(4)
	s_barrier
	s_waitcnt lgkmcnt(0)
	s_setprio 0
	s_waitcnt lgkmcnt(0)
	v_mfma_f32_16x16x32_bf16 v[60:63], v[64:67], v[132:135], v[60:63]
	v_mfma_f32_16x16x32_bf16 v[56:59], v[64:67], v[140:143], v[56:59]
	v_mfma_f32_16x16x32_bf16 v[52:55], v[80:83], v[132:135], v[52:55]
	v_mfma_f32_16x16x32_bf16 v[48:51], v[80:83], v[140:143], v[48:51]
	v_mfma_f32_16x16x32_bf16 v[44:47], v[194:197], v[132:135], v[44:47]
	v_mfma_f32_16x16x32_bf16 v[40:43], v[194:197], v[140:143], v[40:43]
	v_mfma_f32_16x16x32_bf16 v[36:39], v[202:205], v[132:135], v[36:39]
	v_mfma_f32_16x16x32_bf16 v[32:35], v[202:205], v[140:143], v[32:35]
	v_mfma_f32_16x16x32_bf16 v[60:63], v[76:79], v[136:139], v[60:63]
	v_mfma_f32_16x16x32_bf16 v[56:59], v[76:79], v[174:177], v[56:59]
	v_mfma_f32_16x16x32_bf16 v[52:55], v[84:87], v[136:139], v[52:55]
	v_mfma_f32_16x16x32_bf16 v[48:51], v[84:87], v[174:177], v[48:51]
	v_mfma_f32_16x16x32_bf16 v[44:47], v[198:201], v[136:139], v[44:47]
	v_mfma_f32_16x16x32_bf16 v[40:43], v[198:201], v[174:177], v[40:43]
	v_mfma_f32_16x16x32_bf16 v[36:39], v[206:209], v[136:139], v[36:39]
	v_mfma_f32_16x16x32_bf16 v[32:35], v[206:209], v[174:177], v[32:35]
	s_setprio 0
	s_setprio 0
	v_mfma_f32_16x16x32_bf16 v[28:31], v[64:67], v[210:213], v[28:31]
	v_mfma_f32_16x16x32_bf16 v[24:27], v[64:67], v[218:221], v[24:27]
	v_mfma_f32_16x16x32_bf16 v[12:15], v[194:197], v[210:213], v[12:15]
	v_mfma_f32_16x16x32_bf16 v[8:11], v[194:197], v[218:221], v[8:11]
	v_mfma_f32_16x16x32_bf16 v[20:23], v[80:83], v[210:213], v[20:23]
	v_mfma_f32_16x16x32_bf16 v[16:19], v[80:83], v[218:221], v[16:19]
	v_mfma_f32_16x16x32_bf16 v[4:7], v[202:205], v[210:213], v[4:7]
	v_mfma_f32_16x16x32_bf16 v[0:3], v[202:205], v[218:221], v[0:3]
	v_mfma_f32_16x16x32_bf16 v[28:31], v[76:79], v[214:217], v[28:31]
	v_mfma_f32_16x16x32_bf16 v[24:27], v[76:79], v[160:163], v[24:27]
	v_mfma_f32_16x16x32_bf16 v[12:15], v[198:201], v[214:217], v[12:15]
	v_mfma_f32_16x16x32_bf16 v[8:11], v[198:201], v[160:163], v[8:11]
	v_mfma_f32_16x16x32_bf16 v[132:135], v[84:87], v[214:217], v[20:23]
	v_mfma_f32_16x16x32_bf16 v[136:139], v[84:87], v[160:163], v[16:19]
	v_mfma_f32_16x16x32_bf16 v[140:143], v[206:209], v[214:217], v[4:7]
	v_mfma_f32_16x16x32_bf16 v[160:163], v[206:209], v[160:163], v[0:3]
	s_setprio 0
	s_barrier
	s_nop 0
	ds_read_b128 v[0:3], v158
	ds_read_b128 v[4:7], v158 offset:1024
	ds_read_b128 v[16:19], v158 offset:2048
	ds_read_b128 v[172:175], v158 offset:3072
	ds_read_b128 v[20:23], v154 offset:32768
	ds_read_b128 v[194:197], v154 offset:33792
	ds_read_b128 v[198:201], v153 offset:32768
	ds_read_b128 v[202:205], v153 offset:33792
	ds_read_b128 v[206:209], v151 offset:32768
	ds_read_b128 v[210:213], v151 offset:33792
	ds_read_b128 v[214:217], v150 offset:32768
	ds_read_b128 v[218:221], v150 offset:33792
	s_waitcnt vmcnt(2)
	s_barrier
; #define LDA(dst, b, h) for (int m = 0; m < 4; ++m) for (int k = 0; k < 2; ++k) \
;     dst[m][k] = *reinterpret_cast<const bf16x8*>((char*)SA(b, h) + lds_byte(wr * 64 + m * 16 + fr, k * 32 + fq * 8))
; #define LDB(dst, b, h) for (int n = 0; n < 2; ++n) for (int k = 0; k < 2; ++k) \
;     dst[n][k] = *reinterpret_cast<const bf16x8*>((char*)SB(b, h) + lds_byte(wc * 32 + n * 16 + fr, k * 32 + fq * 8))
; #define MMA(ai, bj, At_, Bt_) do { __builtin_amdgcn_s_setprio(1); \
;     for (int k = 0; k < 2; ++k) for (int m = 0; m < 4; ++m) for (int n = 0; n < 2; ++n) \
;       acc[ai][bj][m][n] = __builtin_amdgcn_mfma_f32_16x16x32_bf16(At_[m][k], Bt_[n][k], acc[ai][bj][m][n], 0, 0, 0); \
;     __builtin_amdgcn_s_setprio(0); } while (0)
; #define WAIT_V(n) asm volatile("s_waitcnt vmcnt(" #n ")" ::: "memory")
; #define WAIT_L(n) asm volatile("s_waitcnt lgkmcnt(" #n ")" ::: "memory")
; #define BAR __builtin_amdgcn_s_barrier()
; template <int EPI, int lda, int ldb, int N, int K>
; __device__ __forceinline__ void gemm_phase(const u16* __restrict__ A, const u16* __restrict__ Bt, const GemmEpi ep, int wv) {
;     ...
;     { LDB(B0, 1, 0); LDA(At, 1, 0); WAIT_V(2); BAR; WAIT_L(0); MMA(0, 0, At, B0); BAR;
;       LDB(B1, 1, 1); WAIT_V(0); BAR; WAIT_L(0); MMA(0, 1, At, B1); BAR;
;       LDA(At, 1, 1); BAR; WAIT_L(0); MMA(1, 0, At, B0); MMA(1, 1, At, B1); BAR; }
;     if (wr == 0) BAR;
	s_waitcnt lgkmcnt(0)
	s_setprio 0
	s_waitcnt lgkmcnt(0)
	v_mfma_f32_16x16x32_bf16 v[64:67], v[20:23], v[0:3], v[124:127]
	v_mfma_f32_16x16x32_bf16 v[76:79], v[20:23], v[16:19], v[120:123]
	v_mfma_f32_16x16x32_bf16 v[80:83], v[198:201], v[0:3], v[116:119]
	v_mfma_f32_16x16x32_bf16 v[84:87], v[198:201], v[16:19], v[112:115]
	v_mfma_f32_16x16x32_bf16 v[108:111], v[206:209], v[0:3], v[108:111]
	v_mfma_f32_16x16x32_bf16 v[104:107], v[206:209], v[16:19], v[104:107]
	v_mfma_f32_16x16x32_bf16 v[120:123], v[214:217], v[0:3], v[100:103]
	v_mfma_f32_16x16x32_bf16 v[124:127], v[214:217], v[16:19], v[96:99]
	v_mfma_f32_16x16x32_bf16 v[116:119], v[194:197], v[4:7], v[64:67]
	v_mfma_f32_16x16x32_bf16 v[112:115], v[194:197], v[172:175], v[76:79]
	v_mfma_f32_16x16x32_bf16 v[100:103], v[202:205], v[4:7], v[80:83]
	v_mfma_f32_16x16x32_bf16 v[96:99], v[202:205], v[172:175], v[84:87]
	v_mfma_f32_16x16x32_bf16 v[84:87], v[210:213], v[4:7], v[108:111]
	v_mfma_f32_16x16x32_bf16 v[80:83], v[210:213], v[172:175], v[104:107]
	v_mfma_f32_16x16x32_bf16 v[76:79], v[218:221], v[4:7], v[120:123]
	v_mfma_f32_16x16x32_bf16 v[64:67], v[218:221], v[172:175], v[124:127]
	s_setprio 0
	s_barrier
	ds_read_b128 v[222:225], v156
	ds_read_b128 v[226:229], v156 offset:1024
	ds_read_b128 v[230:233], v156 offset:2048
	ds_read_b128 v[156:159], v156 offset:3072
	s_waitcnt vmcnt(0)
	s_barrier
	s_waitcnt lgkmcnt(0)
	s_setprio 0
	s_waitcnt lgkmcnt(0)
	v_mfma_f32_16x16x32_bf16 v[92:95], v[20:23], v[222:225], v[92:95]
	v_mfma_f32_16x16x32_bf16 v[20:23], v[20:23], v[230:233], v[88:91]
	v_mfma_f32_16x16x32_bf16 v[88:91], v[198:201], v[222:225], v[178:181]
	v_mfma_f32_16x16x32_bf16 v[104:107], v[198:201], v[230:233], v[182:185]
	v_mfma_f32_16x16x32_bf16 v[176:179], v[206:209], v[222:225], v[186:189]
	v_mfma_f32_16x16x32_bf16 v[72:75], v[206:209], v[230:233], v[72:75]
	v_mfma_f32_16x16x32_bf16 v[68:71], v[214:217], v[222:225], v[68:71]
	v_mfma_f32_16x16x32_bf16 v[180:183], v[214:217], v[230:233], v[190:193]
	v_mfma_f32_16x16x32_bf16 v[124:127], v[194:197], v[226:229], v[92:95]
	v_mfma_f32_16x16x32_bf16 v[120:123], v[194:197], v[156:159], v[20:23]
	v_mfma_f32_16x16x32_bf16 v[108:111], v[202:205], v[226:229], v[88:91]
	v_mfma_f32_16x16x32_bf16 v[104:107], v[202:205], v[156:159], v[104:107]
	v_mfma_f32_16x16x32_bf16 v[92:95], v[210:213], v[226:229], v[176:179]
	v_mfma_f32_16x16x32_bf16 v[88:91], v[210:213], v[156:159], v[72:75]
	v_mfma_f32_16x16x32_bf16 v[72:75], v[218:221], v[226:229], v[68:71]
	v_mfma_f32_16x16x32_bf16 v[68:71], v[218:221], v[156:159], v[180:183]
	s_setprio 0
	s_barrier
	ds_read_b128 v[176:179], v154 offset:49152
	ds_read_b128 v[180:183], v154 offset:50176
	ds_read_b128 v[184:187], v153 offset:49152
	ds_read_b128 v[188:191], v153 offset:50176
	ds_read_b128 v[192:195], v151 offset:49152
	ds_read_b128 v[196:199], v151 offset:50176
	ds_read_b128 v[200:203], v150 offset:49152
	ds_read_b128 v[204:207], v150 offset:50176
	s_barrier
	s_waitcnt lgkmcnt(0)
	s_setprio 0
	s_waitcnt lgkmcnt(0)
	v_mfma_f32_16x16x32_bf16 v[20:23], v[176:179], v[0:3], v[60:63]
	v_mfma_f32_16x16x32_bf16 v[56:59], v[176:179], v[16:19], v[56:59]
	v_mfma_f32_16x16x32_bf16 v[60:63], v[184:187], v[0:3], v[52:55]
	v_mfma_f32_16x16x32_bf16 v[208:211], v[184:187], v[16:19], v[48:51]
	v_mfma_f32_16x16x32_bf16 v[44:47], v[192:195], v[0:3], v[44:47]
	v_mfma_f32_16x16x32_bf16 v[40:43], v[192:195], v[16:19], v[40:43]
	v_mfma_f32_16x16x32_bf16 v[0:3], v[200:203], v[0:3], v[36:39]
	v_mfma_f32_16x16x32_bf16 v[212:215], v[200:203], v[16:19], v[32:35]
	v_mfma_f32_16x16x32_bf16 v[52:55], v[180:183], v[4:7], v[20:23]
	v_mfma_f32_16x16x32_bf16 v[48:51], v[180:183], v[172:175], v[56:59]
	v_mfma_f32_16x16x32_bf16 v[36:39], v[188:191], v[4:7], v[60:63]
	v_mfma_f32_16x16x32_bf16 v[32:35], v[188:191], v[172:175], v[208:211]
	v_mfma_f32_16x16x32_bf16 v[20:23], v[196:199], v[4:7], v[44:47]
	v_mfma_f32_16x16x32_bf16 v[16:19], v[196:199], v[172:175], v[40:43]
	v_mfma_f32_16x16x32_bf16 v[4:7], v[204:207], v[4:7], v[0:3]
	v_mfma_f32_16x16x32_bf16 v[0:3], v[204:207], v[172:175], v[212:215]
	s_setprio 0
	s_setprio 0
	v_mfma_f32_16x16x32_bf16 v[28:31], v[176:179], v[222:225], v[28:31]
	v_mfma_f32_16x16x32_bf16 v[24:27], v[176:179], v[230:233], v[24:27]
	v_mfma_f32_16x16x32_bf16 v[40:43], v[184:187], v[222:225], v[132:135]
	v_mfma_f32_16x16x32_bf16 v[132:135], v[184:187], v[230:233], v[136:139]
	v_mfma_f32_16x16x32_bf16 v[12:15], v[192:195], v[222:225], v[12:15]
	v_mfma_f32_16x16x32_bf16 v[8:11], v[192:195], v[230:233], v[8:11]
	v_mfma_f32_16x16x32_bf16 v[136:139], v[200:203], v[222:225], v[140:143]
	v_mfma_f32_16x16x32_bf16 v[140:143], v[200:203], v[230:233], v[160:163]
	v_mfma_f32_16x16x32_bf16 v[60:63], v[180:183], v[226:229], v[28:31]
	v_mfma_f32_16x16x32_bf16 v[56:59], v[180:183], v[156:159], v[24:27]
	v_mfma_f32_16x16x32_bf16 v[44:47], v[188:191], v[226:229], v[40:43]
	v_mfma_f32_16x16x32_bf16 v[40:43], v[188:191], v[156:159], v[132:135]
	v_mfma_f32_16x16x32_bf16 v[28:31], v[196:199], v[226:229], v[12:15]
	v_mfma_f32_16x16x32_bf16 v[24:27], v[196:199], v[156:159], v[8:11]
	v_mfma_f32_16x16x32_bf16 v[12:15], v[204:207], v[226:229], v[136:139]
	v_mfma_f32_16x16x32_bf16 v[8:11], v[204:207], v[156:159], v[140:143]
	s_setprio 0
	v_cmp_gt_u32_e32 vcc, s46, v147
	s_barrier
	s_and_saveexec_b64 s[28:29], vcc
	s_cbranch_execz .LBB0_1627
	s_barrier
